# v066 + GEMM loops: saddr-form LDS-DMA loads (45 VALU adds removed), template lgkmcnt(8) pacing waits removed, vmcnt(6) split into vmcnt(8)+vmcnt(10) (one more phase for every DMA load to land)
# speedup vs baseline: 1.0069x; 1.0046x over previous
.LBB0_329:
	s_add_u32 s19, s16, 0xfff80080
	s_addc_u32 s26, s17, -1
	s_add_i32 s31, 0, 0x10000
	v_add_u32_e32 v2, s31, v158
	ds_read_b128 v[132:135], v2
	ds_read_b128 v[148:151], v2 offset:1024
	ds_read_b128 v[152:155], v2 offset:2048
	ds_read_b128 v[160:163], v2 offset:3072
	s_cmp_eq_u32 s15, 28
	s_cselect_b32 s39, s37, s26
	s_cselect_b32 s38, s36, s19
	s_cselect_b32 s27, s49, s14
	s_cselect_b32 s26, s48, s10
	s_add_i32 m0, s6, 0xc000
	ds_read_b128 v[164:167], v159
	ds_read_b128 v[168:171], v159 offset:1024
	ds_read_b128 v[172:175], v159 offset:2048
	ds_read_b128 v[176:179], v159 offset:3072
	ds_read_b128 v[180:183], v159 offset:4096
	ds_read_b128 v[184:187], v159 offset:5120
	ds_read_b128 v[188:191], v159 offset:6144
	ds_read_b128 v[192:195], v159 offset:7168
	global_load_lds_dwordx4 v144, s[16:17]
	s_add_i32 m0, s6, 0xe000
	s_nop 0
	global_load_lds_dwordx4 v146, s[16:17]
	s_barrier
	s_waitcnt lgkmcnt(0)
	v_mfma_f32_16x16x32_f16 v[128:131], v[132:135], v[164:167], v[128:131]
	v_mfma_f32_16x16x32_f16 v[124:127], v[152:155], v[164:167], v[124:127]
	v_mfma_f32_16x16x32_f16 v[112:115], v[132:135], v[172:175], v[112:115]
	v_mfma_f32_16x16x32_f16 v[108:111], v[152:155], v[172:175], v[108:111]
	v_mfma_f32_16x16x32_f16 v[96:99], v[132:135], v[180:183], v[96:99]
	v_mfma_f32_16x16x32_f16 v[92:95], v[152:155], v[180:183], v[92:95]
	v_mfma_f32_16x16x32_f16 v[80:83], v[132:135], v[188:191], v[80:83]
	v_mfma_f32_16x16x32_f16 v[76:79], v[152:155], v[188:191], v[76:79]
	v_mfma_f32_16x16x32_f16 v[128:131], v[148:151], v[168:171], v[128:131]
	v_mfma_f32_16x16x32_f16 v[124:127], v[160:163], v[168:171], v[124:127]
	v_mfma_f32_16x16x32_f16 v[112:115], v[148:151], v[176:179], v[112:115]
	v_mfma_f32_16x16x32_f16 v[108:111], v[160:163], v[176:179], v[108:111]
	v_mfma_f32_16x16x32_f16 v[96:99], v[148:151], v[184:187], v[96:99]
	v_mfma_f32_16x16x32_f16 v[92:95], v[160:163], v[184:187], v[92:95]
	v_mfma_f32_16x16x32_f16 v[80:83], v[148:151], v[192:195], v[80:83]
	v_mfma_f32_16x16x32_f16 v[76:79], v[160:163], v[192:195], v[76:79]
	s_barrier
	s_add_i32 s19, 0, 0x14000
	s_add_i32 s31, s31, s5
	v_add_u32_e32 v2, s19, v158
	v_lshl_add_u64 v[214:215], s[26:27], 0, v[138:139]
	s_mov_b32 m0, s31
	ds_read_b128 v[196:199], v2
	ds_read_b128 v[200:203], v2 offset:1024
	ds_read_b128 v[206:209], v2 offset:2048
	ds_read_b128 v[210:213], v2 offset:3072
	global_load_lds_dwordx4 v[214:215], off
	v_lshl_add_u64 v[216:217], s[26:27], 0, v[142:143]
	s_add_i32 m0, s31, 0x2000
	s_nop 0
	global_load_lds_dwordx4 v[216:217], off
	s_waitcnt vmcnt(10)
	s_barrier
	s_waitcnt lgkmcnt(0)
	v_mfma_f32_16x16x32_f16 v[120:123], v[196:199], v[164:167], v[120:123]
	v_mfma_f32_16x16x32_f16 v[116:119], v[206:209], v[164:167], v[116:119]
	v_mfma_f32_16x16x32_f16 v[104:107], v[196:199], v[172:175], v[104:107]
	v_mfma_f32_16x16x32_f16 v[100:103], v[206:209], v[172:175], v[100:103]
	v_mfma_f32_16x16x32_f16 v[88:91], v[196:199], v[180:183], v[88:91]
	v_mfma_f32_16x16x32_f16 v[84:87], v[206:209], v[180:183], v[84:87]
	v_mfma_f32_16x16x32_f16 v[72:75], v[196:199], v[188:191], v[72:75]
	v_mfma_f32_16x16x32_f16 v[68:71], v[206:209], v[188:191], v[68:71]
	v_mfma_f32_16x16x32_f16 v[120:123], v[200:203], v[168:171], v[120:123]
	v_mfma_f32_16x16x32_f16 v[116:119], v[210:213], v[168:171], v[116:119]
	v_mfma_f32_16x16x32_f16 v[104:107], v[200:203], v[176:179], v[104:107]
	v_mfma_f32_16x16x32_f16 v[100:103], v[210:213], v[176:179], v[100:103]
	v_mfma_f32_16x16x32_f16 v[88:91], v[200:203], v[184:187], v[88:91]
	v_mfma_f32_16x16x32_f16 v[84:87], v[210:213], v[184:187], v[84:87]
	v_mfma_f32_16x16x32_f16 v[72:75], v[200:203], v[192:195], v[72:75]
	v_mfma_f32_16x16x32_f16 v[68:71], v[210:213], v[192:195], v[68:71]
	s_mov_b32 m0, s6
	v_lshl_add_u64 v[218:219], s[38:39], 0, v[136:137]
	s_barrier
	ds_read_b128 v[164:167], v159 offset:16384
	ds_read_b128 v[168:171], v159 offset:17408
	ds_read_b128 v[172:175], v159 offset:18432
	ds_read_b128 v[176:179], v159 offset:19456
	ds_read_b128 v[180:183], v159 offset:20480
	ds_read_b128 v[184:187], v159 offset:21504
	ds_read_b128 v[188:191], v159 offset:22528
	ds_read_b128 v[192:195], v159 offset:23552
	global_load_lds_dwordx4 v[218:219], off
	v_lshl_add_u64 v[220:221], s[38:39], 0, v[140:141]
	s_mov_b32 m0, s7
	s_nop 0
	global_load_lds_dwordx4 v[220:221], off
	s_barrier
	s_waitcnt lgkmcnt(0)
	v_mfma_f32_16x16x32_f16 v[64:67], v[132:135], v[164:167], v[64:67]
	v_mfma_f32_16x16x32_f16 v[60:63], v[152:155], v[164:167], v[60:63]
	v_mfma_f32_16x16x32_f16 v[48:51], v[132:135], v[172:175], v[48:51]
	v_mfma_f32_16x16x32_f16 v[44:47], v[152:155], v[172:175], v[44:47]
	v_mfma_f32_16x16x32_f16 v[32:35], v[132:135], v[180:183], v[32:35]
	v_mfma_f32_16x16x32_f16 v[28:31], v[152:155], v[180:183], v[28:31]
	v_mfma_f32_16x16x32_f16 v[16:19], v[132:135], v[188:191], v[16:19]
	v_mfma_f32_16x16x32_f16 v[12:15], v[152:155], v[188:191], v[12:15]
	v_mfma_f32_16x16x32_f16 v[64:67], v[148:151], v[168:171], v[64:67]
	v_mfma_f32_16x16x32_f16 v[60:63], v[160:163], v[168:171], v[60:63]
	v_mfma_f32_16x16x32_f16 v[48:51], v[148:151], v[176:179], v[48:51]
	v_mfma_f32_16x16x32_f16 v[44:47], v[160:163], v[176:179], v[44:47]
	v_mfma_f32_16x16x32_f16 v[32:35], v[148:151], v[184:187], v[32:35]
	v_mfma_f32_16x16x32_f16 v[28:31], v[160:163], v[184:187], v[28:31]
	v_mfma_f32_16x16x32_f16 v[16:19], v[148:151], v[192:195], v[16:19]
	v_mfma_f32_16x16x32_f16 v[12:15], v[160:163], v[192:195], v[12:15]
	s_barrier
	s_add_u32 s42, s26, 0x80000
	s_addc_u32 s43, s27, 0
	s_add_i32 s19, s19, s5
	s_mov_b32 m0, s19
	s_nop 0
	global_load_lds_dwordx4 v138, s[42:43]
	s_add_i32 m0, s19, 0x2000
	s_nop 0
	global_load_lds_dwordx4 v142, s[42:43]
	s_waitcnt vmcnt(8)
	s_barrier
	v_mfma_f32_16x16x32_f16 v[56:59], v[196:199], v[164:167], v[56:59]
	v_mfma_f32_16x16x32_f16 v[52:55], v[206:209], v[164:167], v[52:55]
	v_mfma_f32_16x16x32_f16 v[40:43], v[196:199], v[172:175], v[40:43]
	v_mfma_f32_16x16x32_f16 v[36:39], v[206:209], v[172:175], v[36:39]
	v_mfma_f32_16x16x32_f16 v[24:27], v[196:199], v[180:183], v[24:27]
	v_mfma_f32_16x16x32_f16 v[20:23], v[206:209], v[180:183], v[20:23]
	v_mfma_f32_16x16x32_f16 v[8:11], v[196:199], v[188:191], v[8:11]
	v_mfma_f32_16x16x32_f16 v[4:7], v[206:209], v[188:191], v[4:7]
	v_mfma_f32_16x16x32_f16 v[56:59], v[200:203], v[168:171], v[56:59]
	v_mfma_f32_16x16x32_f16 v[52:55], v[210:213], v[168:171], v[52:55]
	v_mfma_f32_16x16x32_f16 v[40:43], v[200:203], v[176:179], v[40:43]
	v_mfma_f32_16x16x32_f16 v[36:39], v[210:213], v[176:179], v[36:39]
	v_mfma_f32_16x16x32_f16 v[24:27], v[200:203], v[184:187], v[24:27]
	v_mfma_f32_16x16x32_f16 v[20:23], v[210:213], v[184:187], v[20:23]
	v_mfma_f32_16x16x32_f16 v[8:11], v[200:203], v[192:195], v[8:11]
	v_mfma_f32_16x16x32_f16 v[4:7], v[210:213], v[192:195], v[4:7]
	s_add_i32 s19, 0, 0x18000
	v_add_u32_e32 v2, s19, v158
	s_barrier
	ds_read_b128 v[132:135], v2
	ds_read_b128 v[148:151], v2 offset:1024
	ds_read_b128 v[152:155], v2 offset:2048
	ds_read_b128 v[160:163], v2 offset:3072
	s_add_u32 s38, s38, 0x80000
	s_addc_u32 s39, s39, 0
	s_mov_b32 m0, s8
	ds_read_b128 v[164:167], v159 offset:32768
	ds_read_b128 v[168:171], v159 offset:33792
	ds_read_b128 v[172:175], v159 offset:34816
	ds_read_b128 v[176:179], v159 offset:35840
	ds_read_b128 v[180:183], v159 offset:36864
	ds_read_b128 v[184:187], v159 offset:37888
	ds_read_b128 v[188:191], v159 offset:38912
	ds_read_b128 v[192:195], v159 offset:39936
	global_load_lds_dwordx4 v136, s[38:39]
	s_mov_b32 m0, s9
	s_nop 0
	global_load_lds_dwordx4 v140, s[38:39]
	s_barrier
	s_waitcnt lgkmcnt(0)
	v_mfma_f32_16x16x32_f16 v[128:131], v[132:135], v[164:167], v[128:131]
	v_mfma_f32_16x16x32_f16 v[124:127], v[152:155], v[164:167], v[124:127]
	v_mfma_f32_16x16x32_f16 v[112:115], v[132:135], v[172:175], v[112:115]
	v_mfma_f32_16x16x32_f16 v[108:111], v[152:155], v[172:175], v[108:111]
	v_mfma_f32_16x16x32_f16 v[96:99], v[132:135], v[180:183], v[96:99]
	v_mfma_f32_16x16x32_f16 v[92:95], v[152:155], v[180:183], v[92:95]
	v_mfma_f32_16x16x32_f16 v[80:83], v[132:135], v[188:191], v[80:83]
	v_mfma_f32_16x16x32_f16 v[76:79], v[152:155], v[188:191], v[76:79]
	v_mfma_f32_16x16x32_f16 v[128:131], v[148:151], v[168:171], v[128:131]
	v_mfma_f32_16x16x32_f16 v[124:127], v[160:163], v[168:171], v[124:127]
	v_mfma_f32_16x16x32_f16 v[112:115], v[148:151], v[176:179], v[112:115]
	v_mfma_f32_16x16x32_f16 v[108:111], v[160:163], v[176:179], v[108:111]
	v_mfma_f32_16x16x32_f16 v[96:99], v[148:151], v[184:187], v[96:99]
	v_mfma_f32_16x16x32_f16 v[92:95], v[160:163], v[184:187], v[92:95]
	v_mfma_f32_16x16x32_f16 v[80:83], v[148:151], v[192:195], v[80:83]
	v_mfma_f32_16x16x32_f16 v[76:79], v[160:163], v[192:195], v[76:79]
	s_barrier
	s_add_i32 s31, 0, 0x1c000
	s_add_i32 s19, s19, s5
	v_add_u32_e32 v2, s31, v158
	v_lshl_add_u64 v[214:215], v[214:215], 0, s[88:89]
	s_mov_b32 m0, s19
	ds_read_b128 v[196:199], v2
	ds_read_b128 v[200:203], v2 offset:1024
	ds_read_b128 v[206:209], v2 offset:2048
	ds_read_b128 v[210:213], v2 offset:3072
	global_load_lds_dwordx4 v[214:215], off
	v_lshl_add_u64 v[214:215], v[216:217], 0, s[88:89]
	s_add_i32 m0, s19, 0x2000
	s_nop 0
	global_load_lds_dwordx4 v[214:215], off
	s_waitcnt vmcnt(10)
	s_barrier
	s_waitcnt lgkmcnt(0)
	v_mfma_f32_16x16x32_f16 v[120:123], v[196:199], v[164:167], v[120:123]
	v_mfma_f32_16x16x32_f16 v[116:119], v[206:209], v[164:167], v[116:119]
	v_mfma_f32_16x16x32_f16 v[104:107], v[196:199], v[172:175], v[104:107]
	v_mfma_f32_16x16x32_f16 v[100:103], v[206:209], v[172:175], v[100:103]
	v_mfma_f32_16x16x32_f16 v[88:91], v[196:199], v[180:183], v[88:91]
	v_mfma_f32_16x16x32_f16 v[84:87], v[206:209], v[180:183], v[84:87]
	v_mfma_f32_16x16x32_f16 v[72:75], v[196:199], v[188:191], v[72:75]
	v_mfma_f32_16x16x32_f16 v[68:71], v[206:209], v[188:191], v[68:71]
	v_mfma_f32_16x16x32_f16 v[120:123], v[200:203], v[168:171], v[120:123]
	v_mfma_f32_16x16x32_f16 v[116:119], v[210:213], v[168:171], v[116:119]
	v_mfma_f32_16x16x32_f16 v[104:107], v[200:203], v[176:179], v[104:107]
	v_mfma_f32_16x16x32_f16 v[100:103], v[210:213], v[176:179], v[100:103]
	v_mfma_f32_16x16x32_f16 v[88:91], v[200:203], v[184:187], v[88:91]
	v_mfma_f32_16x16x32_f16 v[84:87], v[210:213], v[184:187], v[84:87]
	v_mfma_f32_16x16x32_f16 v[72:75], v[200:203], v[192:195], v[72:75]
	v_mfma_f32_16x16x32_f16 v[68:71], v[210:213], v[192:195], v[68:71]
	s_mov_b32 m0, s30
	v_lshl_add_u64 v[214:215], v[218:219], 0, s[88:89]
	s_barrier
	ds_read_b128 v[164:167], v159 offset:49152
	ds_read_b128 v[168:171], v159 offset:50176
	ds_read_b128 v[172:175], v159 offset:51200
	ds_read_b128 v[176:179], v159 offset:52224
	ds_read_b128 v[180:183], v159 offset:53248
	ds_read_b128 v[184:187], v159 offset:54272
	ds_read_b128 v[188:191], v159 offset:55296
	ds_read_b128 v[192:195], v159 offset:56320
	global_load_lds_dwordx4 v[214:215], off
	v_lshl_add_u64 v[214:215], v[220:221], 0, s[88:89]
	s_mov_b32 m0, s52
	s_nop 0
	global_load_lds_dwordx4 v[214:215], off
	s_barrier
	s_waitcnt lgkmcnt(0)
	v_mfma_f32_16x16x32_f16 v[64:67], v[132:135], v[164:167], v[64:67]
	v_mfma_f32_16x16x32_f16 v[60:63], v[152:155], v[164:167], v[60:63]
	v_mfma_f32_16x16x32_f16 v[48:51], v[132:135], v[172:175], v[48:51]
	v_mfma_f32_16x16x32_f16 v[44:47], v[152:155], v[172:175], v[44:47]
	v_mfma_f32_16x16x32_f16 v[32:35], v[132:135], v[180:183], v[32:35]
	v_mfma_f32_16x16x32_f16 v[28:31], v[152:155], v[180:183], v[28:31]
	v_mfma_f32_16x16x32_f16 v[16:19], v[132:135], v[188:191], v[16:19]
	v_mfma_f32_16x16x32_f16 v[12:15], v[152:155], v[188:191], v[12:15]
	v_mfma_f32_16x16x32_f16 v[64:67], v[148:151], v[168:171], v[64:67]
	v_mfma_f32_16x16x32_f16 v[60:63], v[160:163], v[168:171], v[60:63]
	v_mfma_f32_16x16x32_f16 v[48:51], v[148:151], v[176:179], v[48:51]
	v_mfma_f32_16x16x32_f16 v[44:47], v[160:163], v[176:179], v[44:47]
	v_mfma_f32_16x16x32_f16 v[32:35], v[148:151], v[184:187], v[32:35]
	v_mfma_f32_16x16x32_f16 v[28:31], v[160:163], v[184:187], v[28:31]
	v_mfma_f32_16x16x32_f16 v[16:19], v[148:151], v[192:195], v[16:19]
	v_mfma_f32_16x16x32_f16 v[12:15], v[160:163], v[192:195], v[12:15]
	s_barrier
	s_add_u32 s26, s26, 0x80080
	s_addc_u32 s27, s27, 0
	s_add_i32 s19, s31, s5
	s_mov_b32 m0, s19
	s_nop 0
	global_load_lds_dwordx4 v138, s[26:27]
	s_add_i32 m0, s19, 0x2000
	s_nop 0
	global_load_lds_dwordx4 v142, s[26:27]
	s_waitcnt vmcnt(8)
	s_barrier
	v_mfma_f32_16x16x32_f16 v[56:59], v[196:199], v[164:167], v[56:59]
	v_mfma_f32_16x16x32_f16 v[52:55], v[206:209], v[164:167], v[52:55]
	v_mfma_f32_16x16x32_f16 v[40:43], v[196:199], v[172:175], v[40:43]
	v_mfma_f32_16x16x32_f16 v[36:39], v[206:209], v[172:175], v[36:39]
	v_mfma_f32_16x16x32_f16 v[24:27], v[196:199], v[180:183], v[24:27]
	v_mfma_f32_16x16x32_f16 v[20:23], v[206:209], v[180:183], v[20:23]
	v_mfma_f32_16x16x32_f16 v[8:11], v[196:199], v[188:191], v[8:11]
	v_mfma_f32_16x16x32_f16 v[4:7], v[206:209], v[188:191], v[4:7]
	v_mfma_f32_16x16x32_f16 v[56:59], v[200:203], v[168:171], v[56:59]
	v_mfma_f32_16x16x32_f16 v[52:55], v[210:213], v[168:171], v[52:55]
	v_mfma_f32_16x16x32_f16 v[40:43], v[200:203], v[176:179], v[40:43]
	v_mfma_f32_16x16x32_f16 v[36:39], v[210:213], v[176:179], v[36:39]
	v_mfma_f32_16x16x32_f16 v[24:27], v[200:203], v[184:187], v[24:27]
	v_mfma_f32_16x16x32_f16 v[20:23], v[210:213], v[184:187], v[20:23]
	v_mfma_f32_16x16x32_f16 v[8:11], v[200:203], v[192:195], v[8:11]
	v_mfma_f32_16x16x32_f16 v[4:7], v[210:213], v[192:195], v[4:7]
	s_add_i32 s15, s15, 2
	s_add_u32 s16, s16, 0x100
	s_addc_u32 s17, s17, 0
	s_add_u32 s10, s10, 0x100
	s_addc_u32 s14, s14, 0
	s_cmp_gt_u32 s15, 29
	s_barrier
	s_cbranch_scc0 .LBB0_329
	s_lshl_b32 s19, s11, 8
	v_mov_b32_e32 v2, v156
	s_add_i32 s10, s19, s12
	v_mov_b32_e32 v132, v157
	v_add_u32_e32 v161, s10, v2
	s_lshl_b32 s10, s29, 8
	s_or_b32 s14, s10, s13
	s_cmp_gt_i32 s29, 1
	v_lshlrev_b32_e32 v154, 3, v132
	v_add_u32_e32 v160, s14, v154
	s_cselect_b64 s[16:17], -1, 0
	s_add_i32 s14, s29, -14
	s_cmp_gt_u32 s14, 5
	s_cselect_b64 s[38:39], -1, 0
	s_sub_i32 s14, s29, 20
	s_cmp_gt_u32 s14, 23
	s_cselect_b64 s[50:51], -1, 0
	s_cmp_eq_u32 s29, 44
	s_mul_i32 s14, s29, 0x42
	s_cselect_b64 s[42:43], -1, 0
	s_addk_i32 s14, 0xfad8
	s_ashr_i32 s15, s14, 31
	s_ashr_i32 s26, s11, 31
	s_add_u32 s14, s14, s11
	s_addc_u32 s15, s15, s26
	v_lshlrev_b32_e32 v133, 7, v2
	s_lshl_b64 s[26:27], s[14:15], 17
	v_and_b32_e32 v132, 0xffffe000, v161
	v_and_b32_e32 v162, 0x1f80, v133
	v_bfe_u32 v133, v161, 6, 7
	s_movk_i32 s14, 0x4000
	v_or3_b32 v132, v132, v133, v162
	v_cmp_gt_i32_e32 vcc, s14, v161
	s_sub_i32 s29, s10, s19
	s_addk_i32 s29, 0xf200
	v_cndmask_b32_e32 v132, v161, v132, vcc
	v_mad_i64_i32 v[152:153], s[14:15], v132, s33, 0
	v_add_u32_e32 v132, s12, v2
	v_ashrrev_i32_e32 v133, 31, v132
	v_lshlrev_b64 v[150:151], 9, v[132:133]
	v_add_u32_e32 v132, s29, v161
	s_mov_b32 s14, 0x8400
	v_mad_i64_i32 v[148:149], s[14:15], v132, s14, 0
	s_sub_i32 s11, s19, s10
	v_cvt_pk_f16_f32 v135, v126, v127
	v_cvt_pk_f16_f32 v134, v124, v125
	v_cvt_pk_f16_f32 v133, v130, v131
	v_cvt_pk_f16_f32 v132, v128, v129
	s_mov_b64 s[14:15], -1
	s_and_b64 vcc, exec, s[16:17]
	s_cbranch_vccz .LBB0_340
	s_and_b64 vcc, exec, s[38:39]
	s_cbranch_vccz .LBB0_337
	s_and_b64 vcc, exec, s[50:51]
	s_cbranch_vccz .LBB0_334
	v_add_u32_e32 v155, 0xffffe200, v160
	v_cndmask_b32_e64 v166, v160, v155, s[42:43]
	v_lshl_add_u64 v[164:165], s[22:23], 0, v[152:153]
	v_ashrrev_i32_e32 v167, 31, v166
	v_lshl_add_u64 v[164:165], v[166:167], 1, v[164:165]
	global_store_dwordx4 v[164:165], v[132:135], off
	s_mov_b64 s[14:15], 0

.LBB0_885:
	s_add_i32 s37, 0, 0x10000
	v_add_u32_e32 v216, s37, v12
	ds_read_b128 v[14:17], v216
	ds_read_b128 v[18:21], v216 offset:1024
	ds_read_b128 v[22:25], v216 offset:2048
	ds_read_b128 v[26:29], v216 offset:3072
	s_add_u32 s30, s38, 0x400080
	s_addc_u32 s31, s39, 0
	s_add_i32 s42, s6, 0xc000
	v_lshl_add_u64 v[62:63], s[30:31], 0, v[8:9]
	s_mov_b32 m0, s42
	s_add_i32 s17, s6, 0xe000
	ds_read_b128 v[30:33], v13
	ds_read_b128 v[34:37], v13 offset:1024
	ds_read_b128 v[38:41], v13 offset:2048
	ds_read_b128 v[42:45], v13 offset:3072
	ds_read_b128 v[46:49], v13 offset:4096
	ds_read_b128 v[50:53], v13 offset:5120
	ds_read_b128 v[54:57], v13 offset:6144
	ds_read_b128 v[58:61], v13 offset:7168
	global_load_lds_dwordx4 v[62:63], off
	v_lshl_add_u64 v[62:63], s[30:31], 0, v[6:7]
	s_mov_b32 m0, s17
	s_nop 0
	global_load_lds_dwordx4 v[62:63], off
	s_barrier
	s_waitcnt lgkmcnt(0)
	v_mfma_f32_16x16x32_f16 v[62:65], v[14:17], v[30:33], 0
	v_mfma_f32_16x16x32_f16 v[66:69], v[22:25], v[30:33], 0
	v_mfma_f32_16x16x32_f16 v[70:73], v[14:17], v[38:41], 0
	v_mfma_f32_16x16x32_f16 v[74:77], v[22:25], v[38:41], 0
	v_mfma_f32_16x16x32_f16 v[78:81], v[14:17], v[46:49], 0
	v_mfma_f32_16x16x32_f16 v[82:85], v[22:25], v[46:49], 0
	v_mfma_f32_16x16x32_f16 v[86:89], v[14:17], v[54:57], 0
	v_mfma_f32_16x16x32_f16 v[90:93], v[22:25], v[54:57], 0
	v_mfma_f32_16x16x32_f16 v[62:65], v[18:21], v[34:37], v[62:65]
	v_mfma_f32_16x16x32_f16 v[66:69], v[26:29], v[34:37], v[66:69]
	v_mfma_f32_16x16x32_f16 v[70:73], v[18:21], v[42:45], v[70:73]
	v_mfma_f32_16x16x32_f16 v[74:77], v[26:29], v[42:45], v[74:77]
	v_mfma_f32_16x16x32_f16 v[78:81], v[18:21], v[50:53], v[78:81]
	v_mfma_f32_16x16x32_f16 v[82:85], v[26:29], v[50:53], v[82:85]
	v_mfma_f32_16x16x32_f16 v[86:89], v[18:21], v[58:61], v[86:89]
	v_mfma_f32_16x16x32_f16 v[90:93], v[26:29], v[58:61], v[90:93]
	s_barrier
	s_add_i32 s43, 0, 0x14000
	v_lshl_add_u64 v[202:203], s[40:41], 0, v[2:3]
	s_mov_b64 s[44:45], 0x100
	s_add_i32 s37, s37, s5
	v_add_u32_e32 v217, s43, v12
	v_lshl_add_u64 v[110:111], v[202:203], 0, s[44:45]
	s_mov_b32 m0, s37
	v_lshl_add_u64 v[210:211], s[40:41], 0, v[4:5]
	s_add_i32 s30, s37, 0x2000
	ds_read_b128 v[94:97], v217
	ds_read_b128 v[98:101], v217 offset:1024
	ds_read_b128 v[102:105], v217 offset:2048
	ds_read_b128 v[106:109], v217 offset:3072
	global_load_lds_dwordx4 v[110:111], off
	v_lshl_add_u64 v[110:111], v[210:211], 0, s[44:45]
	s_mov_b32 m0, s30
	s_nop 0
	global_load_lds_dwordx4 v[110:111], off
	s_barrier
	s_waitcnt lgkmcnt(0)
	v_mfma_f32_16x16x32_f16 v[110:113], v[94:97], v[30:33], 0
	v_mfma_f32_16x16x32_f16 v[30:33], v[102:105], v[30:33], 0
	v_mfma_f32_16x16x32_f16 v[110:113], v[98:101], v[34:37], v[110:113]
	v_mfma_f32_16x16x32_f16 v[30:33], v[106:109], v[34:37], v[30:33]
	v_mfma_f32_16x16x32_f16 v[34:37], v[94:97], v[38:41], 0
	v_mfma_f32_16x16x32_f16 v[38:41], v[102:105], v[38:41], 0
	v_mfma_f32_16x16x32_f16 v[34:37], v[98:101], v[42:45], v[34:37]
	v_mfma_f32_16x16x32_f16 v[38:41], v[106:109], v[42:45], v[38:41]
	v_mfma_f32_16x16x32_f16 v[42:45], v[94:97], v[46:49], 0
	v_mfma_f32_16x16x32_f16 v[46:49], v[102:105], v[46:49], 0
	v_mfma_f32_16x16x32_f16 v[42:45], v[98:101], v[50:53], v[42:45]
	v_mfma_f32_16x16x32_f16 v[46:49], v[106:109], v[50:53], v[46:49]
	v_mfma_f32_16x16x32_f16 v[50:53], v[94:97], v[54:57], 0
	v_mfma_f32_16x16x32_f16 v[54:57], v[102:105], v[54:57], 0
	v_mfma_f32_16x16x32_f16 v[50:53], v[98:101], v[58:61], v[50:53]
	v_mfma_f32_16x16x32_f16 v[54:57], v[106:109], v[58:61], v[54:57]
	v_lshl_add_u64 v[212:213], s[38:39], 0, v[8:9]
	s_mov_b32 m0, s6
	v_lshl_add_u64 v[142:143], v[212:213], 0, s[44:45]
	v_lshl_add_u64 v[214:215], s[38:39], 0, v[6:7]
	s_barrier
	ds_read_b128 v[58:61], v13 offset:16384
	ds_read_b128 v[114:117], v13 offset:17408
	ds_read_b128 v[118:121], v13 offset:18432
	ds_read_b128 v[122:125], v13 offset:19456
	ds_read_b128 v[126:129], v13 offset:20480
	ds_read_b128 v[130:133], v13 offset:21504
	ds_read_b128 v[134:137], v13 offset:22528
	ds_read_b128 v[138:141], v13 offset:23552
	global_load_lds_dwordx4 v[142:143], off
	v_lshl_add_u64 v[142:143], v[214:215], 0, s[44:45]
	s_mov_b32 m0, s7
	s_nop 0
	global_load_lds_dwordx4 v[142:143], off
	s_barrier
	s_waitcnt lgkmcnt(0)
	v_mfma_f32_16x16x32_f16 v[142:145], v[14:17], v[58:61], 0
	v_mfma_f32_16x16x32_f16 v[150:153], v[14:17], v[118:121], 0
	v_mfma_f32_16x16x32_f16 v[158:161], v[14:17], v[126:129], 0
	v_mfma_f32_16x16x32_f16 v[14:17], v[14:17], v[134:137], 0
	v_mfma_f32_16x16x32_f16 v[142:145], v[18:21], v[114:117], v[142:145]
	v_mfma_f32_16x16x32_f16 v[146:149], v[22:25], v[58:61], 0
	v_mfma_f32_16x16x32_f16 v[150:153], v[18:21], v[122:125], v[150:153]
	v_mfma_f32_16x16x32_f16 v[154:157], v[22:25], v[118:121], 0
	v_mfma_f32_16x16x32_f16 v[158:161], v[18:21], v[130:133], v[158:161]
	v_mfma_f32_16x16x32_f16 v[162:165], v[22:25], v[126:129], 0
	v_mfma_f32_16x16x32_f16 v[14:17], v[18:21], v[138:141], v[14:17]
	v_mfma_f32_16x16x32_f16 v[18:21], v[22:25], v[134:137], 0
	v_mfma_f32_16x16x32_f16 v[146:149], v[26:29], v[114:117], v[146:149]
	v_mfma_f32_16x16x32_f16 v[154:157], v[26:29], v[122:125], v[154:157]
	v_mfma_f32_16x16x32_f16 v[162:165], v[26:29], v[130:133], v[162:165]
	v_mfma_f32_16x16x32_f16 v[18:21], v[26:29], v[138:141], v[18:21]
	s_barrier
	s_add_u32 s44, s40, 0x10100
	s_addc_u32 s45, s41, 0
	s_add_i32 s43, s43, s5
	v_lshl_add_u64 v[22:23], s[44:45], 0, v[2:3]
	s_mov_b32 m0, s43
	s_add_i32 s31, s43, 0x2000
	global_load_lds_dwordx4 v[22:23], off
	v_lshl_add_u64 v[22:23], s[44:45], 0, v[4:5]
	s_mov_b32 m0, s31
	s_nop 0
	global_load_lds_dwordx4 v[22:23], off
	s_waitcnt vmcnt(6)
	s_barrier
	v_mfma_f32_16x16x32_f16 v[22:25], v[94:97], v[58:61], 0
	v_mfma_f32_16x16x32_f16 v[26:29], v[102:105], v[58:61], 0
	v_mfma_f32_16x16x32_f16 v[22:25], v[98:101], v[114:117], v[22:25]
	v_mfma_f32_16x16x32_f16 v[26:29], v[106:109], v[114:117], v[26:29]
	v_mfma_f32_16x16x32_f16 v[58:61], v[94:97], v[118:121], 0
	v_mfma_f32_16x16x32_f16 v[114:117], v[102:105], v[118:121], 0
	v_mfma_f32_16x16x32_f16 v[118:121], v[94:97], v[126:129], 0
	v_mfma_f32_16x16x32_f16 v[94:97], v[94:97], v[134:137], 0
	v_mfma_f32_16x16x32_f16 v[58:61], v[98:101], v[122:125], v[58:61]
	v_mfma_f32_16x16x32_f16 v[114:117], v[106:109], v[122:125], v[114:117]
	v_mfma_f32_16x16x32_f16 v[118:121], v[98:101], v[130:133], v[118:121]
	v_mfma_f32_16x16x32_f16 v[122:125], v[102:105], v[126:129], 0
	v_mfma_f32_16x16x32_f16 v[94:97], v[98:101], v[138:141], v[94:97]
	v_mfma_f32_16x16x32_f16 v[98:101], v[102:105], v[134:137], 0
	v_mfma_f32_16x16x32_f16 v[122:125], v[106:109], v[130:133], v[122:125]
	v_mfma_f32_16x16x32_f16 v[98:101], v[106:109], v[138:141], v[98:101]
	s_add_i32 s46, 0, 0x18000
	v_add_u32_e32 v218, s46, v12
	s_barrier
	ds_read_b128 v[102:105], v218
	ds_read_b128 v[106:109], v218 offset:1024
	ds_read_b128 v[126:129], v218 offset:2048
	ds_read_b128 v[130:133], v218 offset:3072
	s_add_u32 s44, s38, 0x400100
	s_addc_u32 s45, s39, 0
	s_mov_b32 m0, s8
	v_lshl_add_u64 v[190:191], s[44:45], 0, v[8:9]
	ds_read_b128 v[134:137], v13 offset:32768
	ds_read_b128 v[138:141], v13 offset:33792
	ds_read_b128 v[166:169], v13 offset:34816
	ds_read_b128 v[170:173], v13 offset:35840
	ds_read_b128 v[174:177], v13 offset:36864
	ds_read_b128 v[178:181], v13 offset:37888
	ds_read_b128 v[182:185], v13 offset:38912
	ds_read_b128 v[186:189], v13 offset:39936
	global_load_lds_dwordx4 v[190:191], off
	v_lshl_add_u64 v[190:191], s[44:45], 0, v[6:7]
	s_mov_b32 m0, s9
	s_nop 0
	global_load_lds_dwordx4 v[190:191], off
	s_barrier
	s_waitcnt lgkmcnt(0)
	v_mfma_f32_16x16x32_f16 v[62:65], v[102:105], v[134:137], v[62:65]
	v_mfma_f32_16x16x32_f16 v[66:69], v[126:129], v[134:137], v[66:69]
	v_mfma_f32_16x16x32_f16 v[70:73], v[102:105], v[166:169], v[70:73]
	v_mfma_f32_16x16x32_f16 v[74:77], v[126:129], v[166:169], v[74:77]
	v_mfma_f32_16x16x32_f16 v[78:81], v[102:105], v[174:177], v[78:81]
	v_mfma_f32_16x16x32_f16 v[82:85], v[126:129], v[174:177], v[82:85]
	v_mfma_f32_16x16x32_f16 v[86:89], v[102:105], v[182:185], v[86:89]
	v_mfma_f32_16x16x32_f16 v[90:93], v[126:129], v[182:185], v[90:93]
	v_mfma_f32_16x16x32_f16 v[62:65], v[106:109], v[138:141], v[62:65]
	v_mfma_f32_16x16x32_f16 v[66:69], v[130:133], v[138:141], v[66:69]
	v_mfma_f32_16x16x32_f16 v[70:73], v[106:109], v[170:173], v[70:73]
	v_mfma_f32_16x16x32_f16 v[74:77], v[130:133], v[170:173], v[74:77]
	v_mfma_f32_16x16x32_f16 v[78:81], v[106:109], v[178:181], v[78:81]
	v_mfma_f32_16x16x32_f16 v[82:85], v[130:133], v[178:181], v[82:85]
	v_mfma_f32_16x16x32_f16 v[86:89], v[106:109], v[186:189], v[86:89]
	v_mfma_f32_16x16x32_f16 v[90:93], v[130:133], v[186:189], v[90:93]
	s_barrier
	s_add_i32 s48, 0, 0x1c000
	s_mov_b64 s[50:51], 0x180
	s_add_i32 s45, s46, s5
	v_add_u32_e32 v219, s48, v12
	v_lshl_add_u64 v[202:203], v[202:203], 0, s[50:51]
	s_mov_b32 m0, s45
	s_add_i32 s44, s45, 0x2000
	ds_read_b128 v[190:193], v219
	ds_read_b128 v[194:197], v219 offset:1024
	ds_read_b128 v[198:201], v219 offset:2048
	ds_read_b128 v[206:209], v219 offset:3072
	global_load_lds_dwordx4 v[202:203], off
	v_lshl_add_u64 v[202:203], v[210:211], 0, s[50:51]
	s_mov_b32 m0, s44
	s_nop 0
	global_load_lds_dwordx4 v[202:203], off
	s_barrier
	s_waitcnt lgkmcnt(0)
	v_mfma_f32_16x16x32_f16 v[110:113], v[190:193], v[134:137], v[110:113]
	v_mfma_f32_16x16x32_f16 v[30:33], v[198:201], v[134:137], v[30:33]
	v_mfma_f32_16x16x32_f16 v[34:37], v[190:193], v[166:169], v[34:37]
	v_mfma_f32_16x16x32_f16 v[38:41], v[198:201], v[166:169], v[38:41]
	v_mfma_f32_16x16x32_f16 v[42:45], v[190:193], v[174:177], v[42:45]
	v_mfma_f32_16x16x32_f16 v[46:49], v[198:201], v[174:177], v[46:49]
	v_mfma_f32_16x16x32_f16 v[50:53], v[190:193], v[182:185], v[50:53]
	v_mfma_f32_16x16x32_f16 v[54:57], v[198:201], v[182:185], v[54:57]
	v_mfma_f32_16x16x32_f16 v[110:113], v[194:197], v[138:141], v[110:113]
	v_mfma_f32_16x16x32_f16 v[30:33], v[206:209], v[138:141], v[30:33]
	v_mfma_f32_16x16x32_f16 v[34:37], v[194:197], v[170:173], v[34:37]
	v_mfma_f32_16x16x32_f16 v[38:41], v[206:209], v[170:173], v[38:41]
	v_mfma_f32_16x16x32_f16 v[42:45], v[194:197], v[178:181], v[42:45]
	v_mfma_f32_16x16x32_f16 v[46:49], v[206:209], v[178:181], v[46:49]
	v_mfma_f32_16x16x32_f16 v[50:53], v[194:197], v[186:189], v[50:53]
	v_mfma_f32_16x16x32_f16 v[54:57], v[206:209], v[186:189], v[54:57]
	s_mov_b32 m0, s10
	v_lshl_add_u64 v[202:203], v[212:213], 0, s[50:51]
	s_barrier
	ds_read_b128 v[134:137], v13 offset:49152
	ds_read_b128 v[138:141], v13 offset:50176
	ds_read_b128 v[166:169], v13 offset:51200
	ds_read_b128 v[170:173], v13 offset:52224
	ds_read_b128 v[174:177], v13 offset:53248
	ds_read_b128 v[178:181], v13 offset:54272
	ds_read_b128 v[182:185], v13 offset:55296
	ds_read_b128 v[186:189], v13 offset:56320
	global_load_lds_dwordx4 v[202:203], off
	v_lshl_add_u64 v[202:203], v[214:215], 0, s[50:51]
	s_mov_b32 m0, s11
	s_nop 0
	global_load_lds_dwordx4 v[202:203], off
	s_barrier
	s_waitcnt lgkmcnt(0)
	v_mfma_f32_16x16x32_f16 v[142:145], v[102:105], v[134:137], v[142:145]
	v_mfma_f32_16x16x32_f16 v[146:149], v[126:129], v[134:137], v[146:149]
	v_mfma_f32_16x16x32_f16 v[150:153], v[102:105], v[166:169], v[150:153]
	v_mfma_f32_16x16x32_f16 v[154:157], v[126:129], v[166:169], v[154:157]
	v_mfma_f32_16x16x32_f16 v[158:161], v[102:105], v[174:177], v[158:161]
	v_mfma_f32_16x16x32_f16 v[162:165], v[126:129], v[174:177], v[162:165]
	v_mfma_f32_16x16x32_f16 v[14:17], v[102:105], v[182:185], v[14:17]
	v_mfma_f32_16x16x32_f16 v[18:21], v[126:129], v[182:185], v[18:21]
	v_mfma_f32_16x16x32_f16 v[142:145], v[106:109], v[138:141], v[142:145]
	v_mfma_f32_16x16x32_f16 v[146:149], v[130:133], v[138:141], v[146:149]
	v_mfma_f32_16x16x32_f16 v[150:153], v[106:109], v[170:173], v[150:153]
	v_mfma_f32_16x16x32_f16 v[154:157], v[130:133], v[170:173], v[154:157]
	v_mfma_f32_16x16x32_f16 v[158:161], v[106:109], v[178:181], v[158:161]
	v_mfma_f32_16x16x32_f16 v[162:165], v[130:133], v[178:181], v[162:165]
	v_mfma_f32_16x16x32_f16 v[14:17], v[106:109], v[186:189], v[14:17]
	v_mfma_f32_16x16x32_f16 v[18:21], v[130:133], v[186:189], v[18:21]
	s_barrier
	s_add_u32 s46, s40, 0x10180
	s_addc_u32 s47, s41, 0
	s_add_i32 s41, s48, s5
	v_lshl_add_u64 v[102:103], s[46:47], 0, v[2:3]
	s_mov_b32 m0, s41
	s_add_i32 s40, s41, 0x2000
	global_load_lds_dwordx4 v[102:103], off
	v_lshl_add_u64 v[102:103], s[46:47], 0, v[4:5]
	s_mov_b32 m0, s40
	s_nop 0
	global_load_lds_dwordx4 v[102:103], off
	s_waitcnt vmcnt(6)
	s_barrier
	v_mfma_f32_16x16x32_f16 v[22:25], v[190:193], v[134:137], v[22:25]
	v_mfma_f32_16x16x32_f16 v[26:29], v[198:201], v[134:137], v[26:29]
	v_mfma_f32_16x16x32_f16 v[58:61], v[190:193], v[166:169], v[58:61]
	v_mfma_f32_16x16x32_f16 v[102:105], v[198:201], v[166:169], v[114:117]
	v_mfma_f32_16x16x32_f16 v[106:109], v[190:193], v[174:177], v[118:121]
	v_mfma_f32_16x16x32_f16 v[114:117], v[198:201], v[174:177], v[122:125]
	v_mfma_f32_16x16x32_f16 v[94:97], v[190:193], v[182:185], v[94:97]
	v_mfma_f32_16x16x32_f16 v[98:101], v[198:201], v[182:185], v[98:101]
	v_mfma_f32_16x16x32_f16 v[22:25], v[194:197], v[138:141], v[22:25]
	v_mfma_f32_16x16x32_f16 v[26:29], v[206:209], v[138:141], v[26:29]
	v_mfma_f32_16x16x32_f16 v[58:61], v[194:197], v[170:173], v[58:61]
	v_mfma_f32_16x16x32_f16 v[102:105], v[206:209], v[170:173], v[102:105]
	v_mfma_f32_16x16x32_f16 v[106:109], v[194:197], v[178:181], v[106:109]
	v_mfma_f32_16x16x32_f16 v[114:117], v[206:209], v[178:181], v[114:117]
	v_mfma_f32_16x16x32_f16 v[94:97], v[194:197], v[186:189], v[94:97]
	v_mfma_f32_16x16x32_f16 v[98:101], v[206:209], v[186:189], v[98:101]
	s_barrier
	ds_read_b128 v[118:121], v216
	ds_read_b128 v[122:125], v216 offset:1024
	ds_read_b128 v[126:129], v216 offset:2048
	ds_read_b128 v[130:133], v216 offset:3072
	s_add_u32 s38, s38, 0x400180
	s_addc_u32 s39, s39, 0
	s_mov_b32 m0, s42
	v_lshl_add_u64 v[190:191], s[38:39], 0, v[8:9]
	ds_read_b128 v[134:137], v13
	ds_read_b128 v[138:141], v13 offset:1024
	ds_read_b128 v[166:169], v13 offset:2048
	ds_read_b128 v[170:173], v13 offset:3072
	ds_read_b128 v[174:177], v13 offset:4096
	ds_read_b128 v[178:181], v13 offset:5120
	ds_read_b128 v[182:185], v13 offset:6144
	ds_read_b128 v[186:189], v13 offset:7168
	global_load_lds_dwordx4 v[190:191], off
	v_lshl_add_u64 v[190:191], s[38:39], 0, v[6:7]
	s_mov_b32 m0, s17
	s_nop 0
	global_load_lds_dwordx4 v[190:191], off
	s_barrier
	s_waitcnt lgkmcnt(0)
	v_mfma_f32_16x16x32_f16 v[62:65], v[118:121], v[134:137], v[62:65]
	v_mfma_f32_16x16x32_f16 v[66:69], v[126:129], v[134:137], v[66:69]
	v_mfma_f32_16x16x32_f16 v[70:73], v[118:121], v[166:169], v[70:73]
	v_mfma_f32_16x16x32_f16 v[74:77], v[126:129], v[166:169], v[74:77]
	v_mfma_f32_16x16x32_f16 v[78:81], v[118:121], v[174:177], v[78:81]
	v_mfma_f32_16x16x32_f16 v[82:85], v[126:129], v[174:177], v[82:85]
	v_mfma_f32_16x16x32_f16 v[86:89], v[118:121], v[182:185], v[86:89]
	v_mfma_f32_16x16x32_f16 v[90:93], v[126:129], v[182:185], v[90:93]
	v_mfma_f32_16x16x32_f16 v[62:65], v[122:125], v[138:141], v[62:65]
	v_mfma_f32_16x16x32_f16 v[66:69], v[130:133], v[138:141], v[66:69]
	v_mfma_f32_16x16x32_f16 v[70:73], v[122:125], v[170:173], v[70:73]
	v_mfma_f32_16x16x32_f16 v[74:77], v[130:133], v[170:173], v[74:77]
	v_mfma_f32_16x16x32_f16 v[78:81], v[122:125], v[178:181], v[78:81]
	v_mfma_f32_16x16x32_f16 v[82:85], v[130:133], v[178:181], v[82:85]
	v_mfma_f32_16x16x32_f16 v[86:89], v[122:125], v[186:189], v[86:89]
	v_mfma_f32_16x16x32_f16 v[90:93], v[130:133], v[186:189], v[90:93]
	s_barrier
	s_mov_b32 m0, s37
	v_lshl_add_u64 v[202:203], s[26:27], 0, v[2:3]
	ds_read_b128 v[190:193], v217
	ds_read_b128 v[194:197], v217 offset:1024
	ds_read_b128 v[198:201], v217 offset:2048
	ds_read_b128 v[206:209], v217 offset:3072
	global_load_lds_dwordx4 v[202:203], off
	v_lshl_add_u64 v[210:211], s[26:27], 0, v[4:5]
	s_mov_b32 m0, s30
	s_nop 0
	global_load_lds_dwordx4 v[210:211], off
	s_barrier
	s_waitcnt lgkmcnt(0)
	v_mfma_f32_16x16x32_f16 v[110:113], v[190:193], v[134:137], v[110:113]
	v_mfma_f32_16x16x32_f16 v[30:33], v[198:201], v[134:137], v[30:33]
	v_mfma_f32_16x16x32_f16 v[34:37], v[190:193], v[166:169], v[34:37]
	v_mfma_f32_16x16x32_f16 v[38:41], v[198:201], v[166:169], v[38:41]
	v_mfma_f32_16x16x32_f16 v[42:45], v[190:193], v[174:177], v[42:45]
	v_mfma_f32_16x16x32_f16 v[46:49], v[198:201], v[174:177], v[46:49]
	v_mfma_f32_16x16x32_f16 v[50:53], v[190:193], v[182:185], v[50:53]
	v_mfma_f32_16x16x32_f16 v[54:57], v[198:201], v[182:185], v[54:57]
	v_mfma_f32_16x16x32_f16 v[110:113], v[194:197], v[138:141], v[110:113]
	v_mfma_f32_16x16x32_f16 v[30:33], v[206:209], v[138:141], v[30:33]
	v_mfma_f32_16x16x32_f16 v[34:37], v[194:197], v[170:173], v[34:37]
	v_mfma_f32_16x16x32_f16 v[38:41], v[206:209], v[170:173], v[38:41]
	v_mfma_f32_16x16x32_f16 v[42:45], v[194:197], v[178:181], v[42:45]
	v_mfma_f32_16x16x32_f16 v[46:49], v[206:209], v[178:181], v[46:49]
	v_mfma_f32_16x16x32_f16 v[50:53], v[194:197], v[186:189], v[50:53]
	v_mfma_f32_16x16x32_f16 v[54:57], v[206:209], v[186:189], v[54:57]
	s_mov_b32 m0, s6
	v_lshl_add_u64 v[212:213], s[18:19], 0, v[8:9]
	s_barrier
	ds_read_b128 v[134:137], v13 offset:16384
	ds_read_b128 v[138:141], v13 offset:17408
	ds_read_b128 v[166:169], v13 offset:18432
	ds_read_b128 v[170:173], v13 offset:19456
	ds_read_b128 v[174:177], v13 offset:20480
	ds_read_b128 v[178:181], v13 offset:21504
	ds_read_b128 v[182:185], v13 offset:22528
	ds_read_b128 v[186:189], v13 offset:23552
	global_load_lds_dwordx4 v[212:213], off
	v_lshl_add_u64 v[214:215], s[18:19], 0, v[6:7]
	s_mov_b32 m0, s7
	s_nop 0
	global_load_lds_dwordx4 v[214:215], off
	s_barrier
	s_waitcnt lgkmcnt(0)
	v_mfma_f32_16x16x32_f16 v[142:145], v[118:121], v[134:137], v[142:145]
	v_mfma_f32_16x16x32_f16 v[146:149], v[126:129], v[134:137], v[146:149]
	v_mfma_f32_16x16x32_f16 v[150:153], v[118:121], v[166:169], v[150:153]
	v_mfma_f32_16x16x32_f16 v[154:157], v[126:129], v[166:169], v[154:157]
	v_mfma_f32_16x16x32_f16 v[158:161], v[118:121], v[174:177], v[158:161]
	v_mfma_f32_16x16x32_f16 v[162:165], v[126:129], v[174:177], v[162:165]
	v_mfma_f32_16x16x32_f16 v[14:17], v[118:121], v[182:185], v[14:17]
	v_mfma_f32_16x16x32_f16 v[18:21], v[126:129], v[182:185], v[18:21]
	v_mfma_f32_16x16x32_f16 v[142:145], v[122:125], v[138:141], v[142:145]
	v_mfma_f32_16x16x32_f16 v[146:149], v[130:133], v[138:141], v[146:149]
	v_mfma_f32_16x16x32_f16 v[150:153], v[122:125], v[170:173], v[150:153]
	v_mfma_f32_16x16x32_f16 v[154:157], v[130:133], v[170:173], v[154:157]
	v_mfma_f32_16x16x32_f16 v[158:161], v[122:125], v[178:181], v[158:161]
	v_mfma_f32_16x16x32_f16 v[162:165], v[130:133], v[178:181], v[162:165]
	v_mfma_f32_16x16x32_f16 v[14:17], v[122:125], v[186:189], v[14:17]
	v_mfma_f32_16x16x32_f16 v[18:21], v[130:133], v[186:189], v[18:21]
	s_barrier
	s_add_u32 s38, s26, 0x10000
	s_addc_u32 s39, s27, 0
	s_mov_b32 m0, s43
	v_lshl_add_u64 v[118:119], s[38:39], 0, v[2:3]
	global_load_lds_dwordx4 v[118:119], off
	v_lshl_add_u64 v[118:119], s[38:39], 0, v[4:5]
	s_mov_b32 m0, s31
	s_nop 0
	global_load_lds_dwordx4 v[118:119], off
	s_waitcnt vmcnt(6)
	s_barrier
	v_mfma_f32_16x16x32_f16 v[22:25], v[190:193], v[134:137], v[22:25]
	v_mfma_f32_16x16x32_f16 v[26:29], v[198:201], v[134:137], v[26:29]
	v_mfma_f32_16x16x32_f16 v[58:61], v[190:193], v[166:169], v[58:61]
	v_mfma_f32_16x16x32_f16 v[102:105], v[198:201], v[166:169], v[102:105]
	v_mfma_f32_16x16x32_f16 v[106:109], v[190:193], v[174:177], v[106:109]
	v_mfma_f32_16x16x32_f16 v[114:117], v[198:201], v[174:177], v[114:117]
	v_mfma_f32_16x16x32_f16 v[94:97], v[190:193], v[182:185], v[94:97]
	v_mfma_f32_16x16x32_f16 v[98:101], v[198:201], v[182:185], v[98:101]
	v_mfma_f32_16x16x32_f16 v[22:25], v[194:197], v[138:141], v[22:25]
	v_mfma_f32_16x16x32_f16 v[26:29], v[206:209], v[138:141], v[26:29]
	v_mfma_f32_16x16x32_f16 v[58:61], v[194:197], v[170:173], v[58:61]
	v_mfma_f32_16x16x32_f16 v[102:105], v[206:209], v[170:173], v[102:105]
	v_mfma_f32_16x16x32_f16 v[106:109], v[194:197], v[178:181], v[106:109]
	v_mfma_f32_16x16x32_f16 v[114:117], v[206:209], v[178:181], v[114:117]
	v_mfma_f32_16x16x32_f16 v[94:97], v[194:197], v[186:189], v[94:97]
	v_mfma_f32_16x16x32_f16 v[98:101], v[206:209], v[186:189], v[98:101]
	s_barrier
	ds_read_b128 v[118:121], v218
	ds_read_b128 v[122:125], v218 offset:1024
	ds_read_b128 v[126:129], v218 offset:2048
	ds_read_b128 v[130:133], v218 offset:3072
	s_add_u32 s30, s18, 0x400000
	s_addc_u32 s31, s19, 0
	s_mov_b32 m0, s8
	v_lshl_add_u64 v[190:191], s[30:31], 0, v[8:9]
	ds_read_b128 v[134:137], v13 offset:32768
	ds_read_b128 v[138:141], v13 offset:33792
	ds_read_b128 v[166:169], v13 offset:34816
	ds_read_b128 v[170:173], v13 offset:35840
	ds_read_b128 v[174:177], v13 offset:36864
	ds_read_b128 v[178:181], v13 offset:37888
	ds_read_b128 v[182:185], v13 offset:38912
	ds_read_b128 v[186:189], v13 offset:39936
	global_load_lds_dwordx4 v[190:191], off
	v_lshl_add_u64 v[190:191], s[30:31], 0, v[6:7]
	s_mov_b32 m0, s9
	s_nop 0
	global_load_lds_dwordx4 v[190:191], off
	s_barrier
	s_waitcnt lgkmcnt(0)
	v_mfma_f32_16x16x32_f16 v[62:65], v[118:121], v[134:137], v[62:65]
	v_mfma_f32_16x16x32_f16 v[66:69], v[126:129], v[134:137], v[66:69]
	v_mfma_f32_16x16x32_f16 v[70:73], v[118:121], v[166:169], v[70:73]
	v_mfma_f32_16x16x32_f16 v[74:77], v[126:129], v[166:169], v[74:77]
	v_mfma_f32_16x16x32_f16 v[78:81], v[118:121], v[174:177], v[78:81]
	v_mfma_f32_16x16x32_f16 v[82:85], v[126:129], v[174:177], v[82:85]
	v_mfma_f32_16x16x32_f16 v[86:89], v[118:121], v[182:185], v[86:89]
	v_mfma_f32_16x16x32_f16 v[90:93], v[126:129], v[182:185], v[90:93]
	v_mfma_f32_16x16x32_f16 v[62:65], v[122:125], v[138:141], v[62:65]
	v_mfma_f32_16x16x32_f16 v[66:69], v[130:133], v[138:141], v[66:69]
	v_mfma_f32_16x16x32_f16 v[70:73], v[122:125], v[170:173], v[70:73]
	v_mfma_f32_16x16x32_f16 v[74:77], v[130:133], v[170:173], v[74:77]
	v_mfma_f32_16x16x32_f16 v[78:81], v[122:125], v[178:181], v[78:81]
	v_mfma_f32_16x16x32_f16 v[82:85], v[130:133], v[178:181], v[82:85]
	v_mfma_f32_16x16x32_f16 v[86:89], v[122:125], v[186:189], v[86:89]
	v_mfma_f32_16x16x32_f16 v[90:93], v[130:133], v[186:189], v[90:93]
	s_barrier
	s_mov_b32 m0, s45
	v_lshl_add_u64 v[202:203], v[202:203], 0, s[88:89]
	ds_read_b128 v[190:193], v219
	ds_read_b128 v[194:197], v219 offset:1024
	ds_read_b128 v[198:201], v219 offset:2048
	ds_read_b128 v[206:209], v219 offset:3072
	global_load_lds_dwordx4 v[202:203], off
	v_lshl_add_u64 v[202:203], v[210:211], 0, s[88:89]
	s_mov_b32 m0, s44
	s_nop 0
	global_load_lds_dwordx4 v[202:203], off
	s_barrier
	s_waitcnt lgkmcnt(0)
	v_mfma_f32_16x16x32_f16 v[110:113], v[190:193], v[134:137], v[110:113]
	v_mfma_f32_16x16x32_f16 v[30:33], v[198:201], v[134:137], v[30:33]
	v_mfma_f32_16x16x32_f16 v[34:37], v[190:193], v[166:169], v[34:37]
	v_mfma_f32_16x16x32_f16 v[38:41], v[198:201], v[166:169], v[38:41]
	v_mfma_f32_16x16x32_f16 v[42:45], v[190:193], v[174:177], v[42:45]
	v_mfma_f32_16x16x32_f16 v[46:49], v[198:201], v[174:177], v[46:49]
	v_mfma_f32_16x16x32_f16 v[50:53], v[190:193], v[182:185], v[50:53]
	v_mfma_f32_16x16x32_f16 v[54:57], v[198:201], v[182:185], v[54:57]
	v_mfma_f32_16x16x32_f16 v[110:113], v[194:197], v[138:141], v[110:113]
	v_mfma_f32_16x16x32_f16 v[30:33], v[206:209], v[138:141], v[30:33]
	v_mfma_f32_16x16x32_f16 v[34:37], v[194:197], v[170:173], v[34:37]
	v_mfma_f32_16x16x32_f16 v[38:41], v[206:209], v[170:173], v[38:41]
	v_mfma_f32_16x16x32_f16 v[42:45], v[194:197], v[178:181], v[42:45]
	v_mfma_f32_16x16x32_f16 v[46:49], v[206:209], v[178:181], v[46:49]
	v_mfma_f32_16x16x32_f16 v[50:53], v[194:197], v[186:189], v[50:53]
	v_mfma_f32_16x16x32_f16 v[54:57], v[206:209], v[186:189], v[54:57]
	s_mov_b32 m0, s10
	v_lshl_add_u64 v[202:203], v[212:213], 0, s[88:89]
	s_barrier
	ds_read_b128 v[134:137], v13 offset:49152
	ds_read_b128 v[138:141], v13 offset:50176
	ds_read_b128 v[166:169], v13 offset:51200
	ds_read_b128 v[170:173], v13 offset:52224
	ds_read_b128 v[174:177], v13 offset:53248
	ds_read_b128 v[178:181], v13 offset:54272
	ds_read_b128 v[182:185], v13 offset:55296
	ds_read_b128 v[186:189], v13 offset:56320
	global_load_lds_dwordx4 v[202:203], off
	v_lshl_add_u64 v[202:203], v[214:215], 0, s[88:89]
	s_mov_b32 m0, s11
	s_nop 0
	global_load_lds_dwordx4 v[202:203], off
	s_barrier
	s_waitcnt lgkmcnt(0)
	v_mfma_f32_16x16x32_f16 v[142:145], v[118:121], v[134:137], v[142:145]
	v_mfma_f32_16x16x32_f16 v[146:149], v[126:129], v[134:137], v[146:149]
	v_mfma_f32_16x16x32_f16 v[150:153], v[118:121], v[166:169], v[150:153]
	v_mfma_f32_16x16x32_f16 v[154:157], v[126:129], v[166:169], v[154:157]
	v_mfma_f32_16x16x32_f16 v[158:161], v[118:121], v[174:177], v[158:161]
	v_mfma_f32_16x16x32_f16 v[162:165], v[126:129], v[174:177], v[162:165]
	v_mfma_f32_16x16x32_f16 v[14:17], v[118:121], v[182:185], v[14:17]
	v_mfma_f32_16x16x32_f16 v[18:21], v[126:129], v[182:185], v[18:21]
	v_mfma_f32_16x16x32_f16 v[142:145], v[122:125], v[138:141], v[142:145]
	v_mfma_f32_16x16x32_f16 v[146:149], v[130:133], v[138:141], v[146:149]
	v_mfma_f32_16x16x32_f16 v[150:153], v[122:125], v[170:173], v[150:153]
	v_mfma_f32_16x16x32_f16 v[154:157], v[130:133], v[170:173], v[154:157]
	v_mfma_f32_16x16x32_f16 v[158:161], v[122:125], v[178:181], v[158:161]
	v_mfma_f32_16x16x32_f16 v[162:165], v[130:133], v[178:181], v[162:165]
	v_mfma_f32_16x16x32_f16 v[14:17], v[122:125], v[186:189], v[14:17]
	v_mfma_f32_16x16x32_f16 v[18:21], v[130:133], v[186:189], v[18:21]
	s_barrier
	s_add_u32 s30, s26, 0x10080
	s_addc_u32 s31, s27, 0
	s_mov_b32 m0, s41
	v_lshl_add_u64 v[118:119], s[30:31], 0, v[2:3]
	global_load_lds_dwordx4 v[118:119], off
	v_lshl_add_u64 v[118:119], s[30:31], 0, v[4:5]
	s_mov_b32 m0, s40
	s_nop 0
	global_load_lds_dwordx4 v[118:119], off
	s_waitcnt vmcnt(6)
	s_barrier
	v_mfma_f32_16x16x32_f16 v[22:25], v[190:193], v[134:137], v[22:25]
	v_mfma_f32_16x16x32_f16 v[26:29], v[198:201], v[134:137], v[26:29]
	v_mfma_f32_16x16x32_f16 v[58:61], v[190:193], v[166:169], v[58:61]
	v_mfma_f32_16x16x32_f16 v[102:105], v[198:201], v[166:169], v[102:105]
	v_mfma_f32_16x16x32_f16 v[106:109], v[190:193], v[174:177], v[106:109]
	v_mfma_f32_16x16x32_f16 v[114:117], v[198:201], v[174:177], v[114:117]
	v_mfma_f32_16x16x32_f16 v[94:97], v[190:193], v[182:185], v[94:97]
	v_mfma_f32_16x16x32_f16 v[98:101], v[198:201], v[182:185], v[98:101]
	v_mfma_f32_16x16x32_f16 v[22:25], v[194:197], v[138:141], v[22:25]
	v_mfma_f32_16x16x32_f16 v[26:29], v[206:209], v[138:141], v[26:29]
	v_mfma_f32_16x16x32_f16 v[58:61], v[194:197], v[170:173], v[58:61]
	v_mfma_f32_16x16x32_f16 v[102:105], v[206:209], v[170:173], v[102:105]
	v_mfma_f32_16x16x32_f16 v[106:109], v[194:197], v[178:181], v[106:109]
	v_mfma_f32_16x16x32_f16 v[114:117], v[206:209], v[178:181], v[114:117]
	v_mfma_f32_16x16x32_f16 v[94:97], v[194:197], v[186:189], v[94:97]
	v_mfma_f32_16x16x32_f16 v[98:101], v[206:209], v[186:189], v[98:101]
	v_mov_b32_e32 v118, v10
	s_lshl_b32 s17, s29, 8
	s_barrier
	v_mov_b32_e32 v119, v11
	s_add_i32 s17, s17, s12
	v_add_u32_e32 v118, s17, v118
	s_ashr_i32 s37, s36, 31
	v_lshl_add_u32 v120, v119, 2, s13
	s_lshl_b64 s[30:31], s[36:37], 10
	v_ashrrev_i32_e32 v119, 31, v118
	v_readlane_b32 s36, v252, 62
	v_lshlrev_b64 v[118:119], 15, v[118:119]
	v_readlane_b32 s37, v252, 63
	v_ashrrev_i32_e32 v121, 31, v120
	s_mov_b32 s17, 0x80000
	v_lshl_add_u64 v[118:119], s[36:37], 0, v[118:119]
	v_lshl_add_u64 v[118:119], v[118:119], 0, s[30:31]
	v_lshl_add_u64 v[118:119], v[120:121], 2, v[118:119]
	global_store_dwordx4 v[118:119], v[62:65], off
	global_store_dwordx4 v[118:119], v[66:69], off offset:64
	global_store_dwordx4 v[118:119], v[110:113], off offset:512
	global_store_dwordx4 v[118:119], v[30:33], off offset:576
	s_mov_b64 s[30:31], 0x80000
	s_mov_b32 s36, s15
	v_add_co_u32_e32 v32, vcc, s17, v118
	s_mov_b32 s17, 0x100000
	s_nop 0
	v_addc_co_u32_e32 v33, vcc, 0, v119, vcc
	v_lshl_add_u64 v[30:31], v[118:119], 0, s[30:31]
	global_store_dwordx4 v[32:33], v[70:73], off
	global_store_dwordx4 v[30:31], v[74:77], off offset:64
	global_store_dwordx4 v[30:31], v[34:37], off offset:512
	global_store_dwordx4 v[30:31], v[38:41], off offset:576
	v_add_co_u32_e32 v32, vcc, s17, v118
	s_mov_b64 s[30:31], 0x100000
	s_nop 0
	v_addc_co_u32_e32 v33, vcc, 0, v119, vcc
	s_mov_b32 s17, 0x180000
	v_lshl_add_u64 v[30:31], v[118:119], 0, s[30:31]
	global_store_dwordx4 v[32:33], v[78:81], off
	global_store_dwordx4 v[30:31], v[82:85], off offset:64
	global_store_dwordx4 v[30:31], v[42:45], off offset:512
	global_store_dwordx4 v[30:31], v[46:49], off offset:576
	v_add_co_u32_e32 v32, vcc, s17, v118
	s_mov_b64 s[30:31], 0x180000
	s_nop 0
	v_addc_co_u32_e32 v33, vcc, 0, v119, vcc
	s_mov_b32 s17, 0x400000
	v_lshl_add_u64 v[30:31], v[118:119], 0, s[30:31]
	global_store_dwordx4 v[32:33], v[86:89], off
	global_store_dwordx4 v[30:31], v[90:93], off offset:64
	global_store_dwordx4 v[30:31], v[50:53], off offset:512
	global_store_dwordx4 v[30:31], v[54:57], off offset:576
	v_add_co_u32_e32 v32, vcc, s17, v118
	s_mov_b64 s[30:31], 0x400000
	s_nop 0
	v_addc_co_u32_e32 v33, vcc, 0, v119, vcc
	s_mov_b32 s17, 0x480000
	v_lshl_add_u64 v[30:31], v[118:119], 0, s[30:31]
	global_store_dwordx4 v[32:33], v[142:145], off
	global_store_dwordx4 v[30:31], v[146:149], off offset:64
	global_store_dwordx4 v[30:31], v[22:25], off offset:512
	global_store_dwordx4 v[30:31], v[26:29], off offset:576
	s_mov_b64 s[30:31], 0x480000
	v_add_co_u32_e32 v24, vcc, s17, v118
	s_mov_b32 s17, 0x500000
	s_nop 0
	v_addc_co_u32_e32 v25, vcc, 0, v119, vcc
	v_lshl_add_u64 v[22:23], v[118:119], 0, s[30:31]
	global_store_dwordx4 v[24:25], v[150:153], off
	global_store_dwordx4 v[22:23], v[154:157], off offset:64
	global_store_dwordx4 v[22:23], v[58:61], off offset:512
	global_store_dwordx4 v[22:23], v[102:105], off offset:576
	v_add_co_u32_e32 v24, vcc, s17, v118
	s_mov_b64 s[30:31], 0x500000
	s_nop 0
	v_addc_co_u32_e32 v25, vcc, 0, v119, vcc
	v_lshl_add_u64 v[22:23], v[118:119], 0, s[30:31]
	global_store_dwordx4 v[24:25], v[158:161], off
	global_store_dwordx4 v[22:23], v[162:165], off offset:64
	global_store_dwordx4 v[22:23], v[106:109], off offset:512
	global_store_dwordx4 v[22:23], v[114:117], off offset:576
	v_add_co_u32_e32 v24, vcc, 0x580000, v118
	s_mov_b64 s[30:31], 0x580000
	s_nop 0
	v_addc_co_u32_e32 v25, vcc, 0, v119, vcc
	s_andn2_b64 vcc, exec, s[34:35]
	s_mov_b32 s29, s16
	s_mov_b64 s[40:41], s[26:27]
	s_mov_b64 s[38:39], s[18:19]
	v_lshl_add_u64 v[22:23], v[118:119], 0, s[30:31]
	global_store_dwordx4 v[24:25], v[14:17], off
	global_store_dwordx4 v[22:23], v[18:21], off offset:64
	global_store_dwordx4 v[22:23], v[94:97], off offset:512
	global_store_dwordx4 v[22:23], v[98:101], off offset:576
	s_cbranch_vccz .LBB0_888

.LBB0_1341:
	s_add_u32 s29, s26, 0xffc00080
	s_addc_u32 s31, s27, -1
	s_add_i32 s48, 0, 0x10000
	v_add_u32_e32 v2, s48, v190
	ds_read_b128 v[28:31], v2
	ds_read_b128 v[32:35], v2 offset:1024
	ds_read_b128 v[100:103], v2 offset:2048
	ds_read_b128 v[112:115], v2 offset:3072
	s_cmp_eq_u32 s19, 4
	s_cselect_b32 s43, s35, s31
	s_cselect_b32 s42, s34, s29
	s_cselect_b32 s39, s37, s17
	s_cselect_b32 s38, s36, s11
	s_add_i32 m0, s7, 0xc000
	ds_read_b128 v[124:127], v191
	ds_read_b128 v[136:139], v191 offset:1024
	ds_read_b128 v[148:151], v191 offset:2048
	ds_read_b128 v[156:159], v191 offset:3072
	ds_read_b128 v[164:167], v191 offset:4096
	ds_read_b128 v[168:171], v191 offset:5120
	ds_read_b128 v[184:187], v191 offset:6144
	ds_read_b128 v[192:195], v191 offset:7168
	global_load_lds_dwordx4 v180, s[26:27]
	s_add_i32 m0, s7, 0xe000
	s_nop 0
	global_load_lds_dwordx4 v182, s[26:27]
	s_barrier
	s_waitcnt lgkmcnt(0)
	v_mfma_f32_16x16x32_f16 v[160:163], v[28:31], v[124:127], v[160:163]
	v_mfma_f32_16x16x32_f16 v[152:155], v[100:103], v[124:127], v[152:155]
	v_mfma_f32_16x16x32_f16 v[132:135], v[28:31], v[148:151], v[132:135]
	v_mfma_f32_16x16x32_f16 v[128:131], v[100:103], v[148:151], v[128:131]
	v_mfma_f32_16x16x32_f16 v[108:111], v[28:31], v[164:167], v[108:111]
	v_mfma_f32_16x16x32_f16 v[104:107], v[100:103], v[164:167], v[104:107]
	v_mfma_f32_16x16x32_f16 v[88:91], v[28:31], v[184:187], v[88:91]
	v_mfma_f32_16x16x32_f16 v[84:87], v[100:103], v[184:187], v[84:87]
	v_mfma_f32_16x16x32_f16 v[160:163], v[32:35], v[136:139], v[160:163]
	v_mfma_f32_16x16x32_f16 v[152:155], v[112:115], v[136:139], v[152:155]
	v_mfma_f32_16x16x32_f16 v[132:135], v[32:35], v[156:159], v[132:135]
	v_mfma_f32_16x16x32_f16 v[128:131], v[112:115], v[156:159], v[128:131]
	v_mfma_f32_16x16x32_f16 v[108:111], v[32:35], v[168:171], v[108:111]
	v_mfma_f32_16x16x32_f16 v[104:107], v[112:115], v[168:171], v[104:107]
	v_mfma_f32_16x16x32_f16 v[88:91], v[32:35], v[192:195], v[88:91]
	v_mfma_f32_16x16x32_f16 v[84:87], v[112:115], v[192:195], v[84:87]
	s_barrier
	s_add_i32 s29, 0, 0x14000
	s_add_i32 s31, s48, s6
	v_add_u32_e32 v2, s29, v190
	v_lshl_add_u64 v[214:215], s[38:39], 0, v[176:177]
	s_mov_b32 m0, s31
	ds_read_b128 v[196:199], v2
	ds_read_b128 v[200:203], v2 offset:1024
	ds_read_b128 v[206:209], v2 offset:2048
	ds_read_b128 v[210:213], v2 offset:3072
	global_load_lds_dwordx4 v[214:215], off
	v_lshl_add_u64 v[216:217], s[38:39], 0, v[172:173]
	s_add_i32 m0, s31, 0x2000
	s_nop 0
	global_load_lds_dwordx4 v[216:217], off
	s_waitcnt vmcnt(10)
	s_barrier
	s_waitcnt lgkmcnt(0)
	v_mfma_f32_16x16x32_f16 v[144:147], v[196:199], v[124:127], v[144:147]
	v_mfma_f32_16x16x32_f16 v[120:123], v[196:199], v[148:151], v[120:123]
	v_mfma_f32_16x16x32_f16 v[116:119], v[206:209], v[148:151], v[116:119]
	v_mfma_f32_16x16x32_f16 v[96:99], v[196:199], v[164:167], v[96:99]
	v_mfma_f32_16x16x32_f16 v[92:95], v[206:209], v[164:167], v[92:95]
	v_mfma_f32_16x16x32_f16 v[80:83], v[196:199], v[184:187], v[80:83]
	v_mfma_f32_16x16x32_f16 v[76:79], v[206:209], v[184:187], v[76:79]
	v_mfma_f32_16x16x32_f16 v[144:147], v[200:203], v[136:139], v[144:147]
	v_mfma_f32_16x16x32_f16 v[124:127], v[206:209], v[124:127], v[140:143]
	v_mfma_f32_16x16x32_f16 v[120:123], v[200:203], v[156:159], v[120:123]
	v_mfma_f32_16x16x32_f16 v[116:119], v[210:213], v[156:159], v[116:119]
	v_mfma_f32_16x16x32_f16 v[96:99], v[200:203], v[168:171], v[96:99]
	v_mfma_f32_16x16x32_f16 v[92:95], v[210:213], v[168:171], v[92:95]
	v_mfma_f32_16x16x32_f16 v[80:83], v[200:203], v[192:195], v[80:83]
	v_mfma_f32_16x16x32_f16 v[76:79], v[210:213], v[192:195], v[76:79]
	v_mfma_f32_16x16x32_f16 v[124:127], v[210:213], v[136:139], v[124:127]
	s_mov_b32 m0, s7
	v_lshl_add_u64 v[218:219], s[42:43], 0, v[178:179]
	s_barrier
	ds_read_b128 v[136:139], v191 offset:16384
	ds_read_b128 v[140:143], v191 offset:17408
	ds_read_b128 v[148:151], v191 offset:18432
	ds_read_b128 v[156:159], v191 offset:19456
	ds_read_b128 v[164:167], v191 offset:20480
	ds_read_b128 v[168:171], v191 offset:21504
	ds_read_b128 v[184:187], v191 offset:22528
	ds_read_b128 v[192:195], v191 offset:23552
	global_load_lds_dwordx4 v[218:219], off
	v_lshl_add_u64 v[220:221], s[42:43], 0, v[174:175]
	s_mov_b32 m0, s8
	s_nop 0
	global_load_lds_dwordx4 v[220:221], off
	s_barrier
	s_waitcnt lgkmcnt(0)
	v_mfma_f32_16x16x32_f16 v[72:75], v[28:31], v[136:139], v[72:75]
	v_mfma_f32_16x16x32_f16 v[68:71], v[100:103], v[136:139], v[68:71]
	v_mfma_f32_16x16x32_f16 v[56:59], v[28:31], v[148:151], v[56:59]
	v_mfma_f32_16x16x32_f16 v[52:55], v[100:103], v[148:151], v[52:55]
	v_mfma_f32_16x16x32_f16 v[40:43], v[28:31], v[164:167], v[40:43]
	v_mfma_f32_16x16x32_f16 v[36:39], v[100:103], v[164:167], v[36:39]
	v_mfma_f32_16x16x32_f16 v[16:19], v[28:31], v[184:187], v[16:19]
	v_mfma_f32_16x16x32_f16 v[12:15], v[100:103], v[184:187], v[12:15]
	v_mfma_f32_16x16x32_f16 v[72:75], v[32:35], v[140:143], v[72:75]
	v_mfma_f32_16x16x32_f16 v[68:71], v[112:115], v[140:143], v[68:71]
	v_mfma_f32_16x16x32_f16 v[56:59], v[32:35], v[156:159], v[56:59]
	v_mfma_f32_16x16x32_f16 v[52:55], v[112:115], v[156:159], v[52:55]
	v_mfma_f32_16x16x32_f16 v[40:43], v[32:35], v[168:171], v[40:43]
	v_mfma_f32_16x16x32_f16 v[36:39], v[112:115], v[168:171], v[36:39]
	v_mfma_f32_16x16x32_f16 v[16:19], v[32:35], v[192:195], v[16:19]
	v_mfma_f32_16x16x32_f16 v[12:15], v[112:115], v[192:195], v[12:15]
	s_barrier
	s_add_u32 s48, s38, 0x20000
	s_addc_u32 s49, s39, 0
	s_add_i32 s29, s29, s6
	s_mov_b32 m0, s29
	s_nop 0
	global_load_lds_dwordx4 v176, s[48:49]
	s_add_i32 m0, s29, 0x2000
	s_nop 0
	global_load_lds_dwordx4 v172, s[48:49]
	s_waitcnt vmcnt(8)
	s_barrier
	v_mfma_f32_16x16x32_f16 v[48:51], v[196:199], v[148:151], v[48:51]
	v_mfma_f32_16x16x32_f16 v[44:47], v[206:209], v[148:151], v[44:47]
	v_mfma_f32_16x16x32_f16 v[24:27], v[196:199], v[164:167], v[24:27]
	v_mfma_f32_16x16x32_f16 v[20:23], v[206:209], v[164:167], v[20:23]
	v_mfma_f32_16x16x32_f16 v[8:11], v[196:199], v[184:187], v[8:11]
	v_mfma_f32_16x16x32_f16 v[4:7], v[206:209], v[184:187], v[4:7]
	v_mfma_f32_16x16x32_f16 v[28:31], v[196:199], v[136:139], v[64:67]
	v_mfma_f32_16x16x32_f16 v[32:35], v[206:209], v[136:139], v[60:63]
	v_mfma_f32_16x16x32_f16 v[48:51], v[200:203], v[156:159], v[48:51]
	v_mfma_f32_16x16x32_f16 v[44:47], v[210:213], v[156:159], v[44:47]
	v_mfma_f32_16x16x32_f16 v[24:27], v[200:203], v[168:171], v[24:27]
	v_mfma_f32_16x16x32_f16 v[20:23], v[210:213], v[168:171], v[20:23]
	v_mfma_f32_16x16x32_f16 v[8:11], v[200:203], v[192:195], v[8:11]
	v_mfma_f32_16x16x32_f16 v[4:7], v[210:213], v[192:195], v[4:7]
	v_mfma_f32_16x16x32_f16 v[28:31], v[200:203], v[140:143], v[28:31]
	v_mfma_f32_16x16x32_f16 v[32:35], v[210:213], v[140:143], v[32:35]
	s_add_i32 s29, 0, 0x18000
	v_add_u32_e32 v2, s29, v190
	s_barrier
	ds_read_b128 v[60:63], v2
	ds_read_b128 v[64:67], v2 offset:1024
	ds_read_b128 v[100:103], v2 offset:2048
	ds_read_b128 v[112:115], v2 offset:3072
	s_add_u32 s42, s42, 0x400000
	s_addc_u32 s43, s43, 0
	s_mov_b32 m0, s9
	ds_read_b128 v[136:139], v191 offset:32768
	ds_read_b128 v[140:143], v191 offset:33792
	ds_read_b128 v[148:151], v191 offset:34816
	ds_read_b128 v[156:159], v191 offset:35840
	ds_read_b128 v[164:167], v191 offset:36864
	ds_read_b128 v[168:171], v191 offset:37888
	ds_read_b128 v[184:187], v191 offset:38912
	ds_read_b128 v[192:195], v191 offset:39936
	global_load_lds_dwordx4 v178, s[42:43]
	s_mov_b32 m0, s12
	s_nop 0
	global_load_lds_dwordx4 v174, s[42:43]
	s_barrier
	s_waitcnt lgkmcnt(0)
	v_mfma_f32_16x16x32_f16 v[160:163], v[60:63], v[136:139], v[160:163]
	v_mfma_f32_16x16x32_f16 v[152:155], v[100:103], v[136:139], v[152:155]
	v_mfma_f32_16x16x32_f16 v[132:135], v[60:63], v[148:151], v[132:135]
	v_mfma_f32_16x16x32_f16 v[128:131], v[100:103], v[148:151], v[128:131]
	v_mfma_f32_16x16x32_f16 v[108:111], v[60:63], v[164:167], v[108:111]
	v_mfma_f32_16x16x32_f16 v[104:107], v[100:103], v[164:167], v[104:107]
	v_mfma_f32_16x16x32_f16 v[88:91], v[60:63], v[184:187], v[88:91]
	v_mfma_f32_16x16x32_f16 v[84:87], v[100:103], v[184:187], v[84:87]
	v_mfma_f32_16x16x32_f16 v[160:163], v[64:67], v[140:143], v[160:163]
	v_mfma_f32_16x16x32_f16 v[152:155], v[112:115], v[140:143], v[152:155]
	v_mfma_f32_16x16x32_f16 v[132:135], v[64:67], v[156:159], v[132:135]
	v_mfma_f32_16x16x32_f16 v[128:131], v[112:115], v[156:159], v[128:131]
	v_mfma_f32_16x16x32_f16 v[108:111], v[64:67], v[168:171], v[108:111]
	v_mfma_f32_16x16x32_f16 v[104:107], v[112:115], v[168:171], v[104:107]
	v_mfma_f32_16x16x32_f16 v[88:91], v[64:67], v[192:195], v[88:91]
	v_mfma_f32_16x16x32_f16 v[84:87], v[112:115], v[192:195], v[84:87]
	s_barrier
	s_add_i32 s31, 0, 0x1c000
	s_add_i32 s29, s29, s6
	v_add_u32_e32 v2, s31, v190
	v_lshl_add_u64 v[214:215], v[214:215], 0, s[88:89]
	s_mov_b32 m0, s29
	ds_read_b128 v[196:199], v2
	ds_read_b128 v[200:203], v2 offset:1024
	ds_read_b128 v[206:209], v2 offset:2048
	ds_read_b128 v[210:213], v2 offset:3072
	global_load_lds_dwordx4 v[214:215], off
	v_lshl_add_u64 v[214:215], v[216:217], 0, s[88:89]
	s_add_i32 m0, s29, 0x2000
	s_nop 0
	global_load_lds_dwordx4 v[214:215], off
	s_waitcnt vmcnt(10)
	s_barrier
	s_waitcnt lgkmcnt(0)
	v_mfma_f32_16x16x32_f16 v[144:147], v[196:199], v[136:139], v[144:147]
	v_mfma_f32_16x16x32_f16 v[124:127], v[206:209], v[136:139], v[124:127]
	v_mfma_f32_16x16x32_f16 v[120:123], v[196:199], v[148:151], v[120:123]
	v_mfma_f32_16x16x32_f16 v[116:119], v[206:209], v[148:151], v[116:119]
	v_mfma_f32_16x16x32_f16 v[96:99], v[196:199], v[164:167], v[96:99]
	v_mfma_f32_16x16x32_f16 v[92:95], v[206:209], v[164:167], v[92:95]
	v_mfma_f32_16x16x32_f16 v[80:83], v[196:199], v[184:187], v[80:83]
	v_mfma_f32_16x16x32_f16 v[76:79], v[206:209], v[184:187], v[76:79]
	v_mfma_f32_16x16x32_f16 v[144:147], v[200:203], v[140:143], v[144:147]
	v_mfma_f32_16x16x32_f16 v[140:143], v[210:213], v[140:143], v[124:127]
	v_mfma_f32_16x16x32_f16 v[120:123], v[200:203], v[156:159], v[120:123]
	v_mfma_f32_16x16x32_f16 v[116:119], v[210:213], v[156:159], v[116:119]
	v_mfma_f32_16x16x32_f16 v[96:99], v[200:203], v[168:171], v[96:99]
	v_mfma_f32_16x16x32_f16 v[92:95], v[210:213], v[168:171], v[92:95]
	v_mfma_f32_16x16x32_f16 v[80:83], v[200:203], v[192:195], v[80:83]
	v_mfma_f32_16x16x32_f16 v[76:79], v[210:213], v[192:195], v[76:79]
	s_mov_b32 m0, s15
	v_lshl_add_u64 v[214:215], v[218:219], 0, s[88:89]
	s_barrier
	ds_read_b128 v[124:127], v191 offset:49152
	ds_read_b128 v[136:139], v191 offset:50176
	ds_read_b128 v[148:151], v191 offset:51200
	ds_read_b128 v[156:159], v191 offset:52224
	ds_read_b128 v[164:167], v191 offset:53248
	ds_read_b128 v[168:171], v191 offset:54272
	ds_read_b128 v[184:187], v191 offset:55296
	ds_read_b128 v[192:195], v191 offset:56320
	global_load_lds_dwordx4 v[214:215], off
	v_lshl_add_u64 v[214:215], v[220:221], 0, s[88:89]
	s_mov_b32 m0, s30
	s_nop 0
	global_load_lds_dwordx4 v[214:215], off
	s_barrier
	s_waitcnt lgkmcnt(0)
	v_mfma_f32_16x16x32_f16 v[72:75], v[60:63], v[124:127], v[72:75]
	v_mfma_f32_16x16x32_f16 v[68:71], v[100:103], v[124:127], v[68:71]
	v_mfma_f32_16x16x32_f16 v[56:59], v[60:63], v[148:151], v[56:59]
	v_mfma_f32_16x16x32_f16 v[52:55], v[100:103], v[148:151], v[52:55]
	v_mfma_f32_16x16x32_f16 v[40:43], v[60:63], v[164:167], v[40:43]
	v_mfma_f32_16x16x32_f16 v[36:39], v[100:103], v[164:167], v[36:39]
	v_mfma_f32_16x16x32_f16 v[16:19], v[60:63], v[184:187], v[16:19]
	v_mfma_f32_16x16x32_f16 v[12:15], v[100:103], v[184:187], v[12:15]
	v_mfma_f32_16x16x32_f16 v[72:75], v[64:67], v[136:139], v[72:75]
	v_mfma_f32_16x16x32_f16 v[68:71], v[112:115], v[136:139], v[68:71]
	v_mfma_f32_16x16x32_f16 v[56:59], v[64:67], v[156:159], v[56:59]
	v_mfma_f32_16x16x32_f16 v[52:55], v[112:115], v[156:159], v[52:55]
	v_mfma_f32_16x16x32_f16 v[40:43], v[64:67], v[168:171], v[40:43]
	v_mfma_f32_16x16x32_f16 v[36:39], v[112:115], v[168:171], v[36:39]
	v_mfma_f32_16x16x32_f16 v[16:19], v[64:67], v[192:195], v[16:19]
	v_mfma_f32_16x16x32_f16 v[12:15], v[112:115], v[192:195], v[12:15]
	s_barrier
	s_add_u32 s38, s38, 0x20080
	s_addc_u32 s39, s39, 0
	s_add_i32 s29, s31, s6
	s_mov_b32 m0, s29
	s_nop 0
	global_load_lds_dwordx4 v176, s[38:39]
	s_add_i32 m0, s29, 0x2000
	s_nop 0
	global_load_lds_dwordx4 v172, s[38:39]
	s_waitcnt vmcnt(8)
	s_barrier
	v_mfma_f32_16x16x32_f16 v[28:31], v[196:199], v[124:127], v[28:31]
	v_mfma_f32_16x16x32_f16 v[64:67], v[200:203], v[136:139], v[28:31]
	v_mfma_f32_16x16x32_f16 v[28:31], v[206:209], v[124:127], v[32:35]
	v_mfma_f32_16x16x32_f16 v[60:63], v[210:213], v[136:139], v[28:31]
	v_mfma_f32_16x16x32_f16 v[28:31], v[196:199], v[148:151], v[48:51]
	v_mfma_f32_16x16x32_f16 v[48:51], v[200:203], v[156:159], v[28:31]
	v_mfma_f32_16x16x32_f16 v[28:31], v[206:209], v[148:151], v[44:47]
	v_mfma_f32_16x16x32_f16 v[24:27], v[196:199], v[164:167], v[24:27]
	v_mfma_f32_16x16x32_f16 v[20:23], v[206:209], v[164:167], v[20:23]
	v_mfma_f32_16x16x32_f16 v[8:11], v[196:199], v[184:187], v[8:11]
	v_mfma_f32_16x16x32_f16 v[4:7], v[206:209], v[184:187], v[4:7]
	v_mfma_f32_16x16x32_f16 v[44:47], v[210:213], v[156:159], v[28:31]
	v_mfma_f32_16x16x32_f16 v[24:27], v[200:203], v[168:171], v[24:27]
	v_mfma_f32_16x16x32_f16 v[20:23], v[210:213], v[168:171], v[20:23]
	v_mfma_f32_16x16x32_f16 v[8:11], v[200:203], v[192:195], v[8:11]
	v_mfma_f32_16x16x32_f16 v[4:7], v[210:213], v[192:195], v[4:7]
	s_add_i32 s19, s19, 2
	s_add_u32 s26, s26, 0x100
	s_addc_u32 s27, s27, 0
	s_add_u32 s11, s11, 0x100
	s_addc_u32 s17, s17, 0
	s_cmp_gt_u32 s19, 5
	s_barrier
	s_cbranch_scc0 .LBB0_1341
	v_mov_b32_e32 v2, v188
	s_lshl_b32 s10, s10, 8
	s_lshl_b32 s26, s16, 4
	v_mov_b32_e32 v28, v189
	s_add_i32 s10, s10, s44
	s_ashr_i32 s27, s26, 31
	v_add_u32_e32 v100, s10, v2
	v_lshlrev_b32_e32 v2, 3, v28
	s_lshl_b64 s[10:11], s[26:27], 2
	v_and_b32_e32 v193, 8, v2
	s_add_u32 s10, s13, s10
	v_add_u32_e32 v186, s45, v2
	s_addc_u32 s11, s14, s11
	v_lshlrev_b32_e32 v2, 2, v193
	s_ashr_i32 s17, s16, 31
	v_lshl_add_u64 v[28:29], s[10:11], 0, v[2:3]
	s_lshl_b64 s[10:11], s[16:17], 10
	v_readlane_b32 s16, v253, 2
	v_readlane_b32 s17, v253, 3
	s_add_u32 s10, s16, s10
	v_ashrrev_i32_e32 v187, 31, v186
	s_addc_u32 s11, s17, s11
	v_ashrrev_i32_e32 v101, 31, v100
	v_lshlrev_b32_e32 v192, 4, v100
	v_lshl_add_u64 v[102:103], v[186:187], 1, s[10:11]
	v_lshlrev_b64 v[100:101], 15, v[100:101]
	v_lshl_add_u64 v[184:185], v[102:103], 0, v[100:101]
	s_mov_b64 s[10:11], 0x80000
	v_lshl_add_u64 v[148:149], v[184:185], 0, s[10:11]
	s_mov_b64 s[10:11], 0x100000
	v_lshl_add_u64 v[124:125], v[184:185], 0, s[10:11]
	s_mov_b64 s[10:11], 0x180000
	v_lshl_add_u64 v[100:101], v[184:185], 0, s[10:11]
	s_mov_b32 s10, 0x180000
	v_add_co_u32_e32 v102, vcc, s10, v184
	s_mov_b32 s10, 0x100000
	s_nop 0
	v_addc_co_u32_e32 v103, vcc, 0, v185, vcc
	flat_load_dwordx4 v[32:35], v[28:29]
	s_nop 0
	flat_load_dwordx4 v[28:31], v[28:29] offset:16
	s_mov_b32 s38, 0x3a800000
	global_load_dwordx4 v[112:115], v[102:103], off
	v_add_co_u32_e32 v102, vcc, s10, v184
	s_mov_b32 s10, 0x80000
	s_nop 0
	v_addc_co_u32_e32 v103, vcc, 0, v185, vcc
	global_load_dwordx4 v[136:139], v[102:103], off
	v_add_co_u32_e32 v102, vcc, s10, v184
	v_readlane_b32 s16, v253, 25
	s_nop 0
	v_addc_co_u32_e32 v103, vcc, 0, v185, vcc
	global_load_dwordx4 v[156:159], v[102:103], off
	global_load_dwordx4 v[164:167], v[184:185], off offset:256
	global_load_dwordx4 v[168:171], v[184:185], off
	s_nop 0
	global_load_dwordx4 v[100:103], v[100:101], off offset:256
	s_nop 0
	global_load_dwordx4 v[124:127], v[124:125], off offset:256
	s_nop 0
	global_load_dwordx4 v[148:151], v[148:149], off offset:256
	v_readlane_b32 s17, v253, 26
	s_lshl_b64 s[42:43], s[26:27], 1
	s_mov_b64 s[10:11], 0x400000
	s_mov_b64 s[26:27], s[34:35]
	s_waitcnt vmcnt(0)
	s_nop 0
	v_cvt_f32_f16_e32 v194, v168
	v_cvt_f32_f16_sdwa v195, v168 dst_sel:DWORD dst_unused:UNUSED_PAD src0_sel:WORD_1
	s_waitcnt lgkmcnt(0)
	v_pk_mul_f32 v[194:195], v[32:33], v[194:195]
	s_nop 0
	v_pk_fma_f32 v[160:161], v[160:161], s[38:39], v[194:195] op_sel_hi:[1,0,1]
	s_nop 0
	v_mul_f32_e32 v2, 0x3d372713, v160
	v_mul_f32_e32 v2, v160, v2
	v_fma_f32 v2, v160, v2, v160
	v_mul_f32_e32 v2, 0x3f4c422a, v2
	v_mul_f32_e32 v2, -2.0, v2
	v_mul_f32_e32 v2, 0x3fb8aa3b, v2
	v_exp_f32_e32 v2, v2
	s_nop 0
	v_add_f32_e32 v2, 1.0, v2
	v_rcp_f32_e32 v194, v2
	v_mul_f32_e32 v2, 0x3d372713, v161
	v_mul_f32_e32 v2, v161, v2
	v_fma_f32 v2, v161, v2, v161
	v_mul_f32_e32 v2, 0x3f4c422a, v2
	v_mul_f32_e32 v2, -2.0, v2
	v_mul_f32_e32 v2, 0x3fb8aa3b, v2
	v_exp_f32_e32 v2, v2
	s_nop 0
	v_add_f32_e32 v2, 1.0, v2
	v_rcp_f32_e32 v195, v2
	s_nop 0
	v_pk_mul_f32 v[160:161], v[160:161], v[194:195]
	s_nop 0
	v_cvt_pk_f16_f32 v2, v160, v161
	v_cvt_f32_f16_e32 v160, v170
	v_cvt_f32_f16_sdwa v161, v170 dst_sel:DWORD dst_unused:UNUSED_PAD src0_sel:WORD_1
	v_pk_mul_f32 v[160:161], v[28:29], v[160:161]
	s_nop 0
	v_pk_fma_f32 v[152:153], v[152:153], s[38:39], v[160:161] op_sel_hi:[1,0,1]
	s_nop 0
	v_mul_f32_e32 v160, 0x3d372713, v152
	v_mul_f32_e32 v161, 0x3d372713, v153
	v_mul_f32_e32 v160, v152, v160
	v_mul_f32_e32 v161, v153, v161
	v_fma_f32 v160, v152, v160, v152
	v_fma_f32 v161, v153, v161, v153
	v_mul_f32_e32 v160, 0x3f4c422a, v160
	v_mul_f32_e32 v161, 0x3f4c422a, v161
	v_mul_f32_e32 v160, -2.0, v160
	v_mul_f32_e32 v161, -2.0, v161
	v_mul_f32_e32 v160, 0x3fb8aa3b, v160
	v_mul_f32_e32 v161, 0x3fb8aa3b, v161
	v_exp_f32_e32 v160, v160
	v_exp_f32_e32 v161, v161
	v_add_f32_e32 v160, 1.0, v160
	v_add_f32_e32 v161, 1.0, v161
	v_rcp_f32_e32 v160, v160
	v_rcp_f32_e32 v161, v161
	s_nop 0
	v_pk_mul_f32 v[152:153], v[152:153], v[160:161]
	s_nop 0
	v_cvt_pk_f16_f32 v168, v152, v153
	v_cvt_f32_f16_e32 v152, v169
	v_cvt_f32_f16_sdwa v153, v169 dst_sel:DWORD dst_unused:UNUSED_PAD src0_sel:WORD_1
	v_pk_mul_f32 v[152:153], v[34:35], v[152:153]
	s_nop 0
	v_pk_fma_f32 v[152:153], v[162:163], s[38:39], v[152:153] op_sel_hi:[1,0,1]
	s_nop 0
	v_mul_f32_e32 v160, 0x3d372713, v152
	v_mul_f32_e32 v161, 0x3d372713, v153
	v_mul_f32_e32 v160, v152, v160
	v_mul_f32_e32 v161, v153, v161
	v_fma_f32 v160, v152, v160, v152
	v_fma_f32 v161, v153, v161, v153
	v_mul_f32_e32 v160, 0x3f4c422a, v160
	v_mul_f32_e32 v161, 0x3f4c422a, v161
	v_mul_f32_e32 v160, -2.0, v160
	v_mul_f32_e32 v161, -2.0, v161
	v_mul_f32_e32 v160, 0x3fb8aa3b, v160
	v_mul_f32_e32 v161, 0x3fb8aa3b, v161
	v_exp_f32_e32 v160, v160
	v_exp_f32_e32 v161, v161
	v_add_f32_e32 v160, 1.0, v160
	v_add_f32_e32 v161, 1.0, v161
	v_rcp_f32_e32 v160, v160
	v_rcp_f32_e32 v161, v161
	s_nop 0
	v_pk_mul_f32 v[152:153], v[152:153], v[160:161]
	s_nop 0
	v_cvt_pk_f16_f32 v161, v152, v153
	v_cvt_f32_f16_e32 v152, v171
	v_cvt_f32_f16_sdwa v153, v171 dst_sel:DWORD dst_unused:UNUSED_PAD src0_sel:WORD_1
	v_pk_mul_f32 v[152:153], v[30:31], v[152:153]
	s_nop 0
	v_pk_fma_f32 v[152:153], v[154:155], s[38:39], v[152:153] op_sel_hi:[1,0,1]
	s_nop 0
	v_mul_f32_e32 v154, 0x3d372713, v152
	v_mul_f32_e32 v155, 0x3d372713, v153
	v_mul_f32_e32 v154, v152, v154
	v_mul_f32_e32 v155, v153, v155
	v_fma_f32 v154, v152, v154, v152
	v_fma_f32 v155, v153, v155, v153
	v_mul_f32_e32 v154, 0x3f4c422a, v154
	v_mul_f32_e32 v155, 0x3f4c422a, v155
	v_mul_f32_e32 v154, -2.0, v154
	v_mul_f32_e32 v155, -2.0, v155
	v_mul_f32_e32 v154, 0x3fb8aa3b, v154
	v_mul_f32_e32 v155, 0x3fb8aa3b, v155
	v_exp_f32_e32 v154, v154
	v_exp_f32_e32 v155, v155
	v_add_f32_e32 v154, 1.0, v154
	v_add_f32_e32 v155, 1.0, v155
	v_rcp_f32_e32 v154, v154
	v_rcp_f32_e32 v155, v155
	s_nop 0
	v_pk_mul_f32 v[152:153], v[152:153], v[154:155]
	v_lshrrev_b32_e32 v154, 4, v2
	v_and_b32_e32 v154, 0x10001, v154
	v_add3_u32 v2, v2, v154, s21
	v_and_b32_e32 v160, 0xfff0fff0, v2
	v_lshrrev_b32_e32 v2, 4, v161
	v_and_b32_e32 v2, 0x10001, v2
	v_add3_u32 v2, v161, v2, s21
	v_and_b32_e32 v161, 0xfff0fff0, v2
	v_lshrrev_b32_e32 v2, 4, v168
	v_cvt_pk_f16_f32 v153, v152, v153
	v_ashrrev_i32_e32 v152, 4, v186
	v_and_b32_e32 v2, 0x10001, v2
	v_add3_u32 v2, v168, v2, s21
	v_add_u32_e32 v154, v152, v192
	v_and_b32_e32 v162, 0xfff0fff0, v2
	v_lshrrev_b32_e32 v2, 4, v153
	v_ashrrev_i32_e32 v155, 31, v154
	v_and_b32_e32 v2, 0x10001, v2
	v_lshlrev_b64 v[154:155], 10, v[154:155]
	v_add3_u32 v2, v153, v2, s21
	v_lshl_add_u64 v[154:155], s[16:17], 0, v[154:155]
	v_and_b32_e32 v163, 0xfff0fff0, v2
	v_lshl_add_u64 v[154:155], v[154:155], 0, s[42:43]
	v_lshlrev_b32_e32 v2, 1, v193
	v_lshl_add_u64 v[154:155], v[154:155], 0, v[2:3]
	global_store_dwordx4 v[154:155], v[160:163], off
	v_cvt_f32_f16_e32 v154, v164
	v_cvt_f32_f16_sdwa v155, v164 dst_sel:DWORD dst_unused:UNUSED_PAD src0_sel:WORD_1
	v_add_u32_e32 v153, 0x80, v186
	v_pk_mul_f32 v[154:155], v[32:33], v[154:155]
	s_nop 0
	v_pk_fma_f32 v[144:145], v[144:145], s[38:39], v[154:155] op_sel_hi:[1,0,1]
	s_nop 0
	v_mul_f32_e32 v154, 0x3d372713, v144
	v_mul_f32_e32 v155, 0x3d372713, v145
	v_mul_f32_e32 v154, v144, v154
	v_mul_f32_e32 v155, v145, v155
	v_fma_f32 v154, v144, v154, v144
	v_fma_f32 v155, v145, v155, v145
	v_mul_f32_e32 v154, 0x3f4c422a, v154
	v_mul_f32_e32 v155, 0x3f4c422a, v155
	v_mul_f32_e32 v154, -2.0, v154
	v_mul_f32_e32 v155, -2.0, v155
	v_mul_f32_e32 v154, 0x3fb8aa3b, v154
	v_mul_f32_e32 v155, 0x3fb8aa3b, v155
	v_exp_f32_e32 v154, v154
	v_exp_f32_e32 v155, v155
	v_add_f32_e32 v154, 1.0, v154
	v_add_f32_e32 v155, 1.0, v155
	v_rcp_f32_e32 v154, v154
	v_rcp_f32_e32 v155, v155
	s_nop 0
	v_pk_mul_f32 v[144:145], v[144:145], v[154:155]
	s_nop 0
	v_cvt_pk_f16_f32 v154, v144, v145
	v_cvt_f32_f16_e32 v144, v166
	v_cvt_f32_f16_sdwa v145, v166 dst_sel:DWORD dst_unused:UNUSED_PAD src0_sel:WORD_1
	v_pk_mul_f32 v[144:145], v[28:29], v[144:145]
	s_nop 0
	v_pk_fma_f32 v[140:141], v[140:141], s[38:39], v[144:145] op_sel_hi:[1,0,1]
	s_nop 0
	v_mul_f32_e32 v144, 0x3d372713, v140
	v_mul_f32_e32 v145, 0x3d372713, v141
	v_mul_f32_e32 v144, v140, v144
	v_mul_f32_e32 v145, v141, v145
	v_fma_f32 v144, v140, v144, v140
	v_fma_f32 v145, v141, v145, v141
	v_mul_f32_e32 v144, 0x3f4c422a, v144
	v_mul_f32_e32 v145, 0x3f4c422a, v145
	v_mul_f32_e32 v144, -2.0, v144
	v_mul_f32_e32 v145, -2.0, v145
	v_mul_f32_e32 v144, 0x3fb8aa3b, v144
	v_mul_f32_e32 v145, 0x3fb8aa3b, v145
	v_exp_f32_e32 v144, v144
	v_exp_f32_e32 v145, v145
	v_add_f32_e32 v144, 1.0, v144
	v_add_f32_e32 v145, 1.0, v145
	v_rcp_f32_e32 v144, v144
	v_rcp_f32_e32 v145, v145
	s_nop 0
	v_pk_mul_f32 v[140:141], v[140:141], v[144:145]
	s_nop 0
	v_cvt_pk_f16_f32 v155, v140, v141
	v_cvt_f32_f16_e32 v140, v165
	v_cvt_f32_f16_sdwa v141, v165 dst_sel:DWORD dst_unused:UNUSED_PAD src0_sel:WORD_1
	v_pk_mul_f32 v[140:141], v[34:35], v[140:141]
	s_nop 0
	v_pk_fma_f32 v[140:141], v[146:147], s[38:39], v[140:141] op_sel_hi:[1,0,1]
	s_nop 0
	v_mul_f32_e32 v144, 0x3d372713, v140
	v_mul_f32_e32 v145, 0x3d372713, v141
	v_mul_f32_e32 v144, v140, v144
	v_mul_f32_e32 v145, v141, v145
	v_fma_f32 v144, v140, v144, v140
	v_fma_f32 v145, v141, v145, v141
	v_mul_f32_e32 v144, 0x3f4c422a, v144
	v_mul_f32_e32 v145, 0x3f4c422a, v145
	v_mul_f32_e32 v144, -2.0, v144
	v_mul_f32_e32 v145, -2.0, v145
	v_mul_f32_e32 v144, 0x3fb8aa3b, v144
	v_mul_f32_e32 v145, 0x3fb8aa3b, v145
	v_exp_f32_e32 v144, v144
	v_exp_f32_e32 v145, v145
	v_add_f32_e32 v144, 1.0, v144
	v_add_f32_e32 v145, 1.0, v145
	v_rcp_f32_e32 v144, v144
	v_rcp_f32_e32 v145, v145
	s_nop 0
	v_pk_mul_f32 v[140:141], v[140:141], v[144:145]
	s_nop 0
	v_cvt_pk_f16_f32 v144, v140, v141
	v_cvt_f32_f16_e32 v140, v167
	v_cvt_f32_f16_sdwa v141, v167 dst_sel:DWORD dst_unused:UNUSED_PAD src0_sel:WORD_1
	v_pk_mul_f32 v[140:141], v[30:31], v[140:141]
	s_nop 0
	v_pk_fma_f32 v[140:141], v[142:143], s[38:39], v[140:141] op_sel_hi:[1,0,1]
	s_nop 0
	v_mul_f32_e32 v142, 0x3d372713, v140
	v_mul_f32_e32 v143, 0x3d372713, v141
	v_mul_f32_e32 v142, v140, v142
	v_mul_f32_e32 v143, v141, v143
	v_fma_f32 v142, v140, v142, v140
	v_fma_f32 v143, v141, v143, v141
	v_mul_f32_e32 v142, 0x3f4c422a, v142
	v_mul_f32_e32 v143, 0x3f4c422a, v143
	v_mul_f32_e32 v142, -2.0, v142
	v_mul_f32_e32 v143, -2.0, v143
	v_mul_f32_e32 v142, 0x3fb8aa3b, v142
	v_mul_f32_e32 v143, 0x3fb8aa3b, v143
	v_exp_f32_e32 v142, v142
	v_exp_f32_e32 v143, v143
	v_add_f32_e32 v142, 1.0, v142
	v_add_f32_e32 v143, 1.0, v143
	v_rcp_f32_e32 v142, v142
	v_rcp_f32_e32 v143, v143
	s_nop 0
	v_pk_mul_f32 v[140:141], v[140:141], v[142:143]
	s_nop 0
	v_cvt_pk_f16_f32 v141, v140, v141
	v_ashrrev_i32_e32 v140, 4, v153
	v_lshrrev_b32_e32 v143, 4, v144
	v_add_u32_e32 v146, v140, v192
	v_and_b32_e32 v143, 0x10001, v143
	v_ashrrev_i32_e32 v147, 31, v146
	v_lshrrev_b32_e32 v142, 4, v154
	v_add3_u32 v143, v144, v143, s21
	v_lshrrev_b32_e32 v144, 4, v155
	v_lshrrev_b32_e32 v145, 4, v141
	v_lshlrev_b64 v[146:147], 10, v[146:147]
	v_and_b32_e32 v142, 0x10001, v142
	v_and_b32_e32 v144, 0x10001, v144
	v_and_b32_e32 v145, 0x10001, v145
	v_lshl_add_u64 v[146:147], s[16:17], 0, v[146:147]
	v_add3_u32 v142, v154, v142, s21
	v_add3_u32 v144, v155, v144, s21
	v_add3_u32 v141, v141, v145, s21
	v_lshl_add_u64 v[146:147], v[146:147], 0, s[42:43]
	v_and_b32_e32 v142, 0xfff0fff0, v142
	v_and_b32_e32 v143, 0xfff0fff0, v143
	v_and_b32_e32 v144, 0xfff0fff0, v144
	v_and_b32_e32 v145, 0xfff0fff0, v141
	v_lshl_add_u64 v[146:147], v[146:147], 0, v[2:3]
	global_store_dwordx4 v[146:147], v[142:145], off
	v_add_u32_e32 v141, 0x100, v192
	s_nop 0
	v_cvt_f32_f16_e32 v142, v156
	v_cvt_f32_f16_sdwa v143, v156 dst_sel:DWORD dst_unused:UNUSED_PAD src0_sel:WORD_1
	v_pk_mul_f32 v[142:143], v[32:33], v[142:143]
	s_nop 0
	v_pk_fma_f32 v[132:133], v[132:133], s[38:39], v[142:143] op_sel_hi:[1,0,1]
	s_nop 0
	v_mul_f32_e32 v142, 0x3d372713, v132
	v_mul_f32_e32 v143, 0x3d372713, v133
	v_mul_f32_e32 v142, v132, v142
	v_mul_f32_e32 v143, v133, v143
	v_fma_f32 v142, v132, v142, v132
	v_fma_f32 v143, v133, v143, v133
	v_mul_f32_e32 v142, 0x3f4c422a, v142
	v_mul_f32_e32 v143, 0x3f4c422a, v143
	v_mul_f32_e32 v142, -2.0, v142
	v_mul_f32_e32 v143, -2.0, v143
	v_mul_f32_e32 v142, 0x3fb8aa3b, v142
	v_mul_f32_e32 v143, 0x3fb8aa3b, v143
	v_exp_f32_e32 v142, v142
	v_exp_f32_e32 v143, v143
	v_add_f32_e32 v142, 1.0, v142
	v_add_f32_e32 v143, 1.0, v143
	v_rcp_f32_e32 v142, v142
	v_rcp_f32_e32 v143, v143
	s_nop 0
	v_pk_mul_f32 v[132:133], v[132:133], v[142:143]
	s_nop 0
	v_cvt_pk_f16_f32 v142, v132, v133
	v_cvt_f32_f16_e32 v132, v158
	v_cvt_f32_f16_sdwa v133, v158 dst_sel:DWORD dst_unused:UNUSED_PAD src0_sel:WORD_1
	v_pk_mul_f32 v[132:133], v[28:29], v[132:133]
	s_nop 0
	v_pk_fma_f32 v[128:129], v[128:129], s[38:39], v[132:133] op_sel_hi:[1,0,1]
	s_nop 0
	v_mul_f32_e32 v132, 0x3d372713, v128
	v_mul_f32_e32 v133, 0x3d372713, v129
	v_mul_f32_e32 v132, v128, v132
	v_mul_f32_e32 v133, v129, v133
	v_fma_f32 v132, v128, v132, v128
	v_fma_f32 v133, v129, v133, v129
	v_mul_f32_e32 v132, 0x3f4c422a, v132
	v_mul_f32_e32 v133, 0x3f4c422a, v133
	v_mul_f32_e32 v132, -2.0, v132
	v_mul_f32_e32 v133, -2.0, v133
	v_mul_f32_e32 v132, 0x3fb8aa3b, v132
	v_mul_f32_e32 v133, 0x3fb8aa3b, v133
	v_exp_f32_e32 v132, v132
	v_exp_f32_e32 v133, v133
	v_add_f32_e32 v132, 1.0, v132
	v_add_f32_e32 v133, 1.0, v133
	v_rcp_f32_e32 v132, v132
	v_rcp_f32_e32 v133, v133
	s_nop 0
	v_pk_mul_f32 v[128:129], v[128:129], v[132:133]
	s_nop 0
	v_cvt_pk_f16_f32 v143, v128, v129
	v_cvt_f32_f16_e32 v128, v157
	v_cvt_f32_f16_sdwa v129, v157 dst_sel:DWORD dst_unused:UNUSED_PAD src0_sel:WORD_1
	v_pk_mul_f32 v[128:129], v[34:35], v[128:129]
	s_nop 0
	v_pk_fma_f32 v[128:129], v[134:135], s[38:39], v[128:129] op_sel_hi:[1,0,1]
	s_nop 0
	v_mul_f32_e32 v132, 0x3d372713, v128
	v_mul_f32_e32 v133, 0x3d372713, v129
	v_mul_f32_e32 v132, v128, v132
	v_mul_f32_e32 v133, v129, v133
	v_fma_f32 v132, v128, v132, v128
	v_fma_f32 v133, v129, v133, v129
	v_mul_f32_e32 v132, 0x3f4c422a, v132
	v_mul_f32_e32 v133, 0x3f4c422a, v133
	v_mul_f32_e32 v132, -2.0, v132
	v_mul_f32_e32 v133, -2.0, v133
	v_mul_f32_e32 v132, 0x3fb8aa3b, v132
	v_mul_f32_e32 v133, 0x3fb8aa3b, v133
	v_exp_f32_e32 v132, v132
	v_exp_f32_e32 v133, v133
	v_add_f32_e32 v132, 1.0, v132
	v_add_f32_e32 v133, 1.0, v133
	v_rcp_f32_e32 v132, v132
	v_rcp_f32_e32 v133, v133
	s_nop 0
	v_pk_mul_f32 v[128:129], v[128:129], v[132:133]
	s_nop 0
	v_cvt_pk_f16_f32 v132, v128, v129
	v_cvt_f32_f16_e32 v128, v159
	v_cvt_f32_f16_sdwa v129, v159 dst_sel:DWORD dst_unused:UNUSED_PAD src0_sel:WORD_1
	v_pk_mul_f32 v[128:129], v[30:31], v[128:129]
	s_nop 0
	v_pk_fma_f32 v[128:129], v[130:131], s[38:39], v[128:129] op_sel_hi:[1,0,1]
	s_nop 0
	v_mul_f32_e32 v130, 0x3d372713, v128
	v_mul_f32_e32 v131, 0x3d372713, v129
	v_mul_f32_e32 v130, v128, v130
	v_mul_f32_e32 v131, v129, v131
	v_fma_f32 v130, v128, v130, v128
	v_fma_f32 v131, v129, v131, v129
	v_mul_f32_e32 v130, 0x3f4c422a, v130
	v_mul_f32_e32 v131, 0x3f4c422a, v131
	v_mul_f32_e32 v130, -2.0, v130
	v_mul_f32_e32 v131, -2.0, v131
	v_mul_f32_e32 v130, 0x3fb8aa3b, v130
	v_mul_f32_e32 v131, 0x3fb8aa3b, v131
	v_exp_f32_e32 v130, v130
	v_exp_f32_e32 v131, v131
	v_add_f32_e32 v130, 1.0, v130
	v_add_f32_e32 v131, 1.0, v131
	v_rcp_f32_e32 v130, v130
	v_rcp_f32_e32 v131, v131
	s_nop 0
	v_pk_mul_f32 v[128:129], v[128:129], v[130:131]
	s_nop 0
	v_cvt_pk_f16_f32 v131, v128, v129
	v_lshrrev_b32_e32 v129, 4, v132
	v_and_b32_e32 v129, 0x10001, v129
	v_add3_u32 v129, v132, v129, s21
	v_lshrrev_b32_e32 v132, 4, v131
	v_and_b32_e32 v132, 0x10001, v132
	v_add3_u32 v131, v131, v132, s21
	v_add_u32_e32 v132, v152, v141
	v_ashrrev_i32_e32 v133, 31, v132
	v_lshrrev_b32_e32 v128, 4, v142
	v_lshrrev_b32_e32 v130, 4, v143
	v_lshlrev_b64 v[132:133], 10, v[132:133]
	v_and_b32_e32 v128, 0x10001, v128
	v_and_b32_e32 v130, 0x10001, v130
	v_lshl_add_u64 v[132:133], s[16:17], 0, v[132:133]
	v_add3_u32 v128, v142, v128, s21
	v_add3_u32 v130, v143, v130, s21
	v_lshl_add_u64 v[132:133], v[132:133], 0, s[42:43]
	v_and_b32_e32 v128, 0xfff0fff0, v128
	v_and_b32_e32 v129, 0xfff0fff0, v129
	v_and_b32_e32 v130, 0xfff0fff0, v130
	v_and_b32_e32 v131, 0xfff0fff0, v131
	v_lshl_add_u64 v[132:133], v[132:133], 0, v[2:3]
	global_store_dwordx4 v[132:133], v[128:131], off
	s_nop 1
	v_cvt_f32_f16_e32 v128, v148
	v_cvt_f32_f16_sdwa v129, v148 dst_sel:DWORD dst_unused:UNUSED_PAD src0_sel:WORD_1
	v_pk_mul_f32 v[128:129], v[32:33], v[128:129]
	s_nop 0
	v_pk_fma_f32 v[120:121], v[120:121], s[38:39], v[128:129] op_sel_hi:[1,0,1]
	s_nop 0
	v_mul_f32_e32 v128, 0x3d372713, v120
	v_mul_f32_e32 v129, 0x3d372713, v121
	v_mul_f32_e32 v128, v120, v128
	v_mul_f32_e32 v129, v121, v129
	v_fma_f32 v128, v120, v128, v120
	v_fma_f32 v129, v121, v129, v121
	v_mul_f32_e32 v128, 0x3f4c422a, v128
	v_mul_f32_e32 v129, 0x3f4c422a, v129
	v_mul_f32_e32 v128, -2.0, v128
	v_mul_f32_e32 v129, -2.0, v129
	v_mul_f32_e32 v128, 0x3fb8aa3b, v128
	v_mul_f32_e32 v129, 0x3fb8aa3b, v129
	v_exp_f32_e32 v128, v128
	v_exp_f32_e32 v129, v129
	v_add_f32_e32 v128, 1.0, v128
	v_add_f32_e32 v129, 1.0, v129
	v_rcp_f32_e32 v128, v128
	v_rcp_f32_e32 v129, v129
	s_nop 0
	v_pk_mul_f32 v[120:121], v[120:121], v[128:129]
	s_nop 0
	v_cvt_pk_f16_f32 v128, v120, v121
	v_cvt_f32_f16_e32 v120, v150
	v_cvt_f32_f16_sdwa v121, v150 dst_sel:DWORD dst_unused:UNUSED_PAD src0_sel:WORD_1
	v_pk_mul_f32 v[120:121], v[28:29], v[120:121]
	s_nop 0
	v_pk_fma_f32 v[116:117], v[116:117], s[38:39], v[120:121] op_sel_hi:[1,0,1]
	s_nop 0
	v_mul_f32_e32 v120, 0x3d372713, v116
	v_mul_f32_e32 v121, 0x3d372713, v117
	v_mul_f32_e32 v120, v116, v120
	v_mul_f32_e32 v121, v117, v121
	v_fma_f32 v120, v116, v120, v116
	v_fma_f32 v121, v117, v121, v117
	v_mul_f32_e32 v120, 0x3f4c422a, v120
	v_mul_f32_e32 v121, 0x3f4c422a, v121
	v_mul_f32_e32 v120, -2.0, v120
	v_mul_f32_e32 v121, -2.0, v121
	v_mul_f32_e32 v120, 0x3fb8aa3b, v120
	v_mul_f32_e32 v121, 0x3fb8aa3b, v121
	v_exp_f32_e32 v120, v120
	v_exp_f32_e32 v121, v121
	v_add_f32_e32 v120, 1.0, v120
	v_add_f32_e32 v121, 1.0, v121
	v_rcp_f32_e32 v120, v120
	v_rcp_f32_e32 v121, v121
	s_nop 0
	v_pk_mul_f32 v[116:117], v[116:117], v[120:121]
	s_nop 0
	v_cvt_pk_f16_f32 v129, v116, v117
	v_cvt_f32_f16_e32 v116, v149
	v_cvt_f32_f16_sdwa v117, v149 dst_sel:DWORD dst_unused:UNUSED_PAD src0_sel:WORD_1
	v_pk_mul_f32 v[116:117], v[34:35], v[116:117]
	s_nop 0
	v_pk_fma_f32 v[116:117], v[122:123], s[38:39], v[116:117] op_sel_hi:[1,0,1]
	s_nop 0
	v_mul_f32_e32 v120, 0x3d372713, v116
	v_mul_f32_e32 v121, 0x3d372713, v117
	v_mul_f32_e32 v120, v116, v120
	v_mul_f32_e32 v121, v117, v121
	v_fma_f32 v120, v116, v120, v116
	v_fma_f32 v121, v117, v121, v117
	v_mul_f32_e32 v120, 0x3f4c422a, v120
	v_mul_f32_e32 v121, 0x3f4c422a, v121
	v_mul_f32_e32 v120, -2.0, v120
	v_mul_f32_e32 v121, -2.0, v121
	v_mul_f32_e32 v120, 0x3fb8aa3b, v120
	v_mul_f32_e32 v121, 0x3fb8aa3b, v121
	v_exp_f32_e32 v120, v120
	v_exp_f32_e32 v121, v121
	v_add_f32_e32 v120, 1.0, v120
	v_add_f32_e32 v121, 1.0, v121
	v_rcp_f32_e32 v120, v120
	v_rcp_f32_e32 v121, v121
	s_nop 0
	v_pk_mul_f32 v[116:117], v[116:117], v[120:121]
	s_nop 0
	v_cvt_pk_f16_f32 v120, v116, v117
	v_cvt_f32_f16_e32 v116, v151
	v_cvt_f32_f16_sdwa v117, v151 dst_sel:DWORD dst_unused:UNUSED_PAD src0_sel:WORD_1
	v_pk_mul_f32 v[116:117], v[30:31], v[116:117]
	s_nop 0
	v_pk_fma_f32 v[116:117], v[118:119], s[38:39], v[116:117] op_sel_hi:[1,0,1]
	s_nop 0
	v_mul_f32_e32 v118, 0x3d372713, v116
	v_mul_f32_e32 v119, 0x3d372713, v117
	v_mul_f32_e32 v118, v116, v118
	v_mul_f32_e32 v119, v117, v119
	v_fma_f32 v118, v116, v118, v116
	v_fma_f32 v119, v117, v119, v117
	v_mul_f32_e32 v118, 0x3f4c422a, v118
	v_mul_f32_e32 v119, 0x3f4c422a, v119
	v_mul_f32_e32 v118, -2.0, v118
	v_mul_f32_e32 v119, -2.0, v119
	v_mul_f32_e32 v118, 0x3fb8aa3b, v118
	v_mul_f32_e32 v119, 0x3fb8aa3b, v119
	v_exp_f32_e32 v118, v118
	v_exp_f32_e32 v119, v119
	v_add_f32_e32 v118, 1.0, v118
	v_add_f32_e32 v119, 1.0, v119
	v_rcp_f32_e32 v118, v118
	v_rcp_f32_e32 v119, v119
	s_nop 0
	v_pk_mul_f32 v[116:117], v[116:117], v[118:119]
	s_nop 0
	v_cvt_pk_f16_f32 v119, v116, v117
	v_lshrrev_b32_e32 v117, 4, v120
	v_and_b32_e32 v117, 0x10001, v117
	v_add3_u32 v117, v120, v117, s21
	v_lshrrev_b32_e32 v120, 4, v119
	v_and_b32_e32 v120, 0x10001, v120
	v_add3_u32 v119, v119, v120, s21
	v_add_u32_e32 v120, v140, v141
	v_ashrrev_i32_e32 v121, 31, v120
	v_lshrrev_b32_e32 v116, 4, v128
	v_lshrrev_b32_e32 v118, 4, v129
	v_lshlrev_b64 v[120:121], 10, v[120:121]
	v_and_b32_e32 v116, 0x10001, v116
	v_and_b32_e32 v118, 0x10001, v118
	v_lshl_add_u64 v[120:121], s[16:17], 0, v[120:121]
	v_add3_u32 v116, v128, v116, s21
	v_add3_u32 v118, v129, v118, s21
	v_lshl_add_u64 v[120:121], v[120:121], 0, s[42:43]
	v_and_b32_e32 v116, 0xfff0fff0, v116
	v_and_b32_e32 v117, 0xfff0fff0, v117
	v_and_b32_e32 v118, 0xfff0fff0, v118
	v_and_b32_e32 v119, 0xfff0fff0, v119
	v_lshl_add_u64 v[120:121], v[120:121], 0, v[2:3]
	global_store_dwordx4 v[120:121], v[116:119], off
	s_nop 1
	v_cvt_f32_f16_e32 v118, v136
	v_cvt_f32_f16_sdwa v119, v136 dst_sel:DWORD dst_unused:UNUSED_PAD src0_sel:WORD_1
	v_add_u32_e32 v116, 0x200, v192
	v_pk_mul_f32 v[118:119], v[32:33], v[118:119]
	s_nop 0
	v_pk_fma_f32 v[108:109], v[108:109], s[38:39], v[118:119] op_sel_hi:[1,0,1]
	s_nop 0
	v_mul_f32_e32 v117, 0x3d372713, v108
	v_mul_f32_e32 v117, v108, v117
	v_fma_f32 v117, v108, v117, v108
	v_mul_f32_e32 v117, 0x3f4c422a, v117
	v_mul_f32_e32 v117, -2.0, v117
	v_mul_f32_e32 v117, 0x3fb8aa3b, v117
	v_exp_f32_e32 v117, v117
	s_nop 0
	v_add_f32_e32 v117, 1.0, v117
	v_rcp_f32_e32 v118, v117
	v_mul_f32_e32 v117, 0x3d372713, v109
	v_mul_f32_e32 v117, v109, v117
	v_fma_f32 v117, v109, v117, v109
	v_mul_f32_e32 v117, 0x3f4c422a, v117
	v_mul_f32_e32 v117, -2.0, v117
	v_mul_f32_e32 v117, 0x3fb8aa3b, v117
	v_exp_f32_e32 v117, v117
	s_nop 0
	v_add_f32_e32 v117, 1.0, v117
	v_rcp_f32_e32 v119, v117
	s_nop 0
	v_pk_mul_f32 v[108:109], v[108:109], v[118:119]
	s_nop 0
	v_cvt_pk_f16_f32 v117, v108, v109
	v_cvt_f32_f16_e32 v108, v138
	v_cvt_f32_f16_sdwa v109, v138 dst_sel:DWORD dst_unused:UNUSED_PAD src0_sel:WORD_1
	v_pk_mul_f32 v[108:109], v[28:29], v[108:109]
	s_nop 0
	v_pk_fma_f32 v[104:105], v[104:105], s[38:39], v[108:109] op_sel_hi:[1,0,1]
	s_nop 0
	v_mul_f32_e32 v108, 0x3d372713, v104
	v_mul_f32_e32 v109, 0x3d372713, v105
	v_mul_f32_e32 v108, v104, v108
	v_mul_f32_e32 v109, v105, v109
	v_fma_f32 v108, v104, v108, v104
	v_fma_f32 v109, v105, v109, v105
	v_mul_f32_e32 v108, 0x3f4c422a, v108
	v_mul_f32_e32 v109, 0x3f4c422a, v109
	v_mul_f32_e32 v108, -2.0, v108
	v_mul_f32_e32 v109, -2.0, v109
	v_mul_f32_e32 v108, 0x3fb8aa3b, v108
	v_mul_f32_e32 v109, 0x3fb8aa3b, v109
	v_exp_f32_e32 v108, v108
	v_exp_f32_e32 v109, v109
	v_add_f32_e32 v108, 1.0, v108
	v_add_f32_e32 v109, 1.0, v109
	v_rcp_f32_e32 v108, v108
	v_rcp_f32_e32 v109, v109
	s_nop 0
	v_pk_mul_f32 v[104:105], v[104:105], v[108:109]
	s_nop 0
	v_cvt_pk_f16_f32 v118, v104, v105
	v_cvt_f32_f16_e32 v104, v137
	v_cvt_f32_f16_sdwa v105, v137 dst_sel:DWORD dst_unused:UNUSED_PAD src0_sel:WORD_1
	v_pk_mul_f32 v[104:105], v[34:35], v[104:105]
	s_nop 0
	v_pk_fma_f32 v[104:105], v[110:111], s[38:39], v[104:105] op_sel_hi:[1,0,1]
	s_nop 0
	v_mul_f32_e32 v108, 0x3d372713, v104
	v_mul_f32_e32 v109, 0x3d372713, v105
	v_mul_f32_e32 v108, v104, v108
	v_mul_f32_e32 v109, v105, v109
	v_fma_f32 v108, v104, v108, v104
	v_fma_f32 v109, v105, v109, v105
	v_mul_f32_e32 v108, 0x3f4c422a, v108
	v_mul_f32_e32 v109, 0x3f4c422a, v109
	v_mul_f32_e32 v108, -2.0, v108
	v_mul_f32_e32 v109, -2.0, v109
	v_mul_f32_e32 v108, 0x3fb8aa3b, v108
	v_mul_f32_e32 v109, 0x3fb8aa3b, v109
	v_exp_f32_e32 v108, v108
	v_exp_f32_e32 v109, v109
	v_add_f32_e32 v108, 1.0, v108
	v_add_f32_e32 v109, 1.0, v109
	v_rcp_f32_e32 v108, v108
	v_rcp_f32_e32 v109, v109
	s_nop 0
	v_pk_mul_f32 v[104:105], v[104:105], v[108:109]
	s_nop 0
	v_cvt_pk_f16_f32 v108, v104, v105
	v_cvt_f32_f16_e32 v104, v139
	v_cvt_f32_f16_sdwa v105, v139 dst_sel:DWORD dst_unused:UNUSED_PAD src0_sel:WORD_1
	v_pk_mul_f32 v[104:105], v[30:31], v[104:105]
	s_nop 0
	v_pk_fma_f32 v[104:105], v[106:107], s[38:39], v[104:105] op_sel_hi:[1,0,1]
	s_nop 0
	v_mul_f32_e32 v106, 0x3d372713, v104
	v_mul_f32_e32 v107, 0x3d372713, v105
	v_mul_f32_e32 v106, v104, v106
	v_mul_f32_e32 v107, v105, v107
	v_fma_f32 v106, v104, v106, v104
	v_fma_f32 v107, v105, v107, v105
	v_mul_f32_e32 v106, 0x3f4c422a, v106
	v_mul_f32_e32 v107, 0x3f4c422a, v107
	v_mul_f32_e32 v106, -2.0, v106
	v_mul_f32_e32 v107, -2.0, v107
	v_mul_f32_e32 v106, 0x3fb8aa3b, v106
	v_mul_f32_e32 v107, 0x3fb8aa3b, v107
	v_exp_f32_e32 v106, v106
	v_exp_f32_e32 v107, v107
	v_add_f32_e32 v106, 1.0, v106
	v_add_f32_e32 v107, 1.0, v107
	v_rcp_f32_e32 v106, v106
	v_rcp_f32_e32 v107, v107
	s_nop 0
	v_pk_mul_f32 v[104:105], v[104:105], v[106:107]
	s_nop 0
	v_cvt_pk_f16_f32 v107, v104, v105
	v_lshrrev_b32_e32 v105, 4, v108
	v_and_b32_e32 v105, 0x10001, v105
	v_add3_u32 v105, v108, v105, s21
	v_lshrrev_b32_e32 v108, 4, v107
	v_and_b32_e32 v108, 0x10001, v108
	v_add3_u32 v107, v107, v108, s21
	v_add_u32_e32 v108, v152, v116
	v_ashrrev_i32_e32 v109, 31, v108
	v_lshrrev_b32_e32 v104, 4, v117
	v_lshrrev_b32_e32 v106, 4, v118
	v_lshlrev_b64 v[108:109], 10, v[108:109]
	v_and_b32_e32 v104, 0x10001, v104
	v_and_b32_e32 v106, 0x10001, v106
	v_lshl_add_u64 v[108:109], s[16:17], 0, v[108:109]
	v_add3_u32 v104, v117, v104, s21
	v_add3_u32 v106, v118, v106, s21
	v_lshl_add_u64 v[108:109], v[108:109], 0, s[42:43]
	v_and_b32_e32 v104, 0xfff0fff0, v104
	v_and_b32_e32 v105, 0xfff0fff0, v105
	v_and_b32_e32 v106, 0xfff0fff0, v106
	v_and_b32_e32 v107, 0xfff0fff0, v107
	v_lshl_add_u64 v[108:109], v[108:109], 0, v[2:3]
	global_store_dwordx4 v[108:109], v[104:107], off
	s_nop 1
	v_cvt_f32_f16_e32 v104, v124
	v_cvt_f32_f16_sdwa v105, v124 dst_sel:DWORD dst_unused:UNUSED_PAD src0_sel:WORD_1
	v_pk_mul_f32 v[104:105], v[32:33], v[104:105]
	s_nop 0
	v_pk_fma_f32 v[96:97], v[96:97], s[38:39], v[104:105] op_sel_hi:[1,0,1]
	s_nop 0
	v_mul_f32_e32 v104, 0x3d372713, v96
	v_mul_f32_e32 v105, 0x3d372713, v97
	v_mul_f32_e32 v104, v96, v104
	v_mul_f32_e32 v105, v97, v105
	v_fma_f32 v104, v96, v104, v96
	v_fma_f32 v105, v97, v105, v97
	v_mul_f32_e32 v104, 0x3f4c422a, v104
	v_mul_f32_e32 v105, 0x3f4c422a, v105
	v_mul_f32_e32 v104, -2.0, v104
	v_mul_f32_e32 v105, -2.0, v105
	v_mul_f32_e32 v104, 0x3fb8aa3b, v104
	v_mul_f32_e32 v105, 0x3fb8aa3b, v105
	v_exp_f32_e32 v104, v104
	v_exp_f32_e32 v105, v105
	v_add_f32_e32 v104, 1.0, v104
	v_add_f32_e32 v105, 1.0, v105
	v_rcp_f32_e32 v104, v104
	v_rcp_f32_e32 v105, v105
	s_nop 0
	v_pk_mul_f32 v[96:97], v[96:97], v[104:105]
	s_nop 0
	v_cvt_pk_f16_f32 v104, v96, v97
	v_cvt_f32_f16_e32 v96, v126
	v_cvt_f32_f16_sdwa v97, v126 dst_sel:DWORD dst_unused:UNUSED_PAD src0_sel:WORD_1
	v_pk_mul_f32 v[96:97], v[28:29], v[96:97]
	s_nop 0
	v_pk_fma_f32 v[92:93], v[92:93], s[38:39], v[96:97] op_sel_hi:[1,0,1]
	s_nop 0
	v_mul_f32_e32 v96, 0x3d372713, v92
	v_mul_f32_e32 v97, 0x3d372713, v93
	v_mul_f32_e32 v96, v92, v96
	v_mul_f32_e32 v97, v93, v97
	v_fma_f32 v96, v92, v96, v92
	v_fma_f32 v97, v93, v97, v93
	v_mul_f32_e32 v96, 0x3f4c422a, v96
	v_mul_f32_e32 v97, 0x3f4c422a, v97
	v_mul_f32_e32 v96, -2.0, v96
	v_mul_f32_e32 v97, -2.0, v97
	v_mul_f32_e32 v96, 0x3fb8aa3b, v96
	v_mul_f32_e32 v97, 0x3fb8aa3b, v97
	v_exp_f32_e32 v96, v96
	v_exp_f32_e32 v97, v97
	v_add_f32_e32 v96, 1.0, v96
	v_add_f32_e32 v97, 1.0, v97
	v_rcp_f32_e32 v96, v96
	v_rcp_f32_e32 v97, v97
	s_nop 0
	v_pk_mul_f32 v[92:93], v[92:93], v[96:97]
	s_nop 0
	v_cvt_pk_f16_f32 v105, v92, v93
	v_cvt_f32_f16_e32 v92, v125
	v_cvt_f32_f16_sdwa v93, v125 dst_sel:DWORD dst_unused:UNUSED_PAD src0_sel:WORD_1
	v_pk_mul_f32 v[92:93], v[34:35], v[92:93]
	s_nop 0
	v_pk_fma_f32 v[92:93], v[98:99], s[38:39], v[92:93] op_sel_hi:[1,0,1]
	s_nop 0
	v_mul_f32_e32 v96, 0x3d372713, v92
	v_mul_f32_e32 v97, 0x3d372713, v93
	v_mul_f32_e32 v96, v92, v96
	v_mul_f32_e32 v97, v93, v97
	v_fma_f32 v96, v92, v96, v92
	v_fma_f32 v97, v93, v97, v93
	v_mul_f32_e32 v96, 0x3f4c422a, v96
	v_mul_f32_e32 v97, 0x3f4c422a, v97
	v_mul_f32_e32 v96, -2.0, v96
	v_mul_f32_e32 v97, -2.0, v97
	v_mul_f32_e32 v96, 0x3fb8aa3b, v96
	v_mul_f32_e32 v97, 0x3fb8aa3b, v97
	v_exp_f32_e32 v96, v96
	v_exp_f32_e32 v97, v97
	v_add_f32_e32 v96, 1.0, v96
	v_add_f32_e32 v97, 1.0, v97
	v_rcp_f32_e32 v96, v96
	v_rcp_f32_e32 v97, v97
	s_nop 0
	v_pk_mul_f32 v[92:93], v[92:93], v[96:97]
	s_nop 0
	v_cvt_pk_f16_f32 v96, v92, v93
	v_cvt_f32_f16_e32 v92, v127
	v_cvt_f32_f16_sdwa v93, v127 dst_sel:DWORD dst_unused:UNUSED_PAD src0_sel:WORD_1
	v_pk_mul_f32 v[92:93], v[30:31], v[92:93]
	s_nop 0
	v_pk_fma_f32 v[92:93], v[94:95], s[38:39], v[92:93] op_sel_hi:[1,0,1]
	s_nop 0
	v_mul_f32_e32 v94, 0x3d372713, v92
	v_mul_f32_e32 v95, 0x3d372713, v93
	v_mul_f32_e32 v94, v92, v94
	v_mul_f32_e32 v95, v93, v95
	v_fma_f32 v94, v92, v94, v92
	v_fma_f32 v95, v93, v95, v93
	v_mul_f32_e32 v94, 0x3f4c422a, v94
	v_mul_f32_e32 v95, 0x3f4c422a, v95
	v_mul_f32_e32 v94, -2.0, v94
	v_mul_f32_e32 v95, -2.0, v95
	v_mul_f32_e32 v94, 0x3fb8aa3b, v94
	v_mul_f32_e32 v95, 0x3fb8aa3b, v95
	v_exp_f32_e32 v94, v94
	v_exp_f32_e32 v95, v95
	v_add_f32_e32 v94, 1.0, v94
	v_add_f32_e32 v95, 1.0, v95
	v_rcp_f32_e32 v94, v94
	v_rcp_f32_e32 v95, v95
	s_nop 0
	v_pk_mul_f32 v[92:93], v[92:93], v[94:95]
	s_nop 0
	v_cvt_pk_f16_f32 v95, v92, v93
	v_lshrrev_b32_e32 v93, 4, v96
	v_and_b32_e32 v93, 0x10001, v93
	v_add3_u32 v93, v96, v93, s21
	v_lshrrev_b32_e32 v96, 4, v95
	v_and_b32_e32 v96, 0x10001, v96
	v_add3_u32 v95, v95, v96, s21
	v_add_u32_e32 v96, v140, v116
	v_ashrrev_i32_e32 v97, 31, v96
	v_lshrrev_b32_e32 v92, 4, v104
	v_lshrrev_b32_e32 v94, 4, v105
	v_lshlrev_b64 v[96:97], 10, v[96:97]
	v_and_b32_e32 v92, 0x10001, v92
	v_and_b32_e32 v94, 0x10001, v94
	v_lshl_add_u64 v[96:97], s[16:17], 0, v[96:97]
	v_add3_u32 v92, v104, v92, s21
	v_add3_u32 v94, v105, v94, s21
	v_lshl_add_u64 v[96:97], v[96:97], 0, s[42:43]
	v_and_b32_e32 v92, 0xfff0fff0, v92
	v_and_b32_e32 v93, 0xfff0fff0, v93
	v_and_b32_e32 v94, 0xfff0fff0, v94
	v_and_b32_e32 v95, 0xfff0fff0, v95
	v_lshl_add_u64 v[96:97], v[96:97], 0, v[2:3]
	global_store_dwordx4 v[96:97], v[92:95], off
	v_add_u32_e32 v104, 0x800, v192
	s_nop 0
	v_cvt_f32_f16_e32 v94, v112
	v_cvt_f32_f16_sdwa v95, v112 dst_sel:DWORD dst_unused:UNUSED_PAD src0_sel:WORD_1
	v_add_u32_e32 v92, 0x300, v192
	v_pk_mul_f32 v[94:95], v[32:33], v[94:95]
	s_nop 0
	v_pk_fma_f32 v[88:89], v[88:89], s[38:39], v[94:95] op_sel_hi:[1,0,1]
	s_nop 0
	v_mul_f32_e32 v93, 0x3d372713, v88
	v_mul_f32_e32 v93, v88, v93
	v_fma_f32 v93, v88, v93, v88
	v_mul_f32_e32 v93, 0x3f4c422a, v93
	v_mul_f32_e32 v93, -2.0, v93
	v_mul_f32_e32 v93, 0x3fb8aa3b, v93
	v_exp_f32_e32 v93, v93
	s_nop 0
	v_add_f32_e32 v93, 1.0, v93
	v_rcp_f32_e32 v94, v93
	v_mul_f32_e32 v93, 0x3d372713, v89
	v_mul_f32_e32 v93, v89, v93
	v_fma_f32 v93, v89, v93, v89
	v_mul_f32_e32 v93, 0x3f4c422a, v93
	v_mul_f32_e32 v93, -2.0, v93
	v_mul_f32_e32 v93, 0x3fb8aa3b, v93
	v_exp_f32_e32 v93, v93
	s_nop 0
	v_add_f32_e32 v93, 1.0, v93
	v_rcp_f32_e32 v95, v93
	s_nop 0
	v_pk_mul_f32 v[88:89], v[88:89], v[94:95]
	s_nop 0
	v_cvt_pk_f16_f32 v93, v88, v89
	v_cvt_f32_f16_e32 v88, v114
	v_cvt_f32_f16_sdwa v89, v114 dst_sel:DWORD dst_unused:UNUSED_PAD src0_sel:WORD_1
	v_pk_mul_f32 v[88:89], v[28:29], v[88:89]
	s_nop 0
	v_pk_fma_f32 v[84:85], v[84:85], s[38:39], v[88:89] op_sel_hi:[1,0,1]
	s_nop 0
	v_mul_f32_e32 v88, 0x3d372713, v84
	v_mul_f32_e32 v89, 0x3d372713, v85
	v_mul_f32_e32 v88, v84, v88
	v_mul_f32_e32 v89, v85, v89
	v_fma_f32 v88, v84, v88, v84
	v_fma_f32 v89, v85, v89, v85
	v_mul_f32_e32 v88, 0x3f4c422a, v88
	v_mul_f32_e32 v89, 0x3f4c422a, v89
	v_mul_f32_e32 v88, -2.0, v88
	v_mul_f32_e32 v89, -2.0, v89
	v_mul_f32_e32 v88, 0x3fb8aa3b, v88
	v_mul_f32_e32 v89, 0x3fb8aa3b, v89
	v_exp_f32_e32 v88, v88
	v_exp_f32_e32 v89, v89
	v_add_f32_e32 v88, 1.0, v88
	v_add_f32_e32 v89, 1.0, v89
	v_rcp_f32_e32 v88, v88
	v_rcp_f32_e32 v89, v89
	s_nop 0
	v_pk_mul_f32 v[84:85], v[84:85], v[88:89]
	s_nop 0
	v_cvt_pk_f16_f32 v94, v84, v85
	v_cvt_f32_f16_e32 v84, v113
	v_cvt_f32_f16_sdwa v85, v113 dst_sel:DWORD dst_unused:UNUSED_PAD src0_sel:WORD_1
	v_pk_mul_f32 v[84:85], v[34:35], v[84:85]
	s_nop 0
	v_pk_fma_f32 v[84:85], v[90:91], s[38:39], v[84:85] op_sel_hi:[1,0,1]
	s_nop 0
	v_mul_f32_e32 v88, 0x3d372713, v84
	v_mul_f32_e32 v89, 0x3d372713, v85
	v_mul_f32_e32 v88, v84, v88
	v_mul_f32_e32 v89, v85, v89
	v_fma_f32 v88, v84, v88, v84
	v_fma_f32 v89, v85, v89, v85
	v_mul_f32_e32 v88, 0x3f4c422a, v88
	v_mul_f32_e32 v89, 0x3f4c422a, v89
	v_mul_f32_e32 v88, -2.0, v88
	v_mul_f32_e32 v89, -2.0, v89
	v_mul_f32_e32 v88, 0x3fb8aa3b, v88
	v_mul_f32_e32 v89, 0x3fb8aa3b, v89
	v_exp_f32_e32 v88, v88
	v_exp_f32_e32 v89, v89
	v_add_f32_e32 v88, 1.0, v88
	v_add_f32_e32 v89, 1.0, v89
	v_rcp_f32_e32 v88, v88
	v_rcp_f32_e32 v89, v89
	s_nop 0
	v_pk_mul_f32 v[84:85], v[84:85], v[88:89]
	s_nop 0
	v_cvt_pk_f16_f32 v88, v84, v85
	v_cvt_f32_f16_e32 v84, v115
	v_cvt_f32_f16_sdwa v85, v115 dst_sel:DWORD dst_unused:UNUSED_PAD src0_sel:WORD_1
	v_pk_mul_f32 v[84:85], v[30:31], v[84:85]
	s_nop 0
	v_pk_fma_f32 v[84:85], v[86:87], s[38:39], v[84:85] op_sel_hi:[1,0,1]
	s_nop 0
	v_mul_f32_e32 v86, 0x3d372713, v84
	v_mul_f32_e32 v87, 0x3d372713, v85
	v_mul_f32_e32 v86, v84, v86
	v_mul_f32_e32 v87, v85, v87
	v_fma_f32 v86, v84, v86, v84
	v_fma_f32 v87, v85, v87, v85
	v_mul_f32_e32 v86, 0x3f4c422a, v86
	v_mul_f32_e32 v87, 0x3f4c422a, v87
	v_mul_f32_e32 v86, -2.0, v86
	v_mul_f32_e32 v87, -2.0, v87
	v_mul_f32_e32 v86, 0x3fb8aa3b, v86
	v_mul_f32_e32 v87, 0x3fb8aa3b, v87
	v_exp_f32_e32 v86, v86
	v_exp_f32_e32 v87, v87
	v_add_f32_e32 v86, 1.0, v86
	v_add_f32_e32 v87, 1.0, v87
	v_rcp_f32_e32 v86, v86
	v_rcp_f32_e32 v87, v87
	s_nop 0
	v_pk_mul_f32 v[84:85], v[84:85], v[86:87]
	s_nop 0
	v_cvt_pk_f16_f32 v87, v84, v85
	v_lshrrev_b32_e32 v85, 4, v88
	v_and_b32_e32 v85, 0x10001, v85
	v_add3_u32 v85, v88, v85, s21
	v_lshrrev_b32_e32 v88, 4, v87
	v_and_b32_e32 v88, 0x10001, v88
	v_add3_u32 v87, v87, v88, s21
	v_add_u32_e32 v88, v152, v92
	v_ashrrev_i32_e32 v89, 31, v88
	v_lshrrev_b32_e32 v84, 4, v93
	v_lshrrev_b32_e32 v86, 4, v94
	v_lshlrev_b64 v[88:89], 10, v[88:89]
	v_and_b32_e32 v84, 0x10001, v84
	v_and_b32_e32 v86, 0x10001, v86
	v_lshl_add_u64 v[88:89], s[16:17], 0, v[88:89]
	v_add3_u32 v84, v93, v84, s21
	v_add3_u32 v86, v94, v86, s21
	v_lshl_add_u64 v[88:89], v[88:89], 0, s[42:43]
	v_and_b32_e32 v84, 0xfff0fff0, v84
	v_and_b32_e32 v85, 0xfff0fff0, v85
	v_and_b32_e32 v86, 0xfff0fff0, v86
	v_and_b32_e32 v87, 0xfff0fff0, v87
	v_lshl_add_u64 v[88:89], v[88:89], 0, v[2:3]
	global_store_dwordx4 v[88:89], v[84:87], off
	s_nop 1
	v_cvt_f32_f16_e32 v84, v100
	v_cvt_f32_f16_sdwa v85, v100 dst_sel:DWORD dst_unused:UNUSED_PAD src0_sel:WORD_1
	v_pk_mul_f32 v[84:85], v[32:33], v[84:85]
	s_nop 0
	v_pk_fma_f32 v[80:81], v[80:81], s[38:39], v[84:85] op_sel_hi:[1,0,1]
	s_nop 0
	v_mul_f32_e32 v84, 0x3d372713, v80
	v_mul_f32_e32 v85, 0x3d372713, v81
	v_mul_f32_e32 v84, v80, v84
	v_mul_f32_e32 v85, v81, v85
	v_fma_f32 v84, v80, v84, v80
	v_fma_f32 v85, v81, v85, v81
	v_mul_f32_e32 v84, 0x3f4c422a, v84
	v_mul_f32_e32 v85, 0x3f4c422a, v85
	v_mul_f32_e32 v84, -2.0, v84
	v_mul_f32_e32 v85, -2.0, v85
	v_mul_f32_e32 v84, 0x3fb8aa3b, v84
	v_mul_f32_e32 v85, 0x3fb8aa3b, v85
	v_exp_f32_e32 v84, v84
	v_exp_f32_e32 v85, v85
	v_add_f32_e32 v84, 1.0, v84
	v_add_f32_e32 v85, 1.0, v85
	v_rcp_f32_e32 v84, v84
	v_rcp_f32_e32 v85, v85
	s_nop 0
	v_pk_mul_f32 v[80:81], v[80:81], v[84:85]
	s_nop 0
	v_cvt_pk_f16_f32 v84, v80, v81
	v_cvt_f32_f16_e32 v80, v102
	v_cvt_f32_f16_sdwa v81, v102 dst_sel:DWORD dst_unused:UNUSED_PAD src0_sel:WORD_1
	v_pk_mul_f32 v[80:81], v[28:29], v[80:81]
	s_nop 0
	v_pk_fma_f32 v[76:77], v[76:77], s[38:39], v[80:81] op_sel_hi:[1,0,1]
	s_nop 0
	v_mul_f32_e32 v80, 0x3d372713, v76
	v_mul_f32_e32 v81, 0x3d372713, v77
	v_mul_f32_e32 v80, v76, v80
	v_mul_f32_e32 v81, v77, v81
	v_fma_f32 v80, v76, v80, v76
	v_fma_f32 v81, v77, v81, v77
	v_mul_f32_e32 v80, 0x3f4c422a, v80
	v_mul_f32_e32 v81, 0x3f4c422a, v81
	v_mul_f32_e32 v80, -2.0, v80
	v_mul_f32_e32 v81, -2.0, v81
	v_mul_f32_e32 v80, 0x3fb8aa3b, v80
	v_mul_f32_e32 v81, 0x3fb8aa3b, v81
	v_exp_f32_e32 v80, v80
	v_exp_f32_e32 v81, v81
	v_add_f32_e32 v80, 1.0, v80
	v_add_f32_e32 v81, 1.0, v81
	v_rcp_f32_e32 v80, v80
	v_rcp_f32_e32 v81, v81
	s_nop 0
	v_pk_mul_f32 v[76:77], v[76:77], v[80:81]
	s_nop 0
	v_cvt_pk_f16_f32 v85, v76, v77
	v_cvt_f32_f16_e32 v76, v101
	v_cvt_f32_f16_sdwa v77, v101 dst_sel:DWORD dst_unused:UNUSED_PAD src0_sel:WORD_1
	v_lshl_add_u64 v[100:101], v[184:185], 0, s[10:11]
	s_mov_b64 s[10:11], 0x480000
	v_pk_mul_f32 v[76:77], v[34:35], v[76:77]
	s_nop 0
	v_pk_fma_f32 v[76:77], v[82:83], s[38:39], v[76:77] op_sel_hi:[1,0,1]
	s_nop 0
	v_mul_f32_e32 v80, 0x3d372713, v76
	v_mul_f32_e32 v81, 0x3d372713, v77
	v_mul_f32_e32 v80, v76, v80
	v_mul_f32_e32 v81, v77, v81
	v_fma_f32 v80, v76, v80, v76
	v_fma_f32 v81, v77, v81, v77
	v_mul_f32_e32 v80, 0x3f4c422a, v80
	v_mul_f32_e32 v81, 0x3f4c422a, v81
	v_mul_f32_e32 v80, -2.0, v80
	v_mul_f32_e32 v81, -2.0, v81
	v_mul_f32_e32 v80, 0x3fb8aa3b, v80
	v_mul_f32_e32 v81, 0x3fb8aa3b, v81
	v_exp_f32_e32 v80, v80
	v_exp_f32_e32 v81, v81
	v_add_f32_e32 v80, 1.0, v80
	v_add_f32_e32 v81, 1.0, v81
	v_rcp_f32_e32 v80, v80
	v_rcp_f32_e32 v81, v81
	s_nop 0
	v_pk_mul_f32 v[76:77], v[76:77], v[80:81]
	s_nop 0
	v_cvt_pk_f16_f32 v80, v76, v77
	v_cvt_f32_f16_e32 v76, v103
	v_cvt_f32_f16_sdwa v77, v103 dst_sel:DWORD dst_unused:UNUSED_PAD src0_sel:WORD_1
	v_pk_mul_f32 v[76:77], v[30:31], v[76:77]
	s_nop 0
	v_pk_fma_f32 v[76:77], v[78:79], s[38:39], v[76:77] op_sel_hi:[1,0,1]
	s_nop 0
	v_mul_f32_e32 v78, 0x3d372713, v76
	v_mul_f32_e32 v79, 0x3d372713, v77
	v_mul_f32_e32 v78, v76, v78
	v_mul_f32_e32 v79, v77, v79
	v_fma_f32 v78, v76, v78, v76
	v_fma_f32 v79, v77, v79, v77
	v_mul_f32_e32 v78, 0x3f4c422a, v78
	v_mul_f32_e32 v79, 0x3f4c422a, v79
	v_mul_f32_e32 v78, -2.0, v78
	v_mul_f32_e32 v79, -2.0, v79
	v_mul_f32_e32 v78, 0x3fb8aa3b, v78
	v_mul_f32_e32 v79, 0x3fb8aa3b, v79
	v_exp_f32_e32 v78, v78
	v_exp_f32_e32 v79, v79
	v_add_f32_e32 v78, 1.0, v78
	v_add_f32_e32 v79, 1.0, v79
	v_rcp_f32_e32 v78, v78
	v_rcp_f32_e32 v79, v79
	s_nop 0
	v_pk_mul_f32 v[76:77], v[76:77], v[78:79]
	s_nop 0
	v_cvt_pk_f16_f32 v79, v76, v77
	v_lshrrev_b32_e32 v77, 4, v80
	v_and_b32_e32 v77, 0x10001, v77
	v_add3_u32 v77, v80, v77, s21
	v_lshrrev_b32_e32 v80, 4, v79
	v_and_b32_e32 v80, 0x10001, v80
	v_add3_u32 v79, v79, v80, s21
	v_add_u32_e32 v80, v140, v92
	v_ashrrev_i32_e32 v81, 31, v80
	v_lshrrev_b32_e32 v76, 4, v84
	v_lshrrev_b32_e32 v78, 4, v85
	v_lshlrev_b64 v[80:81], 10, v[80:81]
	v_and_b32_e32 v76, 0x10001, v76
	v_and_b32_e32 v78, 0x10001, v78
	v_lshl_add_u64 v[80:81], s[16:17], 0, v[80:81]
	v_add3_u32 v76, v84, v76, s21
	v_add3_u32 v78, v85, v78, s21
	v_lshl_add_u64 v[80:81], v[80:81], 0, s[42:43]
	v_lshl_add_u64 v[92:93], v[184:185], 0, s[10:11]
	s_mov_b64 s[10:11], 0x500000
	v_and_b32_e32 v76, 0xfff0fff0, v76
	v_and_b32_e32 v77, 0xfff0fff0, v77
	v_and_b32_e32 v78, 0xfff0fff0, v78
	v_and_b32_e32 v79, 0xfff0fff0, v79
	v_lshl_add_u64 v[80:81], v[80:81], 0, v[2:3]
	v_lshl_add_u64 v[84:85], v[184:185], 0, s[10:11]
	s_mov_b64 s[10:11], 0x580000
	global_store_dwordx4 v[80:81], v[76:79], off
	s_nop 1
	v_lshl_add_u64 v[76:77], v[184:185], 0, s[10:11]
	s_mov_b32 s10, 0x580000
	v_add_co_u32_e32 v78, vcc, s10, v184
	s_mov_b32 s10, 0x500000
	s_nop 0
	v_addc_co_u32_e32 v79, vcc, 0, v185, vcc
	global_load_dwordx4 v[80:83], v[78:79], off
	v_add_co_u32_e32 v78, vcc, s10, v184
	s_mov_b32 s10, 0x480000
	s_nop 0
	v_addc_co_u32_e32 v79, vcc, 0, v185, vcc
	global_load_dwordx4 v[88:91], v[78:79], off
	v_add_co_u32_e32 v78, vcc, s10, v184
	s_mov_b32 s10, 0x400000
	s_nop 0
	v_addc_co_u32_e32 v79, vcc, 0, v185, vcc
	global_load_dwordx4 v[96:99], v[78:79], off
	v_add_co_u32_e32 v78, vcc, s10, v184
	s_mov_b32 s10, s18
	s_nop 0
	v_addc_co_u32_e32 v79, vcc, 0, v185, vcc
	global_load_dwordx4 v[106:109], v[78:79], off
	s_nop 0
	global_load_dwordx4 v[76:79], v[76:77], off offset:256
	s_nop 0
	global_load_dwordx4 v[84:87], v[84:85], off offset:256
	s_nop 0
	global_load_dwordx4 v[92:95], v[92:93], off offset:256
	s_nop 0
	global_load_dwordx4 v[100:103], v[100:101], off offset:256
	s_waitcnt vmcnt(0)
	s_nop 0
	v_cvt_f32_f16_e32 v110, v106
	v_cvt_f32_f16_sdwa v111, v106 dst_sel:DWORD dst_unused:UNUSED_PAD src0_sel:WORD_1
	s_and_b64 vcc, exec, s[40:41]
	v_pk_mul_f32 v[110:111], v[32:33], v[110:111]
	s_nop 0
	v_pk_fma_f32 v[72:73], v[72:73], s[38:39], v[110:111] op_sel_hi:[1,0,1]
	s_nop 0
	v_mul_f32_e32 v105, 0x3d372713, v72
	v_mul_f32_e32 v105, v72, v105
	v_fma_f32 v105, v72, v105, v72
	v_mul_f32_e32 v105, 0x3f4c422a, v105
	v_mul_f32_e32 v105, -2.0, v105
	v_mul_f32_e32 v105, 0x3fb8aa3b, v105
	v_exp_f32_e32 v105, v105
	s_nop 0
	v_add_f32_e32 v105, 1.0, v105
	v_rcp_f32_e32 v110, v105
	v_mul_f32_e32 v105, 0x3d372713, v73
	v_mul_f32_e32 v105, v73, v105
	v_fma_f32 v105, v73, v105, v73
	v_mul_f32_e32 v105, 0x3f4c422a, v105
	v_mul_f32_e32 v105, -2.0, v105
	v_mul_f32_e32 v105, 0x3fb8aa3b, v105
	v_exp_f32_e32 v105, v105
	s_nop 0
	v_add_f32_e32 v105, 1.0, v105
	v_rcp_f32_e32 v111, v105
	s_nop 0
	v_pk_mul_f32 v[72:73], v[72:73], v[110:111]
	s_nop 0
	v_cvt_pk_f16_f32 v105, v72, v73
	v_cvt_f32_f16_e32 v72, v108
	v_cvt_f32_f16_sdwa v73, v108 dst_sel:DWORD dst_unused:UNUSED_PAD src0_sel:WORD_1
	v_pk_mul_f32 v[72:73], v[28:29], v[72:73]
	s_nop 0
	v_pk_fma_f32 v[68:69], v[68:69], s[38:39], v[72:73] op_sel_hi:[1,0,1]
	s_nop 0
	v_mul_f32_e32 v72, 0x3d372713, v68
	v_mul_f32_e32 v73, 0x3d372713, v69
	v_mul_f32_e32 v72, v68, v72
	v_mul_f32_e32 v73, v69, v73
	v_fma_f32 v72, v68, v72, v68
	v_fma_f32 v73, v69, v73, v69
	v_mul_f32_e32 v72, 0x3f4c422a, v72
	v_mul_f32_e32 v73, 0x3f4c422a, v73
	v_mul_f32_e32 v72, -2.0, v72
	v_mul_f32_e32 v73, -2.0, v73
	v_mul_f32_e32 v72, 0x3fb8aa3b, v72
	v_mul_f32_e32 v73, 0x3fb8aa3b, v73
	v_exp_f32_e32 v72, v72
	v_exp_f32_e32 v73, v73
	v_add_f32_e32 v72, 1.0, v72
	v_add_f32_e32 v73, 1.0, v73
	v_rcp_f32_e32 v72, v72
	v_rcp_f32_e32 v73, v73
	s_nop 0
	v_pk_mul_f32 v[68:69], v[68:69], v[72:73]
	s_nop 0
	v_cvt_pk_f16_f32 v106, v68, v69
	v_cvt_f32_f16_e32 v68, v107
	v_cvt_f32_f16_sdwa v69, v107 dst_sel:DWORD dst_unused:UNUSED_PAD src0_sel:WORD_1
	v_pk_mul_f32 v[68:69], v[34:35], v[68:69]
	s_nop 0
	v_pk_fma_f32 v[68:69], v[74:75], s[38:39], v[68:69] op_sel_hi:[1,0,1]
	s_nop 0
	v_mul_f32_e32 v72, 0x3d372713, v68
	v_mul_f32_e32 v73, 0x3d372713, v69
	v_mul_f32_e32 v72, v68, v72
	v_mul_f32_e32 v73, v69, v73
	v_fma_f32 v72, v68, v72, v68
	v_fma_f32 v73, v69, v73, v69
	v_mul_f32_e32 v72, 0x3f4c422a, v72
	v_mul_f32_e32 v73, 0x3f4c422a, v73
	v_mul_f32_e32 v72, -2.0, v72
	v_mul_f32_e32 v73, -2.0, v73
	v_mul_f32_e32 v72, 0x3fb8aa3b, v72
	v_mul_f32_e32 v73, 0x3fb8aa3b, v73
	v_exp_f32_e32 v72, v72
	v_exp_f32_e32 v73, v73
	v_add_f32_e32 v72, 1.0, v72
	v_add_f32_e32 v73, 1.0, v73
	v_rcp_f32_e32 v72, v72
	v_rcp_f32_e32 v73, v73
	s_nop 0
	v_pk_mul_f32 v[68:69], v[68:69], v[72:73]
	s_nop 0
	v_cvt_pk_f16_f32 v72, v68, v69
	v_cvt_f32_f16_e32 v68, v109
	v_cvt_f32_f16_sdwa v69, v109 dst_sel:DWORD dst_unused:UNUSED_PAD src0_sel:WORD_1
	v_pk_mul_f32 v[68:69], v[30:31], v[68:69]
	s_nop 0
	v_pk_fma_f32 v[68:69], v[70:71], s[38:39], v[68:69] op_sel_hi:[1,0,1]
	s_nop 0
	v_mul_f32_e32 v70, 0x3d372713, v68
	v_mul_f32_e32 v71, 0x3d372713, v69
	v_mul_f32_e32 v70, v68, v70
	v_mul_f32_e32 v71, v69, v71
	v_fma_f32 v70, v68, v70, v68
	v_fma_f32 v71, v69, v71, v69
	v_mul_f32_e32 v70, 0x3f4c422a, v70
	v_mul_f32_e32 v71, 0x3f4c422a, v71
	v_mul_f32_e32 v70, -2.0, v70
	v_mul_f32_e32 v71, -2.0, v71
	v_mul_f32_e32 v70, 0x3fb8aa3b, v70
	v_mul_f32_e32 v71, 0x3fb8aa3b, v71
	v_exp_f32_e32 v70, v70
	v_exp_f32_e32 v71, v71
	v_add_f32_e32 v70, 1.0, v70
	v_add_f32_e32 v71, 1.0, v71
	v_rcp_f32_e32 v70, v70
	v_rcp_f32_e32 v71, v71
	s_nop 0
	v_pk_mul_f32 v[68:69], v[68:69], v[70:71]
	s_nop 0
	v_cvt_pk_f16_f32 v71, v68, v69
	v_lshrrev_b32_e32 v69, 4, v72
	v_and_b32_e32 v69, 0x10001, v69
	v_add3_u32 v69, v72, v69, s21
	v_lshrrev_b32_e32 v72, 4, v71
	v_and_b32_e32 v72, 0x10001, v72
	v_add3_u32 v71, v71, v72, s21
	v_add_u32_e32 v72, v152, v104
	v_ashrrev_i32_e32 v73, 31, v72
	v_lshrrev_b32_e32 v68, 4, v105
	v_lshrrev_b32_e32 v70, 4, v106
	v_lshlrev_b64 v[72:73], 10, v[72:73]
	v_and_b32_e32 v68, 0x10001, v68
	v_and_b32_e32 v70, 0x10001, v70
	v_lshl_add_u64 v[72:73], s[16:17], 0, v[72:73]
	v_add3_u32 v68, v105, v68, s21
	v_add3_u32 v70, v106, v70, s21
	v_lshl_add_u64 v[72:73], v[72:73], 0, s[42:43]
	v_and_b32_e32 v68, 0xfff0fff0, v68
	v_and_b32_e32 v69, 0xfff0fff0, v69
	v_and_b32_e32 v70, 0xfff0fff0, v70
	v_and_b32_e32 v71, 0xfff0fff0, v71
	v_lshl_add_u64 v[72:73], v[72:73], 0, v[2:3]
	global_store_dwordx4 v[72:73], v[68:71], off
	s_nop 1
	v_cvt_f32_f16_e32 v68, v100
	v_cvt_f32_f16_sdwa v69, v100 dst_sel:DWORD dst_unused:UNUSED_PAD src0_sel:WORD_1
	v_pk_mul_f32 v[68:69], v[32:33], v[68:69]
	s_nop 0
	v_pk_fma_f32 v[64:65], v[64:65], s[38:39], v[68:69] op_sel_hi:[1,0,1]
	s_nop 0
	v_mul_f32_e32 v68, 0x3d372713, v64
	v_mul_f32_e32 v69, 0x3d372713, v65
	v_mul_f32_e32 v68, v64, v68
	v_mul_f32_e32 v69, v65, v69
	v_fma_f32 v68, v64, v68, v64
	v_fma_f32 v69, v65, v69, v65
	v_mul_f32_e32 v68, 0x3f4c422a, v68
	v_mul_f32_e32 v69, 0x3f4c422a, v69
	v_mul_f32_e32 v68, -2.0, v68
	v_mul_f32_e32 v69, -2.0, v69
	v_mul_f32_e32 v68, 0x3fb8aa3b, v68
	v_mul_f32_e32 v69, 0x3fb8aa3b, v69
	v_exp_f32_e32 v68, v68
	v_exp_f32_e32 v69, v69
	v_add_f32_e32 v68, 1.0, v68
	v_add_f32_e32 v69, 1.0, v69
	v_rcp_f32_e32 v68, v68
	v_rcp_f32_e32 v69, v69
	s_nop 0
	v_pk_mul_f32 v[64:65], v[64:65], v[68:69]
	s_nop 0
	v_cvt_pk_f16_f32 v68, v64, v65
	v_cvt_f32_f16_e32 v64, v102
	v_cvt_f32_f16_sdwa v65, v102 dst_sel:DWORD dst_unused:UNUSED_PAD src0_sel:WORD_1
	v_pk_mul_f32 v[64:65], v[28:29], v[64:65]
	s_nop 0
	v_pk_fma_f32 v[60:61], v[60:61], s[38:39], v[64:65] op_sel_hi:[1,0,1]
	s_nop 0
	v_mul_f32_e32 v64, 0x3d372713, v60
	v_mul_f32_e32 v65, 0x3d372713, v61
	v_mul_f32_e32 v64, v60, v64
	v_mul_f32_e32 v65, v61, v65
	v_fma_f32 v64, v60, v64, v60
	v_fma_f32 v65, v61, v65, v61
	v_mul_f32_e32 v64, 0x3f4c422a, v64
	v_mul_f32_e32 v65, 0x3f4c422a, v65
	v_mul_f32_e32 v64, -2.0, v64
	v_mul_f32_e32 v65, -2.0, v65
	v_mul_f32_e32 v64, 0x3fb8aa3b, v64
	v_mul_f32_e32 v65, 0x3fb8aa3b, v65
	v_exp_f32_e32 v64, v64
	v_exp_f32_e32 v65, v65
	v_add_f32_e32 v64, 1.0, v64
	v_add_f32_e32 v65, 1.0, v65
	v_rcp_f32_e32 v64, v64
	v_rcp_f32_e32 v65, v65
	s_nop 0
	v_pk_mul_f32 v[60:61], v[60:61], v[64:65]
	s_nop 0
	v_cvt_pk_f16_f32 v69, v60, v61
	v_cvt_f32_f16_e32 v60, v101
	v_cvt_f32_f16_sdwa v61, v101 dst_sel:DWORD dst_unused:UNUSED_PAD src0_sel:WORD_1
	v_pk_mul_f32 v[60:61], v[34:35], v[60:61]
	s_nop 0
	v_pk_fma_f32 v[60:61], v[66:67], s[38:39], v[60:61] op_sel_hi:[1,0,1]
	s_nop 0
	v_mul_f32_e32 v64, 0x3d372713, v60
	v_mul_f32_e32 v65, 0x3d372713, v61
	v_mul_f32_e32 v64, v60, v64
	v_mul_f32_e32 v65, v61, v65
	v_fma_f32 v64, v60, v64, v60
	v_fma_f32 v65, v61, v65, v61
	v_mul_f32_e32 v64, 0x3f4c422a, v64
	v_mul_f32_e32 v65, 0x3f4c422a, v65
	v_mul_f32_e32 v64, -2.0, v64
	v_mul_f32_e32 v65, -2.0, v65
	v_mul_f32_e32 v64, 0x3fb8aa3b, v64
	v_mul_f32_e32 v65, 0x3fb8aa3b, v65
	v_exp_f32_e32 v64, v64
	v_exp_f32_e32 v65, v65
	v_add_f32_e32 v64, 1.0, v64
	v_add_f32_e32 v65, 1.0, v65
	v_rcp_f32_e32 v64, v64
	v_rcp_f32_e32 v65, v65
	s_nop 0
	v_pk_mul_f32 v[60:61], v[60:61], v[64:65]
	s_nop 0
	v_cvt_pk_f16_f32 v64, v60, v61
	v_cvt_f32_f16_e32 v60, v103
	v_cvt_f32_f16_sdwa v61, v103 dst_sel:DWORD dst_unused:UNUSED_PAD src0_sel:WORD_1
	v_pk_mul_f32 v[60:61], v[30:31], v[60:61]
	s_nop 0
	v_pk_fma_f32 v[60:61], v[62:63], s[38:39], v[60:61] op_sel_hi:[1,0,1]
	s_nop 0
	v_mul_f32_e32 v62, 0x3d372713, v60
	v_mul_f32_e32 v63, 0x3d372713, v61
	v_mul_f32_e32 v62, v60, v62
	v_mul_f32_e32 v63, v61, v63
	v_fma_f32 v62, v60, v62, v60
	v_fma_f32 v63, v61, v63, v61
	v_mul_f32_e32 v62, 0x3f4c422a, v62
	v_mul_f32_e32 v63, 0x3f4c422a, v63
	v_mul_f32_e32 v62, -2.0, v62
	v_mul_f32_e32 v63, -2.0, v63
	v_mul_f32_e32 v62, 0x3fb8aa3b, v62
	v_mul_f32_e32 v63, 0x3fb8aa3b, v63
	v_exp_f32_e32 v62, v62
	v_exp_f32_e32 v63, v63
	v_add_f32_e32 v62, 1.0, v62
	v_add_f32_e32 v63, 1.0, v63
	v_rcp_f32_e32 v62, v62
	v_rcp_f32_e32 v63, v63
	s_nop 0
	v_pk_mul_f32 v[60:61], v[60:61], v[62:63]
	s_nop 0
	v_cvt_pk_f16_f32 v63, v60, v61
	v_lshrrev_b32_e32 v61, 4, v64
	v_and_b32_e32 v61, 0x10001, v61
	v_add3_u32 v61, v64, v61, s21
	v_lshrrev_b32_e32 v64, 4, v63
	v_and_b32_e32 v64, 0x10001, v64
	v_add3_u32 v63, v63, v64, s21
	v_add_u32_e32 v64, v140, v104
	v_ashrrev_i32_e32 v65, 31, v64
	v_lshrrev_b32_e32 v60, 4, v68
	v_lshrrev_b32_e32 v62, 4, v69
	v_lshlrev_b64 v[64:65], 10, v[64:65]
	v_and_b32_e32 v60, 0x10001, v60
	v_and_b32_e32 v62, 0x10001, v62
	v_lshl_add_u64 v[64:65], s[16:17], 0, v[64:65]
	v_add3_u32 v60, v68, v60, s21
	v_add3_u32 v62, v69, v62, s21
	v_lshl_add_u64 v[64:65], v[64:65], 0, s[42:43]
	v_and_b32_e32 v60, 0xfff0fff0, v60
	v_and_b32_e32 v61, 0xfff0fff0, v61
	v_and_b32_e32 v62, 0xfff0fff0, v62
	v_and_b32_e32 v63, 0xfff0fff0, v63
	v_lshl_add_u64 v[64:65], v[64:65], 0, v[2:3]
	global_store_dwordx4 v[64:65], v[60:63], off
	s_nop 1
	v_cvt_f32_f16_e32 v62, v96
	v_cvt_f32_f16_sdwa v63, v96 dst_sel:DWORD dst_unused:UNUSED_PAD src0_sel:WORD_1
	v_add_u32_e32 v60, 0x900, v192
	v_pk_mul_f32 v[62:63], v[32:33], v[62:63]
	s_nop 0
	v_pk_fma_f32 v[56:57], v[56:57], s[38:39], v[62:63] op_sel_hi:[1,0,1]
	s_nop 0
	v_mul_f32_e32 v61, 0x3d372713, v56
	v_mul_f32_e32 v61, v56, v61
	v_fma_f32 v61, v56, v61, v56
	v_mul_f32_e32 v61, 0x3f4c422a, v61
	v_mul_f32_e32 v61, -2.0, v61
	v_mul_f32_e32 v61, 0x3fb8aa3b, v61
	v_exp_f32_e32 v61, v61
	s_nop 0
	v_add_f32_e32 v61, 1.0, v61
	v_rcp_f32_e32 v62, v61
	v_mul_f32_e32 v61, 0x3d372713, v57
	v_mul_f32_e32 v61, v57, v61
	v_fma_f32 v61, v57, v61, v57
	v_mul_f32_e32 v61, 0x3f4c422a, v61
	v_mul_f32_e32 v61, -2.0, v61
	v_mul_f32_e32 v61, 0x3fb8aa3b, v61
	v_exp_f32_e32 v61, v61
	s_nop 0
	v_add_f32_e32 v61, 1.0, v61
	v_rcp_f32_e32 v63, v61
	s_nop 0
	v_pk_mul_f32 v[56:57], v[56:57], v[62:63]
	s_nop 0
	v_cvt_pk_f16_f32 v61, v56, v57
	v_cvt_f32_f16_e32 v56, v98
	v_cvt_f32_f16_sdwa v57, v98 dst_sel:DWORD dst_unused:UNUSED_PAD src0_sel:WORD_1
	v_pk_mul_f32 v[56:57], v[28:29], v[56:57]
	s_nop 0
	v_pk_fma_f32 v[52:53], v[52:53], s[38:39], v[56:57] op_sel_hi:[1,0,1]
	s_nop 0
	v_mul_f32_e32 v56, 0x3d372713, v52
	v_mul_f32_e32 v57, 0x3d372713, v53
	v_mul_f32_e32 v56, v52, v56
	v_mul_f32_e32 v57, v53, v57
	v_fma_f32 v56, v52, v56, v52
	v_fma_f32 v57, v53, v57, v53
	v_mul_f32_e32 v56, 0x3f4c422a, v56
	v_mul_f32_e32 v57, 0x3f4c422a, v57
	v_mul_f32_e32 v56, -2.0, v56
	v_mul_f32_e32 v57, -2.0, v57
	v_mul_f32_e32 v56, 0x3fb8aa3b, v56
	v_mul_f32_e32 v57, 0x3fb8aa3b, v57
	v_exp_f32_e32 v56, v56
	v_exp_f32_e32 v57, v57
	v_add_f32_e32 v56, 1.0, v56
	v_add_f32_e32 v57, 1.0, v57
	v_rcp_f32_e32 v56, v56
	v_rcp_f32_e32 v57, v57
	s_nop 0
	v_pk_mul_f32 v[52:53], v[52:53], v[56:57]
	s_nop 0
	v_cvt_pk_f16_f32 v62, v52, v53
	v_cvt_f32_f16_e32 v52, v97
	v_cvt_f32_f16_sdwa v53, v97 dst_sel:DWORD dst_unused:UNUSED_PAD src0_sel:WORD_1
	v_pk_mul_f32 v[52:53], v[34:35], v[52:53]
	s_nop 0
	v_pk_fma_f32 v[52:53], v[58:59], s[38:39], v[52:53] op_sel_hi:[1,0,1]
	s_nop 0
	v_mul_f32_e32 v56, 0x3d372713, v52
	v_mul_f32_e32 v57, 0x3d372713, v53
	v_mul_f32_e32 v56, v52, v56
	v_mul_f32_e32 v57, v53, v57
	v_fma_f32 v56, v52, v56, v52
	v_fma_f32 v57, v53, v57, v53
	v_mul_f32_e32 v56, 0x3f4c422a, v56
	v_mul_f32_e32 v57, 0x3f4c422a, v57
	v_mul_f32_e32 v56, -2.0, v56
	v_mul_f32_e32 v57, -2.0, v57
	v_mul_f32_e32 v56, 0x3fb8aa3b, v56
	v_mul_f32_e32 v57, 0x3fb8aa3b, v57
	v_exp_f32_e32 v56, v56
	v_exp_f32_e32 v57, v57
	v_add_f32_e32 v56, 1.0, v56
	v_add_f32_e32 v57, 1.0, v57
	v_rcp_f32_e32 v56, v56
	v_rcp_f32_e32 v57, v57
	s_nop 0
	v_pk_mul_f32 v[52:53], v[52:53], v[56:57]
	s_nop 0
	v_cvt_pk_f16_f32 v56, v52, v53
	v_cvt_f32_f16_e32 v52, v99
	v_cvt_f32_f16_sdwa v53, v99 dst_sel:DWORD dst_unused:UNUSED_PAD src0_sel:WORD_1
	v_pk_mul_f32 v[52:53], v[30:31], v[52:53]
	s_nop 0
	v_pk_fma_f32 v[52:53], v[54:55], s[38:39], v[52:53] op_sel_hi:[1,0,1]
	s_nop 0
	v_mul_f32_e32 v54, 0x3d372713, v52
	v_mul_f32_e32 v55, 0x3d372713, v53
	v_mul_f32_e32 v54, v52, v54
	v_mul_f32_e32 v55, v53, v55
	v_fma_f32 v54, v52, v54, v52
	v_fma_f32 v55, v53, v55, v53
	v_mul_f32_e32 v54, 0x3f4c422a, v54
	v_mul_f32_e32 v55, 0x3f4c422a, v55
	v_mul_f32_e32 v54, -2.0, v54
	v_mul_f32_e32 v55, -2.0, v55
	v_mul_f32_e32 v54, 0x3fb8aa3b, v54
	v_mul_f32_e32 v55, 0x3fb8aa3b, v55
	v_exp_f32_e32 v54, v54
	v_exp_f32_e32 v55, v55
	v_add_f32_e32 v54, 1.0, v54
	v_add_f32_e32 v55, 1.0, v55
	v_rcp_f32_e32 v54, v54
	v_rcp_f32_e32 v55, v55
	s_nop 0
	v_pk_mul_f32 v[52:53], v[52:53], v[54:55]
	s_nop 0
	v_cvt_pk_f16_f32 v55, v52, v53
	v_lshrrev_b32_e32 v53, 4, v56
	v_and_b32_e32 v53, 0x10001, v53
	v_add3_u32 v53, v56, v53, s21
	v_lshrrev_b32_e32 v56, 4, v55
	v_and_b32_e32 v56, 0x10001, v56
	v_add3_u32 v55, v55, v56, s21
	v_add_u32_e32 v56, v152, v60
	v_ashrrev_i32_e32 v57, 31, v56
	v_lshrrev_b32_e32 v52, 4, v61
	v_lshrrev_b32_e32 v54, 4, v62
	v_lshlrev_b64 v[56:57], 10, v[56:57]
	v_and_b32_e32 v52, 0x10001, v52
	v_and_b32_e32 v54, 0x10001, v54
	v_lshl_add_u64 v[56:57], s[16:17], 0, v[56:57]
	v_add3_u32 v52, v61, v52, s21
	v_add3_u32 v54, v62, v54, s21
	v_lshl_add_u64 v[56:57], v[56:57], 0, s[42:43]
	v_and_b32_e32 v52, 0xfff0fff0, v52
	v_and_b32_e32 v53, 0xfff0fff0, v53
	v_and_b32_e32 v54, 0xfff0fff0, v54
	v_and_b32_e32 v55, 0xfff0fff0, v55
	v_lshl_add_u64 v[56:57], v[56:57], 0, v[2:3]
	global_store_dwordx4 v[56:57], v[52:55], off
	s_nop 1
	v_cvt_f32_f16_e32 v52, v92
	v_cvt_f32_f16_sdwa v53, v92 dst_sel:DWORD dst_unused:UNUSED_PAD src0_sel:WORD_1
	v_pk_mul_f32 v[52:53], v[32:33], v[52:53]
	s_nop 0
	v_pk_fma_f32 v[48:49], v[48:49], s[38:39], v[52:53] op_sel_hi:[1,0,1]
	s_nop 0
	v_mul_f32_e32 v52, 0x3d372713, v48
	v_mul_f32_e32 v53, 0x3d372713, v49
	v_mul_f32_e32 v52, v48, v52
	v_mul_f32_e32 v53, v49, v53
	v_fma_f32 v52, v48, v52, v48
	v_fma_f32 v53, v49, v53, v49
	v_mul_f32_e32 v52, 0x3f4c422a, v52
	v_mul_f32_e32 v53, 0x3f4c422a, v53
	v_mul_f32_e32 v52, -2.0, v52
	v_mul_f32_e32 v53, -2.0, v53
	v_mul_f32_e32 v52, 0x3fb8aa3b, v52
	v_mul_f32_e32 v53, 0x3fb8aa3b, v53
	v_exp_f32_e32 v52, v52
	v_exp_f32_e32 v53, v53
	v_add_f32_e32 v52, 1.0, v52
	v_add_f32_e32 v53, 1.0, v53
	v_rcp_f32_e32 v52, v52
	v_rcp_f32_e32 v53, v53
	s_nop 0
	v_pk_mul_f32 v[48:49], v[48:49], v[52:53]
	s_nop 0
	v_cvt_pk_f16_f32 v52, v48, v49
	v_cvt_f32_f16_e32 v48, v94
	v_cvt_f32_f16_sdwa v49, v94 dst_sel:DWORD dst_unused:UNUSED_PAD src0_sel:WORD_1
	v_pk_mul_f32 v[48:49], v[28:29], v[48:49]
	s_nop 0
	v_pk_fma_f32 v[44:45], v[44:45], s[38:39], v[48:49] op_sel_hi:[1,0,1]
	s_nop 0
	v_mul_f32_e32 v48, 0x3d372713, v44
	v_mul_f32_e32 v49, 0x3d372713, v45
	v_mul_f32_e32 v48, v44, v48
	v_mul_f32_e32 v49, v45, v49
	v_fma_f32 v48, v44, v48, v44
	v_fma_f32 v49, v45, v49, v45
	v_mul_f32_e32 v48, 0x3f4c422a, v48
	v_mul_f32_e32 v49, 0x3f4c422a, v49
	v_mul_f32_e32 v48, -2.0, v48
	v_mul_f32_e32 v49, -2.0, v49
	v_mul_f32_e32 v48, 0x3fb8aa3b, v48
	v_mul_f32_e32 v49, 0x3fb8aa3b, v49
	v_exp_f32_e32 v48, v48
	v_exp_f32_e32 v49, v49
	v_add_f32_e32 v48, 1.0, v48
	v_add_f32_e32 v49, 1.0, v49
	v_rcp_f32_e32 v48, v48
	v_rcp_f32_e32 v49, v49
	s_nop 0
	v_pk_mul_f32 v[44:45], v[44:45], v[48:49]
	s_nop 0
	v_cvt_pk_f16_f32 v53, v44, v45
	v_cvt_f32_f16_e32 v44, v93
	v_cvt_f32_f16_sdwa v45, v93 dst_sel:DWORD dst_unused:UNUSED_PAD src0_sel:WORD_1
	v_pk_mul_f32 v[44:45], v[34:35], v[44:45]
	s_nop 0
	v_pk_fma_f32 v[44:45], v[50:51], s[38:39], v[44:45] op_sel_hi:[1,0,1]
	s_nop 0
	v_mul_f32_e32 v48, 0x3d372713, v44
	v_mul_f32_e32 v49, 0x3d372713, v45
	v_mul_f32_e32 v48, v44, v48
	v_mul_f32_e32 v49, v45, v49
	v_fma_f32 v48, v44, v48, v44
	v_fma_f32 v49, v45, v49, v45
	v_mul_f32_e32 v48, 0x3f4c422a, v48
	v_mul_f32_e32 v49, 0x3f4c422a, v49
	v_mul_f32_e32 v48, -2.0, v48
	v_mul_f32_e32 v49, -2.0, v49
	v_mul_f32_e32 v48, 0x3fb8aa3b, v48
	v_mul_f32_e32 v49, 0x3fb8aa3b, v49
	v_exp_f32_e32 v48, v48
	v_exp_f32_e32 v49, v49
	v_add_f32_e32 v48, 1.0, v48
	v_add_f32_e32 v49, 1.0, v49
	v_rcp_f32_e32 v48, v48
	v_rcp_f32_e32 v49, v49
	s_nop 0
	v_pk_mul_f32 v[44:45], v[44:45], v[48:49]
	s_nop 0
	v_cvt_pk_f16_f32 v48, v44, v45
	v_cvt_f32_f16_e32 v44, v95
	v_cvt_f32_f16_sdwa v45, v95 dst_sel:DWORD dst_unused:UNUSED_PAD src0_sel:WORD_1
	v_pk_mul_f32 v[44:45], v[30:31], v[44:45]
	s_nop 0
	v_pk_fma_f32 v[44:45], v[46:47], s[38:39], v[44:45] op_sel_hi:[1,0,1]
	s_nop 0
	v_mul_f32_e32 v46, 0x3d372713, v44
	v_mul_f32_e32 v47, 0x3d372713, v45
	v_mul_f32_e32 v46, v44, v46
	v_mul_f32_e32 v47, v45, v47
	v_fma_f32 v46, v44, v46, v44
	v_fma_f32 v47, v45, v47, v45
	v_mul_f32_e32 v46, 0x3f4c422a, v46
	v_mul_f32_e32 v47, 0x3f4c422a, v47
	v_mul_f32_e32 v46, -2.0, v46
	v_mul_f32_e32 v47, -2.0, v47
	v_mul_f32_e32 v46, 0x3fb8aa3b, v46
	v_mul_f32_e32 v47, 0x3fb8aa3b, v47
	v_exp_f32_e32 v46, v46
	v_exp_f32_e32 v47, v47
	v_add_f32_e32 v46, 1.0, v46
	v_add_f32_e32 v47, 1.0, v47
	v_rcp_f32_e32 v46, v46
	v_rcp_f32_e32 v47, v47
	s_nop 0
	v_pk_mul_f32 v[44:45], v[44:45], v[46:47]
	s_nop 0
	v_cvt_pk_f16_f32 v47, v44, v45
	v_lshrrev_b32_e32 v45, 4, v48
	v_and_b32_e32 v45, 0x10001, v45
	v_add3_u32 v45, v48, v45, s21
	v_lshrrev_b32_e32 v48, 4, v47
	v_and_b32_e32 v48, 0x10001, v48
	v_add3_u32 v47, v47, v48, s21
	v_add_u32_e32 v48, v140, v60
	v_ashrrev_i32_e32 v49, 31, v48
	v_lshrrev_b32_e32 v44, 4, v52
	v_lshrrev_b32_e32 v46, 4, v53
	v_lshlrev_b64 v[48:49], 10, v[48:49]
	v_and_b32_e32 v44, 0x10001, v44
	v_and_b32_e32 v46, 0x10001, v46
	v_lshl_add_u64 v[48:49], s[16:17], 0, v[48:49]
	v_add3_u32 v44, v52, v44, s21
	v_add3_u32 v46, v53, v46, s21
	v_lshl_add_u64 v[48:49], v[48:49], 0, s[42:43]
	v_and_b32_e32 v44, 0xfff0fff0, v44
	v_and_b32_e32 v45, 0xfff0fff0, v45
	v_and_b32_e32 v46, 0xfff0fff0, v46
	v_and_b32_e32 v47, 0xfff0fff0, v47
	v_lshl_add_u64 v[48:49], v[48:49], 0, v[2:3]
	global_store_dwordx4 v[48:49], v[44:47], off
	s_nop 1
	v_cvt_f32_f16_e32 v46, v88
	v_cvt_f32_f16_sdwa v47, v88 dst_sel:DWORD dst_unused:UNUSED_PAD src0_sel:WORD_1
	v_add_u32_e32 v44, 0xa00, v192
	v_pk_mul_f32 v[46:47], v[32:33], v[46:47]
	s_nop 0
	v_pk_fma_f32 v[40:41], v[40:41], s[38:39], v[46:47] op_sel_hi:[1,0,1]
	s_nop 0
	v_mul_f32_e32 v45, 0x3d372713, v40
	v_mul_f32_e32 v45, v40, v45
	v_fma_f32 v45, v40, v45, v40
	v_mul_f32_e32 v45, 0x3f4c422a, v45
	v_mul_f32_e32 v45, -2.0, v45
	v_mul_f32_e32 v45, 0x3fb8aa3b, v45
	v_exp_f32_e32 v45, v45
	s_nop 0
	v_add_f32_e32 v45, 1.0, v45
	v_rcp_f32_e32 v46, v45
	v_mul_f32_e32 v45, 0x3d372713, v41
	v_mul_f32_e32 v45, v41, v45
	v_fma_f32 v45, v41, v45, v41
	v_mul_f32_e32 v45, 0x3f4c422a, v45
	v_mul_f32_e32 v45, -2.0, v45
	v_mul_f32_e32 v45, 0x3fb8aa3b, v45
	v_exp_f32_e32 v45, v45
	s_nop 0
	v_add_f32_e32 v45, 1.0, v45
	v_rcp_f32_e32 v47, v45
	s_nop 0
	v_pk_mul_f32 v[40:41], v[40:41], v[46:47]
	s_nop 0
	v_cvt_pk_f16_f32 v45, v40, v41
	v_cvt_f32_f16_e32 v40, v90
	v_cvt_f32_f16_sdwa v41, v90 dst_sel:DWORD dst_unused:UNUSED_PAD src0_sel:WORD_1
	v_pk_mul_f32 v[40:41], v[28:29], v[40:41]
	s_nop 0
	v_pk_fma_f32 v[36:37], v[36:37], s[38:39], v[40:41] op_sel_hi:[1,0,1]
	s_nop 0
	v_mul_f32_e32 v40, 0x3d372713, v36
	v_mul_f32_e32 v41, 0x3d372713, v37
	v_mul_f32_e32 v40, v36, v40
	v_mul_f32_e32 v41, v37, v41
	v_fma_f32 v40, v36, v40, v36
	v_fma_f32 v41, v37, v41, v37
	v_mul_f32_e32 v40, 0x3f4c422a, v40
	v_mul_f32_e32 v41, 0x3f4c422a, v41
	v_mul_f32_e32 v40, -2.0, v40
	v_mul_f32_e32 v41, -2.0, v41
	v_mul_f32_e32 v40, 0x3fb8aa3b, v40
	v_mul_f32_e32 v41, 0x3fb8aa3b, v41
	v_exp_f32_e32 v40, v40
	v_exp_f32_e32 v41, v41
	v_add_f32_e32 v40, 1.0, v40
	v_add_f32_e32 v41, 1.0, v41
	v_rcp_f32_e32 v40, v40
	v_rcp_f32_e32 v41, v41
	s_nop 0
	v_pk_mul_f32 v[36:37], v[36:37], v[40:41]
	s_nop 0
	v_cvt_pk_f16_f32 v46, v36, v37
	v_cvt_f32_f16_e32 v36, v89
	v_cvt_f32_f16_sdwa v37, v89 dst_sel:DWORD dst_unused:UNUSED_PAD src0_sel:WORD_1
	v_pk_mul_f32 v[36:37], v[34:35], v[36:37]
	s_nop 0
	v_pk_fma_f32 v[36:37], v[42:43], s[38:39], v[36:37] op_sel_hi:[1,0,1]
	s_nop 0
	v_mul_f32_e32 v40, 0x3d372713, v36
	v_mul_f32_e32 v41, 0x3d372713, v37
	v_mul_f32_e32 v40, v36, v40
	v_mul_f32_e32 v41, v37, v41
	v_fma_f32 v40, v36, v40, v36
	v_fma_f32 v41, v37, v41, v37
	v_mul_f32_e32 v40, 0x3f4c422a, v40
	v_mul_f32_e32 v41, 0x3f4c422a, v41
	v_mul_f32_e32 v40, -2.0, v40
	v_mul_f32_e32 v41, -2.0, v41
	v_mul_f32_e32 v40, 0x3fb8aa3b, v40
	v_mul_f32_e32 v41, 0x3fb8aa3b, v41
	v_exp_f32_e32 v40, v40
	v_exp_f32_e32 v41, v41
	v_add_f32_e32 v40, 1.0, v40
	v_add_f32_e32 v41, 1.0, v41
	v_rcp_f32_e32 v40, v40
	v_rcp_f32_e32 v41, v41
	s_nop 0
	v_pk_mul_f32 v[36:37], v[36:37], v[40:41]
	s_nop 0
	v_cvt_pk_f16_f32 v40, v36, v37
	v_cvt_f32_f16_e32 v36, v91
	v_cvt_f32_f16_sdwa v37, v91 dst_sel:DWORD dst_unused:UNUSED_PAD src0_sel:WORD_1
	v_pk_mul_f32 v[36:37], v[30:31], v[36:37]
	s_nop 0
	v_pk_fma_f32 v[36:37], v[38:39], s[38:39], v[36:37] op_sel_hi:[1,0,1]
	s_nop 0
	v_mul_f32_e32 v38, 0x3d372713, v36
	v_mul_f32_e32 v39, 0x3d372713, v37
	v_mul_f32_e32 v38, v36, v38
	v_mul_f32_e32 v39, v37, v39
	v_fma_f32 v38, v36, v38, v36
	v_fma_f32 v39, v37, v39, v37
	v_mul_f32_e32 v38, 0x3f4c422a, v38
	v_mul_f32_e32 v39, 0x3f4c422a, v39
	v_mul_f32_e32 v38, -2.0, v38
	v_mul_f32_e32 v39, -2.0, v39
	v_mul_f32_e32 v38, 0x3fb8aa3b, v38
	v_mul_f32_e32 v39, 0x3fb8aa3b, v39
	v_exp_f32_e32 v38, v38
	v_exp_f32_e32 v39, v39
	v_add_f32_e32 v38, 1.0, v38
	v_add_f32_e32 v39, 1.0, v39
	v_rcp_f32_e32 v38, v38
	v_rcp_f32_e32 v39, v39
	s_nop 0
	v_pk_mul_f32 v[36:37], v[36:37], v[38:39]
	s_nop 0
	v_cvt_pk_f16_f32 v39, v36, v37
	v_lshrrev_b32_e32 v37, 4, v40
	v_and_b32_e32 v37, 0x10001, v37
	v_add3_u32 v37, v40, v37, s21
	v_lshrrev_b32_e32 v40, 4, v39
	v_and_b32_e32 v40, 0x10001, v40
	v_add3_u32 v39, v39, v40, s21
	v_add_u32_e32 v40, v152, v44
	v_ashrrev_i32_e32 v41, 31, v40
	v_lshrrev_b32_e32 v36, 4, v45
	v_lshrrev_b32_e32 v38, 4, v46
	v_lshlrev_b64 v[40:41], 10, v[40:41]
	v_and_b32_e32 v36, 0x10001, v36
	v_and_b32_e32 v38, 0x10001, v38
	v_lshl_add_u64 v[40:41], s[16:17], 0, v[40:41]
	v_add3_u32 v36, v45, v36, s21
	v_add3_u32 v38, v46, v38, s21
	v_lshl_add_u64 v[40:41], v[40:41], 0, s[42:43]
	v_and_b32_e32 v36, 0xfff0fff0, v36
	v_and_b32_e32 v37, 0xfff0fff0, v37
	v_and_b32_e32 v38, 0xfff0fff0, v38
	v_and_b32_e32 v39, 0xfff0fff0, v39
	v_lshl_add_u64 v[40:41], v[40:41], 0, v[2:3]
	global_store_dwordx4 v[40:41], v[36:39], off
	s_nop 1
	v_cvt_f32_f16_e32 v36, v84
	v_cvt_f32_f16_sdwa v37, v84 dst_sel:DWORD dst_unused:UNUSED_PAD src0_sel:WORD_1
	v_pk_mul_f32 v[36:37], v[32:33], v[36:37]
	s_nop 0
	v_pk_fma_f32 v[24:25], v[24:25], s[38:39], v[36:37] op_sel_hi:[1,0,1]
	s_nop 0
	v_mul_f32_e32 v36, 0x3d372713, v24
	v_mul_f32_e32 v37, 0x3d372713, v25
	v_mul_f32_e32 v36, v24, v36
	v_mul_f32_e32 v37, v25, v37
	v_fma_f32 v36, v24, v36, v24
	v_fma_f32 v37, v25, v37, v25
	v_mul_f32_e32 v36, 0x3f4c422a, v36
	v_mul_f32_e32 v37, 0x3f4c422a, v37
	v_mul_f32_e32 v36, -2.0, v36
	v_mul_f32_e32 v37, -2.0, v37
	v_mul_f32_e32 v36, 0x3fb8aa3b, v36
	v_mul_f32_e32 v37, 0x3fb8aa3b, v37
	v_exp_f32_e32 v36, v36
	v_exp_f32_e32 v37, v37
	v_add_f32_e32 v36, 1.0, v36
	v_add_f32_e32 v37, 1.0, v37
	v_rcp_f32_e32 v36, v36
	v_rcp_f32_e32 v37, v37
	s_nop 0
	v_pk_mul_f32 v[24:25], v[24:25], v[36:37]
	s_nop 0
	v_cvt_pk_f16_f32 v36, v24, v25
	v_cvt_f32_f16_e32 v24, v86
	v_cvt_f32_f16_sdwa v25, v86 dst_sel:DWORD dst_unused:UNUSED_PAD src0_sel:WORD_1
	v_pk_mul_f32 v[24:25], v[28:29], v[24:25]
	s_nop 0
	v_pk_fma_f32 v[20:21], v[20:21], s[38:39], v[24:25] op_sel_hi:[1,0,1]
	s_nop 0
	v_mul_f32_e32 v24, 0x3d372713, v20
	v_mul_f32_e32 v25, 0x3d372713, v21
	v_mul_f32_e32 v24, v20, v24
	v_mul_f32_e32 v25, v21, v25
	v_fma_f32 v24, v20, v24, v20
	v_fma_f32 v25, v21, v25, v21
	v_mul_f32_e32 v24, 0x3f4c422a, v24
	v_mul_f32_e32 v25, 0x3f4c422a, v25
	v_mul_f32_e32 v24, -2.0, v24
	v_mul_f32_e32 v25, -2.0, v25
	v_mul_f32_e32 v24, 0x3fb8aa3b, v24
	v_mul_f32_e32 v25, 0x3fb8aa3b, v25
	v_exp_f32_e32 v24, v24
	v_exp_f32_e32 v25, v25
	v_add_f32_e32 v24, 1.0, v24
	v_add_f32_e32 v25, 1.0, v25
	v_rcp_f32_e32 v24, v24
	v_rcp_f32_e32 v25, v25
	s_nop 0
	v_pk_mul_f32 v[20:21], v[20:21], v[24:25]
	s_nop 0
	v_cvt_pk_f16_f32 v37, v20, v21
	v_cvt_f32_f16_e32 v20, v85
	v_cvt_f32_f16_sdwa v21, v85 dst_sel:DWORD dst_unused:UNUSED_PAD src0_sel:WORD_1
	v_pk_mul_f32 v[20:21], v[34:35], v[20:21]
	s_nop 0
	v_pk_fma_f32 v[20:21], v[26:27], s[38:39], v[20:21] op_sel_hi:[1,0,1]
	s_nop 0
	v_mul_f32_e32 v24, 0x3d372713, v20
	v_mul_f32_e32 v25, 0x3d372713, v21
	v_mul_f32_e32 v24, v20, v24
	v_mul_f32_e32 v25, v21, v25
	v_fma_f32 v24, v20, v24, v20
	v_fma_f32 v25, v21, v25, v21
	v_mul_f32_e32 v24, 0x3f4c422a, v24
	v_mul_f32_e32 v25, 0x3f4c422a, v25
	v_mul_f32_e32 v24, -2.0, v24
	v_mul_f32_e32 v25, -2.0, v25
	v_mul_f32_e32 v24, 0x3fb8aa3b, v24
	v_mul_f32_e32 v25, 0x3fb8aa3b, v25
	v_exp_f32_e32 v24, v24
	v_exp_f32_e32 v25, v25
	v_add_f32_e32 v24, 1.0, v24
	v_add_f32_e32 v25, 1.0, v25
	v_rcp_f32_e32 v24, v24
	v_rcp_f32_e32 v25, v25
	s_nop 0
	v_pk_mul_f32 v[20:21], v[20:21], v[24:25]
	s_nop 0
	v_cvt_pk_f16_f32 v24, v20, v21
	v_cvt_f32_f16_e32 v20, v87
	v_cvt_f32_f16_sdwa v21, v87 dst_sel:DWORD dst_unused:UNUSED_PAD src0_sel:WORD_1
	v_pk_mul_f32 v[20:21], v[30:31], v[20:21]
	s_nop 0
	v_pk_fma_f32 v[20:21], v[22:23], s[38:39], v[20:21] op_sel_hi:[1,0,1]
	s_nop 0
	v_mul_f32_e32 v22, 0x3d372713, v20
	v_mul_f32_e32 v23, 0x3d372713, v21
	v_mul_f32_e32 v22, v20, v22
	v_mul_f32_e32 v23, v21, v23
	v_fma_f32 v22, v20, v22, v20
	v_fma_f32 v23, v21, v23, v21
	v_mul_f32_e32 v22, 0x3f4c422a, v22
	v_mul_f32_e32 v23, 0x3f4c422a, v23
	v_mul_f32_e32 v22, -2.0, v22
	v_mul_f32_e32 v23, -2.0, v23
	v_mul_f32_e32 v22, 0x3fb8aa3b, v22
	v_mul_f32_e32 v23, 0x3fb8aa3b, v23
	v_exp_f32_e32 v22, v22
	v_exp_f32_e32 v23, v23
	v_add_f32_e32 v22, 1.0, v22
	v_add_f32_e32 v23, 1.0, v23
	v_rcp_f32_e32 v22, v22
	v_rcp_f32_e32 v23, v23
	s_nop 0
	v_pk_mul_f32 v[20:21], v[20:21], v[22:23]
	s_nop 0
	v_cvt_pk_f16_f32 v23, v20, v21
	v_lshrrev_b32_e32 v21, 4, v24
	v_and_b32_e32 v21, 0x10001, v21
	v_add3_u32 v21, v24, v21, s21
	v_lshrrev_b32_e32 v24, 4, v23
	v_and_b32_e32 v24, 0x10001, v24
	v_add3_u32 v23, v23, v24, s21
	v_add_u32_e32 v24, v140, v44
	v_ashrrev_i32_e32 v25, 31, v24
	v_lshrrev_b32_e32 v20, 4, v36
	v_lshrrev_b32_e32 v22, 4, v37
	v_lshlrev_b64 v[24:25], 10, v[24:25]
	v_and_b32_e32 v20, 0x10001, v20
	v_and_b32_e32 v22, 0x10001, v22
	v_lshl_add_u64 v[24:25], s[16:17], 0, v[24:25]
	v_add3_u32 v20, v36, v20, s21
	v_add3_u32 v22, v37, v22, s21
	v_lshl_add_u64 v[24:25], v[24:25], 0, s[42:43]
	v_and_b32_e32 v20, 0xfff0fff0, v20
	v_and_b32_e32 v21, 0xfff0fff0, v21
	v_and_b32_e32 v22, 0xfff0fff0, v22
	v_and_b32_e32 v23, 0xfff0fff0, v23
	v_lshl_add_u64 v[24:25], v[24:25], 0, v[2:3]
	global_store_dwordx4 v[24:25], v[20:23], off
	s_nop 1
	v_cvt_f32_f16_e32 v22, v80
	v_cvt_f32_f16_sdwa v23, v80 dst_sel:DWORD dst_unused:UNUSED_PAD src0_sel:WORD_1
	v_add_u32_e32 v20, 0xb00, v192
	v_pk_mul_f32 v[22:23], v[32:33], v[22:23]
	s_nop 0
	v_pk_fma_f32 v[16:17], v[16:17], s[38:39], v[22:23] op_sel_hi:[1,0,1]
	s_nop 0
	v_mul_f32_e32 v21, 0x3d372713, v16
	v_mul_f32_e32 v21, v16, v21
	v_fma_f32 v21, v16, v21, v16
	v_mul_f32_e32 v21, 0x3f4c422a, v21
	v_mul_f32_e32 v21, -2.0, v21
	v_mul_f32_e32 v21, 0x3fb8aa3b, v21
	v_exp_f32_e32 v21, v21
	s_nop 0
	v_add_f32_e32 v21, 1.0, v21
	v_rcp_f32_e32 v22, v21
	v_mul_f32_e32 v21, 0x3d372713, v17
	v_mul_f32_e32 v21, v17, v21
	v_fma_f32 v21, v17, v21, v17
	v_mul_f32_e32 v21, 0x3f4c422a, v21
	v_mul_f32_e32 v21, -2.0, v21
	v_mul_f32_e32 v21, 0x3fb8aa3b, v21
	v_exp_f32_e32 v21, v21
	s_nop 0
	v_add_f32_e32 v21, 1.0, v21
	v_rcp_f32_e32 v23, v21
	s_nop 0
	v_pk_mul_f32 v[16:17], v[16:17], v[22:23]
	s_nop 0
	v_cvt_pk_f16_f32 v21, v16, v17
	v_cvt_f32_f16_e32 v16, v82
	v_cvt_f32_f16_sdwa v17, v82 dst_sel:DWORD dst_unused:UNUSED_PAD src0_sel:WORD_1
	v_pk_mul_f32 v[16:17], v[28:29], v[16:17]
	s_nop 0
	v_pk_fma_f32 v[12:13], v[12:13], s[38:39], v[16:17] op_sel_hi:[1,0,1]
	s_nop 0
	v_mul_f32_e32 v16, 0x3d372713, v12
	v_mul_f32_e32 v17, 0x3d372713, v13
	v_mul_f32_e32 v16, v12, v16
	v_mul_f32_e32 v17, v13, v17
	v_fma_f32 v16, v12, v16, v12
	v_fma_f32 v17, v13, v17, v13
	v_mul_f32_e32 v16, 0x3f4c422a, v16
	v_mul_f32_e32 v17, 0x3f4c422a, v17
	v_mul_f32_e32 v16, -2.0, v16
	v_mul_f32_e32 v17, -2.0, v17
	v_mul_f32_e32 v16, 0x3fb8aa3b, v16
	v_mul_f32_e32 v17, 0x3fb8aa3b, v17
	v_exp_f32_e32 v16, v16
	v_exp_f32_e32 v17, v17
	v_add_f32_e32 v16, 1.0, v16
	v_add_f32_e32 v17, 1.0, v17
	v_rcp_f32_e32 v16, v16
	v_rcp_f32_e32 v17, v17
	s_nop 0
	v_pk_mul_f32 v[12:13], v[12:13], v[16:17]
	s_nop 0
	v_cvt_pk_f16_f32 v22, v12, v13
	v_cvt_f32_f16_e32 v12, v81
	v_cvt_f32_f16_sdwa v13, v81 dst_sel:DWORD dst_unused:UNUSED_PAD src0_sel:WORD_1
	v_pk_mul_f32 v[12:13], v[34:35], v[12:13]
	s_nop 0
	v_pk_fma_f32 v[12:13], v[18:19], s[38:39], v[12:13] op_sel_hi:[1,0,1]
	s_nop 0
	v_mul_f32_e32 v16, 0x3d372713, v12
	v_mul_f32_e32 v17, 0x3d372713, v13
	v_mul_f32_e32 v16, v12, v16
	v_mul_f32_e32 v17, v13, v17
	v_fma_f32 v16, v12, v16, v12
	v_fma_f32 v17, v13, v17, v13
	v_mul_f32_e32 v16, 0x3f4c422a, v16
	v_mul_f32_e32 v17, 0x3f4c422a, v17
	v_mul_f32_e32 v16, -2.0, v16
	v_mul_f32_e32 v17, -2.0, v17
	v_mul_f32_e32 v16, 0x3fb8aa3b, v16
	v_mul_f32_e32 v17, 0x3fb8aa3b, v17
	v_exp_f32_e32 v16, v16
	v_exp_f32_e32 v17, v17
	v_add_f32_e32 v16, 1.0, v16
	v_add_f32_e32 v17, 1.0, v17
	v_rcp_f32_e32 v16, v16
	v_rcp_f32_e32 v17, v17
	s_nop 0
	v_pk_mul_f32 v[12:13], v[12:13], v[16:17]
	s_nop 0
	v_cvt_pk_f16_f32 v16, v12, v13
	v_cvt_f32_f16_e32 v12, v83
	v_cvt_f32_f16_sdwa v13, v83 dst_sel:DWORD dst_unused:UNUSED_PAD src0_sel:WORD_1
	v_pk_mul_f32 v[12:13], v[30:31], v[12:13]
	s_nop 0
	v_pk_fma_f32 v[12:13], v[14:15], s[38:39], v[12:13] op_sel_hi:[1,0,1]
	s_nop 0
	v_mul_f32_e32 v14, 0x3d372713, v12
	v_mul_f32_e32 v15, 0x3d372713, v13
	v_mul_f32_e32 v14, v12, v14
	v_mul_f32_e32 v15, v13, v15
	v_fma_f32 v14, v12, v14, v12
	v_fma_f32 v15, v13, v15, v13
	v_mul_f32_e32 v14, 0x3f4c422a, v14
	v_mul_f32_e32 v15, 0x3f4c422a, v15
	v_mul_f32_e32 v14, -2.0, v14
	v_mul_f32_e32 v15, -2.0, v15
	v_mul_f32_e32 v14, 0x3fb8aa3b, v14
	v_mul_f32_e32 v15, 0x3fb8aa3b, v15
	v_exp_f32_e32 v14, v14
	v_exp_f32_e32 v15, v15
	v_add_f32_e32 v14, 1.0, v14
	v_add_f32_e32 v15, 1.0, v15
	v_rcp_f32_e32 v14, v14
	v_rcp_f32_e32 v15, v15
	s_nop 0
	v_pk_mul_f32 v[12:13], v[12:13], v[14:15]
	s_nop 0
	v_cvt_pk_f16_f32 v15, v12, v13
	v_lshrrev_b32_e32 v13, 4, v16
	v_and_b32_e32 v13, 0x10001, v13
	v_add3_u32 v13, v16, v13, s21
	v_lshrrev_b32_e32 v16, 4, v15
	v_and_b32_e32 v16, 0x10001, v16
	v_add3_u32 v15, v15, v16, s21
	v_add_u32_e32 v16, v152, v20
	v_ashrrev_i32_e32 v17, 31, v16
	v_lshrrev_b32_e32 v12, 4, v21
	v_lshrrev_b32_e32 v14, 4, v22
	v_lshlrev_b64 v[16:17], 10, v[16:17]
	v_and_b32_e32 v12, 0x10001, v12
	v_and_b32_e32 v14, 0x10001, v14
	v_lshl_add_u64 v[16:17], s[16:17], 0, v[16:17]
	v_add3_u32 v12, v21, v12, s21
	v_add3_u32 v14, v22, v14, s21
	v_lshl_add_u64 v[16:17], v[16:17], 0, s[42:43]
	v_and_b32_e32 v12, 0xfff0fff0, v12
	v_and_b32_e32 v13, 0xfff0fff0, v13
	v_and_b32_e32 v14, 0xfff0fff0, v14
	v_and_b32_e32 v15, 0xfff0fff0, v15
	v_lshl_add_u64 v[16:17], v[16:17], 0, v[2:3]
	global_store_dwordx4 v[16:17], v[12:15], off
	s_nop 1
	v_cvt_f32_f16_e32 v12, v76
	v_cvt_f32_f16_sdwa v13, v76 dst_sel:DWORD dst_unused:UNUSED_PAD src0_sel:WORD_1
	v_pk_mul_f32 v[12:13], v[32:33], v[12:13]
	s_nop 0
	v_pk_fma_f32 v[8:9], v[8:9], s[38:39], v[12:13] op_sel_hi:[1,0,1]
	s_nop 0
	v_mul_f32_e32 v12, 0x3d372713, v8
	v_mul_f32_e32 v13, 0x3d372713, v9
	v_mul_f32_e32 v12, v8, v12
	v_mul_f32_e32 v13, v9, v13
	v_fma_f32 v12, v8, v12, v8
	v_fma_f32 v13, v9, v13, v9
	v_mul_f32_e32 v12, 0x3f4c422a, v12
	v_mul_f32_e32 v13, 0x3f4c422a, v13
	v_mul_f32_e32 v12, -2.0, v12
	v_mul_f32_e32 v13, -2.0, v13
	v_mul_f32_e32 v12, 0x3fb8aa3b, v12
	v_mul_f32_e32 v13, 0x3fb8aa3b, v13
	v_exp_f32_e32 v12, v12
	v_exp_f32_e32 v13, v13
	v_add_f32_e32 v12, 1.0, v12
	v_add_f32_e32 v13, 1.0, v13
	v_rcp_f32_e32 v12, v12
	v_rcp_f32_e32 v13, v13
	s_nop 0
	v_pk_mul_f32 v[8:9], v[8:9], v[12:13]
	s_nop 0
	v_cvt_pk_f16_f32 v12, v8, v9
	v_cvt_f32_f16_e32 v8, v78
	v_cvt_f32_f16_sdwa v9, v78 dst_sel:DWORD dst_unused:UNUSED_PAD src0_sel:WORD_1
	v_pk_mul_f32 v[8:9], v[28:29], v[8:9]
	s_nop 0
	v_pk_fma_f32 v[4:5], v[4:5], s[38:39], v[8:9] op_sel_hi:[1,0,1]
	s_nop 0
	v_mul_f32_e32 v8, 0x3d372713, v4
	v_mul_f32_e32 v9, 0x3d372713, v5
	v_mul_f32_e32 v8, v4, v8
	v_mul_f32_e32 v9, v5, v9
	v_fma_f32 v8, v4, v8, v4
	v_fma_f32 v9, v5, v9, v5
	v_mul_f32_e32 v8, 0x3f4c422a, v8
	v_mul_f32_e32 v9, 0x3f4c422a, v9
	v_mul_f32_e32 v8, -2.0, v8
	v_mul_f32_e32 v9, -2.0, v9
	v_mul_f32_e32 v8, 0x3fb8aa3b, v8
	v_mul_f32_e32 v9, 0x3fb8aa3b, v9
	v_exp_f32_e32 v8, v8
	v_exp_f32_e32 v9, v9
	v_add_f32_e32 v8, 1.0, v8
	v_add_f32_e32 v9, 1.0, v9
	v_rcp_f32_e32 v8, v8
	v_rcp_f32_e32 v9, v9
	s_nop 0
	v_pk_mul_f32 v[4:5], v[4:5], v[8:9]
	s_nop 0
	v_cvt_pk_f16_f32 v13, v4, v5
	v_cvt_f32_f16_e32 v4, v77
	v_cvt_f32_f16_sdwa v5, v77 dst_sel:DWORD dst_unused:UNUSED_PAD src0_sel:WORD_1
	v_pk_mul_f32 v[4:5], v[34:35], v[4:5]
	s_nop 0
	v_pk_fma_f32 v[4:5], v[10:11], s[38:39], v[4:5] op_sel_hi:[1,0,1]
	s_nop 0
	v_mul_f32_e32 v8, 0x3d372713, v4
	v_mul_f32_e32 v9, 0x3d372713, v5
	v_mul_f32_e32 v8, v4, v8
	v_mul_f32_e32 v9, v5, v9
	v_fma_f32 v8, v4, v8, v4
	v_fma_f32 v9, v5, v9, v5
	v_mul_f32_e32 v8, 0x3f4c422a, v8
	v_mul_f32_e32 v9, 0x3f4c422a, v9
	v_mul_f32_e32 v8, -2.0, v8
	v_mul_f32_e32 v9, -2.0, v9
	v_mul_f32_e32 v8, 0x3fb8aa3b, v8
	v_mul_f32_e32 v9, 0x3fb8aa3b, v9
	v_exp_f32_e32 v8, v8
	v_exp_f32_e32 v9, v9
	v_add_f32_e32 v8, 1.0, v8
	v_add_f32_e32 v9, 1.0, v9
	v_rcp_f32_e32 v8, v8
	v_rcp_f32_e32 v9, v9
	s_nop 0
	v_pk_mul_f32 v[4:5], v[4:5], v[8:9]
	s_nop 0
	v_cvt_pk_f16_f32 v8, v4, v5
	v_cvt_f32_f16_e32 v4, v79
	v_cvt_f32_f16_sdwa v5, v79 dst_sel:DWORD dst_unused:UNUSED_PAD src0_sel:WORD_1
	v_pk_mul_f32 v[4:5], v[30:31], v[4:5]
	s_nop 0
	v_pk_fma_f32 v[4:5], v[6:7], s[38:39], v[4:5] op_sel_hi:[1,0,1]
	s_mov_b64 s[38:39], s[36:37]
	v_mul_f32_e32 v6, 0x3d372713, v4
	v_mul_f32_e32 v7, 0x3d372713, v5
	v_mul_f32_e32 v6, v4, v6
	v_mul_f32_e32 v7, v5, v7
	v_fma_f32 v6, v4, v6, v4
	v_fma_f32 v7, v5, v7, v5
	v_mul_f32_e32 v6, 0x3f4c422a, v6
	v_mul_f32_e32 v7, 0x3f4c422a, v7
	v_mul_f32_e32 v6, -2.0, v6
	v_mul_f32_e32 v7, -2.0, v7
	v_mul_f32_e32 v6, 0x3fb8aa3b, v6
	v_mul_f32_e32 v7, 0x3fb8aa3b, v7
	v_exp_f32_e32 v6, v6
	v_exp_f32_e32 v7, v7
	v_add_f32_e32 v6, 1.0, v6
	v_add_f32_e32 v7, 1.0, v7
	v_rcp_f32_e32 v6, v6
	v_rcp_f32_e32 v7, v7
	s_nop 0
	v_pk_mul_f32 v[4:5], v[4:5], v[6:7]
	s_nop 0
	v_cvt_pk_f16_f32 v7, v4, v5
	v_lshrrev_b32_e32 v5, 4, v8
	v_and_b32_e32 v5, 0x10001, v5
	v_add3_u32 v5, v8, v5, s21
	v_lshrrev_b32_e32 v8, 4, v7
	v_and_b32_e32 v8, 0x10001, v8
	v_add3_u32 v7, v7, v8, s21
	v_add_u32_e32 v8, v140, v20
	v_ashrrev_i32_e32 v9, 31, v8
	v_lshrrev_b32_e32 v4, 4, v12
	v_lshrrev_b32_e32 v6, 4, v13
	v_lshlrev_b64 v[8:9], 10, v[8:9]
	v_and_b32_e32 v4, 0x10001, v4
	v_and_b32_e32 v6, 0x10001, v6
	v_lshl_add_u64 v[8:9], s[16:17], 0, v[8:9]
	v_add3_u32 v4, v12, v4, s21
	v_add3_u32 v6, v13, v6, s21
	v_lshl_add_u64 v[8:9], v[8:9], 0, s[42:43]
	v_and_b32_e32 v4, 0xfff0fff0, v4
	v_and_b32_e32 v5, 0xfff0fff0, v5
	v_and_b32_e32 v6, 0xfff0fff0, v6
	v_and_b32_e32 v7, 0xfff0fff0, v7
	v_lshl_add_u64 v[8:9], v[8:9], 0, v[2:3]
	global_store_dwordx4 v[8:9], v[4:7], off
	s_mov_b32 s16, s47
	s_cbranch_vccz .LBB0_1338
	s_waitcnt vmcnt(0)
	s_cmpk_gt_u32 s5, 0xff
	s_cbranch_scc1 .LBB0_1345
	s_barrier

.LBB0_1664:
	s_add_u32 s15, s46, 0xfffe0080
	s_addc_u32 s29, s47, -1
	s_add_i32 s30, 0, 0x10000
	v_add_u32_e32 v56, s30, v208
	ds_read_b128 v[32:35], v56
	ds_read_b128 v[40:43], v56 offset:1024
	ds_read_b128 v[48:51], v56 offset:2048
	ds_read_b128 v[56:59], v56 offset:3072
	s_cmp_eq_u32 s14, 4
	s_cselect_b32 s49, s43, s29
	s_cselect_b32 s48, s42, s15
	s_cselect_b32 s39, s45, s11
	s_cselect_b32 s38, s44, s10
	s_add_i32 m0, s8, 0xc000
	ds_read_b128 v[108:111], v209
	ds_read_b128 v[120:123], v209 offset:1024
	ds_read_b128 v[132:135], v209 offset:2048
	ds_read_b128 v[144:147], v209 offset:3072
	ds_read_b128 v[156:159], v209 offset:4096
	ds_read_b128 v[168:171], v209 offset:5120
	ds_read_b128 v[172:175], v209 offset:6144
	ds_read_b128 v[176:179], v209 offset:7168
	global_load_lds_dwordx4 v186, s[46:47]
	s_add_i32 m0, s8, 0xe000
	s_nop 0
	global_load_lds_dwordx4 v188, s[46:47]
	s_barrier
	s_waitcnt lgkmcnt(0)
	v_mfma_f32_16x16x32_f16 v[164:167], v[32:35], v[108:111], v[164:167]
	v_mfma_f32_16x16x32_f16 v[160:163], v[48:51], v[108:111], v[160:163]
	v_mfma_f32_16x16x32_f16 v[140:143], v[32:35], v[132:135], v[140:143]
	v_mfma_f32_16x16x32_f16 v[136:139], v[48:51], v[132:135], v[136:139]
	v_mfma_f32_16x16x32_f16 v[116:119], v[32:35], v[156:159], v[116:119]
	v_mfma_f32_16x16x32_f16 v[112:115], v[48:51], v[156:159], v[112:115]
	v_mfma_f32_16x16x32_f16 v[96:99], v[32:35], v[172:175], v[96:99]
	v_mfma_f32_16x16x32_f16 v[92:95], v[48:51], v[172:175], v[92:95]
	v_mfma_f32_16x16x32_f16 v[164:167], v[40:43], v[120:123], v[164:167]
	v_mfma_f32_16x16x32_f16 v[160:163], v[56:59], v[120:123], v[160:163]
	v_mfma_f32_16x16x32_f16 v[140:143], v[40:43], v[144:147], v[140:143]
	v_mfma_f32_16x16x32_f16 v[136:139], v[56:59], v[144:147], v[136:139]
	v_mfma_f32_16x16x32_f16 v[116:119], v[40:43], v[168:171], v[116:119]
	v_mfma_f32_16x16x32_f16 v[112:115], v[56:59], v[168:171], v[112:115]
	v_mfma_f32_16x16x32_f16 v[96:99], v[40:43], v[176:179], v[96:99]
	v_mfma_f32_16x16x32_f16 v[92:95], v[56:59], v[176:179], v[92:95]
	s_barrier
	s_add_i32 s15, 0, 0x14000
	v_add_u32_e32 v202, s15, v208
	s_add_i32 s29, s30, s7
	ds_read_b128 v[190:193], v202
	ds_read_b128 v[194:197], v202 offset:1024
	ds_read_b128 v[198:201], v202 offset:2048
	ds_read_b128 v[210:213], v202 offset:3072
	v_lshl_add_u64 v[202:203], s[38:39], 0, v[2:3]
	s_mov_b32 m0, s29
	v_lshl_add_u64 v[218:219], s[38:39], 0, v[184:185]
	global_load_lds_dwordx4 v[202:203], off
	s_add_i32 m0, s29, 0x2000
	s_nop 0
	global_load_lds_dwordx4 v[218:219], off
	s_waitcnt vmcnt(10)
	s_barrier
	s_waitcnt lgkmcnt(0)
	v_mfma_f32_16x16x32_f16 v[152:155], v[190:193], v[108:111], v[152:155]
	v_mfma_f32_16x16x32_f16 v[108:111], v[198:201], v[108:111], v[148:151]
	v_mfma_f32_16x16x32_f16 v[124:127], v[198:201], v[132:135], v[124:127]
	v_mfma_f32_16x16x32_f16 v[104:107], v[190:193], v[156:159], v[104:107]
	v_mfma_f32_16x16x32_f16 v[100:103], v[198:201], v[156:159], v[100:103]
	v_mfma_f32_16x16x32_f16 v[88:91], v[190:193], v[172:175], v[88:91]
	v_mfma_f32_16x16x32_f16 v[84:87], v[198:201], v[172:175], v[84:87]
	v_mfma_f32_16x16x32_f16 v[152:155], v[194:197], v[120:123], v[152:155]
	v_mfma_f32_16x16x32_f16 v[108:111], v[210:213], v[120:123], v[108:111]
	v_mfma_f32_16x16x32_f16 v[120:123], v[190:193], v[132:135], v[128:131]
	v_mfma_f32_16x16x32_f16 v[124:127], v[210:213], v[144:147], v[124:127]
	v_mfma_f32_16x16x32_f16 v[104:107], v[194:197], v[168:171], v[104:107]
	v_mfma_f32_16x16x32_f16 v[100:103], v[210:213], v[168:171], v[100:103]
	v_mfma_f32_16x16x32_f16 v[88:91], v[194:197], v[176:179], v[88:91]
	v_mfma_f32_16x16x32_f16 v[84:87], v[210:213], v[176:179], v[84:87]
	v_mfma_f32_16x16x32_f16 v[120:123], v[194:197], v[144:147], v[120:123]
	s_mov_b32 m0, s8
	v_lshl_add_u64 v[220:221], s[48:49], 0, v[180:181]
	s_barrier
	ds_read_b128 v[128:131], v209 offset:16384
	ds_read_b128 v[132:135], v209 offset:17408
	ds_read_b128 v[144:147], v209 offset:18432
	ds_read_b128 v[148:151], v209 offset:19456
	ds_read_b128 v[156:159], v209 offset:20480
	ds_read_b128 v[168:171], v209 offset:21504
	ds_read_b128 v[172:175], v209 offset:22528
	ds_read_b128 v[176:179], v209 offset:23552
	global_load_lds_dwordx4 v[220:221], off
	v_lshl_add_u64 v[232:233], s[48:49], 0, v[182:183]
	s_mov_b32 m0, s9
	s_nop 0
	global_load_lds_dwordx4 v[232:233], off
	s_barrier
	s_waitcnt lgkmcnt(0)
	v_mfma_f32_16x16x32_f16 v[80:83], v[32:35], v[128:131], v[80:83]
	v_mfma_f32_16x16x32_f16 v[76:79], v[48:51], v[128:131], v[76:79]
	v_mfma_f32_16x16x32_f16 v[64:67], v[32:35], v[144:147], v[64:67]
	v_mfma_f32_16x16x32_f16 v[60:63], v[48:51], v[144:147], v[60:63]
	v_mfma_f32_16x16x32_f16 v[36:39], v[32:35], v[156:159], v[36:39]
	v_mfma_f32_16x16x32_f16 v[28:31], v[48:51], v[156:159], v[28:31]
	v_mfma_f32_16x16x32_f16 v[16:19], v[32:35], v[172:175], v[16:19]
	v_mfma_f32_16x16x32_f16 v[12:15], v[48:51], v[172:175], v[12:15]
	v_mfma_f32_16x16x32_f16 v[80:83], v[40:43], v[132:135], v[80:83]
	v_mfma_f32_16x16x32_f16 v[76:79], v[56:59], v[132:135], v[76:79]
	v_mfma_f32_16x16x32_f16 v[64:67], v[40:43], v[148:151], v[64:67]
	v_mfma_f32_16x16x32_f16 v[60:63], v[56:59], v[148:151], v[60:63]
	v_mfma_f32_16x16x32_f16 v[36:39], v[40:43], v[168:171], v[36:39]
	v_mfma_f32_16x16x32_f16 v[28:31], v[56:59], v[168:171], v[28:31]
	v_mfma_f32_16x16x32_f16 v[16:19], v[40:43], v[176:179], v[16:19]
	v_mfma_f32_16x16x32_f16 v[12:15], v[56:59], v[176:179], v[12:15]
	s_barrier
	s_add_u32 s30, s38, 0x20000
	s_addc_u32 s31, s39, 0
	s_add_i32 s15, s15, s7
	v_lshl_add_u64 v[32:33], s[30:31], 0, v[2:3]
	s_mov_b32 m0, s15
	s_nop 0
	global_load_lds_dwordx4 v[32:33], off
	s_add_i32 m0, s15, 0x2000
	s_nop 0
	global_load_lds_dwordx4 v184, s[30:31]
	s_waitcnt vmcnt(8)
	s_barrier
	v_mfma_f32_16x16x32_f16 v[44:47], v[198:201], v[144:147], v[44:47]
	v_mfma_f32_16x16x32_f16 v[24:27], v[190:193], v[156:159], v[24:27]
	v_mfma_f32_16x16x32_f16 v[20:23], v[198:201], v[156:159], v[20:23]
	v_mfma_f32_16x16x32_f16 v[8:11], v[190:193], v[172:175], v[8:11]
	v_mfma_f32_16x16x32_f16 v[4:7], v[198:201], v[172:175], v[4:7]
	v_mfma_f32_16x16x32_f16 v[32:35], v[190:193], v[128:131], v[72:75]
	v_mfma_f32_16x16x32_f16 v[40:43], v[198:201], v[128:131], v[68:71]
	v_mfma_f32_16x16x32_f16 v[48:51], v[190:193], v[144:147], v[52:55]
	v_mfma_f32_16x16x32_f16 v[44:47], v[210:213], v[148:151], v[44:47]
	v_mfma_f32_16x16x32_f16 v[24:27], v[194:197], v[168:171], v[24:27]
	v_mfma_f32_16x16x32_f16 v[20:23], v[210:213], v[168:171], v[20:23]
	v_mfma_f32_16x16x32_f16 v[8:11], v[194:197], v[176:179], v[8:11]
	v_mfma_f32_16x16x32_f16 v[4:7], v[210:213], v[176:179], v[4:7]
	v_mfma_f32_16x16x32_f16 v[32:35], v[194:197], v[132:135], v[32:35]
	v_mfma_f32_16x16x32_f16 v[40:43], v[210:213], v[132:135], v[40:43]
	v_mfma_f32_16x16x32_f16 v[48:51], v[194:197], v[148:151], v[48:51]
	s_add_i32 s15, 0, 0x18000
	v_add_u32_e32 v72, s15, v208
	s_barrier
	ds_read_b128 v[52:55], v72
	ds_read_b128 v[56:59], v72 offset:1024
	ds_read_b128 v[68:71], v72 offset:2048
	ds_read_b128 v[72:75], v72 offset:3072
	s_add_u32 s30, s48, 0x20000
	s_addc_u32 s31, s49, 0
	s_mov_b32 m0, s12
	ds_read_b128 v[128:131], v209 offset:32768
	ds_read_b128 v[132:135], v209 offset:33792
	ds_read_b128 v[144:147], v209 offset:34816
	ds_read_b128 v[156:159], v209 offset:35840
	ds_read_b128 v[168:171], v209 offset:36864
	ds_read_b128 v[172:175], v209 offset:37888
	ds_read_b128 v[176:179], v209 offset:38912
	ds_read_b128 v[190:193], v209 offset:39936
	global_load_lds_dwordx4 v180, s[30:31]
	s_mov_b32 m0, s13
	s_nop 0
	global_load_lds_dwordx4 v182, s[30:31]
	s_barrier
	s_waitcnt lgkmcnt(0)
	v_mfma_f32_16x16x32_f16 v[148:151], v[52:55], v[128:131], v[164:167]
	v_mfma_f32_16x16x32_f16 v[164:167], v[56:59], v[132:135], v[148:151]
	v_mfma_f32_16x16x32_f16 v[148:151], v[68:71], v[128:131], v[160:163]
	v_mfma_f32_16x16x32_f16 v[140:143], v[52:55], v[144:147], v[140:143]
	v_mfma_f32_16x16x32_f16 v[136:139], v[68:71], v[144:147], v[136:139]
	v_mfma_f32_16x16x32_f16 v[116:119], v[52:55], v[168:171], v[116:119]
	v_mfma_f32_16x16x32_f16 v[112:115], v[68:71], v[168:171], v[112:115]
	v_mfma_f32_16x16x32_f16 v[96:99], v[52:55], v[176:179], v[96:99]
	v_mfma_f32_16x16x32_f16 v[92:95], v[68:71], v[176:179], v[92:95]
	v_mfma_f32_16x16x32_f16 v[160:163], v[72:75], v[132:135], v[148:151]
	v_mfma_f32_16x16x32_f16 v[140:143], v[56:59], v[156:159], v[140:143]
	v_mfma_f32_16x16x32_f16 v[136:139], v[72:75], v[156:159], v[136:139]
	v_mfma_f32_16x16x32_f16 v[116:119], v[56:59], v[172:175], v[116:119]
	v_mfma_f32_16x16x32_f16 v[112:115], v[72:75], v[172:175], v[112:115]
	v_mfma_f32_16x16x32_f16 v[96:99], v[56:59], v[190:193], v[96:99]
	v_mfma_f32_16x16x32_f16 v[92:95], v[72:75], v[190:193], v[92:95]
	s_barrier
	s_add_i32 s29, 0, 0x1c000
	v_add_u32_e32 v148, s29, v208
	s_add_i32 s15, s15, s7
	ds_read_b128 v[194:197], v148
	ds_read_b128 v[198:201], v148 offset:1024
	ds_read_b128 v[210:213], v148 offset:2048
	ds_read_b128 v[214:217], v148 offset:3072
	v_lshl_add_u64 v[148:149], v[202:203], 0, s[88:89]
	s_mov_b32 m0, s15
	s_nop 0
	global_load_lds_dwordx4 v[148:149], off
	v_lshl_add_u64 v[148:149], v[218:219], 0, s[88:89]
	s_add_i32 m0, s15, 0x2000
	s_nop 0
	global_load_lds_dwordx4 v[148:149], off
	s_waitcnt vmcnt(10)
	s_barrier
	s_waitcnt lgkmcnt(0)
	v_mfma_f32_16x16x32_f16 v[148:151], v[194:197], v[128:131], v[152:155]
	v_mfma_f32_16x16x32_f16 v[108:111], v[210:213], v[128:131], v[108:111]
	v_mfma_f32_16x16x32_f16 v[152:155], v[198:201], v[132:135], v[148:151]
	v_mfma_f32_16x16x32_f16 v[148:151], v[214:217], v[132:135], v[108:111]
	v_mfma_f32_16x16x32_f16 v[108:111], v[194:197], v[144:147], v[120:123]
	v_mfma_f32_16x16x32_f16 v[128:131], v[198:201], v[156:159], v[108:111]
	v_mfma_f32_16x16x32_f16 v[108:111], v[210:213], v[144:147], v[124:127]
	v_mfma_f32_16x16x32_f16 v[104:107], v[194:197], v[168:171], v[104:107]
	v_mfma_f32_16x16x32_f16 v[100:103], v[210:213], v[168:171], v[100:103]
	v_mfma_f32_16x16x32_f16 v[88:91], v[194:197], v[176:179], v[88:91]
	v_mfma_f32_16x16x32_f16 v[84:87], v[210:213], v[176:179], v[84:87]
	v_mfma_f32_16x16x32_f16 v[124:127], v[214:217], v[156:159], v[108:111]
	v_mfma_f32_16x16x32_f16 v[104:107], v[198:201], v[172:175], v[104:107]
	v_mfma_f32_16x16x32_f16 v[100:103], v[214:217], v[172:175], v[100:103]
	v_mfma_f32_16x16x32_f16 v[88:91], v[198:201], v[190:193], v[88:91]
	v_mfma_f32_16x16x32_f16 v[84:87], v[214:217], v[190:193], v[84:87]
	s_mov_b32 m0, s50
	v_lshl_add_u64 v[190:191], v[220:221], 0, s[88:89]
	s_barrier
	ds_read_b128 v[108:111], v209 offset:49152
	ds_read_b128 v[120:123], v209 offset:50176
	ds_read_b128 v[132:135], v209 offset:51200
	ds_read_b128 v[144:147], v209 offset:52224
	ds_read_b128 v[156:159], v209 offset:53248
	ds_read_b128 v[168:171], v209 offset:54272
	ds_read_b128 v[172:175], v209 offset:55296
	ds_read_b128 v[176:179], v209 offset:56320
	global_load_lds_dwordx4 v[190:191], off
	v_lshl_add_u64 v[190:191], v[232:233], 0, s[88:89]
	s_mov_b32 m0, s51
	s_nop 0
	global_load_lds_dwordx4 v[190:191], off
	s_barrier
	s_waitcnt lgkmcnt(0)
	v_mfma_f32_16x16x32_f16 v[80:83], v[52:55], v[108:111], v[80:83]
	v_mfma_f32_16x16x32_f16 v[76:79], v[68:71], v[108:111], v[76:79]
	v_mfma_f32_16x16x32_f16 v[64:67], v[52:55], v[132:135], v[64:67]
	v_mfma_f32_16x16x32_f16 v[60:63], v[68:71], v[132:135], v[60:63]
	v_mfma_f32_16x16x32_f16 v[36:39], v[52:55], v[156:159], v[36:39]
	v_mfma_f32_16x16x32_f16 v[28:31], v[68:71], v[156:159], v[28:31]
	v_mfma_f32_16x16x32_f16 v[16:19], v[52:55], v[172:175], v[16:19]
	v_mfma_f32_16x16x32_f16 v[12:15], v[68:71], v[172:175], v[12:15]
	v_mfma_f32_16x16x32_f16 v[80:83], v[56:59], v[120:123], v[80:83]
	v_mfma_f32_16x16x32_f16 v[76:79], v[72:75], v[120:123], v[76:79]
	v_mfma_f32_16x16x32_f16 v[64:67], v[56:59], v[144:147], v[64:67]
	v_mfma_f32_16x16x32_f16 v[60:63], v[72:75], v[144:147], v[60:63]
	v_mfma_f32_16x16x32_f16 v[36:39], v[56:59], v[168:171], v[36:39]
	v_mfma_f32_16x16x32_f16 v[28:31], v[72:75], v[168:171], v[28:31]
	v_mfma_f32_16x16x32_f16 v[16:19], v[56:59], v[176:179], v[16:19]
	v_mfma_f32_16x16x32_f16 v[12:15], v[72:75], v[176:179], v[12:15]
	s_barrier
	s_add_u32 s30, s38, 0x20080
	s_addc_u32 s31, s39, 0
	s_add_i32 s15, s29, s7
	v_lshl_add_u64 v[52:53], s[30:31], 0, v[2:3]
	s_mov_b32 m0, s15
	s_nop 0
	global_load_lds_dwordx4 v[52:53], off
	s_add_i32 m0, s15, 0x2000
	s_nop 0
	global_load_lds_dwordx4 v184, s[30:31]
	s_waitcnt vmcnt(8)
	s_barrier
	v_mfma_f32_16x16x32_f16 v[32:35], v[194:197], v[108:111], v[32:35]
	v_mfma_f32_16x16x32_f16 v[72:75], v[198:201], v[120:123], v[32:35]
	v_mfma_f32_16x16x32_f16 v[32:35], v[210:213], v[108:111], v[40:43]
	v_mfma_f32_16x16x32_f16 v[68:71], v[214:217], v[120:123], v[32:35]
	v_mfma_f32_16x16x32_f16 v[32:35], v[194:197], v[132:135], v[48:51]
	v_mfma_f32_16x16x32_f16 v[52:55], v[198:201], v[144:147], v[32:35]
	v_mfma_f32_16x16x32_f16 v[32:35], v[210:213], v[132:135], v[44:47]
	v_mfma_f32_16x16x32_f16 v[24:27], v[194:197], v[156:159], v[24:27]
	v_mfma_f32_16x16x32_f16 v[20:23], v[210:213], v[156:159], v[20:23]
	v_mfma_f32_16x16x32_f16 v[8:11], v[194:197], v[172:175], v[8:11]
	v_mfma_f32_16x16x32_f16 v[4:7], v[210:213], v[172:175], v[4:7]
	v_mfma_f32_16x16x32_f16 v[44:47], v[214:217], v[144:147], v[32:35]
	v_mfma_f32_16x16x32_f16 v[24:27], v[198:201], v[168:171], v[24:27]
	v_mfma_f32_16x16x32_f16 v[20:23], v[214:217], v[168:171], v[20:23]
	v_mfma_f32_16x16x32_f16 v[8:11], v[198:201], v[176:179], v[8:11]
	v_mfma_f32_16x16x32_f16 v[4:7], v[214:217], v[176:179], v[4:7]
	s_add_i32 s14, s14, 2
	s_add_u32 s46, s46, 0x100
	s_addc_u32 s47, s47, 0
	s_add_u32 s10, s10, 0x100
	s_addc_u32 s11, s11, 0
	s_cmp_gt_u32 s14, 5
	s_barrier
	s_cbranch_scc0 .LBB0_1664
	s_lshl_b32 s11, s16, 8
	v_mov_b32_e32 v110, v206
	v_mov_b32_e32 v32, v207
	s_lshl_b32 s10, s26, 8
	s_or_b32 s11, s11, s27
	s_add_i32 s10, s10, s17
	v_lshl_add_u32 v108, v32, 3, s11
	v_ashrrev_i32_e32 v109, 31, v108
	v_add_u32_e32 v194, s10, v110
	v_readlane_b32 s10, v253, 25
	v_lshlrev_b64 v[190:191], 1, v[108:109]
	v_readlane_b32 s11, v253, 26
	v_ashrrev_i32_e32 v195, 31, v194
	v_add_u32_e32 v200, 16, v194
	v_lshl_add_u64 v[32:33], v[108:109], 2, s[18:19]
	v_lshl_add_u64 v[192:193], s[10:11], 0, v[190:191]
	v_lshlrev_b64 v[108:109], 10, v[194:195]
	v_ashrrev_i32_e32 v201, 31, v200
	v_add_u32_e32 v198, 32, v194
	flat_load_dwordx4 v[56:59], v[32:33]
	flat_load_dwordx4 v[48:51], v[32:33] offset:16
	flat_load_dwordx4 v[40:43], v[32:33] offset:512
	s_nop 0
	flat_load_dwordx4 v[32:35], v[32:33] offset:528
	v_lshl_add_u64 v[176:177], v[192:193], 0, v[108:109]
	v_lshlrev_b64 v[108:109], 10, v[200:201]
	v_ashrrev_i32_e32 v199, 31, v198
	v_add_u32_e32 v196, 48, v194
	v_lshl_add_u64 v[168:169], v[192:193], 0, v[108:109]
	v_lshlrev_b64 v[108:109], 10, v[198:199]
	v_ashrrev_i32_e32 v197, 31, v196
	v_lshl_add_u64 v[144:145], v[192:193], 0, v[108:109]
	v_lshlrev_b64 v[108:109], 10, v[196:197]
	v_lshl_add_u64 v[120:121], v[192:193], 0, v[108:109]
	global_load_dwordx4 v[108:111], v[120:121], off offset:256
	s_nop 0
	global_load_dwordx4 v[120:123], v[120:121], off
	s_nop 0
	global_load_dwordx4 v[132:135], v[144:145], off offset:256
	s_nop 0
	global_load_dwordx4 v[144:147], v[144:145], off
	s_nop 0
	global_load_dwordx4 v[156:159], v[168:169], off offset:256
	s_nop 0
	global_load_dwordx4 v[168:171], v[168:169], off
	s_nop 0
	global_load_dwordx4 v[172:175], v[176:177], off offset:256
	s_nop 0
	global_load_dwordx4 v[176:179], v[176:177], off
	v_readlane_b32 s10, v253, 40
	v_lshlrev_b64 v[202:203], 12, v[194:195]
	v_readlane_b32 s11, v253, 41
	s_and_b64 vcc, exec, s[40:41]
	s_mov_b32 s16, s34
	s_mov_b32 s26, s36
	s_mov_b64 s[48:49], s[44:45]
	s_mov_b64 s[38:39], s[42:43]
	s_waitcnt vmcnt(0)
	s_waitcnt lgkmcnt(0)
	v_add_f32_e32 v164, v164, v56
	v_add_f32_e32 v165, v165, v57
	v_mul_f32_e32 v164, 0xbfb8aa3b, v164
	v_mul_f32_e32 v165, 0xbfb8aa3b, v165
	v_exp_f32_e32 v164, v164
	v_exp_f32_e32 v165, v165
	v_add_f32_e32 v160, v160, v48
	v_add_f32_e32 v161, v161, v49
	v_add_f32_e32 v164, 1.0, v164
	v_mul_f32_e32 v160, 0xbfb8aa3b, v160
	v_add_f32_e32 v165, 1.0, v165
	v_mul_f32_e32 v161, 0xbfb8aa3b, v161
	v_rcp_f32_e32 v164, v164
	v_exp_f32_e32 v160, v160
	v_rcp_f32_e32 v165, v165
	v_cvt_f32_f16_e32 v210, v176
	v_cvt_f32_f16_sdwa v211, v176 dst_sel:DWORD dst_unused:UNUSED_PAD src0_sel:WORD_1
	v_exp_f32_e32 v161, v161
	v_add_f32_e32 v160, 1.0, v160
	v_rcp_f32_e32 v160, v160
	v_pk_mul_f32 v[164:165], v[164:165], v[210:211]
	v_add_f32_e32 v161, 1.0, v161
	v_cvt_pk_f16_f32 v176, v164, v165
	v_rcp_f32_e32 v161, v161
	v_cvt_f32_f16_e32 v164, v178
	v_cvt_f32_f16_sdwa v165, v178 dst_sel:DWORD dst_unused:UNUSED_PAD src0_sel:WORD_1
	v_add_f32_e32 v152, v152, v40
	v_add_f32_e32 v153, v153, v41
	v_mul_f32_e32 v152, 0xbfb8aa3b, v152
	v_pk_mul_f32 v[160:161], v[160:161], v[164:165]
	v_cvt_f32_f16_e32 v164, v177
	v_cvt_pk_f16_f32 v178, v160, v161
	v_add_f32_e32 v161, v162, v50
	v_mul_f32_e32 v161, 0xbfb8aa3b, v161
	v_exp_f32_e32 v161, v161
	v_add_f32_e32 v160, v166, v58
	v_mul_f32_e32 v160, 0xbfb8aa3b, v160
	v_exp_f32_e32 v160, v160
	v_add_f32_e32 v161, 1.0, v161
	v_rcp_f32_e32 v162, v161
	v_add_f32_e32 v161, v167, v59
	v_mul_f32_e32 v161, 0xbfb8aa3b, v161
	v_exp_f32_e32 v161, v161
	v_add_f32_e32 v160, 1.0, v160
	v_rcp_f32_e32 v160, v160
	v_cvt_f32_f16_sdwa v165, v177 dst_sel:DWORD dst_unused:UNUSED_PAD src0_sel:WORD_1
	v_add_f32_e32 v161, 1.0, v161
	v_rcp_f32_e32 v161, v161
	v_mul_f32_e32 v153, 0xbfb8aa3b, v153
	v_exp_f32_e32 v152, v152
	v_exp_f32_e32 v153, v153
	v_pk_mul_f32 v[160:161], v[160:161], v[164:165]
	v_add_f32_e32 v148, v148, v32
	v_cvt_pk_f16_f32 v164, v160, v161
	v_add_f32_e32 v160, v163, v51
	v_mul_f32_e32 v160, 0xbfb8aa3b, v160
	v_exp_f32_e32 v160, v160
	v_cvt_f32_f16_sdwa v161, v179 dst_sel:DWORD dst_unused:UNUSED_PAD src0_sel:WORD_1
	v_add_f32_e32 v149, v149, v33
	v_add_f32_e32 v152, 1.0, v152
	v_add_f32_e32 v160, 1.0, v160
	v_rcp_f32_e32 v163, v160
	v_cvt_f32_f16_e32 v160, v179
	v_mul_f32_e32 v148, 0xbfb8aa3b, v148
	v_add_f32_e32 v153, 1.0, v153
	v_mul_f32_e32 v149, 0xbfb8aa3b, v149
	v_pk_mul_f32 v[160:161], v[162:163], v[160:161]
	v_rcp_f32_e32 v152, v152
	v_cvt_pk_f16_f32 v160, v160, v161
	v_lshrrev_b32_e32 v161, 4, v176
	v_and_b32_e32 v161, 0x10001, v161
	v_add3_u32 v161, v176, v161, s21
	v_and_b32_e32 v162, 0xfff0fff0, v161
	v_lshrrev_b32_e32 v161, 4, v164
	v_and_b32_e32 v161, 0x10001, v161
	v_add3_u32 v161, v164, v161, s21
	v_and_b32_e32 v163, 0xfff0fff0, v161
	v_lshrrev_b32_e32 v161, 4, v178
	v_and_b32_e32 v161, 0x10001, v161
	v_add3_u32 v161, v178, v161, s21
	v_and_b32_e32 v164, 0xfff0fff0, v161
	v_lshrrev_b32_e32 v161, 4, v160
	v_and_b32_e32 v161, 0x10001, v161
	v_add3_u32 v160, v160, v161, s21
	v_and_b32_e32 v165, 0xfff0fff0, v160
	v_lshl_add_u64 v[160:161], s[10:11], 0, v[202:203]
	v_lshl_add_u64 v[160:161], v[160:161], 0, v[190:191]
	global_store_dwordx4 v[160:161], v[162:165], off
	v_exp_f32_e32 v148, v148
	v_rcp_f32_e32 v153, v153
	v_cvt_f32_f16_e32 v162, v172
	v_cvt_f32_f16_sdwa v163, v172 dst_sel:DWORD dst_unused:UNUSED_PAD src0_sel:WORD_1
	v_exp_f32_e32 v149, v149
	v_add_f32_e32 v148, 1.0, v148
	v_rcp_f32_e32 v148, v148
	v_pk_mul_f32 v[152:153], v[152:153], v[162:163]
	v_add_f32_e32 v149, 1.0, v149
	v_cvt_pk_f16_f32 v162, v152, v153
	v_rcp_f32_e32 v149, v149
	v_cvt_f32_f16_e32 v152, v174
	v_cvt_f32_f16_sdwa v153, v174 dst_sel:DWORD dst_unused:UNUSED_PAD src0_sel:WORD_1
	v_add_f32_e32 v140, v140, v56
	v_add_f32_e32 v141, v141, v57
	v_mul_f32_e32 v140, 0xbfb8aa3b, v140
	v_pk_mul_f32 v[148:149], v[148:149], v[152:153]
	v_cvt_f32_f16_e32 v152, v173
	v_cvt_pk_f16_f32 v163, v148, v149
	v_add_f32_e32 v149, v150, v34
	v_mul_f32_e32 v149, 0xbfb8aa3b, v149
	v_exp_f32_e32 v149, v149
	v_add_f32_e32 v148, v154, v42
	v_mul_f32_e32 v148, 0xbfb8aa3b, v148
	v_exp_f32_e32 v148, v148
	v_add_f32_e32 v149, 1.0, v149
	v_rcp_f32_e32 v150, v149
	v_add_f32_e32 v149, v155, v43
	v_mul_f32_e32 v149, 0xbfb8aa3b, v149
	v_exp_f32_e32 v149, v149
	v_add_f32_e32 v148, 1.0, v148
	v_rcp_f32_e32 v148, v148
	v_cvt_f32_f16_sdwa v153, v173 dst_sel:DWORD dst_unused:UNUSED_PAD src0_sel:WORD_1
	v_add_f32_e32 v149, 1.0, v149
	v_rcp_f32_e32 v149, v149
	v_mul_f32_e32 v141, 0xbfb8aa3b, v141
	v_exp_f32_e32 v140, v140
	v_exp_f32_e32 v141, v141
	v_pk_mul_f32 v[148:149], v[148:149], v[152:153]
	v_add_f32_e32 v136, v136, v48
	v_cvt_pk_f16_f32 v152, v148, v149
	v_add_f32_e32 v148, v151, v35
	v_mul_f32_e32 v148, 0xbfb8aa3b, v148
	v_exp_f32_e32 v148, v148
	v_cvt_f32_f16_sdwa v149, v175 dst_sel:DWORD dst_unused:UNUSED_PAD src0_sel:WORD_1
	v_add_f32_e32 v137, v137, v49
	v_add_f32_e32 v140, 1.0, v140
	v_add_f32_e32 v148, 1.0, v148
	v_rcp_f32_e32 v151, v148
	v_cvt_f32_f16_e32 v148, v175
	v_mul_f32_e32 v136, 0xbfb8aa3b, v136
	v_add_f32_e32 v141, 1.0, v141
	v_mul_f32_e32 v137, 0xbfb8aa3b, v137
	v_pk_mul_f32 v[148:149], v[150:151], v[148:149]
	v_lshrrev_b32_e32 v150, 4, v163
	v_cvt_pk_f16_f32 v151, v148, v149
	v_lshrrev_b32_e32 v149, 4, v152
	v_and_b32_e32 v149, 0x10001, v149
	v_lshrrev_b32_e32 v148, 4, v162
	v_add3_u32 v149, v152, v149, s21
	v_lshrrev_b32_e32 v152, 4, v151
	v_and_b32_e32 v148, 0x10001, v148
	v_and_b32_e32 v150, 0x10001, v150
	v_and_b32_e32 v152, 0x10001, v152
	v_add3_u32 v148, v162, v148, s21
	v_add3_u32 v150, v163, v150, s21
	v_add3_u32 v151, v151, v152, s21
	v_and_b32_e32 v148, 0xfff0fff0, v148
	v_and_b32_e32 v149, 0xfff0fff0, v149
	v_and_b32_e32 v150, 0xfff0fff0, v150
	v_and_b32_e32 v151, 0xfff0fff0, v151
	global_store_dwordx4 v[160:161], v[148:151], off offset:256
	v_rcp_f32_e32 v140, v140
	v_exp_f32_e32 v136, v136
	v_rcp_f32_e32 v141, v141
	v_cvt_f32_f16_e32 v150, v168
	v_cvt_f32_f16_sdwa v151, v168 dst_sel:DWORD dst_unused:UNUSED_PAD src0_sel:WORD_1
	v_exp_f32_e32 v137, v137
	v_add_f32_e32 v136, 1.0, v136
	v_rcp_f32_e32 v136, v136
	v_pk_mul_f32 v[140:141], v[140:141], v[150:151]
	v_add_f32_e32 v137, 1.0, v137
	v_cvt_pk_f16_f32 v150, v140, v141
	v_rcp_f32_e32 v137, v137
	v_cvt_f32_f16_e32 v140, v170
	v_cvt_f32_f16_sdwa v141, v170 dst_sel:DWORD dst_unused:UNUSED_PAD src0_sel:WORD_1
	v_add_f32_e32 v128, v128, v40
	v_add_f32_e32 v129, v129, v41
	v_mul_f32_e32 v128, 0xbfb8aa3b, v128
	v_pk_mul_f32 v[136:137], v[136:137], v[140:141]
	v_cvt_f32_f16_e32 v140, v169
	v_cvt_pk_f16_f32 v151, v136, v137
	v_add_f32_e32 v137, v138, v50
	v_mul_f32_e32 v137, 0xbfb8aa3b, v137
	v_exp_f32_e32 v137, v137
	v_add_f32_e32 v136, v142, v58
	v_mul_f32_e32 v136, 0xbfb8aa3b, v136
	v_exp_f32_e32 v136, v136
	v_add_f32_e32 v137, 1.0, v137
	v_rcp_f32_e32 v138, v137
	v_add_f32_e32 v137, v143, v59
	v_mul_f32_e32 v137, 0xbfb8aa3b, v137
	v_exp_f32_e32 v137, v137
	v_add_f32_e32 v136, 1.0, v136
	v_rcp_f32_e32 v136, v136
	v_cvt_f32_f16_sdwa v141, v169 dst_sel:DWORD dst_unused:UNUSED_PAD src0_sel:WORD_1
	v_add_f32_e32 v137, 1.0, v137
	v_rcp_f32_e32 v137, v137
	v_mul_f32_e32 v129, 0xbfb8aa3b, v129
	v_exp_f32_e32 v128, v128
	v_exp_f32_e32 v129, v129
	v_pk_mul_f32 v[136:137], v[136:137], v[140:141]
	v_lshlrev_b64 v[148:149], 12, v[200:201]
	v_cvt_pk_f16_f32 v140, v136, v137
	v_add_f32_e32 v136, v139, v51
	v_mul_f32_e32 v136, 0xbfb8aa3b, v136
	v_exp_f32_e32 v136, v136
	v_cvt_f32_f16_sdwa v137, v171 dst_sel:DWORD dst_unused:UNUSED_PAD src0_sel:WORD_1
	v_add_f32_e32 v124, v124, v32
	v_add_f32_e32 v125, v125, v33
	v_add_f32_e32 v136, 1.0, v136
	v_rcp_f32_e32 v139, v136
	v_cvt_f32_f16_e32 v136, v171
	v_add_f32_e32 v128, 1.0, v128
	v_mul_f32_e32 v124, 0xbfb8aa3b, v124
	v_add_f32_e32 v129, 1.0, v129
	v_pk_mul_f32 v[136:137], v[138:139], v[136:137]
	v_mul_f32_e32 v125, 0xbfb8aa3b, v125
	v_cvt_pk_f16_f32 v136, v136, v137
	v_lshrrev_b32_e32 v137, 4, v150
	v_and_b32_e32 v137, 0x10001, v137
	v_add3_u32 v137, v150, v137, s21
	v_and_b32_e32 v138, 0xfff0fff0, v137
	v_lshrrev_b32_e32 v137, 4, v140
	v_and_b32_e32 v137, 0x10001, v137
	v_add3_u32 v137, v140, v137, s21
	v_and_b32_e32 v139, 0xfff0fff0, v137
	v_lshrrev_b32_e32 v137, 4, v151
	v_and_b32_e32 v137, 0x10001, v137
	v_add3_u32 v137, v151, v137, s21
	v_and_b32_e32 v140, 0xfff0fff0, v137
	v_lshrrev_b32_e32 v137, 4, v136
	v_and_b32_e32 v137, 0x10001, v137
	v_add3_u32 v136, v136, v137, s21
	v_and_b32_e32 v141, 0xfff0fff0, v136
	v_lshl_add_u64 v[136:137], s[10:11], 0, v[148:149]
	v_lshl_add_u64 v[136:137], v[136:137], 0, v[190:191]
	global_store_dwordx4 v[136:137], v[138:141], off
	v_rcp_f32_e32 v128, v128
	v_exp_f32_e32 v124, v124
	v_rcp_f32_e32 v129, v129
	v_cvt_f32_f16_e32 v138, v156
	v_cvt_f32_f16_sdwa v139, v156 dst_sel:DWORD dst_unused:UNUSED_PAD src0_sel:WORD_1
	v_exp_f32_e32 v125, v125
	v_add_f32_e32 v124, 1.0, v124
	v_rcp_f32_e32 v124, v124
	v_pk_mul_f32 v[128:129], v[128:129], v[138:139]
	v_add_f32_e32 v125, 1.0, v125
	v_cvt_pk_f16_f32 v138, v128, v129
	v_rcp_f32_e32 v125, v125
	v_cvt_f32_f16_e32 v128, v158
	v_cvt_f32_f16_sdwa v129, v158 dst_sel:DWORD dst_unused:UNUSED_PAD src0_sel:WORD_1
	v_add_f32_e32 v116, v116, v56
	v_add_f32_e32 v117, v117, v57
	v_mul_f32_e32 v116, 0xbfb8aa3b, v116
	v_pk_mul_f32 v[124:125], v[124:125], v[128:129]
	v_cvt_f32_f16_e32 v128, v157
	v_cvt_pk_f16_f32 v139, v124, v125
	v_add_f32_e32 v125, v126, v34
	v_mul_f32_e32 v125, 0xbfb8aa3b, v125
	v_exp_f32_e32 v125, v125
	v_add_f32_e32 v124, v130, v42
	v_mul_f32_e32 v124, 0xbfb8aa3b, v124
	v_exp_f32_e32 v124, v124
	v_add_f32_e32 v125, 1.0, v125
	v_rcp_f32_e32 v126, v125
	v_add_f32_e32 v125, v131, v43
	v_mul_f32_e32 v125, 0xbfb8aa3b, v125
	v_exp_f32_e32 v125, v125
	v_add_f32_e32 v124, 1.0, v124
	v_rcp_f32_e32 v124, v124
	v_cvt_f32_f16_sdwa v129, v157 dst_sel:DWORD dst_unused:UNUSED_PAD src0_sel:WORD_1
	v_add_f32_e32 v125, 1.0, v125
	v_rcp_f32_e32 v125, v125
	v_mul_f32_e32 v117, 0xbfb8aa3b, v117
	v_exp_f32_e32 v116, v116
	v_exp_f32_e32 v117, v117
	v_pk_mul_f32 v[124:125], v[124:125], v[128:129]
	v_add_f32_e32 v112, v112, v48
	v_cvt_pk_f16_f32 v128, v124, v125
	v_add_f32_e32 v124, v127, v35
	v_mul_f32_e32 v124, 0xbfb8aa3b, v124
	v_exp_f32_e32 v124, v124
	v_cvt_f32_f16_sdwa v125, v159 dst_sel:DWORD dst_unused:UNUSED_PAD src0_sel:WORD_1
	v_add_f32_e32 v113, v113, v49
	v_add_f32_e32 v116, 1.0, v116
	v_add_f32_e32 v124, 1.0, v124
	v_rcp_f32_e32 v127, v124
	v_cvt_f32_f16_e32 v124, v159
	v_mul_f32_e32 v112, 0xbfb8aa3b, v112
	v_add_f32_e32 v117, 1.0, v117
	v_mul_f32_e32 v113, 0xbfb8aa3b, v113
	v_pk_mul_f32 v[124:125], v[126:127], v[124:125]
	v_lshrrev_b32_e32 v126, 4, v139
	v_cvt_pk_f16_f32 v127, v124, v125
	v_lshrrev_b32_e32 v125, 4, v128
	v_and_b32_e32 v125, 0x10001, v125
	v_lshrrev_b32_e32 v124, 4, v138
	v_add3_u32 v125, v128, v125, s21
	v_lshrrev_b32_e32 v128, 4, v127
	v_and_b32_e32 v124, 0x10001, v124
	v_and_b32_e32 v126, 0x10001, v126
	v_and_b32_e32 v128, 0x10001, v128
	v_add3_u32 v124, v138, v124, s21
	v_add3_u32 v126, v139, v126, s21
	v_add3_u32 v127, v127, v128, s21
	v_and_b32_e32 v124, 0xfff0fff0, v124
	v_and_b32_e32 v125, 0xfff0fff0, v125
	v_and_b32_e32 v126, 0xfff0fff0, v126
	v_and_b32_e32 v127, 0xfff0fff0, v127
	global_store_dwordx4 v[136:137], v[124:127], off offset:256
	v_rcp_f32_e32 v116, v116
	v_exp_f32_e32 v112, v112
	v_rcp_f32_e32 v117, v117
	v_cvt_f32_f16_e32 v126, v144
	v_cvt_f32_f16_sdwa v127, v144 dst_sel:DWORD dst_unused:UNUSED_PAD src0_sel:WORD_1
	v_exp_f32_e32 v113, v113
	v_add_f32_e32 v112, 1.0, v112
	v_rcp_f32_e32 v112, v112
	v_pk_mul_f32 v[116:117], v[116:117], v[126:127]
	v_add_f32_e32 v113, 1.0, v113
	v_cvt_pk_f16_f32 v126, v116, v117
	v_rcp_f32_e32 v113, v113
	v_cvt_f32_f16_e32 v116, v146
	v_cvt_f32_f16_sdwa v117, v146 dst_sel:DWORD dst_unused:UNUSED_PAD src0_sel:WORD_1
	v_add_f32_e32 v104, v104, v40
	v_add_f32_e32 v105, v105, v41
	v_mul_f32_e32 v104, 0xbfb8aa3b, v104
	v_pk_mul_f32 v[112:113], v[112:113], v[116:117]
	v_cvt_f32_f16_e32 v116, v145
	v_cvt_pk_f16_f32 v127, v112, v113
	v_add_f32_e32 v113, v114, v50
	v_mul_f32_e32 v113, 0xbfb8aa3b, v113
	v_exp_f32_e32 v113, v113
	v_add_f32_e32 v112, v118, v58
	v_mul_f32_e32 v112, 0xbfb8aa3b, v112
	v_exp_f32_e32 v112, v112
	v_add_f32_e32 v113, 1.0, v113
	v_rcp_f32_e32 v114, v113
	v_add_f32_e32 v113, v119, v59
	v_mul_f32_e32 v113, 0xbfb8aa3b, v113
	v_exp_f32_e32 v113, v113
	v_add_f32_e32 v112, 1.0, v112
	v_rcp_f32_e32 v112, v112
	v_cvt_f32_f16_sdwa v117, v145 dst_sel:DWORD dst_unused:UNUSED_PAD src0_sel:WORD_1
	v_add_f32_e32 v113, 1.0, v113
	v_rcp_f32_e32 v113, v113
	v_mul_f32_e32 v105, 0xbfb8aa3b, v105
	v_exp_f32_e32 v104, v104
	v_exp_f32_e32 v105, v105
	v_pk_mul_f32 v[112:113], v[112:113], v[116:117]
	v_lshlrev_b64 v[124:125], 12, v[198:199]
	v_cvt_pk_f16_f32 v116, v112, v113
	v_add_f32_e32 v112, v115, v51
	v_mul_f32_e32 v112, 0xbfb8aa3b, v112
	v_exp_f32_e32 v112, v112
	v_cvt_f32_f16_sdwa v113, v147 dst_sel:DWORD dst_unused:UNUSED_PAD src0_sel:WORD_1
	v_add_f32_e32 v100, v100, v32
	v_add_f32_e32 v101, v101, v33
	v_add_f32_e32 v112, 1.0, v112
	v_rcp_f32_e32 v115, v112
	v_cvt_f32_f16_e32 v112, v147
	v_add_f32_e32 v104, 1.0, v104
	v_mul_f32_e32 v100, 0xbfb8aa3b, v100
	v_add_f32_e32 v105, 1.0, v105
	v_pk_mul_f32 v[112:113], v[114:115], v[112:113]
	v_mul_f32_e32 v101, 0xbfb8aa3b, v101
	v_cvt_pk_f16_f32 v112, v112, v113
	v_lshrrev_b32_e32 v113, 4, v126
	v_and_b32_e32 v113, 0x10001, v113
	v_add3_u32 v113, v126, v113, s21
	v_and_b32_e32 v114, 0xfff0fff0, v113
	v_lshrrev_b32_e32 v113, 4, v116
	v_and_b32_e32 v113, 0x10001, v113
	v_add3_u32 v113, v116, v113, s21
	v_and_b32_e32 v115, 0xfff0fff0, v113
	v_lshrrev_b32_e32 v113, 4, v127
	v_and_b32_e32 v113, 0x10001, v113
	v_add3_u32 v113, v127, v113, s21
	v_and_b32_e32 v116, 0xfff0fff0, v113
	v_lshrrev_b32_e32 v113, 4, v112
	v_and_b32_e32 v113, 0x10001, v113
	v_add3_u32 v112, v112, v113, s21
	v_and_b32_e32 v117, 0xfff0fff0, v112
	v_lshl_add_u64 v[112:113], s[10:11], 0, v[124:125]
	v_lshl_add_u64 v[112:113], v[112:113], 0, v[190:191]
	global_store_dwordx4 v[112:113], v[114:117], off
	v_rcp_f32_e32 v104, v104
	v_exp_f32_e32 v100, v100
	v_rcp_f32_e32 v105, v105
	v_cvt_f32_f16_e32 v114, v132
	v_cvt_f32_f16_sdwa v115, v132 dst_sel:DWORD dst_unused:UNUSED_PAD src0_sel:WORD_1
	v_exp_f32_e32 v101, v101
	v_add_f32_e32 v100, 1.0, v100
	v_rcp_f32_e32 v100, v100
	v_pk_mul_f32 v[104:105], v[104:105], v[114:115]
	v_add_f32_e32 v101, 1.0, v101
	v_cvt_pk_f16_f32 v114, v104, v105
	v_rcp_f32_e32 v101, v101
	v_cvt_f32_f16_e32 v104, v134
	v_cvt_f32_f16_sdwa v105, v134 dst_sel:DWORD dst_unused:UNUSED_PAD src0_sel:WORD_1
	v_add_f32_e32 v96, v96, v56
	v_add_f32_e32 v97, v97, v57
	v_mul_f32_e32 v96, 0xbfb8aa3b, v96
	v_pk_mul_f32 v[100:101], v[100:101], v[104:105]
	v_cvt_f32_f16_e32 v104, v133
	v_cvt_pk_f16_f32 v115, v100, v101
	v_add_f32_e32 v101, v102, v34
	v_mul_f32_e32 v101, 0xbfb8aa3b, v101
	v_exp_f32_e32 v101, v101
	v_add_f32_e32 v100, v106, v42
	v_mul_f32_e32 v100, 0xbfb8aa3b, v100
	v_exp_f32_e32 v100, v100
	v_add_f32_e32 v101, 1.0, v101
	v_rcp_f32_e32 v102, v101
	v_add_f32_e32 v101, v107, v43
	v_mul_f32_e32 v101, 0xbfb8aa3b, v101
	v_exp_f32_e32 v101, v101
	v_add_f32_e32 v100, 1.0, v100
	v_rcp_f32_e32 v100, v100
	v_cvt_f32_f16_sdwa v105, v133 dst_sel:DWORD dst_unused:UNUSED_PAD src0_sel:WORD_1
	v_add_f32_e32 v101, 1.0, v101
	v_rcp_f32_e32 v101, v101
	v_mul_f32_e32 v97, 0xbfb8aa3b, v97
	v_exp_f32_e32 v96, v96
	v_exp_f32_e32 v97, v97
	v_pk_mul_f32 v[100:101], v[100:101], v[104:105]
	v_add_f32_e32 v92, v92, v48
	v_cvt_pk_f16_f32 v104, v100, v101
	v_add_f32_e32 v100, v103, v35
	v_mul_f32_e32 v100, 0xbfb8aa3b, v100
	v_exp_f32_e32 v100, v100
	v_cvt_f32_f16_sdwa v101, v135 dst_sel:DWORD dst_unused:UNUSED_PAD src0_sel:WORD_1
	v_add_f32_e32 v93, v93, v49
	v_add_f32_e32 v96, 1.0, v96
	v_add_f32_e32 v100, 1.0, v100
	v_rcp_f32_e32 v103, v100
	v_cvt_f32_f16_e32 v100, v135
	v_mul_f32_e32 v92, 0xbfb8aa3b, v92
	v_add_f32_e32 v97, 1.0, v97
	v_mul_f32_e32 v93, 0xbfb8aa3b, v93
	v_pk_mul_f32 v[100:101], v[102:103], v[100:101]
	v_lshrrev_b32_e32 v102, 4, v115
	v_cvt_pk_f16_f32 v103, v100, v101
	v_lshrrev_b32_e32 v101, 4, v104
	v_and_b32_e32 v101, 0x10001, v101
	v_lshrrev_b32_e32 v100, 4, v114
	v_add3_u32 v101, v104, v101, s21
	v_lshrrev_b32_e32 v104, 4, v103
	v_and_b32_e32 v100, 0x10001, v100
	v_and_b32_e32 v102, 0x10001, v102
	v_and_b32_e32 v104, 0x10001, v104
	v_add3_u32 v100, v114, v100, s21
	v_add3_u32 v102, v115, v102, s21
	v_add3_u32 v103, v103, v104, s21
	v_and_b32_e32 v100, 0xfff0fff0, v100
	v_and_b32_e32 v101, 0xfff0fff0, v101
	v_and_b32_e32 v102, 0xfff0fff0, v102
	v_and_b32_e32 v103, 0xfff0fff0, v103
	global_store_dwordx4 v[112:113], v[100:103], off offset:256
	v_rcp_f32_e32 v96, v96
	v_exp_f32_e32 v92, v92
	v_rcp_f32_e32 v97, v97
	v_cvt_f32_f16_e32 v102, v120
	v_cvt_f32_f16_sdwa v103, v120 dst_sel:DWORD dst_unused:UNUSED_PAD src0_sel:WORD_1
	v_exp_f32_e32 v93, v93
	v_add_f32_e32 v92, 1.0, v92
	v_rcp_f32_e32 v92, v92
	v_pk_mul_f32 v[96:97], v[96:97], v[102:103]
	v_add_f32_e32 v93, 1.0, v93
	v_cvt_pk_f16_f32 v102, v96, v97
	v_rcp_f32_e32 v93, v93
	v_cvt_f32_f16_e32 v96, v122
	v_cvt_f32_f16_sdwa v97, v122 dst_sel:DWORD dst_unused:UNUSED_PAD src0_sel:WORD_1
	v_add_f32_e32 v88, v88, v40
	v_add_f32_e32 v89, v89, v41
	v_mul_f32_e32 v88, 0xbfb8aa3b, v88
	v_pk_mul_f32 v[92:93], v[92:93], v[96:97]
	v_cvt_f32_f16_e32 v96, v121
	v_cvt_pk_f16_f32 v103, v92, v93
	v_add_f32_e32 v93, v94, v50
	v_mul_f32_e32 v93, 0xbfb8aa3b, v93
	v_exp_f32_e32 v93, v93
	v_add_f32_e32 v92, v98, v58
	v_mul_f32_e32 v92, 0xbfb8aa3b, v92
	v_exp_f32_e32 v92, v92
	v_add_f32_e32 v93, 1.0, v93
	v_rcp_f32_e32 v94, v93
	v_add_f32_e32 v93, v99, v59
	v_mul_f32_e32 v93, 0xbfb8aa3b, v93
	v_exp_f32_e32 v93, v93
	v_add_f32_e32 v92, 1.0, v92
	v_rcp_f32_e32 v92, v92
	v_cvt_f32_f16_sdwa v97, v121 dst_sel:DWORD dst_unused:UNUSED_PAD src0_sel:WORD_1
	v_add_f32_e32 v93, 1.0, v93
	v_rcp_f32_e32 v93, v93
	v_mul_f32_e32 v89, 0xbfb8aa3b, v89
	v_exp_f32_e32 v88, v88
	v_exp_f32_e32 v89, v89
	v_pk_mul_f32 v[92:93], v[92:93], v[96:97]
	v_lshlrev_b64 v[100:101], 12, v[196:197]
	v_cvt_pk_f16_f32 v96, v92, v93
	v_add_f32_e32 v92, v95, v51
	v_mul_f32_e32 v92, 0xbfb8aa3b, v92
	v_exp_f32_e32 v92, v92
	v_cvt_f32_f16_sdwa v93, v123 dst_sel:DWORD dst_unused:UNUSED_PAD src0_sel:WORD_1
	v_add_f32_e32 v84, v84, v32
	v_add_f32_e32 v85, v85, v33
	v_add_f32_e32 v92, 1.0, v92
	v_rcp_f32_e32 v95, v92
	v_cvt_f32_f16_e32 v92, v123
	v_add_f32_e32 v88, 1.0, v88
	v_mul_f32_e32 v84, 0xbfb8aa3b, v84
	v_add_f32_e32 v89, 1.0, v89
	v_pk_mul_f32 v[92:93], v[94:95], v[92:93]
	v_mul_f32_e32 v85, 0xbfb8aa3b, v85
	v_cvt_pk_f16_f32 v92, v92, v93
	v_lshrrev_b32_e32 v93, 4, v102
	v_and_b32_e32 v93, 0x10001, v93
	v_add3_u32 v93, v102, v93, s21
	v_and_b32_e32 v94, 0xfff0fff0, v93
	v_lshrrev_b32_e32 v93, 4, v96
	v_and_b32_e32 v93, 0x10001, v93
	v_add3_u32 v93, v96, v93, s21
	v_and_b32_e32 v95, 0xfff0fff0, v93
	v_lshrrev_b32_e32 v93, 4, v103
	v_and_b32_e32 v93, 0x10001, v93
	v_add3_u32 v93, v103, v93, s21
	v_and_b32_e32 v96, 0xfff0fff0, v93
	v_lshrrev_b32_e32 v93, 4, v92
	v_and_b32_e32 v93, 0x10001, v93
	v_add3_u32 v92, v92, v93, s21
	v_and_b32_e32 v97, 0xfff0fff0, v92
	v_lshl_add_u64 v[92:93], s[10:11], 0, v[100:101]
	v_lshl_add_u64 v[92:93], v[92:93], 0, v[190:191]
	global_store_dwordx4 v[92:93], v[94:97], off
	v_rcp_f32_e32 v88, v88
	v_exp_f32_e32 v84, v84
	v_rcp_f32_e32 v89, v89
	v_cvt_f32_f16_e32 v94, v108
	v_cvt_f32_f16_sdwa v95, v108 dst_sel:DWORD dst_unused:UNUSED_PAD src0_sel:WORD_1
	v_exp_f32_e32 v85, v85
	v_add_f32_e32 v84, 1.0, v84
	v_rcp_f32_e32 v84, v84
	v_pk_mul_f32 v[88:89], v[88:89], v[94:95]
	v_add_f32_e32 v85, 1.0, v85
	v_cvt_pk_f16_f32 v94, v88, v89
	v_rcp_f32_e32 v85, v85
	v_cvt_f32_f16_e32 v88, v110
	v_cvt_f32_f16_sdwa v89, v110 dst_sel:DWORD dst_unused:UNUSED_PAD src0_sel:WORD_1
	v_add_u32_e32 v118, 0x80, v194
	v_ashrrev_i32_e32 v119, 31, v118
	v_add_u32_e32 v116, 0x90, v194
	v_pk_mul_f32 v[84:85], v[84:85], v[88:89]
	v_cvt_f32_f16_e32 v88, v109
	v_cvt_pk_f16_f32 v95, v84, v85
	v_add_f32_e32 v85, v86, v34
	v_mul_f32_e32 v85, 0xbfb8aa3b, v85
	v_exp_f32_e32 v85, v85
	v_add_f32_e32 v84, v90, v42
	v_mul_f32_e32 v84, 0xbfb8aa3b, v84
	v_exp_f32_e32 v84, v84
	v_add_f32_e32 v85, 1.0, v85
	v_rcp_f32_e32 v86, v85
	v_add_f32_e32 v85, v91, v43
	v_mul_f32_e32 v85, 0xbfb8aa3b, v85
	v_exp_f32_e32 v85, v85
	v_add_f32_e32 v84, 1.0, v84
	v_rcp_f32_e32 v84, v84
	v_cvt_f32_f16_sdwa v89, v109 dst_sel:DWORD dst_unused:UNUSED_PAD src0_sel:WORD_1
	v_add_f32_e32 v85, 1.0, v85
	v_rcp_f32_e32 v85, v85
	v_ashrrev_i32_e32 v117, 31, v116
	v_add_u32_e32 v114, 0xa0, v194
	v_ashrrev_i32_e32 v115, 31, v114
	v_pk_mul_f32 v[84:85], v[84:85], v[88:89]
	v_add_u32_e32 v112, 0xb0, v194
	v_cvt_pk_f16_f32 v88, v84, v85
	v_add_f32_e32 v84, v87, v35
	v_mul_f32_e32 v84, 0xbfb8aa3b, v84
	v_exp_f32_e32 v84, v84
	v_cvt_f32_f16_sdwa v85, v111 dst_sel:DWORD dst_unused:UNUSED_PAD src0_sel:WORD_1
	v_ashrrev_i32_e32 v113, 31, v112
	v_add_f32_e32 v80, v80, v56
	v_add_f32_e32 v84, 1.0, v84
	v_rcp_f32_e32 v87, v84
	v_cvt_f32_f16_e32 v84, v111
	v_add_f32_e32 v81, v81, v57
	v_mul_f32_e32 v80, 0xbfb8aa3b, v80
	v_mul_f32_e32 v81, 0xbfb8aa3b, v81
	v_pk_mul_f32 v[84:85], v[86:87], v[84:85]
	v_lshrrev_b32_e32 v86, 4, v95
	v_cvt_pk_f16_f32 v87, v84, v85
	v_lshrrev_b32_e32 v85, 4, v88
	v_and_b32_e32 v85, 0x10001, v85
	v_lshrrev_b32_e32 v84, 4, v94
	v_add3_u32 v85, v88, v85, s21
	v_lshrrev_b32_e32 v88, 4, v87
	v_and_b32_e32 v84, 0x10001, v84
	v_and_b32_e32 v86, 0x10001, v86
	v_and_b32_e32 v88, 0x10001, v88
	v_add3_u32 v84, v94, v84, s21
	v_add3_u32 v86, v95, v86, s21
	v_add3_u32 v87, v87, v88, s21
	v_and_b32_e32 v84, 0xfff0fff0, v84
	v_and_b32_e32 v85, 0xfff0fff0, v85
	v_and_b32_e32 v86, 0xfff0fff0, v86
	v_and_b32_e32 v87, 0xfff0fff0, v87
	global_store_dwordx4 v[92:93], v[84:87], off offset:256
	v_exp_f32_e32 v80, v80
	v_exp_f32_e32 v81, v81
	v_lshlrev_b64 v[84:85], 10, v[118:119]
	v_lshl_add_u64 v[120:121], v[192:193], 0, v[84:85]
	v_lshlrev_b64 v[84:85], 10, v[116:117]
	v_lshl_add_u64 v[104:105], v[192:193], 0, v[84:85]
	v_lshlrev_b64 v[84:85], 10, v[114:115]
	v_lshl_add_u64 v[96:97], v[192:193], 0, v[84:85]
	v_lshlrev_b64 v[84:85], 10, v[112:113]
	v_lshl_add_u64 v[88:89], v[192:193], 0, v[84:85]
	global_load_dwordx4 v[84:87], v[88:89], off offset:256
	s_nop 0
	global_load_dwordx4 v[88:91], v[88:89], off
	s_nop 0
	global_load_dwordx4 v[92:95], v[96:97], off offset:256
	s_nop 0
	global_load_dwordx4 v[96:99], v[96:97], off
	s_nop 0
	global_load_dwordx4 v[100:103], v[104:105], off offset:256
	s_nop 0
	global_load_dwordx4 v[104:107], v[104:105], off
	s_nop 0
	global_load_dwordx4 v[108:111], v[120:121], off offset:256
	s_nop 0
	global_load_dwordx4 v[120:123], v[120:121], off
	v_add_f32_e32 v76, v76, v48
	v_add_f32_e32 v77, v77, v49
	v_add_f32_e32 v80, 1.0, v80
	v_mul_f32_e32 v76, 0xbfb8aa3b, v76
	v_add_f32_e32 v81, 1.0, v81
	v_mul_f32_e32 v77, 0xbfb8aa3b, v77
	s_waitcnt vmcnt(0)
	v_rcp_f32_e32 v80, v80
	v_exp_f32_e32 v76, v76
	v_rcp_f32_e32 v81, v81
	v_cvt_f32_f16_e32 v124, v120
	v_cvt_f32_f16_sdwa v125, v120 dst_sel:DWORD dst_unused:UNUSED_PAD src0_sel:WORD_1
	v_exp_f32_e32 v77, v77
	v_add_f32_e32 v76, 1.0, v76
	v_rcp_f32_e32 v76, v76
	v_pk_mul_f32 v[80:81], v[80:81], v[124:125]
	v_add_f32_e32 v77, 1.0, v77
	v_cvt_pk_f16_f32 v120, v80, v81
	v_rcp_f32_e32 v77, v77
	v_cvt_f32_f16_e32 v80, v122
	v_cvt_f32_f16_sdwa v81, v122 dst_sel:DWORD dst_unused:UNUSED_PAD src0_sel:WORD_1
	v_add_f32_e32 v72, v72, v40
	v_add_f32_e32 v73, v73, v41
	v_mul_f32_e32 v72, 0xbfb8aa3b, v72
	v_pk_mul_f32 v[76:77], v[76:77], v[80:81]
	v_cvt_f32_f16_e32 v80, v121
	v_cvt_pk_f16_f32 v122, v76, v77
	v_add_f32_e32 v77, v78, v50
	v_mul_f32_e32 v77, 0xbfb8aa3b, v77
	v_exp_f32_e32 v77, v77
	v_add_f32_e32 v76, v82, v58
	v_mul_f32_e32 v76, 0xbfb8aa3b, v76
	v_exp_f32_e32 v76, v76
	v_add_f32_e32 v77, 1.0, v77
	v_rcp_f32_e32 v78, v77
	v_add_f32_e32 v77, v83, v59
	v_mul_f32_e32 v77, 0xbfb8aa3b, v77
	v_exp_f32_e32 v77, v77
	v_add_f32_e32 v76, 1.0, v76
	v_rcp_f32_e32 v76, v76
	v_cvt_f32_f16_sdwa v81, v121 dst_sel:DWORD dst_unused:UNUSED_PAD src0_sel:WORD_1
	v_add_f32_e32 v77, 1.0, v77
	v_rcp_f32_e32 v77, v77
	v_mul_f32_e32 v73, 0xbfb8aa3b, v73
	v_exp_f32_e32 v72, v72
	v_exp_f32_e32 v73, v73
	v_pk_mul_f32 v[76:77], v[76:77], v[80:81]
	v_lshlrev_b64 v[118:119], 12, v[118:119]
	v_cvt_pk_f16_f32 v80, v76, v77
	v_add_f32_e32 v76, v79, v51
	v_mul_f32_e32 v76, 0xbfb8aa3b, v76
	v_exp_f32_e32 v76, v76
	v_cvt_f32_f16_sdwa v77, v123 dst_sel:DWORD dst_unused:UNUSED_PAD src0_sel:WORD_1
	v_add_f32_e32 v68, v68, v32
	v_add_f32_e32 v69, v69, v33
	v_add_f32_e32 v76, 1.0, v76
	v_rcp_f32_e32 v79, v76
	v_cvt_f32_f16_e32 v76, v123
	v_add_f32_e32 v72, 1.0, v72
	v_mul_f32_e32 v68, 0xbfb8aa3b, v68
	v_add_f32_e32 v73, 1.0, v73
	v_pk_mul_f32 v[76:77], v[78:79], v[76:77]
	v_mul_f32_e32 v69, 0xbfb8aa3b, v69
	v_cvt_pk_f16_f32 v76, v76, v77
	v_lshrrev_b32_e32 v77, 4, v120
	v_and_b32_e32 v77, 0x10001, v77
	v_add3_u32 v77, v120, v77, s21
	v_and_b32_e32 v78, 0xfff0fff0, v77
	v_lshrrev_b32_e32 v77, 4, v80
	v_and_b32_e32 v77, 0x10001, v77
	v_add3_u32 v77, v80, v77, s21
	v_and_b32_e32 v79, 0xfff0fff0, v77
	v_lshrrev_b32_e32 v77, 4, v122
	v_and_b32_e32 v77, 0x10001, v77
	v_add3_u32 v77, v122, v77, s21
	v_and_b32_e32 v80, 0xfff0fff0, v77
	v_lshrrev_b32_e32 v77, 4, v76
	v_and_b32_e32 v77, 0x10001, v77
	v_add3_u32 v76, v76, v77, s21
	v_and_b32_e32 v81, 0xfff0fff0, v76
	v_lshl_add_u64 v[76:77], s[10:11], 0, v[118:119]
	v_lshl_add_u64 v[76:77], v[76:77], 0, v[190:191]
	global_store_dwordx4 v[76:77], v[78:81], off
	v_rcp_f32_e32 v72, v72
	v_exp_f32_e32 v68, v68
	v_rcp_f32_e32 v73, v73
	v_cvt_f32_f16_e32 v78, v108
	v_cvt_f32_f16_sdwa v79, v108 dst_sel:DWORD dst_unused:UNUSED_PAD src0_sel:WORD_1
	v_exp_f32_e32 v69, v69
	v_add_f32_e32 v68, 1.0, v68
	v_rcp_f32_e32 v68, v68
	v_pk_mul_f32 v[72:73], v[72:73], v[78:79]
	v_add_f32_e32 v69, 1.0, v69
	v_cvt_pk_f16_f32 v78, v72, v73
	v_rcp_f32_e32 v69, v69
	v_cvt_f32_f16_e32 v72, v110
	v_cvt_f32_f16_sdwa v73, v110 dst_sel:DWORD dst_unused:UNUSED_PAD src0_sel:WORD_1
	v_add_f32_e32 v64, v64, v56
	v_add_f32_e32 v65, v65, v57
	v_mul_f32_e32 v64, 0xbfb8aa3b, v64
	v_pk_mul_f32 v[68:69], v[68:69], v[72:73]
	v_cvt_f32_f16_e32 v72, v109
	v_cvt_pk_f16_f32 v79, v68, v69
	v_add_f32_e32 v69, v70, v34
	v_mul_f32_e32 v69, 0xbfb8aa3b, v69
	v_exp_f32_e32 v69, v69
	v_add_f32_e32 v68, v74, v42
	v_mul_f32_e32 v68, 0xbfb8aa3b, v68
	v_exp_f32_e32 v68, v68
	v_add_f32_e32 v69, 1.0, v69
	v_rcp_f32_e32 v70, v69
	v_add_f32_e32 v69, v75, v43
	v_mul_f32_e32 v69, 0xbfb8aa3b, v69
	v_exp_f32_e32 v69, v69
	v_add_f32_e32 v68, 1.0, v68
	v_rcp_f32_e32 v68, v68
	v_cvt_f32_f16_sdwa v73, v109 dst_sel:DWORD dst_unused:UNUSED_PAD src0_sel:WORD_1
	v_add_f32_e32 v69, 1.0, v69
	v_rcp_f32_e32 v69, v69
	v_mul_f32_e32 v65, 0xbfb8aa3b, v65
	v_exp_f32_e32 v64, v64
	v_exp_f32_e32 v65, v65
	v_pk_mul_f32 v[68:69], v[68:69], v[72:73]
	v_add_f32_e32 v60, v60, v48
	v_cvt_pk_f16_f32 v72, v68, v69
	v_add_f32_e32 v68, v71, v35
	v_mul_f32_e32 v68, 0xbfb8aa3b, v68
	v_exp_f32_e32 v68, v68
	v_cvt_f32_f16_sdwa v69, v111 dst_sel:DWORD dst_unused:UNUSED_PAD src0_sel:WORD_1
	v_add_f32_e32 v61, v61, v49
	v_add_f32_e32 v64, 1.0, v64
	v_add_f32_e32 v68, 1.0, v68
	v_rcp_f32_e32 v71, v68
	v_cvt_f32_f16_e32 v68, v111
	v_mul_f32_e32 v60, 0xbfb8aa3b, v60
	v_add_f32_e32 v65, 1.0, v65
	v_mul_f32_e32 v61, 0xbfb8aa3b, v61
	v_pk_mul_f32 v[68:69], v[70:71], v[68:69]
	v_lshrrev_b32_e32 v70, 4, v79
	v_cvt_pk_f16_f32 v71, v68, v69
	v_lshrrev_b32_e32 v69, 4, v72
	v_and_b32_e32 v69, 0x10001, v69
	v_lshrrev_b32_e32 v68, 4, v78
	v_add3_u32 v69, v72, v69, s21
	v_lshrrev_b32_e32 v72, 4, v71
	v_and_b32_e32 v68, 0x10001, v68
	v_and_b32_e32 v70, 0x10001, v70
	v_and_b32_e32 v72, 0x10001, v72
	v_add3_u32 v68, v78, v68, s21
	v_add3_u32 v70, v79, v70, s21
	v_add3_u32 v71, v71, v72, s21
	v_and_b32_e32 v68, 0xfff0fff0, v68
	v_and_b32_e32 v69, 0xfff0fff0, v69
	v_and_b32_e32 v70, 0xfff0fff0, v70
	v_and_b32_e32 v71, 0xfff0fff0, v71
	global_store_dwordx4 v[76:77], v[68:71], off offset:256
	v_rcp_f32_e32 v64, v64
	v_exp_f32_e32 v60, v60
	v_rcp_f32_e32 v65, v65
	v_cvt_f32_f16_e32 v70, v104
	v_cvt_f32_f16_sdwa v71, v104 dst_sel:DWORD dst_unused:UNUSED_PAD src0_sel:WORD_1
	v_exp_f32_e32 v61, v61
	v_add_f32_e32 v60, 1.0, v60
	v_rcp_f32_e32 v60, v60
	v_pk_mul_f32 v[64:65], v[64:65], v[70:71]
	v_add_f32_e32 v61, 1.0, v61
	v_cvt_pk_f16_f32 v70, v64, v65
	v_rcp_f32_e32 v61, v61
	v_cvt_f32_f16_e32 v64, v106
	v_cvt_f32_f16_sdwa v65, v106 dst_sel:DWORD dst_unused:UNUSED_PAD src0_sel:WORD_1
	v_add_f32_e32 v52, v52, v40
	v_add_f32_e32 v53, v53, v41
	v_mul_f32_e32 v52, 0xbfb8aa3b, v52
	v_pk_mul_f32 v[60:61], v[60:61], v[64:65]
	v_cvt_f32_f16_e32 v64, v105
	v_cvt_pk_f16_f32 v71, v60, v61
	v_add_f32_e32 v61, v62, v50
	v_mul_f32_e32 v61, 0xbfb8aa3b, v61
	v_exp_f32_e32 v61, v61
	v_add_f32_e32 v60, v66, v58
	v_mul_f32_e32 v60, 0xbfb8aa3b, v60
	v_exp_f32_e32 v60, v60
	v_add_f32_e32 v61, 1.0, v61
	v_rcp_f32_e32 v62, v61
	v_add_f32_e32 v61, v67, v59
	v_mul_f32_e32 v61, 0xbfb8aa3b, v61
	v_exp_f32_e32 v61, v61
	v_add_f32_e32 v60, 1.0, v60
	v_rcp_f32_e32 v60, v60
	v_cvt_f32_f16_sdwa v65, v105 dst_sel:DWORD dst_unused:UNUSED_PAD src0_sel:WORD_1
	v_add_f32_e32 v61, 1.0, v61
	v_rcp_f32_e32 v61, v61
	v_mul_f32_e32 v53, 0xbfb8aa3b, v53
	v_exp_f32_e32 v52, v52
	v_exp_f32_e32 v53, v53
	v_pk_mul_f32 v[60:61], v[60:61], v[64:65]
	v_lshlrev_b64 v[68:69], 12, v[116:117]
	v_cvt_pk_f16_f32 v64, v60, v61
	v_add_f32_e32 v60, v63, v51
	v_mul_f32_e32 v60, 0xbfb8aa3b, v60
	v_exp_f32_e32 v60, v60
	v_cvt_f32_f16_sdwa v61, v107 dst_sel:DWORD dst_unused:UNUSED_PAD src0_sel:WORD_1
	v_add_f32_e32 v44, v44, v32
	v_add_f32_e32 v45, v45, v33
	v_add_f32_e32 v60, 1.0, v60
	v_rcp_f32_e32 v63, v60
	v_cvt_f32_f16_e32 v60, v107
	v_add_f32_e32 v52, 1.0, v52
	v_mul_f32_e32 v44, 0xbfb8aa3b, v44
	v_add_f32_e32 v53, 1.0, v53
	v_pk_mul_f32 v[60:61], v[62:63], v[60:61]
	v_mul_f32_e32 v45, 0xbfb8aa3b, v45
	v_cvt_pk_f16_f32 v60, v60, v61
	v_lshrrev_b32_e32 v61, 4, v70
	v_and_b32_e32 v61, 0x10001, v61
	v_add3_u32 v61, v70, v61, s21
	v_and_b32_e32 v62, 0xfff0fff0, v61
	v_lshrrev_b32_e32 v61, 4, v64
	v_and_b32_e32 v61, 0x10001, v61
	v_add3_u32 v61, v64, v61, s21
	v_and_b32_e32 v63, 0xfff0fff0, v61
	v_lshrrev_b32_e32 v61, 4, v71
	v_and_b32_e32 v61, 0x10001, v61
	v_add3_u32 v61, v71, v61, s21
	v_and_b32_e32 v64, 0xfff0fff0, v61
	v_lshrrev_b32_e32 v61, 4, v60
	v_and_b32_e32 v61, 0x10001, v61
	v_add3_u32 v60, v60, v61, s21
	v_and_b32_e32 v65, 0xfff0fff0, v60
	v_lshl_add_u64 v[60:61], s[10:11], 0, v[68:69]
	v_lshl_add_u64 v[60:61], v[60:61], 0, v[190:191]
	global_store_dwordx4 v[60:61], v[62:65], off
	v_rcp_f32_e32 v52, v52
	v_exp_f32_e32 v44, v44
	v_rcp_f32_e32 v53, v53
	v_cvt_f32_f16_e32 v62, v100
	v_cvt_f32_f16_sdwa v63, v100 dst_sel:DWORD dst_unused:UNUSED_PAD src0_sel:WORD_1
	v_exp_f32_e32 v45, v45
	v_add_f32_e32 v44, 1.0, v44
	v_rcp_f32_e32 v44, v44
	v_pk_mul_f32 v[52:53], v[52:53], v[62:63]
	v_add_f32_e32 v45, 1.0, v45
	v_cvt_pk_f16_f32 v62, v52, v53
	v_rcp_f32_e32 v45, v45
	v_cvt_f32_f16_e32 v52, v102
	v_cvt_f32_f16_sdwa v53, v102 dst_sel:DWORD dst_unused:UNUSED_PAD src0_sel:WORD_1
	v_add_f32_e32 v36, v36, v56
	v_add_f32_e32 v37, v37, v57
	v_mul_f32_e32 v36, 0xbfb8aa3b, v36
	v_pk_mul_f32 v[44:45], v[44:45], v[52:53]
	v_cvt_f32_f16_e32 v52, v101
	v_cvt_pk_f16_f32 v63, v44, v45
	v_add_f32_e32 v45, v46, v34
	v_mul_f32_e32 v45, 0xbfb8aa3b, v45
	v_exp_f32_e32 v45, v45
	v_add_f32_e32 v44, v54, v42
	v_mul_f32_e32 v44, 0xbfb8aa3b, v44
	v_exp_f32_e32 v44, v44
	v_add_f32_e32 v45, 1.0, v45
	v_rcp_f32_e32 v46, v45
	v_add_f32_e32 v45, v55, v43
	v_mul_f32_e32 v45, 0xbfb8aa3b, v45
	v_exp_f32_e32 v45, v45
	v_add_f32_e32 v44, 1.0, v44
	v_rcp_f32_e32 v44, v44
	v_cvt_f32_f16_sdwa v53, v101 dst_sel:DWORD dst_unused:UNUSED_PAD src0_sel:WORD_1
	v_add_f32_e32 v45, 1.0, v45
	v_rcp_f32_e32 v45, v45
	v_mul_f32_e32 v37, 0xbfb8aa3b, v37
	v_exp_f32_e32 v36, v36
	v_exp_f32_e32 v37, v37
	v_pk_mul_f32 v[44:45], v[44:45], v[52:53]
	v_add_f32_e32 v28, v28, v48
	v_cvt_pk_f16_f32 v52, v44, v45
	v_add_f32_e32 v44, v47, v35
	v_mul_f32_e32 v44, 0xbfb8aa3b, v44
	v_exp_f32_e32 v44, v44
	v_cvt_f32_f16_sdwa v45, v103 dst_sel:DWORD dst_unused:UNUSED_PAD src0_sel:WORD_1
	v_add_f32_e32 v29, v29, v49
	v_add_f32_e32 v36, 1.0, v36
	v_add_f32_e32 v44, 1.0, v44
	v_rcp_f32_e32 v47, v44
	v_cvt_f32_f16_e32 v44, v103
	v_mul_f32_e32 v28, 0xbfb8aa3b, v28
	v_add_f32_e32 v37, 1.0, v37
	v_mul_f32_e32 v29, 0xbfb8aa3b, v29
	v_pk_mul_f32 v[44:45], v[46:47], v[44:45]
	v_lshrrev_b32_e32 v46, 4, v63
	v_cvt_pk_f16_f32 v47, v44, v45
	v_lshrrev_b32_e32 v45, 4, v52
	v_and_b32_e32 v45, 0x10001, v45
	v_lshrrev_b32_e32 v44, 4, v62
	v_add3_u32 v45, v52, v45, s21
	v_lshrrev_b32_e32 v52, 4, v47
	v_and_b32_e32 v44, 0x10001, v44
	v_and_b32_e32 v46, 0x10001, v46
	v_and_b32_e32 v52, 0x10001, v52
	v_add3_u32 v44, v62, v44, s21
	v_add3_u32 v46, v63, v46, s21
	v_add3_u32 v47, v47, v52, s21
	v_and_b32_e32 v44, 0xfff0fff0, v44
	v_and_b32_e32 v45, 0xfff0fff0, v45
	v_and_b32_e32 v46, 0xfff0fff0, v46
	v_and_b32_e32 v47, 0xfff0fff0, v47
	global_store_dwordx4 v[60:61], v[44:47], off offset:256
	v_rcp_f32_e32 v36, v36
	v_exp_f32_e32 v28, v28
	v_rcp_f32_e32 v37, v37
	v_cvt_f32_f16_e32 v46, v96
	v_cvt_f32_f16_sdwa v47, v96 dst_sel:DWORD dst_unused:UNUSED_PAD src0_sel:WORD_1
	v_exp_f32_e32 v29, v29
	v_add_f32_e32 v28, 1.0, v28
	v_rcp_f32_e32 v28, v28
	v_pk_mul_f32 v[36:37], v[36:37], v[46:47]
	v_add_f32_e32 v29, 1.0, v29
	v_cvt_pk_f16_f32 v46, v36, v37
	v_rcp_f32_e32 v29, v29
	v_cvt_f32_f16_e32 v36, v98
	v_cvt_f32_f16_sdwa v37, v98 dst_sel:DWORD dst_unused:UNUSED_PAD src0_sel:WORD_1
	v_add_f32_e32 v24, v24, v40
	v_add_f32_e32 v25, v25, v41
	v_mul_f32_e32 v24, 0xbfb8aa3b, v24
	v_pk_mul_f32 v[28:29], v[28:29], v[36:37]
	v_cvt_f32_f16_e32 v36, v97
	v_cvt_pk_f16_f32 v47, v28, v29
	v_add_f32_e32 v29, v30, v50
	v_mul_f32_e32 v29, 0xbfb8aa3b, v29
	v_exp_f32_e32 v29, v29
	v_add_f32_e32 v28, v38, v58
	v_mul_f32_e32 v28, 0xbfb8aa3b, v28
	v_exp_f32_e32 v28, v28
	v_add_f32_e32 v29, 1.0, v29
	v_rcp_f32_e32 v30, v29
	v_add_f32_e32 v29, v39, v59
	v_mul_f32_e32 v29, 0xbfb8aa3b, v29
	v_exp_f32_e32 v29, v29
	v_add_f32_e32 v28, 1.0, v28
	v_rcp_f32_e32 v28, v28
	v_cvt_f32_f16_sdwa v37, v97 dst_sel:DWORD dst_unused:UNUSED_PAD src0_sel:WORD_1
	v_add_f32_e32 v29, 1.0, v29
	v_rcp_f32_e32 v29, v29
	v_mul_f32_e32 v25, 0xbfb8aa3b, v25
	v_exp_f32_e32 v24, v24
	v_exp_f32_e32 v25, v25
	v_pk_mul_f32 v[28:29], v[28:29], v[36:37]
	v_add_f32_e32 v20, v20, v32
	v_cvt_pk_f16_f32 v37, v28, v29
	v_add_f32_e32 v28, v31, v51
	v_mul_f32_e32 v28, 0xbfb8aa3b, v28
	v_exp_f32_e32 v28, v28
	v_cvt_f32_f16_sdwa v29, v99 dst_sel:DWORD dst_unused:UNUSED_PAD src0_sel:WORD_1
	v_add_f32_e32 v21, v21, v33
	v_add_f32_e32 v24, 1.0, v24
	v_add_f32_e32 v28, 1.0, v28
	v_rcp_f32_e32 v31, v28
	v_cvt_f32_f16_e32 v28, v99
	v_mul_f32_e32 v20, 0xbfb8aa3b, v20
	v_add_f32_e32 v25, 1.0, v25
	v_mul_f32_e32 v21, 0xbfb8aa3b, v21
	v_pk_mul_f32 v[28:29], v[30:31], v[28:29]
	v_rcp_f32_e32 v24, v24
	v_exp_f32_e32 v20, v20
	v_rcp_f32_e32 v25, v25
	v_cvt_f32_f16_e32 v30, v92
	v_cvt_f32_f16_sdwa v31, v92 dst_sel:DWORD dst_unused:UNUSED_PAD src0_sel:WORD_1
	v_exp_f32_e32 v21, v21
	v_add_f32_e32 v20, 1.0, v20
	v_rcp_f32_e32 v20, v20
	v_pk_mul_f32 v[24:25], v[24:25], v[30:31]
	v_add_f32_e32 v21, 1.0, v21
	v_cvt_pk_f16_f32 v30, v24, v25
	v_rcp_f32_e32 v21, v21
	v_cvt_f32_f16_e32 v24, v94
	v_cvt_f32_f16_sdwa v25, v94 dst_sel:DWORD dst_unused:UNUSED_PAD src0_sel:WORD_1
	v_cvt_pk_f16_f32 v28, v28, v29
	v_lshrrev_b32_e32 v29, 4, v46
	v_and_b32_e32 v29, 0x10001, v29
	v_pk_mul_f32 v[20:21], v[20:21], v[24:25]
	v_cvt_f32_f16_e32 v24, v93
	v_cvt_pk_f16_f32 v31, v20, v21
	v_add_f32_e32 v21, v22, v34
	v_mul_f32_e32 v21, 0xbfb8aa3b, v21
	v_exp_f32_e32 v21, v21
	v_add_f32_e32 v20, v26, v42
	v_mul_f32_e32 v20, 0xbfb8aa3b, v20
	v_exp_f32_e32 v20, v20
	v_add_f32_e32 v21, 1.0, v21
	v_rcp_f32_e32 v22, v21
	v_add_f32_e32 v21, v27, v43
	v_mul_f32_e32 v21, 0xbfb8aa3b, v21
	v_exp_f32_e32 v21, v21
	v_add_f32_e32 v20, 1.0, v20
	v_rcp_f32_e32 v20, v20
	v_cvt_f32_f16_sdwa v25, v93 dst_sel:DWORD dst_unused:UNUSED_PAD src0_sel:WORD_1
	v_add_f32_e32 v21, 1.0, v21
	v_rcp_f32_e32 v21, v21
	v_add3_u32 v29, v46, v29, s21
	v_and_b32_e32 v36, 0xfff0fff0, v29
	v_lshrrev_b32_e32 v29, 4, v37
	v_pk_mul_f32 v[20:21], v[20:21], v[24:25]
	v_and_b32_e32 v29, 0x10001, v29
	v_cvt_pk_f16_f32 v24, v20, v21
	v_add_f32_e32 v20, v23, v35
	v_mul_f32_e32 v20, 0xbfb8aa3b, v20
	v_exp_f32_e32 v20, v20
	v_cvt_f32_f16_sdwa v21, v95 dst_sel:DWORD dst_unused:UNUSED_PAD src0_sel:WORD_1
	v_add3_u32 v29, v37, v29, s21
	v_and_b32_e32 v37, 0xfff0fff0, v29
	v_add_f32_e32 v20, 1.0, v20
	v_rcp_f32_e32 v23, v20
	v_cvt_f32_f16_e32 v20, v95
	v_lshrrev_b32_e32 v29, 4, v47
	v_and_b32_e32 v29, 0x10001, v29
	v_add_f32_e32 v16, v16, v56
	v_pk_mul_f32 v[20:21], v[22:23], v[20:21]
	v_add_f32_e32 v17, v17, v57
	v_add3_u32 v29, v47, v29, s21
	v_cvt_pk_f16_f32 v23, v20, v21
	v_lshrrev_b32_e32 v21, 4, v24
	v_mul_f32_e32 v16, 0xbfb8aa3b, v16
	v_mul_f32_e32 v17, 0xbfb8aa3b, v17
	v_and_b32_e32 v38, 0xfff0fff0, v29
	v_lshrrev_b32_e32 v29, 4, v28
	v_and_b32_e32 v21, 0x10001, v21
	v_exp_f32_e32 v16, v16
	v_exp_f32_e32 v17, v17
	v_and_b32_e32 v29, 0x10001, v29
	v_lshrrev_b32_e32 v20, 4, v30
	v_add3_u32 v21, v24, v21, s21
	v_lshrrev_b32_e32 v22, 4, v31
	v_lshrrev_b32_e32 v24, 4, v23
	v_lshlrev_b64 v[44:45], 12, v[114:115]
	v_add3_u32 v28, v28, v29, s21
	v_and_b32_e32 v20, 0x10001, v20
	v_and_b32_e32 v22, 0x10001, v22
	v_and_b32_e32 v24, 0x10001, v24
	v_and_b32_e32 v39, 0xfff0fff0, v28
	v_lshl_add_u64 v[28:29], s[10:11], 0, v[44:45]
	v_add3_u32 v20, v30, v20, s21
	v_add3_u32 v22, v31, v22, s21
	v_add3_u32 v23, v23, v24, s21
	v_add_f32_e32 v12, v12, v48
	v_add_f32_e32 v13, v13, v49
	v_lshl_add_u64 v[28:29], v[28:29], 0, v[190:191]
	v_and_b32_e32 v20, 0xfff0fff0, v20
	v_and_b32_e32 v21, 0xfff0fff0, v21
	v_and_b32_e32 v22, 0xfff0fff0, v22
	v_and_b32_e32 v23, 0xfff0fff0, v23
	v_add_f32_e32 v16, 1.0, v16
	v_mul_f32_e32 v12, 0xbfb8aa3b, v12
	v_add_f32_e32 v17, 1.0, v17
	v_mul_f32_e32 v13, 0xbfb8aa3b, v13
	global_store_dwordx4 v[28:29], v[20:23], off offset:256
	v_rcp_f32_e32 v16, v16
	v_exp_f32_e32 v12, v12
	v_rcp_f32_e32 v17, v17
	v_cvt_f32_f16_e32 v22, v88
	v_cvt_f32_f16_sdwa v23, v88 dst_sel:DWORD dst_unused:UNUSED_PAD src0_sel:WORD_1
	v_exp_f32_e32 v13, v13
	v_add_f32_e32 v12, 1.0, v12
	v_rcp_f32_e32 v12, v12
	v_pk_mul_f32 v[16:17], v[16:17], v[22:23]
	v_add_f32_e32 v13, 1.0, v13
	v_cvt_pk_f16_f32 v22, v16, v17
	v_rcp_f32_e32 v13, v13
	v_cvt_f32_f16_e32 v16, v90
	v_cvt_f32_f16_sdwa v17, v90 dst_sel:DWORD dst_unused:UNUSED_PAD src0_sel:WORD_1
	v_add_f32_e32 v8, v8, v40
	v_add_f32_e32 v9, v9, v41
	v_mul_f32_e32 v8, 0xbfb8aa3b, v8
	v_pk_mul_f32 v[12:13], v[12:13], v[16:17]
	v_cvt_f32_f16_e32 v16, v89
	v_cvt_pk_f16_f32 v23, v12, v13
	v_add_f32_e32 v13, v14, v50
	v_mul_f32_e32 v13, 0xbfb8aa3b, v13
	v_exp_f32_e32 v13, v13
	v_add_f32_e32 v12, v18, v58
	v_mul_f32_e32 v12, 0xbfb8aa3b, v12
	v_exp_f32_e32 v12, v12
	v_add_f32_e32 v13, 1.0, v13
	v_rcp_f32_e32 v14, v13
	v_add_f32_e32 v13, v19, v59
	v_mul_f32_e32 v13, 0xbfb8aa3b, v13
	v_exp_f32_e32 v13, v13
	v_add_f32_e32 v12, 1.0, v12
	v_rcp_f32_e32 v12, v12
	v_cvt_f32_f16_sdwa v17, v89 dst_sel:DWORD dst_unused:UNUSED_PAD src0_sel:WORD_1
	v_add_f32_e32 v13, 1.0, v13
	v_rcp_f32_e32 v13, v13
	v_mul_f32_e32 v9, 0xbfb8aa3b, v9
	v_exp_f32_e32 v8, v8
	v_exp_f32_e32 v9, v9
	v_pk_mul_f32 v[12:13], v[12:13], v[16:17]
	v_lshlrev_b64 v[20:21], 12, v[112:113]
	v_cvt_pk_f16_f32 v16, v12, v13
	v_add_f32_e32 v12, v15, v51
	v_mul_f32_e32 v12, 0xbfb8aa3b, v12
	v_exp_f32_e32 v12, v12
	v_cvt_f32_f16_sdwa v13, v91 dst_sel:DWORD dst_unused:UNUSED_PAD src0_sel:WORD_1
	v_add_f32_e32 v4, v4, v32
	v_add_f32_e32 v5, v5, v33
	v_add_f32_e32 v12, 1.0, v12
	v_rcp_f32_e32 v15, v12
	v_cvt_f32_f16_e32 v12, v91
	v_add_f32_e32 v8, 1.0, v8
	v_mul_f32_e32 v4, 0xbfb8aa3b, v4
	v_add_f32_e32 v9, 1.0, v9
	v_pk_mul_f32 v[12:13], v[14:15], v[12:13]
	v_mul_f32_e32 v5, 0xbfb8aa3b, v5
	v_cvt_pk_f16_f32 v12, v12, v13
	v_lshrrev_b32_e32 v13, 4, v22
	v_and_b32_e32 v13, 0x10001, v13
	v_add3_u32 v13, v22, v13, s21
	v_and_b32_e32 v14, 0xfff0fff0, v13
	v_lshrrev_b32_e32 v13, 4, v16
	v_and_b32_e32 v13, 0x10001, v13
	v_add3_u32 v13, v16, v13, s21
	v_and_b32_e32 v15, 0xfff0fff0, v13
	v_lshrrev_b32_e32 v13, 4, v23
	v_and_b32_e32 v13, 0x10001, v13
	v_add3_u32 v13, v23, v13, s21
	v_and_b32_e32 v16, 0xfff0fff0, v13
	v_lshrrev_b32_e32 v13, 4, v12
	v_and_b32_e32 v13, 0x10001, v13
	v_add3_u32 v12, v12, v13, s21
	v_and_b32_e32 v17, 0xfff0fff0, v12
	v_lshl_add_u64 v[12:13], s[10:11], 0, v[20:21]
	v_lshl_add_u64 v[12:13], v[12:13], 0, v[190:191]
	global_store_dwordx4 v[12:13], v[14:17], off
	v_rcp_f32_e32 v8, v8
	v_exp_f32_e32 v4, v4
	v_rcp_f32_e32 v9, v9
	v_cvt_f32_f16_e32 v14, v84
	v_cvt_f32_f16_sdwa v15, v84 dst_sel:DWORD dst_unused:UNUSED_PAD src0_sel:WORD_1
	v_exp_f32_e32 v5, v5
	v_add_f32_e32 v4, 1.0, v4
	v_rcp_f32_e32 v4, v4
	v_pk_mul_f32 v[8:9], v[8:9], v[14:15]
	v_add_f32_e32 v5, 1.0, v5
	v_cvt_pk_f16_f32 v14, v8, v9
	v_rcp_f32_e32 v5, v5
	v_cvt_f32_f16_e32 v8, v86
	v_cvt_f32_f16_sdwa v9, v86 dst_sel:DWORD dst_unused:UNUSED_PAD src0_sel:WORD_1
	global_store_dwordx4 v[28:29], v[36:39], off
	v_pk_mul_f32 v[4:5], v[4:5], v[8:9]
	s_nop 0
	v_cvt_pk_f16_f32 v15, v4, v5
	v_add_f32_e32 v5, v6, v34
	v_mul_f32_e32 v5, 0xbfb8aa3b, v5
	v_exp_f32_e32 v5, v5
	v_add_f32_e32 v4, v10, v42
	v_mul_f32_e32 v4, 0xbfb8aa3b, v4
	v_exp_f32_e32 v4, v4
	v_add_f32_e32 v5, 1.0, v5
	v_rcp_f32_e32 v6, v5
	v_add_f32_e32 v5, v11, v43
	v_mul_f32_e32 v5, 0xbfb8aa3b, v5
	v_exp_f32_e32 v5, v5
	v_add_f32_e32 v4, 1.0, v4
	v_rcp_f32_e32 v4, v4
	v_cvt_f32_f16_e32 v8, v85
	v_add_f32_e32 v5, 1.0, v5
	v_rcp_f32_e32 v5, v5
	v_cvt_f32_f16_sdwa v9, v85 dst_sel:DWORD dst_unused:UNUSED_PAD src0_sel:WORD_1
	v_pk_mul_f32 v[4:5], v[4:5], v[8:9]
	s_nop 0
	v_cvt_pk_f16_f32 v8, v4, v5
	v_add_f32_e32 v4, v7, v35
	v_mul_f32_e32 v4, 0xbfb8aa3b, v4
	v_exp_f32_e32 v4, v4
	v_cvt_f32_f16_sdwa v5, v87 dst_sel:DWORD dst_unused:UNUSED_PAD src0_sel:WORD_1
	v_add_f32_e32 v4, 1.0, v4
	v_rcp_f32_e32 v7, v4
	v_cvt_f32_f16_e32 v4, v87
	v_pk_mul_f32 v[4:5], v[6:7], v[4:5]
	s_nop 0
	v_cvt_pk_f16_f32 v7, v4, v5
	v_lshrrev_b32_e32 v5, 4, v8
	v_and_b32_e32 v5, 0x10001, v5
	v_lshrrev_b32_e32 v4, 4, v14
	v_add3_u32 v5, v8, v5, s21
	v_lshrrev_b32_e32 v6, 4, v15
	v_lshrrev_b32_e32 v8, 4, v7
	v_and_b32_e32 v4, 0x10001, v4
	v_and_b32_e32 v6, 0x10001, v6
	v_and_b32_e32 v8, 0x10001, v8
	v_add3_u32 v4, v14, v4, s21
	v_add3_u32 v6, v15, v6, s21
	v_add3_u32 v7, v7, v8, s21
	v_and_b32_e32 v4, 0xfff0fff0, v4
	v_and_b32_e32 v5, 0xfff0fff0, v5
	v_and_b32_e32 v6, 0xfff0fff0, v6
	v_and_b32_e32 v7, 0xfff0fff0, v7
	global_store_dwordx4 v[12:13], v[4:7], off offset:256
	s_cbranch_vccz .LBB0_1657
	s_waitcnt vmcnt(0)
	s_cmpk_gt_u32 s4, 0xff
	s_cbranch_scc1 .LBB0_1668
	s_barrier

.LBB0_1742:
	s_add_i32 s19, 0, 0x10000
	v_add_u32_e32 v237, s19, v235
	ds_read_b128 v[134:137], v237
	ds_read_b128 v[138:141], v237 offset:1024
	ds_read_b128 v[142:145], v237 offset:2048
	ds_read_b128 v[146:149], v237 offset:3072
	v_lshl_add_u64 v[198:199], v[132:133], 0, s[16:17]
	s_add_i32 s14, s7, 0xc000
	v_lshl_add_u64 v[182:183], v[198:199], 0, s[26:27]
	s_mov_b32 m0, s14
	v_lshl_add_u64 v[242:243], v[200:201], 0, s[16:17]
	s_add_i32 s15, s7, 0xe000
	ds_read_b128 v[150:153], v236
	ds_read_b128 v[154:157], v236 offset:1024
	ds_read_b128 v[158:161], v236 offset:2048
	ds_read_b128 v[162:165], v236 offset:3072
	ds_read_b128 v[166:169], v236 offset:4096
	ds_read_b128 v[170:173], v236 offset:5120
	ds_read_b128 v[174:177], v236 offset:6144
	ds_read_b128 v[178:181], v236 offset:7168
	global_load_lds_dwordx4 v[182:183], off
	v_lshl_add_u64 v[182:183], v[242:243], 0, s[26:27]
	s_mov_b32 m0, s15
	s_nop 0
	global_load_lds_dwordx4 v[182:183], off
	s_barrier
	s_waitcnt lgkmcnt(0)
	v_mfma_f32_16x16x32_f16 v[80:83], v[134:137], v[150:153], v[80:83]
	v_mfma_f32_16x16x32_f16 v[72:75], v[142:145], v[150:153], v[72:75]
	v_mfma_f32_16x16x32_f16 v[56:59], v[134:137], v[158:161], v[56:59]
	v_mfma_f32_16x16x32_f16 v[68:71], v[142:145], v[158:161], v[68:71]
	v_mfma_f32_16x16x32_f16 v[128:131], v[134:137], v[166:169], v[128:131]
	v_mfma_f32_16x16x32_f16 v[124:127], v[142:145], v[166:169], v[124:127]
	v_mfma_f32_16x16x32_f16 v[116:119], v[134:137], v[174:177], v[116:119]
	v_mfma_f32_16x16x32_f16 v[108:111], v[142:145], v[174:177], v[108:111]
	v_mfma_f32_16x16x32_f16 v[80:83], v[138:141], v[154:157], v[80:83]
	v_mfma_f32_16x16x32_f16 v[72:75], v[146:149], v[154:157], v[72:75]
	v_mfma_f32_16x16x32_f16 v[56:59], v[138:141], v[162:165], v[56:59]
	v_mfma_f32_16x16x32_f16 v[68:71], v[146:149], v[162:165], v[68:71]
	v_mfma_f32_16x16x32_f16 v[128:131], v[138:141], v[170:173], v[128:131]
	v_mfma_f32_16x16x32_f16 v[124:127], v[146:149], v[170:173], v[124:127]
	v_mfma_f32_16x16x32_f16 v[116:119], v[138:141], v[178:181], v[116:119]
	v_mfma_f32_16x16x32_f16 v[108:111], v[146:149], v[178:181], v[108:111]
	s_barrier
	s_add_i32 s63, 0, 0x14000
	v_lshl_add_u64 v[244:245], v[202:203], 0, s[16:17]
	s_add_i32 s19, s19, s5
	v_add_u32_e32 v238, s63, v235
	v_lshl_add_u64 v[240:241], v[244:245], 0, s[30:31]
	s_mov_b32 m0, s19
	v_lshl_add_u64 v[246:247], v[220:221], 0, s[16:17]
	s_add_i32 s37, s19, 0x2000
	ds_read_b128 v[182:185], v238
	ds_read_b128 v[186:189], v238 offset:1024
	ds_read_b128 v[190:193], v238 offset:2048
	ds_read_b128 v[194:197], v238 offset:3072
	global_load_lds_dwordx4 v[240:241], off
	v_lshl_add_u64 v[240:241], v[246:247], 0, s[30:31]
	s_mov_b32 m0, s37
	s_nop 0
	global_load_lds_dwordx4 v[240:241], off
	s_waitcnt vmcnt(10)
	s_barrier
	s_waitcnt lgkmcnt(0)
	v_mfma_f32_16x16x32_f16 v[52:55], v[182:185], v[150:153], v[52:55]
	v_mfma_f32_16x16x32_f16 v[40:43], v[190:193], v[150:153], v[40:43]
	v_mfma_f32_16x16x32_f16 v[36:39], v[182:185], v[158:161], v[36:39]
	v_mfma_f32_16x16x32_f16 v[28:31], v[190:193], v[158:161], v[28:31]
	v_mfma_f32_16x16x32_f16 v[120:123], v[182:185], v[166:169], v[120:123]
	v_mfma_f32_16x16x32_f16 v[112:115], v[190:193], v[166:169], v[112:115]
	v_mfma_f32_16x16x32_f16 v[104:107], v[182:185], v[174:177], v[104:107]
	v_mfma_f32_16x16x32_f16 v[100:103], v[190:193], v[174:177], v[100:103]
	v_mfma_f32_16x16x32_f16 v[52:55], v[186:189], v[154:157], v[52:55]
	v_mfma_f32_16x16x32_f16 v[40:43], v[194:197], v[154:157], v[40:43]
	v_mfma_f32_16x16x32_f16 v[36:39], v[186:189], v[162:165], v[36:39]
	v_mfma_f32_16x16x32_f16 v[28:31], v[194:197], v[162:165], v[28:31]
	v_mfma_f32_16x16x32_f16 v[120:123], v[186:189], v[170:173], v[120:123]
	v_mfma_f32_16x16x32_f16 v[112:115], v[194:197], v[170:173], v[112:115]
	v_mfma_f32_16x16x32_f16 v[104:107], v[186:189], v[178:181], v[104:107]
	v_mfma_f32_16x16x32_f16 v[100:103], v[194:197], v[178:181], v[100:103]
	s_mov_b32 m0, s7
	v_lshl_add_u64 v[240:241], v[198:199], 0, s[30:31]
	s_barrier
	ds_read_b128 v[150:153], v236 offset:16384
	ds_read_b128 v[154:157], v236 offset:17408
	ds_read_b128 v[158:161], v236 offset:18432
	ds_read_b128 v[162:165], v236 offset:19456
	ds_read_b128 v[166:169], v236 offset:20480
	ds_read_b128 v[170:173], v236 offset:21504
	ds_read_b128 v[174:177], v236 offset:22528
	ds_read_b128 v[178:181], v236 offset:23552
	global_load_lds_dwordx4 v[240:241], off
	v_lshl_add_u64 v[240:241], v[242:243], 0, s[30:31]
	s_mov_b32 m0, s8
	s_nop 0
	global_load_lds_dwordx4 v[240:241], off
	s_barrier
	s_waitcnt lgkmcnt(0)
	v_mfma_f32_16x16x32_f16 v[96:99], v[134:137], v[150:153], v[96:99]
	v_mfma_f32_16x16x32_f16 v[92:95], v[142:145], v[150:153], v[92:95]
	v_mfma_f32_16x16x32_f16 v[76:79], v[134:137], v[158:161], v[76:79]
	v_mfma_f32_16x16x32_f16 v[64:67], v[142:145], v[158:161], v[64:67]
	v_mfma_f32_16x16x32_f16 v[44:47], v[134:137], v[166:169], v[44:47]
	v_mfma_f32_16x16x32_f16 v[32:35], v[142:145], v[166:169], v[32:35]
	v_mfma_f32_16x16x32_f16 v[16:19], v[134:137], v[174:177], v[16:19]
	v_mfma_f32_16x16x32_f16 v[12:15], v[142:145], v[174:177], v[12:15]
	v_mfma_f32_16x16x32_f16 v[96:99], v[138:141], v[154:157], v[96:99]
	v_mfma_f32_16x16x32_f16 v[92:95], v[146:149], v[154:157], v[92:95]
	v_mfma_f32_16x16x32_f16 v[76:79], v[138:141], v[162:165], v[76:79]
	v_mfma_f32_16x16x32_f16 v[64:67], v[146:149], v[162:165], v[64:67]
	v_mfma_f32_16x16x32_f16 v[44:47], v[138:141], v[170:173], v[44:47]
	v_mfma_f32_16x16x32_f16 v[32:35], v[146:149], v[170:173], v[32:35]
	v_mfma_f32_16x16x32_f16 v[16:19], v[138:141], v[178:181], v[16:19]
	v_mfma_f32_16x16x32_f16 v[12:15], v[146:149], v[178:181], v[12:15]
	s_barrier
	s_add_i32 s63, s63, s5
	v_lshl_add_u64 v[134:135], v[244:245], 0, s[84:85]
	s_mov_b32 m0, s63
	s_add_i32 s68, s63, 0x2000
	global_load_lds_dwordx4 v[134:135], off
	v_lshl_add_u64 v[134:135], v[246:247], 0, s[84:85]
	s_mov_b32 m0, s68
	s_nop 0
	global_load_lds_dwordx4 v[134:135], off
	s_waitcnt vmcnt(8)
	s_barrier
	v_mfma_f32_16x16x32_f16 v[88:91], v[182:185], v[150:153], v[88:91]
	v_mfma_f32_16x16x32_f16 v[84:87], v[190:193], v[150:153], v[84:87]
	v_mfma_f32_16x16x32_f16 v[60:63], v[182:185], v[158:161], v[60:63]
	v_mfma_f32_16x16x32_f16 v[48:51], v[190:193], v[158:161], v[48:51]
	v_mfma_f32_16x16x32_f16 v[24:27], v[182:185], v[166:169], v[24:27]
	v_mfma_f32_16x16x32_f16 v[20:23], v[190:193], v[166:169], v[20:23]
	v_mfma_f32_16x16x32_f16 v[8:11], v[182:185], v[174:177], v[8:11]
	v_mfma_f32_16x16x32_f16 v[4:7], v[190:193], v[174:177], v[4:7]
	v_mfma_f32_16x16x32_f16 v[88:91], v[186:189], v[154:157], v[88:91]
	v_mfma_f32_16x16x32_f16 v[84:87], v[194:197], v[154:157], v[84:87]
	v_mfma_f32_16x16x32_f16 v[60:63], v[186:189], v[162:165], v[60:63]
	v_mfma_f32_16x16x32_f16 v[48:51], v[194:197], v[162:165], v[48:51]
	v_mfma_f32_16x16x32_f16 v[24:27], v[186:189], v[170:173], v[24:27]
	v_mfma_f32_16x16x32_f16 v[20:23], v[194:197], v[170:173], v[20:23]
	v_mfma_f32_16x16x32_f16 v[8:11], v[186:189], v[178:181], v[8:11]
	v_mfma_f32_16x16x32_f16 v[4:7], v[194:197], v[178:181], v[4:7]
	s_add_i32 s69, 0, 0x18000
	v_add_u32_e32 v239, s69, v235
	s_barrier
	ds_read_b128 v[134:137], v239
	ds_read_b128 v[138:141], v239 offset:1024
	ds_read_b128 v[142:145], v239 offset:2048
	ds_read_b128 v[146:149], v239 offset:3072
	s_mov_b32 m0, s9
	v_lshl_add_u64 v[182:183], v[198:199], 0, s[84:85]
	ds_read_b128 v[150:153], v236 offset:32768
	ds_read_b128 v[154:157], v236 offset:33792
	ds_read_b128 v[158:161], v236 offset:34816
	ds_read_b128 v[162:165], v236 offset:35840
	ds_read_b128 v[166:169], v236 offset:36864
	ds_read_b128 v[170:173], v236 offset:37888
	ds_read_b128 v[174:177], v236 offset:38912
	ds_read_b128 v[178:181], v236 offset:39936
	global_load_lds_dwordx4 v[182:183], off
	v_lshl_add_u64 v[182:183], v[242:243], 0, s[84:85]
	s_mov_b32 m0, s12
	s_nop 0
	global_load_lds_dwordx4 v[182:183], off
	s_barrier
	s_waitcnt lgkmcnt(0)
	v_mfma_f32_16x16x32_f16 v[80:83], v[134:137], v[150:153], v[80:83]
	v_mfma_f32_16x16x32_f16 v[72:75], v[142:145], v[150:153], v[72:75]
	v_mfma_f32_16x16x32_f16 v[56:59], v[134:137], v[158:161], v[56:59]
	v_mfma_f32_16x16x32_f16 v[68:71], v[142:145], v[158:161], v[68:71]
	v_mfma_f32_16x16x32_f16 v[128:131], v[134:137], v[166:169], v[128:131]
	v_mfma_f32_16x16x32_f16 v[124:127], v[142:145], v[166:169], v[124:127]
	v_mfma_f32_16x16x32_f16 v[116:119], v[134:137], v[174:177], v[116:119]
	v_mfma_f32_16x16x32_f16 v[108:111], v[142:145], v[174:177], v[108:111]
	v_mfma_f32_16x16x32_f16 v[80:83], v[138:141], v[154:157], v[80:83]
	v_mfma_f32_16x16x32_f16 v[72:75], v[146:149], v[154:157], v[72:75]
	v_mfma_f32_16x16x32_f16 v[56:59], v[138:141], v[162:165], v[56:59]
	v_mfma_f32_16x16x32_f16 v[68:71], v[146:149], v[162:165], v[68:71]
	v_mfma_f32_16x16x32_f16 v[128:131], v[138:141], v[170:173], v[128:131]
	v_mfma_f32_16x16x32_f16 v[124:127], v[146:149], v[170:173], v[124:127]
	v_mfma_f32_16x16x32_f16 v[116:119], v[138:141], v[178:181], v[116:119]
	v_mfma_f32_16x16x32_f16 v[108:111], v[146:149], v[178:181], v[108:111]
	s_barrier
	s_add_i32 s71, 0, 0x1c000
	s_add_i32 s69, s69, s5
	v_add_u32_e32 v240, s71, v235
	v_lshl_add_u64 v[248:249], v[244:245], 0, s[78:79]
	s_mov_b32 m0, s69
	s_add_i32 s70, s69, 0x2000
	ds_read_b128 v[182:185], v240
	ds_read_b128 v[186:189], v240 offset:1024
	ds_read_b128 v[190:193], v240 offset:2048
	ds_read_b128 v[194:197], v240 offset:3072
	global_load_lds_dwordx4 v[248:249], off
	v_lshl_add_u64 v[248:249], v[246:247], 0, s[78:79]
	s_mov_b32 m0, s70
	s_nop 0
	global_load_lds_dwordx4 v[248:249], off
	s_waitcnt vmcnt(10)
	s_barrier
	s_waitcnt lgkmcnt(0)
	v_mfma_f32_16x16x32_f16 v[52:55], v[182:185], v[150:153], v[52:55]
	v_mfma_f32_16x16x32_f16 v[40:43], v[190:193], v[150:153], v[40:43]
	v_mfma_f32_16x16x32_f16 v[36:39], v[182:185], v[158:161], v[36:39]
	v_mfma_f32_16x16x32_f16 v[28:31], v[190:193], v[158:161], v[28:31]
	v_mfma_f32_16x16x32_f16 v[120:123], v[182:185], v[166:169], v[120:123]
	v_mfma_f32_16x16x32_f16 v[112:115], v[190:193], v[166:169], v[112:115]
	v_mfma_f32_16x16x32_f16 v[104:107], v[182:185], v[174:177], v[104:107]
	v_mfma_f32_16x16x32_f16 v[100:103], v[190:193], v[174:177], v[100:103]
	v_mfma_f32_16x16x32_f16 v[52:55], v[186:189], v[154:157], v[52:55]
	v_mfma_f32_16x16x32_f16 v[40:43], v[194:197], v[154:157], v[40:43]
	v_mfma_f32_16x16x32_f16 v[36:39], v[186:189], v[162:165], v[36:39]
	v_mfma_f32_16x16x32_f16 v[28:31], v[194:197], v[162:165], v[28:31]
	v_mfma_f32_16x16x32_f16 v[120:123], v[186:189], v[170:173], v[120:123]
	v_mfma_f32_16x16x32_f16 v[112:115], v[194:197], v[170:173], v[112:115]
	v_mfma_f32_16x16x32_f16 v[104:107], v[186:189], v[178:181], v[104:107]
	v_mfma_f32_16x16x32_f16 v[100:103], v[194:197], v[178:181], v[100:103]
	s_mov_b32 m0, s39
	v_lshl_add_u64 v[198:199], v[198:199], 0, s[78:79]
	s_barrier
	ds_read_b128 v[150:153], v236 offset:49152
	ds_read_b128 v[154:157], v236 offset:50176
	ds_read_b128 v[158:161], v236 offset:51200
	ds_read_b128 v[162:165], v236 offset:52224
	ds_read_b128 v[166:169], v236 offset:53248
	ds_read_b128 v[170:173], v236 offset:54272
	ds_read_b128 v[174:177], v236 offset:55296
	ds_read_b128 v[178:181], v236 offset:56320
	global_load_lds_dwordx4 v[198:199], off
	v_lshl_add_u64 v[198:199], v[242:243], 0, s[78:79]
	s_mov_b32 m0, s47
	s_nop 0
	global_load_lds_dwordx4 v[198:199], off
	s_barrier
	s_waitcnt lgkmcnt(0)
	v_mfma_f32_16x16x32_f16 v[96:99], v[134:137], v[150:153], v[96:99]
	v_mfma_f32_16x16x32_f16 v[92:95], v[142:145], v[150:153], v[92:95]
	v_mfma_f32_16x16x32_f16 v[76:79], v[134:137], v[158:161], v[76:79]
	v_mfma_f32_16x16x32_f16 v[64:67], v[142:145], v[158:161], v[64:67]
	v_mfma_f32_16x16x32_f16 v[44:47], v[134:137], v[166:169], v[44:47]
	v_mfma_f32_16x16x32_f16 v[32:35], v[142:145], v[166:169], v[32:35]
	v_mfma_f32_16x16x32_f16 v[16:19], v[134:137], v[174:177], v[16:19]
	v_mfma_f32_16x16x32_f16 v[12:15], v[142:145], v[174:177], v[12:15]
	v_mfma_f32_16x16x32_f16 v[96:99], v[138:141], v[154:157], v[96:99]
	v_mfma_f32_16x16x32_f16 v[92:95], v[146:149], v[154:157], v[92:95]
	v_mfma_f32_16x16x32_f16 v[76:79], v[138:141], v[162:165], v[76:79]
	v_mfma_f32_16x16x32_f16 v[64:67], v[146:149], v[162:165], v[64:67]
	v_mfma_f32_16x16x32_f16 v[44:47], v[138:141], v[170:173], v[44:47]
	v_mfma_f32_16x16x32_f16 v[32:35], v[146:149], v[170:173], v[32:35]
	v_mfma_f32_16x16x32_f16 v[16:19], v[138:141], v[178:181], v[16:19]
	v_mfma_f32_16x16x32_f16 v[12:15], v[146:149], v[178:181], v[12:15]
	s_barrier
	s_add_i32 s71, s71, s5
	v_lshl_add_u64 v[134:135], v[244:245], 0, vcc
	s_mov_b32 m0, s71
	s_add_i32 s76, s71, 0x2000
	global_load_lds_dwordx4 v[134:135], off
	v_lshl_add_u64 v[134:135], v[246:247], 0, vcc
	s_mov_b32 m0, s76
	s_nop 0
	global_load_lds_dwordx4 v[134:135], off
	s_waitcnt vmcnt(8)
	s_barrier
	v_mfma_f32_16x16x32_f16 v[88:91], v[182:185], v[150:153], v[88:91]
	v_mfma_f32_16x16x32_f16 v[84:87], v[190:193], v[150:153], v[84:87]
	v_mfma_f32_16x16x32_f16 v[60:63], v[182:185], v[158:161], v[60:63]
	v_mfma_f32_16x16x32_f16 v[48:51], v[190:193], v[158:161], v[48:51]
	v_mfma_f32_16x16x32_f16 v[24:27], v[182:185], v[166:169], v[24:27]
	v_mfma_f32_16x16x32_f16 v[20:23], v[190:193], v[166:169], v[20:23]
	v_mfma_f32_16x16x32_f16 v[8:11], v[182:185], v[174:177], v[8:11]
	v_mfma_f32_16x16x32_f16 v[4:7], v[190:193], v[174:177], v[4:7]
	v_mfma_f32_16x16x32_f16 v[88:91], v[186:189], v[154:157], v[88:91]
	v_mfma_f32_16x16x32_f16 v[84:87], v[194:197], v[154:157], v[84:87]
	v_mfma_f32_16x16x32_f16 v[60:63], v[186:189], v[162:165], v[60:63]
	v_mfma_f32_16x16x32_f16 v[48:51], v[194:197], v[162:165], v[48:51]
	v_mfma_f32_16x16x32_f16 v[24:27], v[186:189], v[170:173], v[24:27]
	v_mfma_f32_16x16x32_f16 v[20:23], v[194:197], v[170:173], v[20:23]
	v_mfma_f32_16x16x32_f16 v[8:11], v[186:189], v[178:181], v[8:11]
	v_mfma_f32_16x16x32_f16 v[4:7], v[194:197], v[178:181], v[4:7]
	s_add_i32 s10, s10, 2
	s_add_u32 s16, s16, 0x100
	s_addc_u32 s17, s17, 0
	s_cmp_lt_u32 s10, 6
	s_barrier
	s_cbranch_scc1 .LBB0_1742
	s_ashr_i32 s78, s48, 31
	s_mul_i32 s10, s46, 0x42
	s_mul_hi_i32 s11, s46, 0x42
	s_add_u32 s10, s10, s48
	v_mov_b32_e32 v132, v233
	v_mov_b32_e32 v133, v234
	s_addc_u32 s11, s11, s78
	s_lshl_b64 s[10:11], s[10:11], 17
	v_readlane_b32 s16, v252, 45
	v_lshlrev_b32_e32 v133, 3, v133
	s_add_u32 s16, s16, s10
	v_readlane_b32 s10, v252, 46
	v_lshlrev_b32_e32 v132, 8, v132
	s_addc_u32 s17, s10, s11
	v_add3_u32 v188, v132, s49, v133
	s_add_u32 s26, s16, 0x4200000
	v_ashrrev_i32_e32 v189, 31, v188
	s_addc_u32 s27, s17, 0
	v_lshlrev_b64 v[132:133], 1, v[188:189]
	v_lshl_add_u64 v[134:135], s[16:17], 0, v[132:133]
	v_lshl_add_u64 v[136:137], s[26:27], 0, v[132:133]
	v_add_u32_e32 v132, 0x1000, v188
	v_ashrrev_i32_e32 v133, 31, v132
	v_lshlrev_b64 v[132:133], 1, v[132:133]
	v_lshl_add_u64 v[138:139], s[16:17], 0, v[132:133]
	v_lshl_add_u64 v[176:177], s[26:27], 0, v[132:133]
	v_add_u32_e32 v132, 0x1080, v188
	v_ashrrev_i32_e32 v133, 31, v132
	v_lshlrev_b64 v[132:133], 1, v[132:133]
	v_lshl_add_u64 v[148:149], s[16:17], 0, v[132:133]
	v_lshl_add_u64 v[168:169], s[26:27], 0, v[132:133]
	v_add_u32_e32 v132, 0x2000, v188
	v_ashrrev_i32_e32 v133, 31, v132
	v_lshlrev_b64 v[132:133], 1, v[132:133]
	v_lshl_add_u64 v[144:145], s[16:17], 0, v[132:133]
	v_lshl_add_u64 v[156:157], s[26:27], 0, v[132:133]
	v_add_u32_e32 v132, 0x2080, v188
	v_ashrrev_i32_e32 v133, 31, v132
	v_lshlrev_b64 v[132:133], 1, v[132:133]
	v_lshl_add_u64 v[146:147], s[16:17], 0, v[132:133]
	v_lshl_add_u64 v[158:159], s[26:27], 0, v[132:133]
	v_add_u32_e32 v132, 0x3000, v188
	v_ashrrev_i32_e32 v133, 31, v132
	v_lshlrev_b64 v[132:133], 1, v[132:133]
	v_lshl_add_u64 v[140:141], s[16:17], 0, v[132:133]
	v_lshl_add_u64 v[150:151], s[26:27], 0, v[132:133]
	v_add_u32_e32 v132, 0x3080, v188
	v_ashrrev_i32_e32 v133, 31, v132
	v_lshlrev_b64 v[132:133], 1, v[132:133]
	v_lshl_add_u64 v[142:143], s[16:17], 0, v[132:133]
	v_lshl_add_u64 v[164:165], s[26:27], 0, v[132:133]
	global_load_dwordx4 v[180:183], v[134:135], off offset:256
	global_load_dwordx4 v[190:193], v[134:135], off
	s_nop 0
	global_load_dwordx4 v[132:135], v[142:143], off
	s_nop 0
	global_load_dwordx4 v[140:143], v[140:141], off
	s_nop 0
	global_load_dwordx4 v[152:155], v[146:147], off
	s_nop 0
	global_load_dwordx4 v[144:147], v[144:145], off
	s_nop 0
	global_load_dwordx4 v[160:163], v[148:149], off
	global_load_dwordx4 v[172:175], v[138:139], off
	global_load_dwordx4 v[184:187], v[136:137], off offset:256
	global_load_dwordx4 v[194:197], v[136:137], off
	s_nop 0
	global_load_dwordx4 v[136:139], v[164:165], off
	s_nop 0
	global_load_dwordx4 v[148:151], v[150:151], off
	s_nop 0
	global_load_dwordx4 v[164:167], v[158:159], off
	s_nop 0
	global_load_dwordx4 v[156:159], v[156:157], off
	s_nop 0
	global_load_dwordx4 v[168:171], v[168:169], off
	s_nop 0
	global_load_dwordx4 v[176:179], v[176:177], off
	s_mov_b32 s10, 6
	s_mov_b64 s[30:31], 0x500
	s_mov_b64 s[84:85], 0x80500
	s_mov_b64 vcc, 0x580
	s_mov_b64 s[52:53], 0x80580
	s_waitcnt vmcnt(0)
	s_nop 0
	v_cvt_f32_f16_e32 v189, v190
	v_rcp_f32_e32 v198, v189
	v_cvt_f32_f16_e32 v189, v192
	v_cvt_f32_f16_e32 v244, v194
	v_cvt_f32_f16_sdwa v245, v194 dst_sel:DWORD dst_unused:UNUSED_PAD src0_sel:WORD_1
	v_cvt_f32_f16_e32 v194, v195
	v_rcp_f32_e32 v242, v189
	v_cvt_f32_f16_sdwa v189, v190 dst_sel:DWORD dst_unused:UNUSED_PAD src0_sel:WORD_1
	v_cvt_f32_f16_sdwa v195, v195 dst_sel:DWORD dst_unused:UNUSED_PAD src0_sel:WORD_1
	v_cvt_f32_f16_e32 v246, v196
	v_cvt_f32_f16_sdwa v247, v196 dst_sel:DWORD dst_unused:UNUSED_PAD src0_sel:WORD_1
	v_rcp_f32_e32 v199, v189
	v_cvt_f32_f16_sdwa v189, v192 dst_sel:DWORD dst_unused:UNUSED_PAD src0_sel:WORD_1
	v_cvt_f32_f16_e32 v196, v186
	v_pk_mul_f32 v[198:199], v[198:199], v[244:245]
	v_rcp_f32_e32 v243, v189
	v_cvt_f32_f16_e32 v189, v191
	v_pk_mul_f32 v[80:81], v[80:81], v[198:199]
	v_rcp_f32_e32 v190, v189
	v_cvt_f32_f16_e32 v189, v193
	v_rcp_f32_e32 v192, v189
	v_cvt_f32_f16_sdwa v189, v191 dst_sel:DWORD dst_unused:UNUSED_PAD src0_sel:WORD_1
	v_rcp_f32_e32 v191, v189
	v_cvt_f32_f16_sdwa v189, v193 dst_sel:DWORD dst_unused:UNUSED_PAD src0_sel:WORD_1
	v_pk_mul_f32 v[190:191], v[190:191], v[194:195]
	s_nop 0
	v_pk_mul_f32 v[82:83], v[82:83], v[190:191]
	v_rcp_f32_e32 v193, v189
	v_cvt_f32_f16_e32 v190, v197
	v_cvt_f32_f16_sdwa v191, v197 dst_sel:DWORD dst_unused:UNUSED_PAD src0_sel:WORD_1
	v_cvt_f32_f16_e32 v189, v180
	v_cvt_f32_f16_sdwa v180, v180 dst_sel:DWORD dst_unused:UNUSED_PAD src0_sel:WORD_1
	v_pk_mul_f32 v[194:195], v[242:243], v[246:247]
	v_pk_mul_f32 v[190:191], v[192:193], v[190:191]
	v_pk_mul_f32 v[72:73], v[72:73], v[194:195]
	v_pk_mul_f32 v[74:75], v[74:75], v[190:191]
	v_rcp_f32_e32 v191, v180
	v_cvt_f32_f16_sdwa v180, v182 dst_sel:DWORD dst_unused:UNUSED_PAD src0_sel:WORD_1
	v_cvt_f32_f16_e32 v194, v184
	v_cvt_f32_f16_sdwa v195, v184 dst_sel:DWORD dst_unused:UNUSED_PAD src0_sel:WORD_1
	v_cvt_f32_f16_e32 v184, v185
	v_rcp_f32_e32 v193, v180
	v_cvt_f32_f16_e32 v180, v181
	v_cvt_f32_f16_sdwa v181, v181 dst_sel:DWORD dst_unused:UNUSED_PAD src0_sel:WORD_1
	v_cvt_f32_f16_sdwa v185, v185 dst_sel:DWORD dst_unused:UNUSED_PAD src0_sel:WORD_1
	v_rcp_f32_e32 v190, v189
	v_rcp_f32_e32 v180, v180
	v_rcp_f32_e32 v181, v181
	v_cvt_f32_f16_e32 v189, v182
	v_cvt_f32_f16_e32 v182, v183
	v_cvt_f32_f16_sdwa v197, v186 dst_sel:DWORD dst_unused:UNUSED_PAD src0_sel:WORD_1
	v_pk_mul_f32 v[180:181], v[180:181], v[184:185]
	v_rcp_f32_e32 v192, v189
	v_pk_mul_f32 v[54:55], v[54:55], v[180:181]
	v_cvt_f32_f16_sdwa v180, v183 dst_sel:DWORD dst_unused:UNUSED_PAD src0_sel:WORD_1
	v_rcp_f32_e32 v182, v182
	v_cvt_f32_f16_sdwa v181, v187 dst_sel:DWORD dst_unused:UNUSED_PAD src0_sel:WORD_1
	v_pk_mul_f32 v[184:185], v[192:193], v[196:197]
	v_rcp_f32_e32 v183, v180
	v_cvt_f32_f16_e32 v180, v187
	v_pk_mul_f32 v[40:41], v[40:41], v[184:185]
	v_cvt_f32_f16_e32 v184, v176
	v_cvt_f32_f16_sdwa v185, v176 dst_sel:DWORD dst_unused:UNUSED_PAD src0_sel:WORD_1
	v_pk_mul_f32 v[180:181], v[182:183], v[180:181]
	v_cvt_f32_f16_e32 v176, v177
	v_pk_mul_f32 v[42:43], v[42:43], v[180:181]
	v_cvt_f32_f16_e32 v180, v172
	v_cvt_f32_f16_e32 v181, v174
	v_cvt_f32_f16_sdwa v172, v172 dst_sel:DWORD dst_unused:UNUSED_PAD src0_sel:WORD_1
	v_cvt_f32_f16_sdwa v177, v177 dst_sel:DWORD dst_unused:UNUSED_PAD src0_sel:WORD_1
	v_cvt_f32_f16_e32 v186, v178
	v_rcp_f32_e32 v182, v181
	v_rcp_f32_e32 v181, v172
	v_cvt_f32_f16_sdwa v172, v174 dst_sel:DWORD dst_unused:UNUSED_PAD src0_sel:WORD_1
	v_cvt_f32_f16_e32 v174, v175
	v_cvt_f32_f16_sdwa v187, v178 dst_sel:DWORD dst_unused:UNUSED_PAD src0_sel:WORD_1
	v_cvt_f32_f16_e32 v178, v170
	v_rcp_f32_e32 v183, v172
	v_cvt_f32_f16_e32 v172, v173
	v_cvt_f32_f16_sdwa v173, v173 dst_sel:DWORD dst_unused:UNUSED_PAD src0_sel:WORD_1
	v_rcp_f32_e32 v174, v174
	v_rcp_f32_e32 v180, v180
	v_rcp_f32_e32 v172, v172
	v_rcp_f32_e32 v173, v173
	v_pk_mul_f32 v[190:191], v[190:191], v[194:195]
	v_pk_mul_f32 v[180:181], v[180:181], v[184:185]
	v_pk_mul_f32 v[52:53], v[52:53], v[190:191]
	v_pk_mul_f32 v[172:173], v[172:173], v[176:177]
	v_pk_mul_f32 v[176:177], v[182:183], v[186:187]
	v_pk_mul_f32 v[58:59], v[58:59], v[172:173]
	v_cvt_f32_f16_sdwa v172, v175 dst_sel:DWORD dst_unused:UNUSED_PAD src0_sel:WORD_1
	v_cvt_f32_f16_sdwa v173, v179 dst_sel:DWORD dst_unused:UNUSED_PAD src0_sel:WORD_1
	v_pk_mul_f32 v[68:69], v[68:69], v[176:177]
	v_cvt_f32_f16_e32 v176, v168
	v_rcp_f32_e32 v175, v172
	v_cvt_f32_f16_e32 v172, v179
	v_cvt_f32_f16_sdwa v177, v168 dst_sel:DWORD dst_unused:UNUSED_PAD src0_sel:WORD_1
	v_cvt_f32_f16_e32 v168, v169
	v_cvt_f32_f16_sdwa v169, v169 dst_sel:DWORD dst_unused:UNUSED_PAD src0_sel:WORD_1
	v_pk_mul_f32 v[172:173], v[174:175], v[172:173]
	v_cvt_f32_f16_sdwa v179, v170 dst_sel:DWORD dst_unused:UNUSED_PAD src0_sel:WORD_1
	v_pk_mul_f32 v[70:71], v[70:71], v[172:173]
	v_cvt_f32_f16_e32 v172, v160
	v_cvt_f32_f16_e32 v173, v162
	v_cvt_f32_f16_sdwa v160, v160 dst_sel:DWORD dst_unused:UNUSED_PAD src0_sel:WORD_1
	v_cvt_f32_f16_e32 v170, v158
	v_rcp_f32_e32 v172, v172
	v_rcp_f32_e32 v174, v173
	v_rcp_f32_e32 v173, v160
	v_cvt_f32_f16_sdwa v160, v162 dst_sel:DWORD dst_unused:UNUSED_PAD src0_sel:WORD_1
	v_cvt_f32_f16_e32 v162, v163
	v_pk_mul_f32 v[56:57], v[56:57], v[180:181]
	v_pk_mul_f32 v[172:173], v[172:173], v[176:177]
	v_rcp_f32_e32 v175, v160
	v_cvt_f32_f16_e32 v160, v161
	v_cvt_f32_f16_sdwa v161, v161 dst_sel:DWORD dst_unused:UNUSED_PAD src0_sel:WORD_1
	v_rcp_f32_e32 v162, v162
	v_pk_mul_f32 v[36:37], v[36:37], v[172:173]
	v_rcp_f32_e32 v160, v160
	v_rcp_f32_e32 v161, v161
	s_nop 0
	v_pk_mul_f32 v[160:161], v[160:161], v[168:169]
	s_nop 0
	v_pk_mul_f32 v[38:39], v[38:39], v[160:161]
	v_cvt_f32_f16_sdwa v160, v163 dst_sel:DWORD dst_unused:UNUSED_PAD src0_sel:WORD_1
	v_cvt_f32_f16_sdwa v161, v171 dst_sel:DWORD dst_unused:UNUSED_PAD src0_sel:WORD_1
	v_pk_mul_f32 v[168:169], v[174:175], v[178:179]
	v_rcp_f32_e32 v163, v160
	v_cvt_f32_f16_e32 v160, v171
	v_pk_mul_f32 v[28:29], v[28:29], v[168:169]
	v_cvt_f32_f16_sdwa v171, v158 dst_sel:DWORD dst_unused:UNUSED_PAD src0_sel:WORD_1
	v_pk_mul_f32 v[160:161], v[162:163], v[160:161]
	s_nop 0
	v_pk_mul_f32 v[30:31], v[30:31], v[160:161]
	v_cvt_f32_f16_e32 v160, v144
	v_cvt_f32_f16_e32 v161, v146
	v_cvt_f32_f16_sdwa v144, v144 dst_sel:DWORD dst_unused:UNUSED_PAD src0_sel:WORD_1
	v_cvt_f32_f16_e32 v162, v156
	v_rcp_f32_e32 v160, v160
	v_rcp_f32_e32 v168, v161
	v_rcp_f32_e32 v161, v144
	v_cvt_f32_f16_sdwa v144, v146 dst_sel:DWORD dst_unused:UNUSED_PAD src0_sel:WORD_1
	v_cvt_f32_f16_sdwa v163, v156 dst_sel:DWORD dst_unused:UNUSED_PAD src0_sel:WORD_1
	v_cvt_f32_f16_e32 v156, v157
	v_cvt_f32_f16_sdwa v157, v157 dst_sel:DWORD dst_unused:UNUSED_PAD src0_sel:WORD_1
	v_rcp_f32_e32 v169, v144
	v_cvt_f32_f16_e32 v144, v145
	v_cvt_f32_f16_sdwa v145, v145 dst_sel:DWORD dst_unused:UNUSED_PAD src0_sel:WORD_1
	v_pk_mul_f32 v[160:161], v[160:161], v[162:163]
	v_cvt_f32_f16_e32 v146, v147
	v_rcp_f32_e32 v144, v144
	v_rcp_f32_e32 v145, v145
	v_pk_mul_f32 v[160:161], v[128:129], v[160:161]
	v_cvt_f32_f16_sdwa v128, v147 dst_sel:DWORD dst_unused:UNUSED_PAD src0_sel:WORD_1
	v_rcp_f32_e32 v146, v146
	v_pk_mul_f32 v[144:145], v[144:145], v[156:157]
	v_cvt_f32_f16_sdwa v129, v159 dst_sel:DWORD dst_unused:UNUSED_PAD src0_sel:WORD_1
	v_pk_mul_f32 v[162:163], v[130:131], v[144:145]
	v_rcp_f32_e32 v147, v128
	v_cvt_f32_f16_e32 v128, v159
	v_pk_mul_f32 v[130:131], v[168:169], v[170:171]
	v_cvt_f32_f16_e32 v145, v155
	v_pk_mul_f32 v[156:157], v[124:125], v[130:131]
	v_cvt_f32_f16_e32 v125, v154
	v_pk_mul_f32 v[128:129], v[146:147], v[128:129]
	v_cvt_f32_f16_e32 v124, v152
	v_pk_mul_f32 v[158:159], v[126:127], v[128:129]
	v_rcp_f32_e32 v126, v125
	v_cvt_f32_f16_sdwa v125, v152 dst_sel:DWORD dst_unused:UNUSED_PAD src0_sel:WORD_1
	v_cvt_f32_f16_e32 v144, v153
	v_rcp_f32_e32 v152, v145
	v_cvt_f32_f16_sdwa v145, v153 dst_sel:DWORD dst_unused:UNUSED_PAD src0_sel:WORD_1
	v_rcp_f32_e32 v124, v124
	v_rcp_f32_e32 v125, v125
	v_cvt_f32_f16_e32 v128, v164
	v_cvt_f32_f16_sdwa v129, v164 dst_sel:DWORD dst_unused:UNUSED_PAD src0_sel:WORD_1
	v_cvt_f32_f16_sdwa v127, v154 dst_sel:DWORD dst_unused:UNUSED_PAD src0_sel:WORD_1
	v_rcp_f32_e32 v144, v144
	v_rcp_f32_e32 v145, v145
	v_cvt_f32_f16_e32 v146, v165
	v_cvt_f32_f16_sdwa v147, v165 dst_sel:DWORD dst_unused:UNUSED_PAD src0_sel:WORD_1
	v_pk_mul_f32 v[124:125], v[124:125], v[128:129]
	v_rcp_f32_e32 v127, v127
	v_cvt_f32_f16_e32 v130, v166
	v_cvt_f32_f16_sdwa v131, v166 dst_sel:DWORD dst_unused:UNUSED_PAD src0_sel:WORD_1
	v_pk_mul_f32 v[128:129], v[144:145], v[146:147]
	v_pk_mul_f32 v[144:145], v[120:121], v[124:125]
	v_cvt_f32_f16_sdwa v120, v155 dst_sel:DWORD dst_unused:UNUSED_PAD src0_sel:WORD_1
	v_pk_mul_f32 v[146:147], v[122:123], v[128:129]
	v_cvt_f32_f16_sdwa v121, v167 dst_sel:DWORD dst_unused:UNUSED_PAD src0_sel:WORD_1
	v_pk_mul_f32 v[122:123], v[126:127], v[130:131]
	v_rcp_f32_e32 v153, v120
	v_cvt_f32_f16_e32 v120, v167
	v_pk_mul_f32 v[124:125], v[112:113], v[122:123]
	v_cvt_f32_f16_e32 v113, v142
	v_cvt_f32_f16_e32 v112, v140
	v_pk_mul_f32 v[120:121], v[152:153], v[120:121]
	v_cvt_f32_f16_e32 v129, v143
	v_pk_mul_f32 v[126:127], v[114:115], v[120:121]
	v_rcp_f32_e32 v114, v113
	v_cvt_f32_f16_sdwa v113, v140 dst_sel:DWORD dst_unused:UNUSED_PAD src0_sel:WORD_1
	v_rcp_f32_e32 v112, v112
	v_cvt_f32_f16_e32 v120, v148
	v_cvt_f32_f16_sdwa v121, v148 dst_sel:DWORD dst_unused:UNUSED_PAD src0_sel:WORD_1
	v_rcp_f32_e32 v113, v113
	v_cvt_f32_f16_sdwa v115, v142 dst_sel:DWORD dst_unused:UNUSED_PAD src0_sel:WORD_1
	v_cvt_f32_f16_e32 v122, v150
	v_cvt_f32_f16_sdwa v123, v150 dst_sel:DWORD dst_unused:UNUSED_PAD src0_sel:WORD_1
	v_pk_mul_f32 v[112:113], v[112:113], v[120:121]
	v_rcp_f32_e32 v115, v115
	v_pk_mul_f32 v[152:153], v[116:117], v[112:113]
	v_cvt_f32_f16_sdwa v112, v143 dst_sel:DWORD dst_unused:UNUSED_PAD src0_sel:WORD_1
	v_cvt_f32_f16_e32 v128, v141
	v_rcp_f32_e32 v130, v129
	v_cvt_f32_f16_sdwa v129, v141 dst_sel:DWORD dst_unused:UNUSED_PAD src0_sel:WORD_1
	v_rcp_f32_e32 v131, v112
	v_cvt_f32_f16_e32 v112, v151
	v_cvt_f32_f16_sdwa v113, v151 dst_sel:DWORD dst_unused:UNUSED_PAD src0_sel:WORD_1
	v_pk_mul_f32 v[114:115], v[114:115], v[122:123]
	v_rcp_f32_e32 v128, v128
	v_rcp_f32_e32 v129, v129
	v_cvt_f32_f16_e32 v140, v149
	v_cvt_f32_f16_sdwa v141, v149 dst_sel:DWORD dst_unused:UNUSED_PAD src0_sel:WORD_1
	v_pk_mul_f32 v[148:149], v[108:109], v[114:115]
	v_cvt_f32_f16_e32 v109, v134
	v_cvt_f32_f16_e32 v117, v135
	v_pk_mul_f32 v[112:113], v[130:131], v[112:113]
	v_pk_mul_f32 v[120:121], v[128:129], v[140:141]
	v_pk_mul_f32 v[150:151], v[110:111], v[112:113]
	v_cvt_f32_f16_e32 v108, v132
	v_rcp_f32_e32 v110, v109
	v_cvt_f32_f16_sdwa v109, v132 dst_sel:DWORD dst_unused:UNUSED_PAD src0_sel:WORD_1
	v_pk_mul_f32 v[154:155], v[118:119], v[120:121]
	v_cvt_f32_f16_e32 v116, v133
	v_rcp_f32_e32 v118, v117
	v_cvt_f32_f16_sdwa v117, v133 dst_sel:DWORD dst_unused:UNUSED_PAD src0_sel:WORD_1
	v_rcp_f32_e32 v108, v108
	v_rcp_f32_e32 v109, v109
	v_cvt_f32_f16_e32 v112, v136
	v_cvt_f32_f16_sdwa v113, v136 dst_sel:DWORD dst_unused:UNUSED_PAD src0_sel:WORD_1
	v_rcp_f32_e32 v116, v116
	v_rcp_f32_e32 v117, v117
	v_cvt_f32_f16_e32 v120, v137
	v_cvt_f32_f16_sdwa v121, v137 dst_sel:DWORD dst_unused:UNUSED_PAD src0_sel:WORD_1
	v_cvt_f32_f16_sdwa v111, v134 dst_sel:DWORD dst_unused:UNUSED_PAD src0_sel:WORD_1
	v_pk_mul_f32 v[108:109], v[108:109], v[112:113]
	v_cvt_f32_f16_e32 v114, v138
	v_pk_mul_f32 v[112:113], v[116:117], v[120:121]
	v_pk_mul_f32 v[120:121], v[104:105], v[108:109]
	v_cvt_f32_f16_sdwa v104, v135 dst_sel:DWORD dst_unused:UNUSED_PAD src0_sel:WORD_1
	v_rcp_f32_e32 v111, v111
	v_cvt_f32_f16_sdwa v115, v138 dst_sel:DWORD dst_unused:UNUSED_PAD src0_sel:WORD_1
	v_cvt_f32_f16_sdwa v105, v139 dst_sel:DWORD dst_unused:UNUSED_PAD src0_sel:WORD_1
	v_rcp_f32_e32 v119, v104
	v_cvt_f32_f16_e32 v104, v139
	v_pk_mul_f32 v[122:123], v[106:107], v[112:113]
	v_pk_mul_f32 v[106:107], v[110:111], v[114:115]
	v_pk_mul_f32 v[104:105], v[118:119], v[104:105]
	v_pk_mul_f32 v[116:117], v[100:101], v[106:107]
	v_add_u32_e32 v100, 0x8000, v188
	v_ashrrev_i32_e32 v101, 31, v100
	v_lshlrev_b64 v[100:101], 1, v[100:101]
	v_pk_mul_f32 v[118:119], v[102:103], v[104:105]
	v_lshl_add_u64 v[104:105], s[16:17], 0, v[100:101]
	v_lshl_add_u64 v[112:113], s[26:27], 0, v[100:101]
	v_add_u32_e32 v100, 0x8080, v188
	v_ashrrev_i32_e32 v101, 31, v100
	v_lshlrev_b64 v[100:101], 1, v[100:101]
	v_lshl_add_u64 v[102:103], s[16:17], 0, v[100:101]
	v_lshl_add_u64 v[114:115], s[26:27], 0, v[100:101]
	v_add_u32_e32 v100, 0x9000, v188
	v_ashrrev_i32_e32 v101, 31, v100
	v_lshlrev_b64 v[100:101], 1, v[100:101]
	v_lshl_add_u64 v[106:107], s[16:17], 0, v[100:101]
	v_lshl_add_u64 v[190:191], s[26:27], 0, v[100:101]
	v_add_u32_e32 v100, 0x9080, v188
	v_ashrrev_i32_e32 v101, 31, v100
	v_lshlrev_b64 v[100:101], 1, v[100:101]
	v_lshl_add_u64 v[140:141], s[16:17], 0, v[100:101]
	v_lshl_add_u64 v[180:181], s[26:27], 0, v[100:101]
	v_add_u32_e32 v100, 0xa000, v188
	v_ashrrev_i32_e32 v101, 31, v100
	v_lshlrev_b64 v[100:101], 1, v[100:101]
	v_lshl_add_u64 v[136:137], s[16:17], 0, v[100:101]
	v_lshl_add_u64 v[176:177], s[26:27], 0, v[100:101]
	v_add_u32_e32 v100, 0xa080, v188
	v_ashrrev_i32_e32 v101, 31, v100
	v_lshlrev_b64 v[100:101], 1, v[100:101]
	v_lshl_add_u64 v[132:133], s[16:17], 0, v[100:101]
	v_lshl_add_u64 v[172:173], s[26:27], 0, v[100:101]
	v_add_u32_e32 v100, 0xb000, v188
	v_ashrrev_i32_e32 v101, 31, v100
	v_lshlrev_b64 v[100:101], 1, v[100:101]
	v_lshl_add_u64 v[128:129], s[16:17], 0, v[100:101]
	v_lshl_add_u64 v[168:169], s[26:27], 0, v[100:101]
	v_add_u32_e32 v100, 0xb080, v188
	v_ashrrev_i32_e32 v101, 31, v100
	v_lshlrev_b64 v[100:101], 1, v[100:101]
	v_lshl_add_u64 v[108:109], s[16:17], 0, v[100:101]
	v_lshl_add_u64 v[164:165], s[26:27], 0, v[100:101]
	global_load_dwordx4 v[108:111], v[108:109], off
	s_nop 0
	global_load_dwordx4 v[128:131], v[128:129], off
	s_nop 0
	global_load_dwordx4 v[132:135], v[132:133], off
	s_nop 0
	global_load_dwordx4 v[136:139], v[136:137], off
	s_nop 0
	global_load_dwordx4 v[140:143], v[140:141], off
	s_nop 0
	global_load_dwordx4 v[184:187], v[106:107], off
	s_nop 0
	global_load_dwordx4 v[100:103], v[102:103], off
	s_nop 0
	global_load_dwordx4 v[104:107], v[104:105], off
	s_nop 0
	global_load_dwordx4 v[164:167], v[164:165], off
	s_nop 0
	global_load_dwordx4 v[168:171], v[168:169], off
	s_nop 0
	global_load_dwordx4 v[172:175], v[172:173], off
	s_nop 0
	global_load_dwordx4 v[176:179], v[176:177], off
	s_nop 0
	global_load_dwordx4 v[180:183], v[180:181], off
	s_nop 0
	global_load_dwordx4 v[188:191], v[190:191], off
	s_nop 0
	global_load_dwordx4 v[192:195], v[114:115], off
	global_load_dwordx4 v[196:199], v[112:113], off
	s_waitcnt vmcnt(0)
	s_nop 0
	v_cvt_f32_f16_e32 v112, v104
	v_cvt_f32_f16_e32 v113, v106
	v_cvt_f32_f16_sdwa v104, v104 dst_sel:DWORD dst_unused:UNUSED_PAD src0_sel:WORD_1
	v_rcp_f32_e32 v242, v113
	v_rcp_f32_e32 v113, v104
	v_cvt_f32_f16_sdwa v104, v106 dst_sel:DWORD dst_unused:UNUSED_PAD src0_sel:WORD_1
	v_rcp_f32_e32 v112, v112
	v_cvt_f32_f16_e32 v114, v196
	v_cvt_f32_f16_sdwa v115, v196 dst_sel:DWORD dst_unused:UNUSED_PAD src0_sel:WORD_1
	v_rcp_f32_e32 v243, v104
	v_cvt_f32_f16_e32 v104, v105
	v_cvt_f32_f16_sdwa v105, v105 dst_sel:DWORD dst_unused:UNUSED_PAD src0_sel:WORD_1
	v_cvt_f32_f16_e32 v196, v197
	v_cvt_f32_f16_sdwa v197, v197 dst_sel:DWORD dst_unused:UNUSED_PAD src0_sel:WORD_1
	v_rcp_f32_e32 v104, v104
	v_rcp_f32_e32 v105, v105
	v_pk_mul_f32 v[112:113], v[112:113], v[114:115]
	v_cvt_f32_f16_e32 v244, v198
	v_cvt_f32_f16_sdwa v245, v198 dst_sel:DWORD dst_unused:UNUSED_PAD src0_sel:WORD_1
	v_cvt_f32_f16_e32 v106, v107
	v_pk_mul_f32 v[112:113], v[96:97], v[112:113]
	v_cvt_f32_f16_sdwa v96, v107 dst_sel:DWORD dst_unused:UNUSED_PAD src0_sel:WORD_1
	v_pk_mul_f32 v[104:105], v[104:105], v[196:197]
	v_rcp_f32_e32 v106, v106
	v_pk_mul_f32 v[114:115], v[98:99], v[104:105]
	v_rcp_f32_e32 v107, v96
	v_cvt_f32_f16_e32 v96, v199
	v_cvt_f32_f16_sdwa v97, v199 dst_sel:DWORD dst_unused:UNUSED_PAD src0_sel:WORD_1
	v_pk_mul_f32 v[98:99], v[242:243], v[244:245]
	s_mov_b64 s[16:17], 0
	v_pk_mul_f32 v[104:105], v[92:93], v[98:99]
	v_cvt_f32_f16_e32 v93, v102
	v_pk_mul_f32 v[96:97], v[106:107], v[96:97]
	v_cvt_f32_f16_e32 v92, v100
	v_pk_mul_f32 v[106:107], v[94:95], v[96:97]
	v_rcp_f32_e32 v96, v93
	v_cvt_f32_f16_sdwa v93, v100 dst_sel:DWORD dst_unused:UNUSED_PAD src0_sel:WORD_1
	v_rcp_f32_e32 v92, v92
	v_cvt_f32_f16_e32 v94, v192
	v_cvt_f32_f16_sdwa v95, v192 dst_sel:DWORD dst_unused:UNUSED_PAD src0_sel:WORD_1
	v_rcp_f32_e32 v93, v93
	v_cvt_f32_f16_sdwa v97, v102 dst_sel:DWORD dst_unused:UNUSED_PAD src0_sel:WORD_1
	v_cvt_f32_f16_e32 v102, v103
	v_cvt_f32_f16_e32 v100, v101
	v_pk_mul_f32 v[92:93], v[92:93], v[94:95]
	v_cvt_f32_f16_sdwa v101, v101 dst_sel:DWORD dst_unused:UNUSED_PAD src0_sel:WORD_1
	v_pk_mul_f32 v[92:93], v[88:89], v[92:93]
	v_cvt_f32_f16_sdwa v88, v103 dst_sel:DWORD dst_unused:UNUSED_PAD src0_sel:WORD_1
	v_rcp_f32_e32 v102, v102
	v_cvt_f32_f16_sdwa v89, v195 dst_sel:DWORD dst_unused:UNUSED_PAD src0_sel:WORD_1
	v_rcp_f32_e32 v100, v100
	v_rcp_f32_e32 v103, v88
	v_cvt_f32_f16_e32 v88, v195
	v_rcp_f32_e32 v101, v101
	v_cvt_f32_f16_e32 v192, v193
	v_cvt_f32_f16_sdwa v193, v193 dst_sel:DWORD dst_unused:UNUSED_PAD src0_sel:WORD_1
	v_rcp_f32_e32 v97, v97
	v_cvt_f32_f16_e32 v98, v194
	v_cvt_f32_f16_sdwa v99, v194 dst_sel:DWORD dst_unused:UNUSED_PAD src0_sel:WORD_1
	v_pk_mul_f32 v[88:89], v[102:103], v[88:89]
	v_pk_mul_f32 v[94:95], v[100:101], v[192:193]
	v_pk_mul_f32 v[86:87], v[86:87], v[88:89]
	v_cvt_f32_f16_e32 v89, v186
	v_cvt_f32_f16_e32 v101, v187
	v_pk_mul_f32 v[94:95], v[90:91], v[94:95]
	v_pk_mul_f32 v[90:91], v[96:97], v[98:99]
	v_cvt_f32_f16_e32 v88, v184
	v_pk_mul_f32 v[84:85], v[84:85], v[90:91]
	v_rcp_f32_e32 v90, v89
	v_cvt_f32_f16_sdwa v89, v184 dst_sel:DWORD dst_unused:UNUSED_PAD src0_sel:WORD_1
	v_cvt_f32_f16_e32 v100, v185
	v_rcp_f32_e32 v184, v101
	v_cvt_f32_f16_sdwa v101, v185 dst_sel:DWORD dst_unused:UNUSED_PAD src0_sel:WORD_1
	v_rcp_f32_e32 v88, v88
	v_rcp_f32_e32 v89, v89
	v_cvt_f32_f16_e32 v96, v188
	v_cvt_f32_f16_sdwa v97, v188 dst_sel:DWORD dst_unused:UNUSED_PAD src0_sel:WORD_1
	v_cvt_f32_f16_sdwa v91, v186 dst_sel:DWORD dst_unused:UNUSED_PAD src0_sel:WORD_1
	v_rcp_f32_e32 v100, v100
	v_rcp_f32_e32 v101, v101
	v_cvt_f32_f16_e32 v102, v189
	v_cvt_f32_f16_sdwa v103, v189 dst_sel:DWORD dst_unused:UNUSED_PAD src0_sel:WORD_1
	v_pk_mul_f32 v[88:89], v[88:89], v[96:97]
	v_rcp_f32_e32 v91, v91
	v_cvt_f32_f16_e32 v98, v190
	v_cvt_f32_f16_sdwa v99, v190 dst_sel:DWORD dst_unused:UNUSED_PAD src0_sel:WORD_1
	v_pk_mul_f32 v[96:97], v[100:101], v[102:103]
	v_pk_mul_f32 v[100:101], v[76:77], v[88:89]
	v_cvt_f32_f16_sdwa v76, v187 dst_sel:DWORD dst_unused:UNUSED_PAD src0_sel:WORD_1
	v_pk_mul_f32 v[102:103], v[78:79], v[96:97]
	v_cvt_f32_f16_sdwa v77, v191 dst_sel:DWORD dst_unused:UNUSED_PAD src0_sel:WORD_1
	v_pk_mul_f32 v[78:79], v[90:91], v[98:99]
	v_rcp_f32_e32 v185, v76
	v_cvt_f32_f16_e32 v76, v191
	v_pk_mul_f32 v[96:97], v[64:65], v[78:79]
	v_cvt_f32_f16_e32 v65, v142
	v_cvt_f32_f16_e32 v79, v143
	v_pk_mul_f32 v[76:77], v[184:185], v[76:77]
	v_cvt_f32_f16_e32 v64, v140
	v_pk_mul_f32 v[98:99], v[66:67], v[76:77]
	v_rcp_f32_e32 v66, v65
	v_cvt_f32_f16_sdwa v65, v140 dst_sel:DWORD dst_unused:UNUSED_PAD src0_sel:WORD_1
	v_cvt_f32_f16_e32 v78, v141
	v_rcp_f32_e32 v90, v79
	v_cvt_f32_f16_sdwa v79, v141 dst_sel:DWORD dst_unused:UNUSED_PAD src0_sel:WORD_1
	v_rcp_f32_e32 v64, v64
	v_rcp_f32_e32 v65, v65
	v_cvt_f32_f16_e32 v76, v180
	v_cvt_f32_f16_sdwa v77, v180 dst_sel:DWORD dst_unused:UNUSED_PAD src0_sel:WORD_1
	v_rcp_f32_e32 v78, v78
	v_rcp_f32_e32 v79, v79
	v_cvt_f32_f16_e32 v140, v181
	v_cvt_f32_f16_sdwa v141, v181 dst_sel:DWORD dst_unused:UNUSED_PAD src0_sel:WORD_1
	v_cvt_f32_f16_sdwa v67, v142 dst_sel:DWORD dst_unused:UNUSED_PAD src0_sel:WORD_1
	v_pk_mul_f32 v[64:65], v[64:65], v[76:77]
	v_cvt_f32_f16_e32 v88, v182
	v_pk_mul_f32 v[76:77], v[78:79], v[140:141]
	v_rcp_f32_e32 v67, v67
	v_cvt_f32_f16_sdwa v89, v182 dst_sel:DWORD dst_unused:UNUSED_PAD src0_sel:WORD_1
	v_pk_mul_f32 v[78:79], v[62:63], v[76:77]
	v_pk_mul_f32 v[76:77], v[60:61], v[64:65]
	v_cvt_f32_f16_sdwa v60, v143 dst_sel:DWORD dst_unused:UNUSED_PAD src0_sel:WORD_1
	v_cvt_f32_f16_sdwa v61, v183 dst_sel:DWORD dst_unused:UNUSED_PAD src0_sel:WORD_1
	v_pk_mul_f32 v[62:63], v[66:67], v[88:89]
	v_cvt_f32_f16_e32 v89, v139
	v_rcp_f32_e32 v91, v60
	v_cvt_f32_f16_e32 v60, v183
	v_pk_mul_f32 v[64:65], v[48:49], v[62:63]
	v_cvt_f32_f16_e32 v49, v138
	v_cvt_f32_f16_e32 v48, v136
	v_pk_mul_f32 v[60:61], v[90:91], v[60:61]
	v_cvt_f32_f16_e32 v88, v137
	v_pk_mul_f32 v[66:67], v[50:51], v[60:61]
	v_rcp_f32_e32 v50, v49
	v_cvt_f32_f16_sdwa v49, v136 dst_sel:DWORD dst_unused:UNUSED_PAD src0_sel:WORD_1
	v_rcp_f32_e32 v48, v48
	v_cvt_f32_f16_e32 v60, v176
	v_cvt_f32_f16_sdwa v61, v176 dst_sel:DWORD dst_unused:UNUSED_PAD src0_sel:WORD_1
	v_rcp_f32_e32 v49, v49
	v_rcp_f32_e32 v90, v89
	v_cvt_f32_f16_sdwa v89, v137 dst_sel:DWORD dst_unused:UNUSED_PAD src0_sel:WORD_1
	v_cvt_f32_f16_sdwa v51, v138 dst_sel:DWORD dst_unused:UNUSED_PAD src0_sel:WORD_1
	v_rcp_f32_e32 v88, v88
	v_cvt_f32_f16_e32 v136, v177
	v_rcp_f32_e32 v89, v89
	v_cvt_f32_f16_sdwa v137, v177 dst_sel:DWORD dst_unused:UNUSED_PAD src0_sel:WORD_1
	v_pk_mul_f32 v[48:49], v[48:49], v[60:61]
	v_rcp_f32_e32 v51, v51
	v_cvt_f32_f16_e32 v62, v178
	v_cvt_f32_f16_sdwa v63, v178 dst_sel:DWORD dst_unused:UNUSED_PAD src0_sel:WORD_1
	v_pk_mul_f32 v[140:141], v[44:45], v[48:49]
	v_cvt_f32_f16_sdwa v44, v139 dst_sel:DWORD dst_unused:UNUSED_PAD src0_sel:WORD_1
	v_pk_mul_f32 v[60:61], v[88:89], v[136:137]
	v_cvt_f32_f16_sdwa v45, v179 dst_sel:DWORD dst_unused:UNUSED_PAD src0_sel:WORD_1
	v_pk_mul_f32 v[142:143], v[46:47], v[60:61]
	v_rcp_f32_e32 v91, v44
	v_cvt_f32_f16_e32 v44, v179
	v_pk_mul_f32 v[46:47], v[50:51], v[62:63]
	v_cvt_f32_f16_e32 v49, v135
	v_pk_mul_f32 v[136:137], v[32:33], v[46:47]
	v_cvt_f32_f16_e32 v33, v134
	v_pk_mul_f32 v[44:45], v[90:91], v[44:45]
	v_cvt_f32_f16_e32 v32, v132
	v_pk_mul_f32 v[138:139], v[34:35], v[44:45]
	v_rcp_f32_e32 v34, v33
	v_cvt_f32_f16_sdwa v33, v132 dst_sel:DWORD dst_unused:UNUSED_PAD src0_sel:WORD_1
	v_cvt_f32_f16_e32 v48, v133
	v_rcp_f32_e32 v50, v49
	v_cvt_f32_f16_sdwa v49, v133 dst_sel:DWORD dst_unused:UNUSED_PAD src0_sel:WORD_1
	v_rcp_f32_e32 v32, v32
	v_rcp_f32_e32 v33, v33
	v_cvt_f32_f16_e32 v44, v172
	v_cvt_f32_f16_sdwa v45, v172 dst_sel:DWORD dst_unused:UNUSED_PAD src0_sel:WORD_1
	v_cvt_f32_f16_sdwa v35, v134 dst_sel:DWORD dst_unused:UNUSED_PAD src0_sel:WORD_1
	v_rcp_f32_e32 v48, v48
	v_rcp_f32_e32 v49, v49
	v_cvt_f32_f16_e32 v60, v173
	v_cvt_f32_f16_sdwa v61, v173 dst_sel:DWORD dst_unused:UNUSED_PAD src0_sel:WORD_1
	v_pk_mul_f32 v[32:33], v[32:33], v[44:45]
	v_rcp_f32_e32 v35, v35
	v_cvt_f32_f16_e32 v46, v174
	v_cvt_f32_f16_sdwa v47, v174 dst_sel:DWORD dst_unused:UNUSED_PAD src0_sel:WORD_1
	v_pk_mul_f32 v[44:45], v[48:49], v[60:61]
	v_pk_mul_f32 v[60:61], v[24:25], v[32:33]
	v_cvt_f32_f16_sdwa v24, v135 dst_sel:DWORD dst_unused:UNUSED_PAD src0_sel:WORD_1
	v_pk_mul_f32 v[62:63], v[26:27], v[44:45]
	v_cvt_f32_f16_sdwa v25, v175 dst_sel:DWORD dst_unused:UNUSED_PAD src0_sel:WORD_1
	v_pk_mul_f32 v[26:27], v[34:35], v[46:47]
	v_rcp_f32_e32 v51, v24
	v_cvt_f32_f16_e32 v24, v175
	v_pk_mul_f32 v[48:49], v[20:21], v[26:27]
	v_cvt_f32_f16_e32 v21, v130
	v_cvt_f32_f16_e32 v20, v128
	v_pk_mul_f32 v[24:25], v[50:51], v[24:25]
	v_cvt_f32_f16_e32 v33, v131
	v_pk_mul_f32 v[50:51], v[22:23], v[24:25]
	v_rcp_f32_e32 v22, v21
	v_cvt_f32_f16_sdwa v21, v128 dst_sel:DWORD dst_unused:UNUSED_PAD src0_sel:WORD_1
	v_rcp_f32_e32 v20, v20
	v_cvt_f32_f16_e32 v24, v168
	v_cvt_f32_f16_sdwa v25, v168 dst_sel:DWORD dst_unused:UNUSED_PAD src0_sel:WORD_1
	v_rcp_f32_e32 v21, v21
	v_cvt_f32_f16_e32 v32, v129
	v_rcp_f32_e32 v34, v33
	v_cvt_f32_f16_sdwa v33, v129 dst_sel:DWORD dst_unused:UNUSED_PAD src0_sel:WORD_1
	v_cvt_f32_f16_sdwa v23, v130 dst_sel:DWORD dst_unused:UNUSED_PAD src0_sel:WORD_1
	v_rcp_f32_e32 v32, v32
	v_cvt_f32_f16_e32 v44, v169
	v_rcp_f32_e32 v33, v33
	v_cvt_f32_f16_sdwa v45, v169 dst_sel:DWORD dst_unused:UNUSED_PAD src0_sel:WORD_1
	v_pk_mul_f32 v[20:21], v[20:21], v[24:25]
	v_rcp_f32_e32 v23, v23
	v_cvt_f32_f16_e32 v26, v170
	v_cvt_f32_f16_sdwa v27, v170 dst_sel:DWORD dst_unused:UNUSED_PAD src0_sel:WORD_1
	v_pk_mul_f32 v[132:133], v[16:17], v[20:21]
	v_cvt_f32_f16_sdwa v16, v131 dst_sel:DWORD dst_unused:UNUSED_PAD src0_sel:WORD_1
	v_pk_mul_f32 v[24:25], v[32:33], v[44:45]
	v_cvt_f32_f16_sdwa v17, v171 dst_sel:DWORD dst_unused:UNUSED_PAD src0_sel:WORD_1
	v_pk_mul_f32 v[134:135], v[18:19], v[24:25]
	v_rcp_f32_e32 v35, v16
	v_cvt_f32_f16_e32 v16, v171
	v_pk_mul_f32 v[18:19], v[22:23], v[26:27]
	v_cvt_f32_f16_e32 v21, v111
	v_pk_mul_f32 v[128:129], v[12:13], v[18:19]
	v_cvt_f32_f16_e32 v13, v110
	v_pk_mul_f32 v[16:17], v[34:35], v[16:17]
	v_cvt_f32_f16_e32 v12, v108
	v_pk_mul_f32 v[130:131], v[14:15], v[16:17]
	v_rcp_f32_e32 v14, v13
	v_cvt_f32_f16_sdwa v13, v108 dst_sel:DWORD dst_unused:UNUSED_PAD src0_sel:WORD_1
	v_rcp_f32_e32 v12, v12
	v_cvt_f32_f16_e32 v16, v164
	v_cvt_f32_f16_sdwa v17, v164 dst_sel:DWORD dst_unused:UNUSED_PAD src0_sel:WORD_1
	v_rcp_f32_e32 v13, v13
	v_cvt_f32_f16_e32 v20, v109
	v_rcp_f32_e32 v22, v21
	v_cvt_f32_f16_sdwa v21, v109 dst_sel:DWORD dst_unused:UNUSED_PAD src0_sel:WORD_1
	v_pk_mul_f32 v[12:13], v[12:13], v[16:17]
	v_cvt_f32_f16_sdwa v15, v110 dst_sel:DWORD dst_unused:UNUSED_PAD src0_sel:WORD_1
	v_pk_mul_f32 v[32:33], v[8:9], v[12:13]
	v_cvt_f32_f16_sdwa v8, v111 dst_sel:DWORD dst_unused:UNUSED_PAD src0_sel:WORD_1
	v_rcp_f32_e32 v20, v20
	v_rcp_f32_e32 v21, v21
	v_cvt_f32_f16_e32 v24, v165
	v_cvt_f32_f16_sdwa v25, v165 dst_sel:DWORD dst_unused:UNUSED_PAD src0_sel:WORD_1
	v_rcp_f32_e32 v15, v15
	v_cvt_f32_f16_e32 v18, v166
	v_cvt_f32_f16_sdwa v19, v166 dst_sel:DWORD dst_unused:UNUSED_PAD src0_sel:WORD_1
	v_rcp_f32_e32 v23, v8
	v_cvt_f32_f16_e32 v8, v167
	v_cvt_f32_f16_sdwa v9, v167 dst_sel:DWORD dst_unused:UNUSED_PAD src0_sel:WORD_1
	v_pk_mul_f32 v[16:17], v[20:21], v[24:25]
	s_mov_b64 s[26:27], 0x80480
	v_pk_mul_f32 v[34:35], v[10:11], v[16:17]
	v_pk_mul_f32 v[10:11], v[14:15], v[18:19]
	v_pk_mul_f32 v[8:9], v[22:23], v[8:9]
	v_pk_mul_f32 v[44:45], v[4:5], v[10:11]
	v_pk_mul_f32 v[46:47], v[6:7], v[8:9]
	v_lshl_add_u64 v[4:5], s[34:35], 0, v[210:211]
.LBB0_1744:
	ds_read_b128 v[6:9], v237
	ds_read_b128 v[10:13], v237 offset:1024
	ds_read_b128 v[14:17], v237 offset:2048
	ds_read_b128 v[18:21], v237 offset:3072
	v_lshl_add_u64 v[246:247], v[4:5], 0, s[16:17]
	s_mov_b32 m0, s14
	v_lshl_add_u64 v[26:27], v[246:247], 0, s[26:27]
	v_lshl_add_u64 v[248:249], v[200:201], 0, s[16:17]
	ds_read_b128 v[22:25], v236
	ds_read_b128 v[88:91], v236 offset:1024
	ds_read_b128 v[108:111], v236 offset:2048
	ds_read_b128 v[164:167], v236 offset:3072
	ds_read_b128 v[168:171], v236 offset:4096
	ds_read_b128 v[172:175], v236 offset:5120
	ds_read_b128 v[176:179], v236 offset:6144
	ds_read_b128 v[180:183], v236 offset:7168
	global_load_lds_dwordx4 v[26:27], off
	v_lshl_add_u64 v[26:27], v[248:249], 0, s[26:27]
	s_mov_b32 m0, s15
	s_nop 0
	global_load_lds_dwordx4 v[26:27], off
	s_barrier
	s_waitcnt lgkmcnt(0)
	v_mfma_f32_16x16x32_f16 v[80:83], v[6:9], v[22:25], v[80:83]
	v_mfma_f32_16x16x32_f16 v[72:75], v[14:17], v[22:25], v[72:75]
	v_mfma_f32_16x16x32_f16 v[56:59], v[6:9], v[108:111], v[56:59]
	v_mfma_f32_16x16x32_f16 v[68:71], v[14:17], v[108:111], v[68:71]
	v_mfma_f32_16x16x32_f16 v[160:163], v[6:9], v[168:171], v[160:163]
	v_mfma_f32_16x16x32_f16 v[156:159], v[14:17], v[168:171], v[156:159]
	v_mfma_f32_16x16x32_f16 v[152:155], v[6:9], v[176:179], v[152:155]
	v_mfma_f32_16x16x32_f16 v[148:151], v[14:17], v[176:179], v[148:151]
	v_mfma_f32_16x16x32_f16 v[80:83], v[10:13], v[88:91], v[80:83]
	v_mfma_f32_16x16x32_f16 v[72:75], v[18:21], v[88:91], v[72:75]
	v_mfma_f32_16x16x32_f16 v[56:59], v[10:13], v[164:167], v[56:59]
	v_mfma_f32_16x16x32_f16 v[68:71], v[18:21], v[164:167], v[68:71]
	v_mfma_f32_16x16x32_f16 v[160:163], v[10:13], v[172:175], v[160:163]
	v_mfma_f32_16x16x32_f16 v[156:159], v[18:21], v[172:175], v[156:159]
	v_mfma_f32_16x16x32_f16 v[152:155], v[10:13], v[180:183], v[152:155]
	v_mfma_f32_16x16x32_f16 v[148:151], v[18:21], v[180:183], v[148:151]
	s_barrier
	v_lshl_add_u64 v[224:225], v[202:203], 0, s[16:17]
	s_mov_b32 m0, s19
	v_lshl_add_u64 v[26:27], v[224:225], 0, s[30:31]
	v_lshl_add_u64 v[226:227], v[220:221], 0, s[16:17]
	ds_read_b128 v[184:187], v238
	ds_read_b128 v[188:191], v238 offset:1024
	ds_read_b128 v[192:195], v238 offset:2048
	ds_read_b128 v[196:199], v238 offset:3072
	global_load_lds_dwordx4 v[26:27], off
	v_lshl_add_u64 v[26:27], v[226:227], 0, s[30:31]
	s_mov_b32 m0, s37
	s_nop 0
	global_load_lds_dwordx4 v[26:27], off
	s_waitcnt vmcnt(10)
	s_barrier
	s_waitcnt lgkmcnt(0)
	v_mfma_f32_16x16x32_f16 v[52:55], v[184:187], v[22:25], v[52:55]
	v_mfma_f32_16x16x32_f16 v[22:25], v[192:195], v[22:25], v[40:43]
	v_mfma_f32_16x16x32_f16 v[40:43], v[184:187], v[168:171], v[144:147]
	v_mfma_f32_16x16x32_f16 v[52:55], v[188:191], v[88:91], v[52:55]
	v_mfma_f32_16x16x32_f16 v[22:25], v[196:199], v[88:91], v[22:25]
	v_mfma_f32_16x16x32_f16 v[88:91], v[188:191], v[172:175], v[40:43]
	v_mfma_f32_16x16x32_f16 v[40:43], v[192:195], v[168:171], v[124:127]
	v_mfma_f32_16x16x32_f16 v[36:39], v[184:187], v[108:111], v[36:39]
	v_mfma_f32_16x16x32_f16 v[26:29], v[192:195], v[108:111], v[28:31]
	v_mfma_f32_16x16x32_f16 v[108:111], v[196:199], v[172:175], v[40:43]
	v_mfma_f32_16x16x32_f16 v[40:43], v[184:187], v[176:179], v[120:123]
	v_mfma_f32_16x16x32_f16 v[120:123], v[188:191], v[180:183], v[40:43]
	v_mfma_f32_16x16x32_f16 v[40:43], v[192:195], v[176:179], v[116:119]
	v_mfma_f32_16x16x32_f16 v[36:39], v[188:191], v[164:167], v[36:39]
	v_mfma_f32_16x16x32_f16 v[26:29], v[196:199], v[164:167], v[26:29]
	v_mfma_f32_16x16x32_f16 v[116:119], v[196:199], v[180:183], v[40:43]
	s_mov_b32 m0, s7
	v_lshl_add_u64 v[30:31], v[246:247], 0, s[30:31]
	s_barrier
	s_nop 0
	ds_read_b128 v[40:43], v236 offset:16384
	ds_read_b128 v[124:127], v236 offset:17408
	ds_read_b128 v[144:147], v236 offset:18432
	ds_read_b128 v[164:167], v236 offset:19456
	ds_read_b128 v[168:171], v236 offset:20480
	ds_read_b128 v[172:175], v236 offset:21504
	ds_read_b128 v[176:179], v236 offset:22528
	ds_read_b128 v[180:183], v236 offset:23552
	global_load_lds_dwordx4 v[30:31], off
	v_lshl_add_u64 v[30:31], v[248:249], 0, s[30:31]
	s_mov_b32 m0, s8
	s_nop 0
	global_load_lds_dwordx4 v[30:31], off
	s_barrier
	s_waitcnt lgkmcnt(0)
	v_mfma_f32_16x16x32_f16 v[112:115], v[6:9], v[40:43], v[112:115]
	v_mfma_f32_16x16x32_f16 v[104:107], v[14:17], v[40:43], v[104:107]
	v_mfma_f32_16x16x32_f16 v[100:103], v[6:9], v[144:147], v[100:103]
	v_mfma_f32_16x16x32_f16 v[96:99], v[14:17], v[144:147], v[96:99]
	v_mfma_f32_16x16x32_f16 v[140:143], v[6:9], v[168:171], v[140:143]
	v_mfma_f32_16x16x32_f16 v[136:139], v[14:17], v[168:171], v[136:139]
	v_mfma_f32_16x16x32_f16 v[6:9], v[6:9], v[176:179], v[132:135]
	v_mfma_f32_16x16x32_f16 v[112:115], v[10:13], v[124:127], v[112:115]
	v_mfma_f32_16x16x32_f16 v[104:107], v[18:21], v[124:127], v[104:107]
	v_mfma_f32_16x16x32_f16 v[100:103], v[10:13], v[164:167], v[100:103]
	v_mfma_f32_16x16x32_f16 v[96:99], v[18:21], v[164:167], v[96:99]
	v_mfma_f32_16x16x32_f16 v[140:143], v[10:13], v[172:175], v[140:143]
	v_mfma_f32_16x16x32_f16 v[136:139], v[18:21], v[172:175], v[136:139]
	v_mfma_f32_16x16x32_f16 v[6:9], v[10:13], v[180:183], v[6:9]
	v_mfma_f32_16x16x32_f16 v[10:13], v[14:17], v[176:179], v[128:131]
	v_mfma_f32_16x16x32_f16 v[10:13], v[18:21], v[180:183], v[10:13]
	s_barrier
	s_mov_b32 m0, s63
	v_lshl_add_u64 v[14:15], v[224:225], 0, s[84:85]
	global_load_lds_dwordx4 v[14:15], off
	v_lshl_add_u64 v[14:15], v[226:227], 0, s[84:85]
	s_mov_b32 m0, s68
	s_nop 0
	global_load_lds_dwordx4 v[14:15], off
	s_waitcnt vmcnt(8)
	s_barrier
	v_mfma_f32_16x16x32_f16 v[14:17], v[184:187], v[40:43], v[92:95]
	v_mfma_f32_16x16x32_f16 v[18:21], v[192:195], v[40:43], v[84:87]
	v_mfma_f32_16x16x32_f16 v[40:43], v[184:187], v[144:147], v[76:79]
	v_mfma_f32_16x16x32_f16 v[76:79], v[188:191], v[164:167], v[40:43]
	v_mfma_f32_16x16x32_f16 v[40:43], v[192:195], v[144:147], v[64:67]
	v_mfma_f32_16x16x32_f16 v[64:67], v[196:199], v[164:167], v[40:43]
	v_mfma_f32_16x16x32_f16 v[40:43], v[184:187], v[168:171], v[60:63]
	v_mfma_f32_16x16x32_f16 v[60:63], v[188:191], v[172:175], v[40:43]
	v_mfma_f32_16x16x32_f16 v[40:43], v[192:195], v[168:171], v[48:51]
	v_mfma_f32_16x16x32_f16 v[48:51], v[196:199], v[172:175], v[40:43]
	v_mfma_f32_16x16x32_f16 v[30:33], v[184:187], v[176:179], v[32:35]
	v_mfma_f32_16x16x32_f16 v[40:43], v[192:195], v[176:179], v[44:47]
	v_mfma_f32_16x16x32_f16 v[32:35], v[188:191], v[180:183], v[30:33]
	v_mfma_f32_16x16x32_f16 v[44:47], v[196:199], v[180:183], v[40:43]
	v_mfma_f32_16x16x32_f16 v[14:17], v[188:191], v[124:127], v[14:17]
	v_mfma_f32_16x16x32_f16 v[18:21], v[196:199], v[124:127], v[18:21]
	s_barrier
	ds_read_b128 v[84:87], v239
	ds_read_b128 v[92:95], v239 offset:1024
	ds_read_b128 v[128:131], v239 offset:2048
	ds_read_b128 v[164:167], v239 offset:3072
	s_mov_b32 m0, s9
	v_lshl_add_u64 v[30:31], v[246:247], 0, s[84:85]
	ds_read_b128 v[40:43], v236 offset:32768
	ds_read_b128 v[124:127], v236 offset:33792
	ds_read_b128 v[132:135], v236 offset:34816
	ds_read_b128 v[144:147], v236 offset:35840
	ds_read_b128 v[168:171], v236 offset:36864
	ds_read_b128 v[172:175], v236 offset:37888
	ds_read_b128 v[176:179], v236 offset:38912
	ds_read_b128 v[180:183], v236 offset:39936
	global_load_lds_dwordx4 v[30:31], off
	v_lshl_add_u64 v[30:31], v[248:249], 0, s[84:85]
	s_mov_b32 m0, s12
	s_nop 0
	global_load_lds_dwordx4 v[30:31], off
	s_barrier
	s_waitcnt lgkmcnt(0)
	v_mfma_f32_16x16x32_f16 v[80:83], v[84:87], v[40:43], v[80:83]
	v_mfma_f32_16x16x32_f16 v[72:75], v[128:131], v[40:43], v[72:75]
	v_mfma_f32_16x16x32_f16 v[56:59], v[84:87], v[132:135], v[56:59]
	v_mfma_f32_16x16x32_f16 v[68:71], v[128:131], v[132:135], v[68:71]
	v_mfma_f32_16x16x32_f16 v[160:163], v[84:87], v[168:171], v[160:163]
	v_mfma_f32_16x16x32_f16 v[156:159], v[128:131], v[168:171], v[156:159]
	v_mfma_f32_16x16x32_f16 v[152:155], v[84:87], v[176:179], v[152:155]
	v_mfma_f32_16x16x32_f16 v[148:151], v[128:131], v[176:179], v[148:151]
	v_mfma_f32_16x16x32_f16 v[80:83], v[92:95], v[124:127], v[80:83]
	v_mfma_f32_16x16x32_f16 v[72:75], v[164:167], v[124:127], v[72:75]
	v_mfma_f32_16x16x32_f16 v[56:59], v[92:95], v[144:147], v[56:59]
	v_mfma_f32_16x16x32_f16 v[68:71], v[164:167], v[144:147], v[68:71]
	v_mfma_f32_16x16x32_f16 v[160:163], v[92:95], v[172:175], v[160:163]
	v_mfma_f32_16x16x32_f16 v[156:159], v[164:167], v[172:175], v[156:159]
	v_mfma_f32_16x16x32_f16 v[152:155], v[92:95], v[180:183], v[152:155]
	v_mfma_f32_16x16x32_f16 v[148:151], v[164:167], v[180:183], v[148:151]
	s_barrier
	s_mov_b32 m0, s69
	v_lshl_add_u64 v[30:31], v[224:225], 0, vcc
	ds_read_b128 v[184:187], v240
	ds_read_b128 v[188:191], v240 offset:1024
	ds_read_b128 v[192:195], v240 offset:2048
	ds_read_b128 v[196:199], v240 offset:3072
	global_load_lds_dwordx4 v[30:31], off
	v_lshl_add_u64 v[30:31], v[226:227], 0, vcc
	s_mov_b32 m0, s70
	s_nop 0
	global_load_lds_dwordx4 v[30:31], off
	s_waitcnt vmcnt(10)
	s_barrier
	s_waitcnt lgkmcnt(0)
	v_mfma_f32_16x16x32_f16 v[22:25], v[192:195], v[40:43], v[22:25]
	v_mfma_f32_16x16x32_f16 v[52:55], v[184:187], v[40:43], v[52:55]
	v_mfma_f32_16x16x32_f16 v[40:43], v[196:199], v[124:127], v[22:25]
	v_mfma_f32_16x16x32_f16 v[22:25], v[184:187], v[132:135], v[36:39]
	v_mfma_f32_16x16x32_f16 v[36:39], v[188:191], v[144:147], v[22:25]
	v_mfma_f32_16x16x32_f16 v[22:25], v[192:195], v[132:135], v[26:29]
	v_mfma_f32_16x16x32_f16 v[28:31], v[196:199], v[144:147], v[22:25]
	v_mfma_f32_16x16x32_f16 v[22:25], v[184:187], v[168:171], v[88:91]
	v_mfma_f32_16x16x32_f16 v[144:147], v[188:191], v[172:175], v[22:25]
	v_mfma_f32_16x16x32_f16 v[22:25], v[192:195], v[168:171], v[108:111]
	v_mfma_f32_16x16x32_f16 v[52:55], v[188:191], v[124:127], v[52:55]
	v_mfma_f32_16x16x32_f16 v[124:127], v[196:199], v[172:175], v[22:25]
	v_mfma_f32_16x16x32_f16 v[22:25], v[184:187], v[176:179], v[120:123]
	v_mfma_f32_16x16x32_f16 v[120:123], v[188:191], v[180:183], v[22:25]
	v_mfma_f32_16x16x32_f16 v[22:25], v[192:195], v[176:179], v[116:119]
	v_mfma_f32_16x16x32_f16 v[116:119], v[196:199], v[180:183], v[22:25]
	s_mov_b32 m0, s39
	v_lshl_add_u64 v[26:27], v[246:247], 0, vcc
	s_barrier
	s_nop 2
	ds_read_b128 v[22:25], v236 offset:49152
	ds_read_b128 v[88:91], v236 offset:50176
	ds_read_b128 v[108:111], v236 offset:51200
	ds_read_b128 v[168:171], v236 offset:52224
	ds_read_b128 v[172:175], v236 offset:53248
	ds_read_b128 v[176:179], v236 offset:54272
	ds_read_b128 v[180:183], v236 offset:55296
	ds_read_b128 v[242:245], v236 offset:56320
	global_load_lds_dwordx4 v[26:27], off
	v_lshl_add_u64 v[26:27], v[248:249], 0, vcc
	s_mov_b32 m0, s47
	s_nop 0
	global_load_lds_dwordx4 v[26:27], off
	s_barrier
	s_waitcnt lgkmcnt(0)
	v_mfma_f32_16x16x32_f16 v[132:135], v[84:87], v[172:175], v[140:143]
	v_mfma_f32_16x16x32_f16 v[140:143], v[92:95], v[176:179], v[132:135]
	v_mfma_f32_16x16x32_f16 v[132:135], v[128:131], v[172:175], v[136:139]
	v_mfma_f32_16x16x32_f16 v[6:9], v[84:87], v[180:183], v[6:9]
	v_mfma_f32_16x16x32_f16 v[112:115], v[84:87], v[22:25], v[112:115]
	v_mfma_f32_16x16x32_f16 v[104:107], v[128:131], v[22:25], v[104:107]
	v_mfma_f32_16x16x32_f16 v[100:103], v[84:87], v[108:111], v[100:103]
	v_mfma_f32_16x16x32_f16 v[96:99], v[128:131], v[108:111], v[96:99]
	v_mfma_f32_16x16x32_f16 v[136:139], v[164:167], v[176:179], v[132:135]
	v_mfma_f32_16x16x32_f16 v[132:135], v[92:95], v[242:245], v[6:9]
	v_mfma_f32_16x16x32_f16 v[6:9], v[128:131], v[180:183], v[10:13]
	v_mfma_f32_16x16x32_f16 v[112:115], v[92:95], v[88:91], v[112:115]
	v_mfma_f32_16x16x32_f16 v[104:107], v[164:167], v[88:91], v[104:107]
	v_mfma_f32_16x16x32_f16 v[100:103], v[92:95], v[168:171], v[100:103]
	v_mfma_f32_16x16x32_f16 v[96:99], v[164:167], v[168:171], v[96:99]
	v_mfma_f32_16x16x32_f16 v[128:131], v[164:167], v[242:245], v[6:9]
	s_barrier
	s_mov_b32 m0, s71
	v_lshl_add_u64 v[6:7], v[224:225], 0, s[52:53]
	global_load_lds_dwordx4 v[6:7], off
	v_lshl_add_u64 v[6:7], v[226:227], 0, s[52:53]
	s_mov_b32 m0, s76
	s_nop 0
	global_load_lds_dwordx4 v[6:7], off
	s_waitcnt vmcnt(8)
	s_barrier
	v_mfma_f32_16x16x32_f16 v[6:9], v[184:187], v[22:25], v[14:17]
	v_mfma_f32_16x16x32_f16 v[92:95], v[188:191], v[88:91], v[6:9]
	v_mfma_f32_16x16x32_f16 v[6:9], v[192:195], v[22:25], v[18:21]
	v_mfma_f32_16x16x32_f16 v[84:87], v[196:199], v[88:91], v[6:9]
	v_mfma_f32_16x16x32_f16 v[6:9], v[184:187], v[108:111], v[76:79]
	v_mfma_f32_16x16x32_f16 v[76:79], v[188:191], v[168:171], v[6:9]
	v_mfma_f32_16x16x32_f16 v[6:9], v[192:195], v[108:111], v[64:67]
	v_mfma_f32_16x16x32_f16 v[64:67], v[196:199], v[168:171], v[6:9]
	v_mfma_f32_16x16x32_f16 v[6:9], v[184:187], v[172:175], v[60:63]
	v_mfma_f32_16x16x32_f16 v[60:63], v[188:191], v[176:179], v[6:9]
	v_mfma_f32_16x16x32_f16 v[6:9], v[192:195], v[172:175], v[48:51]
	v_mfma_f32_16x16x32_f16 v[48:51], v[196:199], v[176:179], v[6:9]
	v_mfma_f32_16x16x32_f16 v[6:9], v[184:187], v[180:183], v[32:35]
	v_mfma_f32_16x16x32_f16 v[32:35], v[188:191], v[242:245], v[6:9]
	v_mfma_f32_16x16x32_f16 v[6:9], v[192:195], v[180:183], v[44:47]
	v_mfma_f32_16x16x32_f16 v[44:47], v[196:199], v[242:245], v[6:9]
	s_add_i32 s10, s10, 2
	s_add_u32 s16, s16, 0x100
	s_addc_u32 s17, s17, 0
	s_cmp_lt_u32 s10, 14
	s_barrier
	s_cbranch_scc1 .LBB0_1744
	s_add_i32 s10, s46, 8
	s_mul_hi_i32 s11, s10, 0x42
	s_mulk_i32 s10, 0x42
	s_add_u32 s10, s10, s48
	v_mov_b32_e32 v4, v233
	v_mov_b32_e32 v5, v234
	s_addc_u32 s11, s11, s78
	s_lshl_b64 s[10:11], s[10:11], 17
	v_readlane_b32 s16, v252, 45
	v_lshlrev_b32_e32 v5, 3, v5
	s_add_u32 s16, s16, s10
	v_readlane_b32 s10, v252, 46
	v_lshlrev_b32_e32 v4, 8, v4
	s_addc_u32 s17, s10, s11
	v_add3_u32 v196, v4, s49, v5
	s_add_u32 s26, s16, 0x4200000
	v_ashrrev_i32_e32 v197, 31, v196
	s_addc_u32 s27, s17, 0
	v_lshlrev_b64 v[4:5], 1, v[196:197]
	v_lshl_add_u64 v[6:7], s[16:17], 0, v[4:5]
	v_lshl_add_u64 v[12:13], s[26:27], 0, v[4:5]
	v_add_u32_e32 v4, 0x1000, v196
	v_ashrrev_i32_e32 v5, 31, v4
	v_lshlrev_b64 v[4:5], 1, v[4:5]
	v_lshl_add_u64 v[14:15], s[16:17], 0, v[4:5]
	v_lshl_add_u64 v[20:21], s[26:27], 0, v[4:5]
	v_add_u32_e32 v4, 0x1080, v196
	v_ashrrev_i32_e32 v5, 31, v4
	v_lshlrev_b64 v[4:5], 1, v[4:5]
	v_lshl_add_u64 v[22:23], s[16:17], 0, v[4:5]
	v_lshl_add_u64 v[26:27], s[26:27], 0, v[4:5]
	v_add_u32_e32 v4, 0x2000, v196
	v_ashrrev_i32_e32 v5, 31, v4
	v_lshlrev_b64 v[4:5], 1, v[4:5]
	v_lshl_add_u64 v[24:25], s[16:17], 0, v[4:5]
	v_lshl_add_u64 v[168:169], s[26:27], 0, v[4:5]
	v_add_u32_e32 v4, 0x2080, v196
	v_ashrrev_i32_e32 v5, 31, v4
	v_lshlrev_b64 v[4:5], 1, v[4:5]
	v_lshl_add_u64 v[16:17], s[16:17], 0, v[4:5]
	v_lshl_add_u64 v[170:171], s[26:27], 0, v[4:5]
	v_add_u32_e32 v4, 0x3000, v196
	v_ashrrev_i32_e32 v5, 31, v4
	v_lshlrev_b64 v[4:5], 1, v[4:5]
	v_lshl_add_u64 v[8:9], s[16:17], 0, v[4:5]
	v_lshl_add_u64 v[176:177], s[26:27], 0, v[4:5]
	v_add_u32_e32 v4, 0x3080, v196
	v_ashrrev_i32_e32 v5, 31, v4
	v_lshlrev_b64 v[4:5], 1, v[4:5]
	v_lshl_add_u64 v[10:11], s[16:17], 0, v[4:5]
	v_lshl_add_u64 v[164:165], s[26:27], 0, v[4:5]
	global_load_dwordx4 v[192:195], v[6:7], off offset:256
	global_load_dwordx4 v[108:111], v[6:7], off
	s_nop 0
	global_load_dwordx4 v[4:7], v[10:11], off
	s_nop 0
	global_load_dwordx4 v[8:11], v[8:9], off
	s_nop 0
	global_load_dwordx4 v[16:19], v[16:17], off
	s_nop 0
	global_load_dwordx4 v[172:175], v[24:25], off
	global_load_dwordx4 v[180:183], v[22:23], off
	global_load_dwordx4 v[188:191], v[14:15], off
	global_load_dwordx4 v[88:91], v[12:13], off offset:256
	global_load_dwordx4 v[198:201], v[12:13], off
	s_nop 0
	global_load_dwordx4 v[164:167], v[164:165], off
	s_nop 0
	global_load_dwordx4 v[12:15], v[176:177], off
	global_load_dwordx4 v[22:25], v[170:171], off
	s_nop 0
	global_load_dwordx4 v[168:171], v[168:169], off
	s_nop 0
	global_load_dwordx4 v[176:179], v[26:27], off
	global_load_dwordx4 v[184:187], v[20:21], off
	s_mov_b32 s29, 14
	s_waitcnt vmcnt(0)
	s_nop 0
	v_cvt_f32_f16_e32 v21, v110
	v_cvt_f32_f16_e32 v20, v108
	v_rcp_f32_e32 v26, v21
	v_cvt_f32_f16_sdwa v21, v108 dst_sel:DWORD dst_unused:UNUSED_PAD src0_sel:WORD_1
	v_rcp_f32_e32 v20, v20
	v_cvt_f32_f16_e32 v202, v198
	v_cvt_f32_f16_sdwa v203, v198 dst_sel:DWORD dst_unused:UNUSED_PAD src0_sel:WORD_1
	v_rcp_f32_e32 v21, v21
	v_cvt_f32_f16_sdwa v27, v110 dst_sel:DWORD dst_unused:UNUSED_PAD src0_sel:WORD_1
	v_cvt_f32_f16_e32 v110, v111
	v_cvt_f32_f16_e32 v108, v109
	v_pk_mul_f32 v[20:21], v[20:21], v[202:203]
	v_cvt_f32_f16_sdwa v109, v109 dst_sel:DWORD dst_unused:UNUSED_PAD src0_sel:WORD_1
	v_pk_mul_f32 v[80:81], v[80:81], v[20:21]
	v_cvt_f32_f16_sdwa v20, v111 dst_sel:DWORD dst_unused:UNUSED_PAD src0_sel:WORD_1
	v_rcp_f32_e32 v110, v110
	v_cvt_f32_f16_sdwa v21, v201 dst_sel:DWORD dst_unused:UNUSED_PAD src0_sel:WORD_1
	v_rcp_f32_e32 v27, v27
	v_rcp_f32_e32 v111, v20
	v_cvt_f32_f16_e32 v20, v201
	v_cvt_f32_f16_e32 v220, v200
	v_cvt_f32_f16_sdwa v221, v200 dst_sel:DWORD dst_unused:UNUSED_PAD src0_sel:WORD_1
	v_rcp_f32_e32 v108, v108
	v_rcp_f32_e32 v109, v109
	v_cvt_f32_f16_e32 v198, v199
	v_cvt_f32_f16_sdwa v199, v199 dst_sel:DWORD dst_unused:UNUSED_PAD src0_sel:WORD_1
	v_pk_mul_f32 v[20:21], v[110:111], v[20:21]
	v_pk_mul_f32 v[26:27], v[26:27], v[220:221]
	v_pk_mul_f32 v[110:111], v[74:75], v[20:21]
	v_cvt_f32_f16_e32 v21, v194
	v_cvt_f32_f16_e32 v75, v195
	v_pk_mul_f32 v[108:109], v[108:109], v[198:199]
	v_cvt_f32_f16_e32 v20, v192
	v_pk_mul_f32 v[82:83], v[82:83], v[108:109]
	v_pk_mul_f32 v[108:109], v[72:73], v[26:27]
	v_rcp_f32_e32 v26, v21
	v_cvt_f32_f16_sdwa v21, v192 dst_sel:DWORD dst_unused:UNUSED_PAD src0_sel:WORD_1
	v_cvt_f32_f16_e32 v72, v88
	v_cvt_f32_f16_sdwa v73, v88 dst_sel:DWORD dst_unused:UNUSED_PAD src0_sel:WORD_1
	v_cvt_f32_f16_e32 v74, v193
	v_rcp_f32_e32 v88, v75
	v_cvt_f32_f16_sdwa v75, v193 dst_sel:DWORD dst_unused:UNUSED_PAD src0_sel:WORD_1
	v_rcp_f32_e32 v20, v20
	v_rcp_f32_e32 v21, v21
	v_rcp_f32_e32 v74, v74
	v_rcp_f32_e32 v75, v75
	v_cvt_f32_f16_e32 v192, v89
	v_cvt_f32_f16_sdwa v193, v89 dst_sel:DWORD dst_unused:UNUSED_PAD src0_sel:WORD_1
	v_pk_mul_f32 v[20:21], v[20:21], v[72:73]
	v_cvt_f32_f16_sdwa v27, v194 dst_sel:DWORD dst_unused:UNUSED_PAD src0_sel:WORD_1
	v_cvt_f32_f16_e32 v198, v90
	v_pk_mul_f32 v[72:73], v[74:75], v[192:193]
	v_cvt_f32_f16_sdwa v199, v90 dst_sel:DWORD dst_unused:UNUSED_PAD src0_sel:WORD_1
	v_pk_mul_f32 v[74:75], v[54:55], v[72:73]
	v_pk_mul_f32 v[72:73], v[52:53], v[20:21]
	v_cvt_f32_f16_sdwa v20, v195 dst_sel:DWORD dst_unused:UNUSED_PAD src0_sel:WORD_1
	v_cvt_f32_f16_sdwa v21, v91 dst_sel:DWORD dst_unused:UNUSED_PAD src0_sel:WORD_1
	v_rcp_f32_e32 v27, v27
	v_cvt_f32_f16_e32 v53, v191
	v_rcp_f32_e32 v89, v20
	v_cvt_f32_f16_e32 v20, v91
	v_pk_mul_f32 v[26:27], v[26:27], v[198:199]
	v_rcp_f32_e32 v54, v53
	v_cvt_f32_f16_e32 v52, v189
	v_pk_mul_f32 v[20:21], v[88:89], v[20:21]
	v_pk_mul_f32 v[88:89], v[40:41], v[26:27]
	v_pk_mul_f32 v[90:91], v[42:43], v[20:21]
	v_cvt_f32_f16_e32 v21, v190
	v_cvt_f32_f16_e32 v20, v188
	v_cvt_f32_f16_e32 v40, v184
	v_cvt_f32_f16_sdwa v41, v184 dst_sel:DWORD dst_unused:UNUSED_PAD src0_sel:WORD_1
	v_rcp_f32_e32 v26, v21
	v_cvt_f32_f16_sdwa v21, v188 dst_sel:DWORD dst_unused:UNUSED_PAD src0_sel:WORD_1
	v_rcp_f32_e32 v20, v20
	v_cvt_f32_f16_sdwa v27, v190 dst_sel:DWORD dst_unused:UNUSED_PAD src0_sel:WORD_1
	v_cvt_f32_f16_e32 v42, v186
	v_rcp_f32_e32 v21, v21
	v_cvt_f32_f16_sdwa v43, v186 dst_sel:DWORD dst_unused:UNUSED_PAD src0_sel:WORD_1
	v_rcp_f32_e32 v27, v27
	v_cvt_f32_f16_sdwa v53, v189 dst_sel:DWORD dst_unused:UNUSED_PAD src0_sel:WORD_1
	v_pk_mul_f32 v[20:21], v[20:21], v[40:41]
	v_rcp_f32_e32 v52, v52
	v_pk_mul_f32 v[56:57], v[56:57], v[20:21]
	v_cvt_f32_f16_sdwa v20, v191 dst_sel:DWORD dst_unused:UNUSED_PAD src0_sel:WORD_1
	v_cvt_f32_f16_sdwa v21, v187 dst_sel:DWORD dst_unused:UNUSED_PAD src0_sel:WORD_1
	v_pk_mul_f32 v[26:27], v[26:27], v[42:43]
	v_cvt_f32_f16_e32 v43, v183
	v_rcp_f32_e32 v55, v20
	v_cvt_f32_f16_e32 v20, v187
	v_rcp_f32_e32 v53, v53
	v_cvt_f32_f16_e32 v184, v185
	v_cvt_f32_f16_sdwa v185, v185 dst_sel:DWORD dst_unused:UNUSED_PAD src0_sel:WORD_1
	v_pk_mul_f32 v[20:21], v[54:55], v[20:21]
	v_pk_mul_f32 v[68:69], v[68:69], v[26:27]
	v_pk_mul_f32 v[70:71], v[70:71], v[20:21]
	v_cvt_f32_f16_e32 v21, v182
	v_cvt_f32_f16_e32 v20, v180
	v_cvt_f32_f16_e32 v42, v181
	v_rcp_f32_e32 v54, v43
	v_rcp_f32_e32 v26, v21
	v_cvt_f32_f16_sdwa v21, v180 dst_sel:DWORD dst_unused:UNUSED_PAD src0_sel:WORD_1
	v_cvt_f32_f16_sdwa v43, v181 dst_sel:DWORD dst_unused:UNUSED_PAD src0_sel:WORD_1
	v_pk_mul_f32 v[40:41], v[52:53], v[184:185]
	v_rcp_f32_e32 v20, v20
	v_pk_mul_f32 v[58:59], v[58:59], v[40:41]
	v_rcp_f32_e32 v21, v21
	v_cvt_f32_f16_e32 v40, v176
	v_cvt_f32_f16_sdwa v41, v176 dst_sel:DWORD dst_unused:UNUSED_PAD src0_sel:WORD_1
	v_rcp_f32_e32 v42, v42
	v_rcp_f32_e32 v43, v43
	v_cvt_f32_f16_e32 v176, v177
	v_cvt_f32_f16_sdwa v177, v177 dst_sel:DWORD dst_unused:UNUSED_PAD src0_sel:WORD_1
	v_pk_mul_f32 v[20:21], v[20:21], v[40:41]
	v_cvt_f32_f16_sdwa v27, v182 dst_sel:DWORD dst_unused:UNUSED_PAD src0_sel:WORD_1
	v_cvt_f32_f16_e32 v52, v178
	v_pk_mul_f32 v[40:41], v[42:43], v[176:177]
	v_cvt_f32_f16_sdwa v53, v178 dst_sel:DWORD dst_unused:UNUSED_PAD src0_sel:WORD_1
	v_pk_mul_f32 v[42:43], v[38:39], v[40:41]
	v_pk_mul_f32 v[40:41], v[36:37], v[20:21]
	v_cvt_f32_f16_sdwa v20, v183 dst_sel:DWORD dst_unused:UNUSED_PAD src0_sel:WORD_1
	v_cvt_f32_f16_sdwa v21, v179 dst_sel:DWORD dst_unused:UNUSED_PAD src0_sel:WORD_1
	v_rcp_f32_e32 v27, v27
	v_cvt_f32_f16_e32 v36, v170
	v_rcp_f32_e32 v55, v20
	v_cvt_f32_f16_e32 v20, v179
	v_pk_mul_f32 v[26:27], v[26:27], v[52:53]
	v_cvt_f32_f16_sdwa v37, v170 dst_sel:DWORD dst_unused:UNUSED_PAD src0_sel:WORD_1
	v_pk_mul_f32 v[52:53], v[28:29], v[26:27]
	v_pk_mul_f32 v[20:21], v[54:55], v[20:21]
	v_cvt_f32_f16_e32 v28, v168
	v_pk_mul_f32 v[54:55], v[30:31], v[20:21]
	v_cvt_f32_f16_e32 v21, v174
	v_cvt_f32_f16_e32 v31, v175
	v_cvt_f32_f16_e32 v20, v172
	v_cvt_f32_f16_e32 v30, v173
	v_rcp_f32_e32 v26, v21
	v_cvt_f32_f16_sdwa v21, v172 dst_sel:DWORD dst_unused:UNUSED_PAD src0_sel:WORD_1
	v_rcp_f32_e32 v38, v31
	v_cvt_f32_f16_sdwa v31, v173 dst_sel:DWORD dst_unused:UNUSED_PAD src0_sel:WORD_1
	v_rcp_f32_e32 v20, v20
	v_rcp_f32_e32 v21, v21
	v_cvt_f32_f16_sdwa v29, v168 dst_sel:DWORD dst_unused:UNUSED_PAD src0_sel:WORD_1
	v_rcp_f32_e32 v30, v30
	v_rcp_f32_e32 v31, v31
	v_cvt_f32_f16_e32 v168, v169
	v_cvt_f32_f16_sdwa v169, v169 dst_sel:DWORD dst_unused:UNUSED_PAD src0_sel:WORD_1
	v_pk_mul_f32 v[20:21], v[20:21], v[28:29]
	v_cvt_f32_f16_sdwa v27, v174 dst_sel:DWORD dst_unused:UNUSED_PAD src0_sel:WORD_1
	v_pk_mul_f32 v[28:29], v[30:31], v[168:169]
	v_rcp_f32_e32 v27, v27
	v_pk_mul_f32 v[30:31], v[162:163], v[28:29]
	v_pk_mul_f32 v[28:29], v[160:161], v[20:21]
	v_cvt_f32_f16_sdwa v20, v175 dst_sel:DWORD dst_unused:UNUSED_PAD src0_sel:WORD_1
	v_cvt_f32_f16_sdwa v21, v171 dst_sel:DWORD dst_unused:UNUSED_PAD src0_sel:WORD_1
	v_pk_mul_f32 v[26:27], v[26:27], v[36:37]
	v_rcp_f32_e32 v39, v20
	v_cvt_f32_f16_e32 v20, v171
	v_pk_mul_f32 v[36:37], v[156:157], v[26:27]
	v_cvt_f32_f16_e32 v156, v22
	v_cvt_f32_f16_sdwa v157, v22 dst_sel:DWORD dst_unused:UNUSED_PAD src0_sel:WORD_1
	v_pk_mul_f32 v[20:21], v[38:39], v[20:21]
	v_cvt_f32_f16_e32 v22, v23
	v_pk_mul_f32 v[38:39], v[158:159], v[20:21]
	v_cvt_f32_f16_e32 v20, v16
	v_cvt_f32_f16_e32 v21, v18
	v_cvt_f32_f16_sdwa v16, v16 dst_sel:DWORD dst_unused:UNUSED_PAD src0_sel:WORD_1
	v_cvt_f32_f16_sdwa v23, v23 dst_sel:DWORD dst_unused:UNUSED_PAD src0_sel:WORD_1
	v_cvt_f32_f16_e32 v158, v24
	v_rcp_f32_e32 v26, v21
	v_rcp_f32_e32 v21, v16
	v_cvt_f32_f16_sdwa v16, v18 dst_sel:DWORD dst_unused:UNUSED_PAD src0_sel:WORD_1
	v_cvt_f32_f16_e32 v18, v19
	v_cvt_f32_f16_sdwa v159, v24 dst_sel:DWORD dst_unused:UNUSED_PAD src0_sel:WORD_1
	v_rcp_f32_e32 v20, v20
	v_rcp_f32_e32 v27, v16
	v_cvt_f32_f16_e32 v16, v17
	v_cvt_f32_f16_sdwa v17, v17 dst_sel:DWORD dst_unused:UNUSED_PAD src0_sel:WORD_1
	v_rcp_f32_e32 v18, v18
	v_pk_mul_f32 v[20:21], v[20:21], v[156:157]
	v_rcp_f32_e32 v16, v16
	v_rcp_f32_e32 v17, v17
	v_pk_mul_f32 v[20:21], v[144:145], v[20:21]
	v_cvt_f32_f16_e32 v144, v165
	v_cvt_f32_f16_sdwa v145, v165 dst_sel:DWORD dst_unused:UNUSED_PAD src0_sel:WORD_1
	v_pk_mul_f32 v[16:17], v[16:17], v[22:23]
	s_nop 0
	v_pk_mul_f32 v[22:23], v[146:147], v[16:17]
	v_cvt_f32_f16_sdwa v16, v19 dst_sel:DWORD dst_unused:UNUSED_PAD src0_sel:WORD_1
	v_cvt_f32_f16_sdwa v17, v25 dst_sel:DWORD dst_unused:UNUSED_PAD src0_sel:WORD_1
	v_rcp_f32_e32 v19, v16
	v_cvt_f32_f16_e32 v16, v25
	v_pk_mul_f32 v[24:25], v[26:27], v[158:159]
	v_pk_mul_f32 v[16:17], v[18:19], v[16:17]
	s_nop 0
	v_pk_mul_f32 v[26:27], v[126:127], v[16:17]
	v_cvt_f32_f16_e32 v16, v8
	v_cvt_f32_f16_e32 v17, v10
	v_cvt_f32_f16_sdwa v8, v8 dst_sel:DWORD dst_unused:UNUSED_PAD src0_sel:WORD_1
	v_pk_mul_f32 v[24:25], v[124:125], v[24:25]
	v_cvt_f32_f16_e32 v18, v12
	v_rcp_f32_e32 v124, v17
	v_rcp_f32_e32 v17, v8
	v_cvt_f32_f16_sdwa v8, v10 dst_sel:DWORD dst_unused:UNUSED_PAD src0_sel:WORD_1
	v_cvt_f32_f16_sdwa v19, v12 dst_sel:DWORD dst_unused:UNUSED_PAD src0_sel:WORD_1
	v_cvt_f32_f16_e32 v12, v13
	v_cvt_f32_f16_sdwa v13, v13 dst_sel:DWORD dst_unused:UNUSED_PAD src0_sel:WORD_1
	v_rcp_f32_e32 v125, v8
	v_cvt_f32_f16_e32 v8, v9
	v_cvt_f32_f16_sdwa v9, v9 dst_sel:DWORD dst_unused:UNUSED_PAD src0_sel:WORD_1
	v_rcp_f32_e32 v16, v16
	v_cvt_f32_f16_e32 v10, v11
	v_rcp_f32_e32 v8, v8
	v_rcp_f32_e32 v9, v9
	v_pk_mul_f32 v[16:17], v[16:17], v[18:19]
	v_rcp_f32_e32 v10, v10
	v_cvt_f32_f16_e32 v126, v14
	v_pk_mul_f32 v[8:9], v[8:9], v[12:13]
	v_cvt_f32_f16_sdwa v127, v14 dst_sel:DWORD dst_unused:UNUSED_PAD src0_sel:WORD_1
	v_pk_mul_f32 v[18:19], v[154:155], v[8:9]
	v_cvt_f32_f16_sdwa v8, v11 dst_sel:DWORD dst_unused:UNUSED_PAD src0_sel:WORD_1
	v_cvt_f32_f16_sdwa v9, v15 dst_sel:DWORD dst_unused:UNUSED_PAD src0_sel:WORD_1
	v_pk_mul_f32 v[12:13], v[124:125], v[126:127]
	v_cvt_f32_f16_e32 v126, v166
	v_rcp_f32_e32 v11, v8
	v_cvt_f32_f16_e32 v8, v15
	v_cvt_f32_f16_sdwa v127, v166 dst_sel:DWORD dst_unused:UNUSED_PAD src0_sel:WORD_1
	v_pk_mul_f32 v[16:17], v[152:153], v[16:17]
	v_pk_mul_f32 v[12:13], v[148:149], v[12:13]
	v_pk_mul_f32 v[8:9], v[10:11], v[8:9]
	v_cvt_f32_f16_e32 v10, v164
	v_pk_mul_f32 v[14:15], v[150:151], v[8:9]
	v_cvt_f32_f16_e32 v8, v4
	v_cvt_f32_f16_e32 v9, v6
	v_cvt_f32_f16_sdwa v4, v4 dst_sel:DWORD dst_unused:UNUSED_PAD src0_sel:WORD_1
	v_cvt_f32_f16_sdwa v11, v164 dst_sel:DWORD dst_unused:UNUSED_PAD src0_sel:WORD_1
	v_rcp_f32_e32 v8, v8
	v_rcp_f32_e32 v124, v9
	v_rcp_f32_e32 v9, v4
	v_cvt_f32_f16_sdwa v4, v6 dst_sel:DWORD dst_unused:UNUSED_PAD src0_sel:WORD_1
	v_cvt_f32_f16_e32 v6, v7
	v_pk_mul_f32 v[8:9], v[8:9], v[10:11]
	v_rcp_f32_e32 v125, v4
	v_cvt_f32_f16_e32 v4, v5
	v_cvt_f32_f16_sdwa v5, v5 dst_sel:DWORD dst_unused:UNUSED_PAD src0_sel:WORD_1
	v_rcp_f32_e32 v6, v6
	v_pk_mul_f32 v[8:9], v[120:121], v[8:9]
	v_rcp_f32_e32 v4, v4
	v_rcp_f32_e32 v5, v5
	v_pk_mul_f32 v[120:121], v[124:125], v[126:127]
	v_pk_mul_f32 v[4:5], v[4:5], v[144:145]
	s_nop 0
	v_pk_mul_f32 v[10:11], v[122:123], v[4:5]
	v_cvt_f32_f16_sdwa v4, v7 dst_sel:DWORD dst_unused:UNUSED_PAD src0_sel:WORD_1
	v_cvt_f32_f16_sdwa v5, v167 dst_sel:DWORD dst_unused:UNUSED_PAD src0_sel:WORD_1
	v_rcp_f32_e32 v7, v4
	v_cvt_f32_f16_e32 v4, v167
	v_pk_mul_f32 v[4:5], v[6:7], v[4:5]
	s_nop 0
	v_pk_mul_f32 v[6:7], v[118:119], v[4:5]
	v_add_u32_e32 v118, 0x8080, v196
	v_ashrrev_i32_e32 v119, 31, v118
	v_lshlrev_b64 v[118:119], 1, v[118:119]
	v_pk_mul_f32 v[4:5], v[116:117], v[120:121]
	v_lshl_add_u64 v[120:121], s[16:17], 0, v[118:119]
	v_lshl_add_u64 v[124:125], s[26:27], 0, v[118:119]
	v_add_u32_e32 v118, 0x9000, v196
	v_ashrrev_i32_e32 v119, 31, v118
	v_lshlrev_b64 v[118:119], 1, v[118:119]
	v_lshl_add_u64 v[126:127], s[16:17], 0, v[118:119]
	v_lshl_add_u64 v[192:193], s[26:27], 0, v[118:119]
	v_add_u32_e32 v118, 0x9080, v196
	v_ashrrev_i32_e32 v119, 31, v118
	v_lshlrev_b64 v[118:119], 1, v[118:119]
	v_lshl_add_u64 v[144:145], s[16:17], 0, v[118:119]
	v_lshl_add_u64 v[184:185], s[26:27], 0, v[118:119]
	v_add_u32_e32 v118, 0xa000, v196
	v_ashrrev_i32_e32 v119, 31, v118
	v_lshlrev_b64 v[118:119], 1, v[118:119]
	v_lshl_add_u64 v[146:147], s[16:17], 0, v[118:119]
	v_lshl_add_u64 v[176:177], s[26:27], 0, v[118:119]
	v_add_u32_e32 v118, 0xa080, v196
	v_ashrrev_i32_e32 v119, 31, v118
	v_lshlrev_b64 v[118:119], 1, v[118:119]
	v_lshl_add_u64 v[152:153], s[16:17], 0, v[118:119]
	v_lshl_add_u64 v[168:169], s[26:27], 0, v[118:119]
	v_add_u32_e32 v118, 0xb000, v196
	v_ashrrev_i32_e32 v119, 31, v118
	v_lshlrev_b64 v[118:119], 1, v[118:119]
	v_lshl_add_u64 v[154:155], s[16:17], 0, v[118:119]
	v_lshl_add_u64 v[160:161], s[26:27], 0, v[118:119]
	v_add_u32_e32 v118, 0xb080, v196
	v_add_u32_e32 v116, 0x8000, v196
	v_ashrrev_i32_e32 v119, 31, v118
	v_ashrrev_i32_e32 v117, 31, v116
	v_lshlrev_b64 v[118:119], 1, v[118:119]
	v_lshlrev_b64 v[116:117], 1, v[116:117]
	v_lshl_add_u64 v[148:149], s[16:17], 0, v[118:119]
	v_lshl_add_u64 v[162:163], s[26:27], 0, v[118:119]
	v_lshl_add_u64 v[122:123], s[16:17], 0, v[116:117]
	v_lshl_add_u64 v[116:117], s[26:27], 0, v[116:117]
	global_load_dwordx4 v[148:151], v[148:149], off
	s_nop 0
	global_load_dwordx4 v[156:159], v[154:155], off
	global_load_dwordx4 v[164:167], v[152:153], off
	global_load_dwordx4 v[172:175], v[146:147], off
	global_load_dwordx4 v[180:183], v[144:145], off
	global_load_dwordx4 v[188:191], v[126:127], off
	s_nop 0
	global_load_dwordx4 v[118:121], v[120:121], off
	s_nop 0
	global_load_dwordx4 v[144:147], v[122:123], off
	global_load_dwordx4 v[152:155], v[162:163], off
	s_nop 0
	global_load_dwordx4 v[160:163], v[160:161], off
	s_nop 0
	global_load_dwordx4 v[168:171], v[168:169], off
	s_nop 0
	global_load_dwordx4 v[176:179], v[176:177], off
	s_nop 0
	global_load_dwordx4 v[184:187], v[184:185], off
	s_nop 0
	global_load_dwordx4 v[192:195], v[192:193], off
	s_nop 0
	global_load_dwordx4 v[196:199], v[124:125], off
	global_load_dwordx4 v[200:203], v[116:117], off
	s_waitcnt vmcnt(0)
	s_nop 0
	v_cvt_f32_f16_e32 v117, v146
	v_cvt_f32_f16_e32 v127, v147
	v_cvt_f32_f16_e32 v116, v144
	v_cvt_f32_f16_e32 v126, v145
	v_rcp_f32_e32 v122, v117
	v_cvt_f32_f16_sdwa v117, v144 dst_sel:DWORD dst_unused:UNUSED_PAD src0_sel:WORD_1
	v_rcp_f32_e32 v144, v127
	v_cvt_f32_f16_sdwa v127, v145 dst_sel:DWORD dst_unused:UNUSED_PAD src0_sel:WORD_1
	v_rcp_f32_e32 v116, v116
	v_rcp_f32_e32 v117, v117
	v_cvt_f32_f16_e32 v124, v200
	v_cvt_f32_f16_sdwa v125, v200 dst_sel:DWORD dst_unused:UNUSED_PAD src0_sel:WORD_1
	v_rcp_f32_e32 v126, v126
	v_rcp_f32_e32 v127, v127
	v_cvt_f32_f16_e32 v200, v201
	v_cvt_f32_f16_sdwa v201, v201 dst_sel:DWORD dst_unused:UNUSED_PAD src0_sel:WORD_1
	v_cvt_f32_f16_sdwa v123, v146 dst_sel:DWORD dst_unused:UNUSED_PAD src0_sel:WORD_1
	v_pk_mul_f32 v[116:117], v[116:117], v[124:125]
	v_cvt_f32_f16_e32 v220, v202
	v_pk_mul_f32 v[124:125], v[126:127], v[200:201]
	v_rcp_f32_e32 v123, v123
	v_pk_mul_f32 v[126:127], v[114:115], v[124:125]
	v_pk_mul_f32 v[124:125], v[112:113], v[116:117]
	v_cvt_f32_f16_sdwa v112, v147 dst_sel:DWORD dst_unused:UNUSED_PAD src0_sel:WORD_1
	v_cvt_f32_f16_sdwa v221, v202 dst_sel:DWORD dst_unused:UNUSED_PAD src0_sel:WORD_1
	v_cvt_f32_f16_sdwa v113, v203 dst_sel:DWORD dst_unused:UNUSED_PAD src0_sel:WORD_1
	v_cvt_f32_f16_e32 v117, v121
	v_rcp_f32_e32 v145, v112
	v_cvt_f32_f16_e32 v112, v203
	v_pk_mul_f32 v[114:115], v[122:123], v[220:221]
	v_cvt_f32_f16_e32 v116, v119
	s_add_u32 s16, s34, 0x80880
	v_pk_mul_f32 v[112:113], v[144:145], v[112:113]
	v_pk_mul_f32 v[144:145], v[104:105], v[114:115]
	v_cvt_f32_f16_e32 v105, v120
	v_pk_mul_f32 v[146:147], v[106:107], v[112:113]
	v_cvt_f32_f16_e32 v104, v118
	v_cvt_f32_f16_sdwa v107, v120 dst_sel:DWORD dst_unused:UNUSED_PAD src0_sel:WORD_1
	v_rcp_f32_e32 v106, v105
	v_cvt_f32_f16_sdwa v105, v118 dst_sel:DWORD dst_unused:UNUSED_PAD src0_sel:WORD_1
	v_rcp_f32_e32 v120, v117
	v_cvt_f32_f16_sdwa v117, v119 dst_sel:DWORD dst_unused:UNUSED_PAD src0_sel:WORD_1
	v_rcp_f32_e32 v104, v104
	v_rcp_f32_e32 v105, v105
	v_cvt_f32_f16_e32 v112, v196
	v_cvt_f32_f16_sdwa v113, v196 dst_sel:DWORD dst_unused:UNUSED_PAD src0_sel:WORD_1
	v_rcp_f32_e32 v116, v116
	v_rcp_f32_e32 v117, v117
	v_cvt_f32_f16_e32 v118, v197
	v_cvt_f32_f16_sdwa v119, v197 dst_sel:DWORD dst_unused:UNUSED_PAD src0_sel:WORD_1
	v_pk_mul_f32 v[104:105], v[104:105], v[112:113]
	v_rcp_f32_e32 v107, v107
	v_cvt_f32_f16_e32 v114, v198
	v_pk_mul_f32 v[112:113], v[116:117], v[118:119]
	v_pk_mul_f32 v[116:117], v[92:93], v[104:105]
	v_cvt_f32_f16_sdwa v92, v121 dst_sel:DWORD dst_unused:UNUSED_PAD src0_sel:WORD_1
	v_cvt_f32_f16_sdwa v115, v198 dst_sel:DWORD dst_unused:UNUSED_PAD src0_sel:WORD_1
	v_cvt_f32_f16_sdwa v93, v199 dst_sel:DWORD dst_unused:UNUSED_PAD src0_sel:WORD_1
	v_pk_mul_f32 v[118:119], v[94:95], v[112:113]
	v_rcp_f32_e32 v121, v92
	v_cvt_f32_f16_e32 v92, v199
	v_pk_mul_f32 v[94:95], v[106:107], v[114:115]
	v_cvt_f32_f16_e32 v105, v191
	v_cvt_f32_f16_e32 v104, v189
	v_pk_mul_f32 v[92:93], v[120:121], v[92:93]
	v_pk_mul_f32 v[120:121], v[84:85], v[94:95]
	v_cvt_f32_f16_e32 v85, v190
	v_pk_mul_f32 v[122:123], v[86:87], v[92:93]
	v_cvt_f32_f16_e32 v84, v188
	v_rcp_f32_e32 v112, v105
	v_rcp_f32_e32 v86, v85
	v_cvt_f32_f16_sdwa v85, v188 dst_sel:DWORD dst_unused:UNUSED_PAD src0_sel:WORD_1
	v_cvt_f32_f16_sdwa v105, v189 dst_sel:DWORD dst_unused:UNUSED_PAD src0_sel:WORD_1
	v_rcp_f32_e32 v84, v84
	v_cvt_f32_f16_e32 v92, v192
	v_rcp_f32_e32 v85, v85
	v_cvt_f32_f16_sdwa v93, v192 dst_sel:DWORD dst_unused:UNUSED_PAD src0_sel:WORD_1
	v_rcp_f32_e32 v104, v104
	v_rcp_f32_e32 v105, v105
	v_cvt_f32_f16_e32 v106, v193
	v_cvt_f32_f16_sdwa v107, v193 dst_sel:DWORD dst_unused:UNUSED_PAD src0_sel:WORD_1
	v_pk_mul_f32 v[84:85], v[84:85], v[92:93]
	v_cvt_f32_f16_sdwa v87, v190 dst_sel:DWORD dst_unused:UNUSED_PAD src0_sel:WORD_1
	v_cvt_f32_f16_e32 v94, v194
	v_pk_mul_f32 v[92:93], v[104:105], v[106:107]
	v_pk_mul_f32 v[104:105], v[100:101], v[84:85]
	v_cvt_f32_f16_sdwa v84, v191 dst_sel:DWORD dst_unused:UNUSED_PAD src0_sel:WORD_1
	v_cvt_f32_f16_sdwa v85, v195 dst_sel:DWORD dst_unused:UNUSED_PAD src0_sel:WORD_1
	v_rcp_f32_e32 v87, v87
	v_cvt_f32_f16_sdwa v95, v194 dst_sel:DWORD dst_unused:UNUSED_PAD src0_sel:WORD_1
	v_rcp_f32_e32 v113, v84
	v_cvt_f32_f16_e32 v84, v195
	v_pk_mul_f32 v[106:107], v[102:103], v[92:93]
	v_pk_mul_f32 v[86:87], v[86:87], v[94:95]
	v_cvt_f32_f16_e32 v92, v184
	v_pk_mul_f32 v[84:85], v[112:113], v[84:85]
	v_pk_mul_f32 v[112:113], v[96:97], v[86:87]
	v_pk_mul_f32 v[114:115], v[98:99], v[84:85]
	v_cvt_f32_f16_e32 v85, v182
	v_cvt_f32_f16_e32 v97, v183
	v_cvt_f32_f16_e32 v84, v180
	v_cvt_f32_f16_e32 v96, v181
	v_rcp_f32_e32 v86, v85
	v_cvt_f32_f16_sdwa v85, v180 dst_sel:DWORD dst_unused:UNUSED_PAD src0_sel:WORD_1
	v_rcp_f32_e32 v100, v97
	v_cvt_f32_f16_sdwa v97, v181 dst_sel:DWORD dst_unused:UNUSED_PAD src0_sel:WORD_1
	v_rcp_f32_e32 v84, v84
	v_rcp_f32_e32 v85, v85
	v_cvt_f32_f16_sdwa v93, v184 dst_sel:DWORD dst_unused:UNUSED_PAD src0_sel:WORD_1
	v_rcp_f32_e32 v96, v96
	v_rcp_f32_e32 v97, v97
	v_cvt_f32_f16_e32 v98, v185
	v_cvt_f32_f16_sdwa v99, v185 dst_sel:DWORD dst_unused:UNUSED_PAD src0_sel:WORD_1
	v_cvt_f32_f16_sdwa v87, v182 dst_sel:DWORD dst_unused:UNUSED_PAD src0_sel:WORD_1
	v_pk_mul_f32 v[84:85], v[84:85], v[92:93]
	v_cvt_f32_f16_e32 v94, v186
	v_pk_mul_f32 v[92:93], v[96:97], v[98:99]
	v_pk_mul_f32 v[96:97], v[76:77], v[84:85]
	v_cvt_f32_f16_sdwa v76, v183 dst_sel:DWORD dst_unused:UNUSED_PAD src0_sel:WORD_1
	v_rcp_f32_e32 v87, v87
	v_cvt_f32_f16_sdwa v95, v186 dst_sel:DWORD dst_unused:UNUSED_PAD src0_sel:WORD_1
	v_cvt_f32_f16_sdwa v77, v187 dst_sel:DWORD dst_unused:UNUSED_PAD src0_sel:WORD_1
	v_rcp_f32_e32 v101, v76
	v_cvt_f32_f16_e32 v76, v187
	v_pk_mul_f32 v[98:99], v[78:79], v[92:93]
	v_pk_mul_f32 v[78:79], v[86:87], v[94:95]
	v_cvt_f32_f16_e32 v85, v175
	v_pk_mul_f32 v[76:77], v[100:101], v[76:77]
	v_pk_mul_f32 v[100:101], v[64:65], v[78:79]
	v_cvt_f32_f16_e32 v65, v174
	v_pk_mul_f32 v[102:103], v[66:67], v[76:77]
	v_cvt_f32_f16_e32 v64, v172
	v_cvt_f32_f16_e32 v84, v173
	v_rcp_f32_e32 v66, v65
	v_cvt_f32_f16_sdwa v65, v172 dst_sel:DWORD dst_unused:UNUSED_PAD src0_sel:WORD_1
	v_rcp_f32_e32 v92, v85
	v_cvt_f32_f16_sdwa v85, v173 dst_sel:DWORD dst_unused:UNUSED_PAD src0_sel:WORD_1
	v_rcp_f32_e32 v64, v64
	v_rcp_f32_e32 v65, v65
	v_cvt_f32_f16_e32 v76, v176
	v_cvt_f32_f16_sdwa v77, v176 dst_sel:DWORD dst_unused:UNUSED_PAD src0_sel:WORD_1
	v_rcp_f32_e32 v84, v84
	v_rcp_f32_e32 v85, v85
	v_cvt_f32_f16_e32 v86, v177
	v_cvt_f32_f16_sdwa v87, v177 dst_sel:DWORD dst_unused:UNUSED_PAD src0_sel:WORD_1
	v_pk_mul_f32 v[64:65], v[64:65], v[76:77]
	v_cvt_f32_f16_sdwa v67, v174 dst_sel:DWORD dst_unused:UNUSED_PAD src0_sel:WORD_1
	v_cvt_f32_f16_e32 v78, v178
	v_pk_mul_f32 v[76:77], v[84:85], v[86:87]
	v_pk_mul_f32 v[84:85], v[140:141], v[64:65]
	v_cvt_f32_f16_sdwa v64, v175 dst_sel:DWORD dst_unused:UNUSED_PAD src0_sel:WORD_1
	v_cvt_f32_f16_sdwa v65, v179 dst_sel:DWORD dst_unused:UNUSED_PAD src0_sel:WORD_1
	v_rcp_f32_e32 v67, v67
	v_cvt_f32_f16_sdwa v79, v178 dst_sel:DWORD dst_unused:UNUSED_PAD src0_sel:WORD_1
	v_rcp_f32_e32 v93, v64
	v_cvt_f32_f16_e32 v64, v179
	v_pk_mul_f32 v[86:87], v[142:143], v[76:77]
	v_pk_mul_f32 v[66:67], v[66:67], v[78:79]
	v_cvt_f32_f16_sdwa v77, v166 dst_sel:DWORD dst_unused:UNUSED_PAD src0_sel:WORD_1
	v_pk_mul_f32 v[64:65], v[92:93], v[64:65]
	v_pk_mul_f32 v[92:93], v[136:137], v[66:67]
	v_pk_mul_f32 v[94:95], v[138:139], v[64:65]
	v_cvt_f32_f16_e32 v65, v166
	v_cvt_f32_f16_e32 v64, v164
	v_cvt_f32_f16_e32 v137, v167
	v_cvt_f32_f16_e32 v66, v168
	v_rcp_f32_e32 v76, v65
	v_cvt_f32_f16_sdwa v65, v164 dst_sel:DWORD dst_unused:UNUSED_PAD src0_sel:WORD_1
	v_rcp_f32_e32 v64, v64
	v_cvt_f32_f16_sdwa v67, v168 dst_sel:DWORD dst_unused:UNUSED_PAD src0_sel:WORD_1
	v_cvt_f32_f16_e32 v136, v165
	v_rcp_f32_e32 v65, v65
	v_rcp_f32_e32 v138, v137
	v_cvt_f32_f16_sdwa v137, v165 dst_sel:DWORD dst_unused:UNUSED_PAD src0_sel:WORD_1
	v_rcp_f32_e32 v136, v136
	v_cvt_f32_f16_e32 v140, v169
	v_cvt_f32_f16_sdwa v141, v169 dst_sel:DWORD dst_unused:UNUSED_PAD src0_sel:WORD_1
	v_rcp_f32_e32 v137, v137
	v_pk_mul_f32 v[64:65], v[64:65], v[66:67]
	v_rcp_f32_e32 v77, v77
	v_cvt_f32_f16_e32 v78, v170
	v_cvt_f32_f16_sdwa v79, v170 dst_sel:DWORD dst_unused:UNUSED_PAD src0_sel:WORD_1
	v_pk_mul_f32 v[64:65], v[60:61], v[64:65]
	v_cvt_f32_f16_sdwa v60, v167 dst_sel:DWORD dst_unused:UNUSED_PAD src0_sel:WORD_1
	v_pk_mul_f32 v[66:67], v[136:137], v[140:141]
	v_cvt_f32_f16_sdwa v61, v171 dst_sel:DWORD dst_unused:UNUSED_PAD src0_sel:WORD_1
	v_pk_mul_f32 v[66:67], v[62:63], v[66:67]
	v_rcp_f32_e32 v139, v60
	v_cvt_f32_f16_e32 v60, v171
	v_pk_mul_f32 v[62:63], v[76:77], v[78:79]
	v_cvt_f32_f16_e32 v137, v159
	v_pk_mul_f32 v[76:77], v[48:49], v[62:63]
	v_cvt_f32_f16_e32 v49, v158
	v_pk_mul_f32 v[60:61], v[138:139], v[60:61]
	v_cvt_f32_f16_e32 v48, v156
	v_pk_mul_f32 v[78:79], v[50:51], v[60:61]
	v_rcp_f32_e32 v60, v49
	v_cvt_f32_f16_sdwa v49, v156 dst_sel:DWORD dst_unused:UNUSED_PAD src0_sel:WORD_1
	v_rcp_f32_e32 v48, v48
	v_cvt_f32_f16_e32 v50, v160
	v_cvt_f32_f16_sdwa v51, v160 dst_sel:DWORD dst_unused:UNUSED_PAD src0_sel:WORD_1
	v_rcp_f32_e32 v49, v49
	v_cvt_f32_f16_sdwa v61, v158 dst_sel:DWORD dst_unused:UNUSED_PAD src0_sel:WORD_1
	v_cvt_f32_f16_e32 v62, v162
	v_cvt_f32_f16_sdwa v63, v162 dst_sel:DWORD dst_unused:UNUSED_PAD src0_sel:WORD_1
	v_pk_mul_f32 v[48:49], v[48:49], v[50:51]
	v_rcp_f32_e32 v61, v61
	v_pk_mul_f32 v[48:49], v[132:133], v[48:49]
	v_cvt_f32_f16_sdwa v132, v159 dst_sel:DWORD dst_unused:UNUSED_PAD src0_sel:WORD_1
	v_rcp_f32_e32 v138, v137
	v_cvt_f32_f16_sdwa v133, v163 dst_sel:DWORD dst_unused:UNUSED_PAD src0_sel:WORD_1
	v_pk_mul_f32 v[60:61], v[60:61], v[62:63]
	v_rcp_f32_e32 v139, v132
	v_cvt_f32_f16_e32 v132, v163
	v_pk_mul_f32 v[60:61], v[128:129], v[60:61]
	v_cvt_f32_f16_e32 v129, v150
	v_cvt_f32_f16_e32 v136, v157
	v_cvt_f32_f16_sdwa v137, v157 dst_sel:DWORD dst_unused:UNUSED_PAD src0_sel:WORD_1
	v_pk_mul_f32 v[62:63], v[138:139], v[132:133]
	v_cvt_f32_f16_e32 v128, v148
	v_pk_mul_f32 v[62:63], v[130:131], v[62:63]
	v_rcp_f32_e32 v130, v129
	v_cvt_f32_f16_sdwa v129, v148 dst_sel:DWORD dst_unused:UNUSED_PAD src0_sel:WORD_1
	v_rcp_f32_e32 v136, v136
	v_rcp_f32_e32 v137, v137
	v_cvt_f32_f16_e32 v140, v161
	v_cvt_f32_f16_sdwa v141, v161 dst_sel:DWORD dst_unused:UNUSED_PAD src0_sel:WORD_1
	v_rcp_f32_e32 v128, v128
	v_rcp_f32_e32 v129, v129
	v_cvt_f32_f16_e32 v132, v152
	v_cvt_f32_f16_sdwa v133, v152 dst_sel:DWORD dst_unused:UNUSED_PAD src0_sel:WORD_1
	v_pk_mul_f32 v[50:51], v[136:137], v[140:141]
	v_cvt_f32_f16_e32 v137, v151
	v_cvt_f32_f16_sdwa v131, v150 dst_sel:DWORD dst_unused:UNUSED_PAD src0_sel:WORD_1
	v_pk_mul_f32 v[128:129], v[128:129], v[132:133]
	v_cvt_f32_f16_e32 v136, v149
	v_rcp_f32_e32 v138, v137
	v_cvt_f32_f16_sdwa v137, v149 dst_sel:DWORD dst_unused:UNUSED_PAD src0_sel:WORD_1
	v_pk_mul_f32 v[32:33], v[32:33], v[128:129]
	v_cvt_f32_f16_sdwa v128, v151 dst_sel:DWORD dst_unused:UNUSED_PAD src0_sel:WORD_1
	v_pk_mul_f32 v[50:51], v[134:135], v[50:51]
	v_rcp_f32_e32 v131, v131
	v_cvt_f32_f16_e32 v134, v154
	v_cvt_f32_f16_sdwa v135, v154 dst_sel:DWORD dst_unused:UNUSED_PAD src0_sel:WORD_1
	v_rcp_f32_e32 v136, v136
	v_rcp_f32_e32 v137, v137
	v_cvt_f32_f16_e32 v140, v153
	v_cvt_f32_f16_sdwa v141, v153 dst_sel:DWORD dst_unused:UNUSED_PAD src0_sel:WORD_1
	v_rcp_f32_e32 v139, v128
	v_cvt_f32_f16_e32 v128, v155
	v_cvt_f32_f16_sdwa v129, v155 dst_sel:DWORD dst_unused:UNUSED_PAD src0_sel:WORD_1
	s_addc_u32 s17, s35, 0
	v_pk_mul_f32 v[132:133], v[136:137], v[140:141]
	v_pk_mul_f32 v[130:131], v[130:131], v[134:135]
	v_pk_mul_f32 v[128:129], v[138:139], v[128:129]
	s_add_u32 s10, s50, 0x900
	v_pk_mul_f32 v[34:35], v[34:35], v[132:133]
	v_pk_mul_f32 v[46:47], v[46:47], v[128:129]
	v_pk_mul_f32 v[44:45], v[44:45], v[130:131]
	s_addc_u32 s11, s51, 0
.LBB0_1746:
	ds_read_b128 v[128:131], v237
	ds_read_b128 v[132:135], v237 offset:1024
	ds_read_b128 v[136:139], v237 offset:2048
	ds_read_b128 v[140:143], v237 offset:3072
	s_add_u32 s26, s16, 0xfff80080
	s_addc_u32 s27, s17, -1
	s_cmp_eq_u32 s29, 28
	s_cselect_b32 s35, s43, s27
	s_cselect_b32 s34, s42, s26
	s_cselect_b32 s27, s45, s11
	s_cselect_b32 s26, s44, s10
	s_mov_b32 m0, s14
	v_lshl_add_u64 v[180:181], s[16:17], 0, v[210:211]
	ds_read_b128 v[148:151], v236
	ds_read_b128 v[152:155], v236 offset:1024
	ds_read_b128 v[156:159], v236 offset:2048
	ds_read_b128 v[160:163], v236 offset:3072
	ds_read_b128 v[164:167], v236 offset:4096
	ds_read_b128 v[168:171], v236 offset:5120
	ds_read_b128 v[172:175], v236 offset:6144
	ds_read_b128 v[176:179], v236 offset:7168
	global_load_lds_dwordx4 v[180:181], off
	v_lshl_add_u64 v[180:181], s[16:17], 0, v[214:215]
	s_mov_b32 m0, s15
	s_nop 0
	global_load_lds_dwordx4 v[180:181], off
	s_barrier
	s_waitcnt lgkmcnt(0)
	v_mfma_f32_16x16x32_f16 v[80:83], v[128:131], v[148:151], v[80:83]
	v_mfma_f32_16x16x32_f16 v[108:111], v[136:139], v[148:151], v[108:111]
	v_mfma_f32_16x16x32_f16 v[56:59], v[128:131], v[156:159], v[56:59]
	v_mfma_f32_16x16x32_f16 v[68:71], v[136:139], v[156:159], v[68:71]
	v_mfma_f32_16x16x32_f16 v[28:31], v[128:131], v[164:167], v[28:31]
	v_mfma_f32_16x16x32_f16 v[36:39], v[136:139], v[164:167], v[36:39]
	v_mfma_f32_16x16x32_f16 v[16:19], v[128:131], v[172:175], v[16:19]
	v_mfma_f32_16x16x32_f16 v[12:15], v[136:139], v[172:175], v[12:15]
	v_mfma_f32_16x16x32_f16 v[80:83], v[132:135], v[152:155], v[80:83]
	v_mfma_f32_16x16x32_f16 v[108:111], v[140:143], v[152:155], v[108:111]
	v_mfma_f32_16x16x32_f16 v[56:59], v[132:135], v[160:163], v[56:59]
	v_mfma_f32_16x16x32_f16 v[68:71], v[140:143], v[160:163], v[68:71]
	v_mfma_f32_16x16x32_f16 v[28:31], v[132:135], v[168:171], v[28:31]
	v_mfma_f32_16x16x32_f16 v[36:39], v[140:143], v[168:171], v[36:39]
	v_mfma_f32_16x16x32_f16 v[16:19], v[132:135], v[176:179], v[16:19]
	v_mfma_f32_16x16x32_f16 v[12:15], v[140:143], v[176:179], v[12:15]
	s_barrier
	s_mov_b32 m0, s19
	v_lshl_add_u64 v[196:197], s[26:27], 0, v[2:3]
	ds_read_b128 v[180:183], v238
	ds_read_b128 v[184:187], v238 offset:1024
	ds_read_b128 v[188:191], v238 offset:2048
	ds_read_b128 v[192:195], v238 offset:3072
	global_load_lds_dwordx4 v[196:197], off
	v_lshl_add_u64 v[198:199], s[26:27], 0, v[206:207]
	s_mov_b32 m0, s37
	s_nop 0
	global_load_lds_dwordx4 v[198:199], off
	s_waitcnt vmcnt(10)
	s_barrier
	s_waitcnt lgkmcnt(0)
	v_mfma_f32_16x16x32_f16 v[72:75], v[180:183], v[148:151], v[72:75]
	v_mfma_f32_16x16x32_f16 v[88:91], v[188:191], v[148:151], v[88:91]
	v_mfma_f32_16x16x32_f16 v[40:43], v[180:183], v[156:159], v[40:43]
	v_mfma_f32_16x16x32_f16 v[52:55], v[188:191], v[156:159], v[52:55]
	v_mfma_f32_16x16x32_f16 v[20:23], v[180:183], v[164:167], v[20:23]
	v_mfma_f32_16x16x32_f16 v[24:27], v[188:191], v[164:167], v[24:27]
	v_mfma_f32_16x16x32_f16 v[8:11], v[180:183], v[172:175], v[8:11]
	v_mfma_f32_16x16x32_f16 v[4:7], v[188:191], v[172:175], v[4:7]
	v_mfma_f32_16x16x32_f16 v[72:75], v[184:187], v[152:155], v[72:75]
	v_mfma_f32_16x16x32_f16 v[88:91], v[192:195], v[152:155], v[88:91]
	v_mfma_f32_16x16x32_f16 v[40:43], v[184:187], v[160:163], v[40:43]
	v_mfma_f32_16x16x32_f16 v[52:55], v[192:195], v[160:163], v[52:55]
	v_mfma_f32_16x16x32_f16 v[20:23], v[184:187], v[168:171], v[20:23]
	v_mfma_f32_16x16x32_f16 v[24:27], v[192:195], v[168:171], v[24:27]
	v_mfma_f32_16x16x32_f16 v[8:11], v[184:187], v[176:179], v[8:11]
	v_mfma_f32_16x16x32_f16 v[4:7], v[192:195], v[176:179], v[4:7]
	s_mov_b32 m0, s7
	v_lshl_add_u64 v[200:201], s[34:35], 0, v[210:211]
	s_barrier
	ds_read_b128 v[148:151], v236 offset:16384
	ds_read_b128 v[152:155], v236 offset:17408
	ds_read_b128 v[156:159], v236 offset:18432
	ds_read_b128 v[160:163], v236 offset:19456
	ds_read_b128 v[164:167], v236 offset:20480
	ds_read_b128 v[168:171], v236 offset:21504
	ds_read_b128 v[172:175], v236 offset:22528
	ds_read_b128 v[176:179], v236 offset:23552
	global_load_lds_dwordx4 v[200:201], off
	v_lshl_add_u64 v[202:203], s[34:35], 0, v[208:209]
	s_mov_b32 m0, s8
	s_nop 0
	global_load_lds_dwordx4 v[202:203], off
	s_barrier
	s_waitcnt lgkmcnt(0)
	v_mfma_f32_16x16x32_f16 v[124:127], v[128:131], v[148:151], v[124:127]
	v_mfma_f32_16x16x32_f16 v[144:147], v[136:139], v[148:151], v[144:147]
	v_mfma_f32_16x16x32_f16 v[104:107], v[128:131], v[156:159], v[104:107]
	v_mfma_f32_16x16x32_f16 v[112:115], v[136:139], v[156:159], v[112:115]
	v_mfma_f32_16x16x32_f16 v[84:87], v[128:131], v[164:167], v[84:87]
	v_mfma_f32_16x16x32_f16 v[92:95], v[136:139], v[164:167], v[92:95]
	v_mfma_f32_16x16x32_f16 v[48:51], v[128:131], v[172:175], v[48:51]
	v_mfma_f32_16x16x32_f16 v[60:63], v[136:139], v[172:175], v[60:63]
	v_mfma_f32_16x16x32_f16 v[124:127], v[132:135], v[152:155], v[124:127]
	v_mfma_f32_16x16x32_f16 v[144:147], v[140:143], v[152:155], v[144:147]
	v_mfma_f32_16x16x32_f16 v[104:107], v[132:135], v[160:163], v[104:107]
	v_mfma_f32_16x16x32_f16 v[112:115], v[140:143], v[160:163], v[112:115]
	v_mfma_f32_16x16x32_f16 v[84:87], v[132:135], v[168:171], v[84:87]
	v_mfma_f32_16x16x32_f16 v[92:95], v[140:143], v[168:171], v[92:95]
	v_mfma_f32_16x16x32_f16 v[48:51], v[132:135], v[176:179], v[48:51]
	v_mfma_f32_16x16x32_f16 v[60:63], v[140:143], v[176:179], v[60:63]
	s_barrier
	s_add_u32 s30, s26, 0x80000
	s_addc_u32 s31, s27, 0
	s_mov_b32 m0, s63
	v_lshl_add_u64 v[128:129], s[30:31], 0, v[2:3]
	global_load_lds_dwordx4 v[128:129], off
	v_lshl_add_u64 v[128:129], s[30:31], 0, v[206:207]
	s_mov_b32 m0, s68
	s_nop 0
	global_load_lds_dwordx4 v[128:129], off
	s_waitcnt vmcnt(8)
	s_barrier
	v_mfma_f32_16x16x32_f16 v[116:119], v[180:183], v[148:151], v[116:119]
	v_mfma_f32_16x16x32_f16 v[120:123], v[188:191], v[148:151], v[120:123]
	v_mfma_f32_16x16x32_f16 v[96:99], v[180:183], v[156:159], v[96:99]
	v_mfma_f32_16x16x32_f16 v[100:103], v[188:191], v[156:159], v[100:103]
	v_mfma_f32_16x16x32_f16 v[64:67], v[180:183], v[164:167], v[64:67]
	v_mfma_f32_16x16x32_f16 v[76:79], v[188:191], v[164:167], v[76:79]
	v_mfma_f32_16x16x32_f16 v[32:35], v[180:183], v[172:175], v[32:35]
	v_mfma_f32_16x16x32_f16 v[44:47], v[188:191], v[172:175], v[44:47]
	v_mfma_f32_16x16x32_f16 v[116:119], v[184:187], v[152:155], v[116:119]
	v_mfma_f32_16x16x32_f16 v[120:123], v[192:195], v[152:155], v[120:123]
	v_mfma_f32_16x16x32_f16 v[96:99], v[184:187], v[160:163], v[96:99]
	v_mfma_f32_16x16x32_f16 v[100:103], v[192:195], v[160:163], v[100:103]
	v_mfma_f32_16x16x32_f16 v[64:67], v[184:187], v[168:171], v[64:67]
	v_mfma_f32_16x16x32_f16 v[76:79], v[192:195], v[168:171], v[76:79]
	v_mfma_f32_16x16x32_f16 v[32:35], v[184:187], v[176:179], v[32:35]
	v_mfma_f32_16x16x32_f16 v[44:47], v[192:195], v[176:179], v[44:47]
	s_barrier
	ds_read_b128 v[128:131], v239
	ds_read_b128 v[132:135], v239 offset:1024
	ds_read_b128 v[136:139], v239 offset:2048
	ds_read_b128 v[140:143], v239 offset:3072
	s_add_u32 s30, s34, 0x80000
	s_addc_u32 s31, s35, 0
	s_mov_b32 m0, s9
	v_lshl_add_u64 v[180:181], s[30:31], 0, v[210:211]
	ds_read_b128 v[148:151], v236 offset:32768
	ds_read_b128 v[152:155], v236 offset:33792
	ds_read_b128 v[156:159], v236 offset:34816
	ds_read_b128 v[160:163], v236 offset:35840
	ds_read_b128 v[164:167], v236 offset:36864
	ds_read_b128 v[168:171], v236 offset:37888
	ds_read_b128 v[172:175], v236 offset:38912
	ds_read_b128 v[176:179], v236 offset:39936
	global_load_lds_dwordx4 v[180:181], off
	v_lshl_add_u64 v[180:181], s[30:31], 0, v[208:209]
	s_mov_b32 m0, s12
	s_nop 0
	global_load_lds_dwordx4 v[180:181], off
	s_barrier
	s_waitcnt lgkmcnt(0)
	v_mfma_f32_16x16x32_f16 v[80:83], v[128:131], v[148:151], v[80:83]
	v_mfma_f32_16x16x32_f16 v[108:111], v[136:139], v[148:151], v[108:111]
	v_mfma_f32_16x16x32_f16 v[56:59], v[128:131], v[156:159], v[56:59]
	v_mfma_f32_16x16x32_f16 v[68:71], v[136:139], v[156:159], v[68:71]
	v_mfma_f32_16x16x32_f16 v[28:31], v[128:131], v[164:167], v[28:31]
	v_mfma_f32_16x16x32_f16 v[36:39], v[136:139], v[164:167], v[36:39]
	v_mfma_f32_16x16x32_f16 v[16:19], v[128:131], v[172:175], v[16:19]
	v_mfma_f32_16x16x32_f16 v[12:15], v[136:139], v[172:175], v[12:15]
	v_mfma_f32_16x16x32_f16 v[80:83], v[132:135], v[152:155], v[80:83]
	v_mfma_f32_16x16x32_f16 v[108:111], v[140:143], v[152:155], v[108:111]
	v_mfma_f32_16x16x32_f16 v[56:59], v[132:135], v[160:163], v[56:59]
	v_mfma_f32_16x16x32_f16 v[68:71], v[140:143], v[160:163], v[68:71]
	v_mfma_f32_16x16x32_f16 v[28:31], v[132:135], v[168:171], v[28:31]
	v_mfma_f32_16x16x32_f16 v[36:39], v[140:143], v[168:171], v[36:39]
	v_mfma_f32_16x16x32_f16 v[16:19], v[132:135], v[176:179], v[16:19]
	v_mfma_f32_16x16x32_f16 v[12:15], v[140:143], v[176:179], v[12:15]
	s_barrier
	s_mov_b32 m0, s69
	v_lshl_add_u64 v[196:197], v[196:197], 0, s[88:89]
	ds_read_b128 v[180:183], v240
	ds_read_b128 v[184:187], v240 offset:1024
	ds_read_b128 v[188:191], v240 offset:2048
	ds_read_b128 v[192:195], v240 offset:3072
	global_load_lds_dwordx4 v[196:197], off
	v_lshl_add_u64 v[196:197], v[198:199], 0, s[88:89]
	s_mov_b32 m0, s70
	s_nop 0
	global_load_lds_dwordx4 v[196:197], off
	s_waitcnt vmcnt(10)
	s_barrier
	s_waitcnt lgkmcnt(0)
	v_mfma_f32_16x16x32_f16 v[72:75], v[180:183], v[148:151], v[72:75]
	v_mfma_f32_16x16x32_f16 v[88:91], v[188:191], v[148:151], v[88:91]
	v_mfma_f32_16x16x32_f16 v[40:43], v[180:183], v[156:159], v[40:43]
	v_mfma_f32_16x16x32_f16 v[52:55], v[188:191], v[156:159], v[52:55]
	v_mfma_f32_16x16x32_f16 v[20:23], v[180:183], v[164:167], v[20:23]
	v_mfma_f32_16x16x32_f16 v[24:27], v[188:191], v[164:167], v[24:27]
	v_mfma_f32_16x16x32_f16 v[8:11], v[180:183], v[172:175], v[8:11]
	v_mfma_f32_16x16x32_f16 v[4:7], v[188:191], v[172:175], v[4:7]
	v_mfma_f32_16x16x32_f16 v[72:75], v[184:187], v[152:155], v[72:75]
	v_mfma_f32_16x16x32_f16 v[88:91], v[192:195], v[152:155], v[88:91]
	v_mfma_f32_16x16x32_f16 v[40:43], v[184:187], v[160:163], v[40:43]
	v_mfma_f32_16x16x32_f16 v[52:55], v[192:195], v[160:163], v[52:55]
	v_mfma_f32_16x16x32_f16 v[20:23], v[184:187], v[168:171], v[20:23]
	v_mfma_f32_16x16x32_f16 v[24:27], v[192:195], v[168:171], v[24:27]
	v_mfma_f32_16x16x32_f16 v[8:11], v[184:187], v[176:179], v[8:11]
	v_mfma_f32_16x16x32_f16 v[4:7], v[192:195], v[176:179], v[4:7]
	s_mov_b32 m0, s39
	v_lshl_add_u64 v[196:197], v[200:201], 0, s[88:89]
	s_barrier
	ds_read_b128 v[148:151], v236 offset:49152
	ds_read_b128 v[152:155], v236 offset:50176
	ds_read_b128 v[156:159], v236 offset:51200
	ds_read_b128 v[160:163], v236 offset:52224
	ds_read_b128 v[164:167], v236 offset:53248
	ds_read_b128 v[168:171], v236 offset:54272
	ds_read_b128 v[172:175], v236 offset:55296
	ds_read_b128 v[176:179], v236 offset:56320
	global_load_lds_dwordx4 v[196:197], off
	v_lshl_add_u64 v[196:197], v[202:203], 0, s[88:89]
	s_mov_b32 m0, s47
	s_nop 0
	global_load_lds_dwordx4 v[196:197], off
	s_barrier
	s_waitcnt lgkmcnt(0)
	v_mfma_f32_16x16x32_f16 v[124:127], v[128:131], v[148:151], v[124:127]
	v_mfma_f32_16x16x32_f16 v[144:147], v[136:139], v[148:151], v[144:147]
	v_mfma_f32_16x16x32_f16 v[104:107], v[128:131], v[156:159], v[104:107]
	v_mfma_f32_16x16x32_f16 v[112:115], v[136:139], v[156:159], v[112:115]
	v_mfma_f32_16x16x32_f16 v[84:87], v[128:131], v[164:167], v[84:87]
	v_mfma_f32_16x16x32_f16 v[92:95], v[136:139], v[164:167], v[92:95]
	v_mfma_f32_16x16x32_f16 v[48:51], v[128:131], v[172:175], v[48:51]
	v_mfma_f32_16x16x32_f16 v[60:63], v[136:139], v[172:175], v[60:63]
	v_mfma_f32_16x16x32_f16 v[124:127], v[132:135], v[152:155], v[124:127]
	v_mfma_f32_16x16x32_f16 v[144:147], v[140:143], v[152:155], v[144:147]
	v_mfma_f32_16x16x32_f16 v[104:107], v[132:135], v[160:163], v[104:107]
	v_mfma_f32_16x16x32_f16 v[112:115], v[140:143], v[160:163], v[112:115]
	v_mfma_f32_16x16x32_f16 v[84:87], v[132:135], v[168:171], v[84:87]
	v_mfma_f32_16x16x32_f16 v[92:95], v[140:143], v[168:171], v[92:95]
	v_mfma_f32_16x16x32_f16 v[48:51], v[132:135], v[176:179], v[48:51]
	v_mfma_f32_16x16x32_f16 v[60:63], v[140:143], v[176:179], v[60:63]
	s_barrier
	s_add_u32 s26, s26, 0x80080
	s_addc_u32 s27, s27, 0
	s_mov_b32 m0, s71
	v_lshl_add_u64 v[128:129], s[26:27], 0, v[2:3]
	global_load_lds_dwordx4 v[128:129], off
	v_lshl_add_u64 v[128:129], s[26:27], 0, v[206:207]
	s_mov_b32 m0, s76
	s_nop 0
	global_load_lds_dwordx4 v[128:129], off
	s_waitcnt vmcnt(8)
	s_barrier
	v_mfma_f32_16x16x32_f16 v[116:119], v[180:183], v[148:151], v[116:119]
	v_mfma_f32_16x16x32_f16 v[120:123], v[188:191], v[148:151], v[120:123]
	v_mfma_f32_16x16x32_f16 v[96:99], v[180:183], v[156:159], v[96:99]
	v_mfma_f32_16x16x32_f16 v[100:103], v[188:191], v[156:159], v[100:103]
	v_mfma_f32_16x16x32_f16 v[64:67], v[180:183], v[164:167], v[64:67]
	v_mfma_f32_16x16x32_f16 v[76:79], v[188:191], v[164:167], v[76:79]
	v_mfma_f32_16x16x32_f16 v[32:35], v[180:183], v[172:175], v[32:35]
	v_mfma_f32_16x16x32_f16 v[44:47], v[188:191], v[172:175], v[44:47]
	v_mfma_f32_16x16x32_f16 v[116:119], v[184:187], v[152:155], v[116:119]
	v_mfma_f32_16x16x32_f16 v[120:123], v[192:195], v[152:155], v[120:123]
	v_mfma_f32_16x16x32_f16 v[96:99], v[184:187], v[160:163], v[96:99]
	v_mfma_f32_16x16x32_f16 v[100:103], v[192:195], v[160:163], v[100:103]
	v_mfma_f32_16x16x32_f16 v[64:67], v[184:187], v[168:171], v[64:67]
	v_mfma_f32_16x16x32_f16 v[76:79], v[192:195], v[168:171], v[76:79]
	v_mfma_f32_16x16x32_f16 v[32:35], v[184:187], v[176:179], v[32:35]
	v_mfma_f32_16x16x32_f16 v[44:47], v[192:195], v[176:179], v[44:47]
	s_add_i32 s29, s29, 2
	s_add_u32 s16, s16, 0x100
	s_addc_u32 s17, s17, 0
	s_add_u32 s10, s10, 0x100
	s_addc_u32 s11, s11, 0
	s_cmp_lt_u32 s29, 30
	s_barrier
	s_cbranch_scc1 .LBB0_1746
	s_add_i32 s10, s46, 16
	s_mul_hi_i32 s11, s10, 0x42
	s_mulk_i32 s10, 0x42
	s_add_u32 s10, s10, s48
	v_mov_b32_e32 v128, v233
	s_addc_u32 s11, s11, s78
	v_mov_b32_e32 v129, v234
	s_lshl_b64 s[10:11], s[10:11], 17
	v_add_u32_e32 v202, s13, v128
	v_lshlrev_b32_e32 v128, 8, v202
	v_lshlrev_b32_e32 v196, 3, v129
	s_add_u32 s10, s4, s10
	s_addc_u32 s11, s6, s11
	v_ashrrev_i32_e32 v197, 31, v196
	v_add_u32_e32 v140, 0x8000, v128
	v_lshl_add_u64 v[130:131], v[196:197], 1, s[10:11]
	v_ashrrev_i32_e32 v141, 31, v140
	v_lshl_add_u64 v[160:161], v[140:141], 1, v[130:131]
	v_add_u32_e32 v140, 0x9000, v128
	v_ashrrev_i32_e32 v129, 31, v128
	v_ashrrev_i32_e32 v141, 31, v140
	v_lshl_add_u64 v[132:133], v[128:129], 1, v[130:131]
	v_add_u32_e32 v134, 0x1000, v128
	v_add_u32_e32 v136, 0x2000, v128
	v_add_u32_e32 v138, 0x3000, v128
	v_lshl_add_u64 v[152:153], v[140:141], 1, v[130:131]
	v_add_u32_e32 v140, 0xa000, v128
	v_add_u32_e32 v128, 0xb000, v128
	v_ashrrev_i32_e32 v135, 31, v134
	v_ashrrev_i32_e32 v137, 31, v136
	v_ashrrev_i32_e32 v139, 31, v138
	v_ashrrev_i32_e32 v141, 31, v140
	v_ashrrev_i32_e32 v129, 31, v128
	v_lshl_add_u64 v[134:135], v[134:135], 1, v[130:131]
	v_lshl_add_u64 v[136:137], v[136:137], 1, v[130:131]
	v_lshl_add_u64 v[138:139], v[138:139], 1, v[130:131]
	v_lshl_add_u64 v[140:141], v[140:141], 1, v[130:131]
	v_lshl_add_u64 v[142:143], v[128:129], 1, v[130:131]
	global_load_dwordx4 v[164:167], v[138:139], off offset:256
	global_load_dwordx4 v[168:171], v[138:139], off
	global_load_dwordx4 v[172:175], v[136:137], off offset:256
	global_load_dwordx4 v[176:179], v[136:137], off
	global_load_dwordx4 v[180:183], v[134:135], off offset:256
	global_load_dwordx4 v[184:187], v[134:135], off
	global_load_dwordx4 v[188:191], v[132:133], off offset:256
	global_load_dwordx4 v[192:195], v[132:133], off
	global_load_dwordx4 v[128:131], v[142:143], off offset:256
	s_nop 0
	global_load_dwordx4 v[132:135], v[142:143], off
	global_load_dwordx4 v[136:139], v[140:141], off offset:256
	s_nop 0
	global_load_dwordx4 v[140:143], v[140:141], off
	s_nop 0
	global_load_dwordx4 v[148:151], v[152:153], off offset:256
	s_nop 0
	global_load_dwordx4 v[152:155], v[152:153], off
	s_nop 0
	global_load_dwordx4 v[156:159], v[160:161], off offset:256
	s_nop 0
	global_load_dwordx4 v[160:163], v[160:161], off
	v_mov_b32_e32 v199, v82
	v_pk_mov_b32 v[82:83], v[82:83], v[108:109] op_sel:[1,0]
	v_lshl_add_u32 v108, s48, 8, v202
	v_mov_b32_e32 v200, v109
	v_ashrrev_i32_e32 v109, 31, v108
	v_mov_b32_e32 v198, v81
	v_mov_b32_e32 v201, v110
	v_lshlrev_b64 v[202:203], 12, v[108:109]
	s_lshl_b32 s10, s46, 8
	s_or_b32 s10, s10, s38
	v_add_u32_e32 v196, s10, v196
	v_readlane_b32 s10, v254, 26
	v_readlane_b32 s11, v254, 27
	v_ashrrev_i32_e32 v197, 31, v196
	s_mov_b32 s46, s18
	s_mov_b32 s48, s36
	s_mov_b64 s[50:51], s[44:45]
	s_mov_b64 s[34:35], s[42:43]
	s_waitcnt vmcnt(0)
	s_nop 0
	v_cvt_f32_f16_e32 v81, v192
	v_cvt_f32_f16_e32 v108, v194
	v_cvt_f32_f16_sdwa v110, v192 dst_sel:DWORD dst_unused:UNUSED_PAD src0_sel:WORD_1
	v_cvt_f32_f16_e32 v220, v193
	v_cvt_f32_f16_sdwa v224, v193 dst_sel:DWORD dst_unused:UNUSED_PAD src0_sel:WORD_1
	v_cvt_f32_f16_sdwa v194, v194 dst_sel:DWORD dst_unused:UNUSED_PAD src0_sel:WORD_1
	v_cvt_f32_f16_e32 v221, v195
	v_rcp_f32_e32 v81, v81
	v_rcp_f32_e32 v109, v108
	v_rcp_f32_e32 v192, v110
	v_rcp_f32_e32 v193, v220
	v_rcp_f32_e32 v108, v224
	v_cvt_f32_f16_sdwa v225, v195 dst_sel:DWORD dst_unused:UNUSED_PAD src0_sel:WORD_1
	v_rcp_f32_e32 v194, v194
	v_rcp_f32_e32 v195, v221
	v_fma_mixlo_f16 v220, v80, v81, 0
	v_pk_mul_f32 v[80:81], v[198:199], v[192:193]
	v_pk_mul_f32 v[82:83], v[82:83], v[108:109]
	v_cvt_pk_f16_f32 v80, v80, v81
	v_cvt_pk_f16_f32 v82, v82, v83
	v_pack_b32_f16 v83, v220, v80
	v_alignbit_b32 v80, v82, v80, 16
	v_pk_mul_f32 v[192:193], v[200:201], v[194:195]
	v_lshrrev_b32_e32 v109, 4, v80
	v_cvt_pk_f16_f32 v81, v192, v193
	v_and_b32_e32 v109, 0x10001, v109
	v_alignbit_b32 v82, v81, v82, 16
	v_add3_u32 v80, v80, v109, s21
	v_rcp_f32_e32 v110, v225
	v_and_b32_e32 v109, 0xfff0fff0, v80
	v_lshrrev_b32_e32 v80, 4, v82
	v_and_b32_e32 v80, 0x10001, v80
	v_add3_u32 v80, v82, v80, s21
	v_cvt_f32_f16_e32 v82, v188
	v_lshrrev_b32_e32 v81, 16, v81
	v_fma_mixhi_f16 v81, v111, v110, 0
	v_and_b32_e32 v110, 0xfff0fff0, v80
	v_lshrrev_b32_e32 v80, 4, v81
	v_lshrrev_b32_e32 v108, 4, v83
	v_and_b32_e32 v80, 0x10001, v80
	v_rcp_f32_e32 v82, v82
	v_and_b32_e32 v108, 0x10001, v108
	v_add3_u32 v80, v81, v80, s21
	v_add3_u32 v83, v83, v108, s21
	v_and_b32_e32 v111, 0xfff0fff0, v80
	v_lshl_add_u64 v[80:81], s[10:11], 0, v[202:203]
	v_and_b32_e32 v108, 0xfff0fff0, v83
	v_lshl_add_u64 v[80:81], v[196:197], 1, v[80:81]
	global_store_dwordx4 v[80:81], v[108:111], off
	v_fma_mixlo_f16 v82, v72, v82, 0
	v_cvt_f32_f16_e32 v72, v190
	v_cvt_f32_f16_sdwa v108, v188 dst_sel:DWORD dst_unused:UNUSED_PAD src0_sel:WORD_1
	v_cvt_f32_f16_sdwa v109, v190 dst_sel:DWORD dst_unused:UNUSED_PAD src0_sel:WORD_1
	v_cvt_f32_f16_e32 v110, v189
	v_rcp_f32_e32 v83, v72
	v_rcp_f32_e32 v108, v108
	v_rcp_f32_e32 v72, v109
	v_rcp_f32_e32 v109, v110
	v_mov_b32_e32 v110, v73
	v_mov_b32_e32 v111, v74
	v_cvt_f32_f16_e32 v73, v191
	v_pk_mul_f32 v[108:109], v[110:111], v[108:109]
	s_mov_b64 s[10:11], 0x10000
	v_cvt_pk_f16_f32 v74, v108, v109
	v_pack_b32_f16 v110, v82, v74
	v_cvt_f32_f16_sdwa v82, v189 dst_sel:DWORD dst_unused:UNUSED_PAD src0_sel:WORD_1
	v_rcp_f32_e32 v73, v73
	v_mov_b32_e32 v108, v89
	v_mov_b32_e32 v109, v90
	v_rcp_f32_e32 v82, v82
	v_pk_mul_f32 v[72:73], v[108:109], v[72:73]
	v_cvt_f32_f16_sdwa v90, v191 dst_sel:DWORD dst_unused:UNUSED_PAD src0_sel:WORD_1
	v_cvt_pk_f16_f32 v89, v72, v73
	v_pk_mov_b32 v[72:73], v[74:75], v[88:89] op_sel:[1,0]
	s_nop 0
	v_pk_mul_f32 v[72:73], v[72:73], v[82:83]
	v_lshrrev_b32_e32 v82, 16, v89
	v_cvt_pk_f16_f32 v72, v72, v73
	v_rcp_f32_e32 v73, v90
	v_alignbit_b32 v74, v72, v74, 16
	v_alignbit_b32 v75, v89, v72, 16
	v_lshrrev_b32_e32 v72, 4, v110
	v_fma_mixhi_f16 v82, v91, v73, 0
	v_lshrrev_b32_e32 v73, 4, v74
	v_and_b32_e32 v73, 0x10001, v73
	v_add3_u32 v73, v74, v73, s21
	v_lshrrev_b32_e32 v74, 4, v75
	v_and_b32_e32 v74, 0x10001, v74
	v_add3_u32 v74, v75, v74, s21
	v_cvt_f32_f16_e32 v75, v184
	v_lshrrev_b32_e32 v83, 4, v82
	v_and_b32_e32 v72, 0x10001, v72
	v_and_b32_e32 v83, 0x10001, v83
	v_rcp_f32_e32 v88, v75
	v_add3_u32 v72, v110, v72, s21
	v_add3_u32 v75, v82, v83, s21
	v_and_b32_e32 v72, 0xfff0fff0, v72
	v_and_b32_e32 v73, 0xfff0fff0, v73
	v_and_b32_e32 v74, 0xfff0fff0, v74
	v_and_b32_e32 v75, 0xfff0fff0, v75
	global_store_dwordx4 v[80:81], v[72:75], off offset:256
	v_cvt_f32_f16_e32 v82, v185
	v_mov_b32_e32 v83, v58
	v_fma_mixlo_f16 v72, v56, v88, 0
	v_cvt_f32_f16_e32 v56, v186
	v_cvt_f32_f16_sdwa v74, v184 dst_sel:DWORD dst_unused:UNUSED_PAD src0_sel:WORD_1
	v_cvt_f32_f16_sdwa v75, v186 dst_sel:DWORD dst_unused:UNUSED_PAD src0_sel:WORD_1
	v_rcp_f32_e32 v73, v56
	v_rcp_f32_e32 v74, v74
	v_rcp_f32_e32 v56, v75
	v_rcp_f32_e32 v75, v82
	v_mov_b32_e32 v82, v57
	v_cvt_f32_f16_e32 v57, v187
	v_pk_mul_f32 v[74:75], v[82:83], v[74:75]
	s_nop 0
	v_cvt_pk_f16_f32 v58, v74, v75
	v_pack_b32_f16 v82, v72, v58
	v_cvt_f32_f16_sdwa v72, v185 dst_sel:DWORD dst_unused:UNUSED_PAD src0_sel:WORD_1
	v_rcp_f32_e32 v57, v57
	v_mov_b32_e32 v74, v69
	v_mov_b32_e32 v75, v70
	v_rcp_f32_e32 v72, v72
	v_pk_mul_f32 v[56:57], v[74:75], v[56:57]
	v_cvt_f32_f16_sdwa v70, v187 dst_sel:DWORD dst_unused:UNUSED_PAD src0_sel:WORD_1
	v_cvt_pk_f16_f32 v69, v56, v57
	v_pk_mov_b32 v[56:57], v[58:59], v[68:69] op_sel:[1,0]
	v_lshrrev_b32_e32 v68, 16, v69
	v_pk_mul_f32 v[56:57], v[56:57], v[72:73]
	s_nop 0
	v_cvt_pk_f16_f32 v56, v56, v57
	v_rcp_f32_e32 v57, v70
	v_alignbit_b32 v58, v56, v58, 16
	v_alignbit_b32 v59, v69, v56, 16
	v_cvt_f32_f16_e32 v70, v180
	v_fma_mixhi_f16 v68, v71, v57, 0
	v_lshrrev_b32_e32 v57, 4, v58
	v_and_b32_e32 v57, 0x10001, v57
	v_add3_u32 v57, v58, v57, s21
	v_lshrrev_b32_e32 v58, 4, v59
	v_and_b32_e32 v58, 0x10001, v58
	v_add3_u32 v58, v59, v58, s21
	v_lshrrev_b32_e32 v59, 4, v68
	v_lshrrev_b32_e32 v56, 4, v82
	v_and_b32_e32 v59, 0x10001, v59
	v_rcp_f32_e32 v72, v70
	v_and_b32_e32 v56, 0x10001, v56
	v_add3_u32 v59, v68, v59, s21
	v_lshl_add_u64 v[68:69], v[80:81], 0, s[10:11]
	s_mov_b32 s10, 0x10000
	v_add3_u32 v56, v82, v56, s21
	v_add_co_u32_e32 v70, vcc, s10, v80
	v_and_b32_e32 v56, 0xfff0fff0, v56
	v_and_b32_e32 v57, 0xfff0fff0, v57
	v_and_b32_e32 v58, 0xfff0fff0, v58
	v_and_b32_e32 v59, 0xfff0fff0, v59
	v_addc_co_u32_e32 v71, vcc, 0, v81, vcc
	global_store_dwordx4 v[70:71], v[56:59], off
	v_cvt_f32_f16_e32 v70, v181
	v_mov_b32_e32 v71, v42
	v_fma_mixlo_f16 v56, v40, v72, 0
	v_cvt_f32_f16_e32 v40, v182
	v_cvt_f32_f16_sdwa v58, v180 dst_sel:DWORD dst_unused:UNUSED_PAD src0_sel:WORD_1
	v_cvt_f32_f16_sdwa v59, v182 dst_sel:DWORD dst_unused:UNUSED_PAD src0_sel:WORD_1
	s_mov_b64 s[10:11], 0x20000
	v_rcp_f32_e32 v57, v40
	v_rcp_f32_e32 v58, v58
	v_rcp_f32_e32 v40, v59
	v_rcp_f32_e32 v59, v70
	v_mov_b32_e32 v70, v41
	v_cvt_f32_f16_e32 v41, v183
	v_pk_mul_f32 v[58:59], v[70:71], v[58:59]
	s_nop 0
	v_cvt_pk_f16_f32 v42, v58, v59
	v_pack_b32_f16 v70, v56, v42
	v_cvt_f32_f16_sdwa v56, v181 dst_sel:DWORD dst_unused:UNUSED_PAD src0_sel:WORD_1
	v_rcp_f32_e32 v41, v41
	v_mov_b32_e32 v58, v53
	v_mov_b32_e32 v59, v54
	v_rcp_f32_e32 v56, v56
	v_pk_mul_f32 v[40:41], v[58:59], v[40:41]
	v_cvt_f32_f16_sdwa v54, v183 dst_sel:DWORD dst_unused:UNUSED_PAD src0_sel:WORD_1
	v_cvt_pk_f16_f32 v53, v40, v41
	v_pk_mov_b32 v[40:41], v[42:43], v[52:53] op_sel:[1,0]
	v_lshrrev_b32_e32 v52, 16, v53
	v_pk_mul_f32 v[40:41], v[40:41], v[56:57]
	s_nop 0
	v_cvt_pk_f16_f32 v40, v40, v41
	v_rcp_f32_e32 v41, v54
	v_alignbit_b32 v42, v40, v42, 16
	v_alignbit_b32 v43, v53, v40, 16
	v_lshrrev_b32_e32 v40, 4, v70
	v_fma_mixhi_f16 v52, v55, v41, 0
	v_lshrrev_b32_e32 v41, 4, v42
	v_and_b32_e32 v41, 0x10001, v41
	v_add3_u32 v41, v42, v41, s21
	v_lshrrev_b32_e32 v42, 4, v43
	v_and_b32_e32 v42, 0x10001, v42
	v_add3_u32 v42, v43, v42, s21
	v_cvt_f32_f16_e32 v43, v176
	v_lshrrev_b32_e32 v53, 4, v52
	v_and_b32_e32 v40, 0x10001, v40
	v_and_b32_e32 v53, 0x10001, v53
	v_rcp_f32_e32 v54, v43
	v_add3_u32 v40, v70, v40, s21
	v_add3_u32 v43, v52, v53, s21
	v_and_b32_e32 v40, 0xfff0fff0, v40
	v_and_b32_e32 v41, 0xfff0fff0, v41
	v_and_b32_e32 v42, 0xfff0fff0, v42
	v_and_b32_e32 v43, 0xfff0fff0, v43
	global_store_dwordx4 v[68:69], v[40:43], off offset:256
	v_cvt_f32_f16_e32 v52, v177
	v_mov_b32_e32 v53, v30
	v_fma_mixlo_f16 v40, v28, v54, 0
	v_cvt_f32_f16_e32 v28, v178
	v_cvt_f32_f16_sdwa v42, v176 dst_sel:DWORD dst_unused:UNUSED_PAD src0_sel:WORD_1
	v_cvt_f32_f16_sdwa v43, v178 dst_sel:DWORD dst_unused:UNUSED_PAD src0_sel:WORD_1
	v_rcp_f32_e32 v41, v28
	v_rcp_f32_e32 v42, v42
	v_rcp_f32_e32 v28, v43
	v_rcp_f32_e32 v43, v52
	v_mov_b32_e32 v52, v29
	v_cvt_f32_f16_e32 v29, v179
	v_pk_mul_f32 v[42:43], v[52:53], v[42:43]
	s_nop 0
	v_cvt_pk_f16_f32 v30, v42, v43
	v_pack_b32_f16 v52, v40, v30
	v_cvt_f32_f16_sdwa v40, v177 dst_sel:DWORD dst_unused:UNUSED_PAD src0_sel:WORD_1
	v_rcp_f32_e32 v29, v29
	v_mov_b32_e32 v42, v37
	v_mov_b32_e32 v43, v38
	v_rcp_f32_e32 v40, v40
	v_pk_mul_f32 v[28:29], v[42:43], v[28:29]
	v_cvt_f32_f16_sdwa v38, v179 dst_sel:DWORD dst_unused:UNUSED_PAD src0_sel:WORD_1
	v_cvt_pk_f16_f32 v37, v28, v29
	v_pk_mov_b32 v[28:29], v[30:31], v[36:37] op_sel:[1,0]
	v_lshrrev_b32_e32 v36, 16, v37
	v_pk_mul_f32 v[28:29], v[28:29], v[40:41]
	s_nop 0
	v_cvt_pk_f16_f32 v28, v28, v29
	v_rcp_f32_e32 v29, v38
	v_alignbit_b32 v30, v28, v30, 16
	v_alignbit_b32 v31, v37, v28, 16
	v_cvt_f32_f16_e32 v38, v172
	v_fma_mixhi_f16 v36, v39, v29, 0
	v_lshrrev_b32_e32 v29, 4, v30
	v_and_b32_e32 v29, 0x10001, v29
	v_add3_u32 v29, v30, v29, s21
	v_lshrrev_b32_e32 v30, 4, v31
	v_and_b32_e32 v30, 0x10001, v30
	v_add3_u32 v30, v31, v30, s21
	v_lshrrev_b32_e32 v31, 4, v36
	v_lshrrev_b32_e32 v28, 4, v52
	v_and_b32_e32 v31, 0x10001, v31
	v_rcp_f32_e32 v40, v38
	v_and_b32_e32 v28, 0x10001, v28
	v_add3_u32 v31, v36, v31, s21
	v_lshl_add_u64 v[36:37], v[80:81], 0, s[10:11]
	s_mov_b32 s10, 0x20000
	v_add3_u32 v28, v52, v28, s21
	v_add_co_u32_e32 v38, vcc, s10, v80
	v_and_b32_e32 v28, 0xfff0fff0, v28
	v_and_b32_e32 v29, 0xfff0fff0, v29
	v_and_b32_e32 v30, 0xfff0fff0, v30
	v_and_b32_e32 v31, 0xfff0fff0, v31
	v_addc_co_u32_e32 v39, vcc, 0, v81, vcc
	global_store_dwordx4 v[38:39], v[28:31], off
	v_cvt_f32_f16_e32 v38, v173
	v_mov_b32_e32 v39, v22
	v_fma_mixlo_f16 v28, v20, v40, 0
	v_cvt_f32_f16_e32 v20, v174
	v_cvt_f32_f16_sdwa v30, v172 dst_sel:DWORD dst_unused:UNUSED_PAD src0_sel:WORD_1
	v_cvt_f32_f16_sdwa v31, v174 dst_sel:DWORD dst_unused:UNUSED_PAD src0_sel:WORD_1
	s_mov_b64 s[10:11], 0x30000
	v_rcp_f32_e32 v29, v20
	v_rcp_f32_e32 v30, v30
	v_rcp_f32_e32 v20, v31
	v_rcp_f32_e32 v31, v38
	v_mov_b32_e32 v38, v21
	v_cvt_f32_f16_e32 v21, v175
	v_pk_mul_f32 v[30:31], v[38:39], v[30:31]
	s_nop 0
	v_cvt_pk_f16_f32 v22, v30, v31
	v_pack_b32_f16 v38, v28, v22
	v_cvt_f32_f16_sdwa v28, v173 dst_sel:DWORD dst_unused:UNUSED_PAD src0_sel:WORD_1
	v_rcp_f32_e32 v21, v21
	v_mov_b32_e32 v30, v25
	v_mov_b32_e32 v31, v26
	v_rcp_f32_e32 v28, v28
	v_pk_mul_f32 v[20:21], v[30:31], v[20:21]
	v_cvt_f32_f16_sdwa v26, v175 dst_sel:DWORD dst_unused:UNUSED_PAD src0_sel:WORD_1
	v_cvt_pk_f16_f32 v25, v20, v21
	v_pk_mov_b32 v[20:21], v[22:23], v[24:25] op_sel:[1,0]
	v_lshrrev_b32_e32 v24, 16, v25
	v_pk_mul_f32 v[20:21], v[20:21], v[28:29]
	s_nop 0
	v_cvt_pk_f16_f32 v20, v20, v21
	v_rcp_f32_e32 v21, v26
	v_alignbit_b32 v22, v20, v22, 16
	v_alignbit_b32 v23, v25, v20, 16
	v_lshrrev_b32_e32 v20, 4, v38
	v_fma_mixhi_f16 v24, v27, v21, 0
	v_lshrrev_b32_e32 v21, 4, v22
	v_and_b32_e32 v21, 0x10001, v21
	v_add3_u32 v21, v22, v21, s21
	v_lshrrev_b32_e32 v22, 4, v23
	v_and_b32_e32 v22, 0x10001, v22
	v_add3_u32 v22, v23, v22, s21
	v_cvt_f32_f16_e32 v23, v168
	v_lshrrev_b32_e32 v25, 4, v24
	v_and_b32_e32 v20, 0x10001, v20
	v_and_b32_e32 v25, 0x10001, v25
	v_rcp_f32_e32 v26, v23
	v_add3_u32 v20, v38, v20, s21
	v_add3_u32 v23, v24, v25, s21
	v_and_b32_e32 v20, 0xfff0fff0, v20
	v_and_b32_e32 v21, 0xfff0fff0, v21
	v_and_b32_e32 v22, 0xfff0fff0, v22
	v_and_b32_e32 v23, 0xfff0fff0, v23
	global_store_dwordx4 v[36:37], v[20:23], off offset:256
	v_cvt_f32_f16_e32 v24, v169
	v_mov_b32_e32 v25, v18
	v_fma_mixlo_f16 v20, v16, v26, 0
	v_cvt_f32_f16_e32 v16, v170
	v_cvt_f32_f16_sdwa v22, v168 dst_sel:DWORD dst_unused:UNUSED_PAD src0_sel:WORD_1
	v_cvt_f32_f16_sdwa v23, v170 dst_sel:DWORD dst_unused:UNUSED_PAD src0_sel:WORD_1
	v_rcp_f32_e32 v21, v16
	v_rcp_f32_e32 v22, v22
	v_rcp_f32_e32 v16, v23
	v_rcp_f32_e32 v23, v24
	v_mov_b32_e32 v24, v17
	v_cvt_f32_f16_e32 v17, v171
	v_pk_mul_f32 v[22:23], v[24:25], v[22:23]
	s_nop 0
	v_cvt_pk_f16_f32 v18, v22, v23
	v_pack_b32_f16 v24, v20, v18
	v_rcp_f32_e32 v17, v17
	v_cvt_f32_f16_sdwa v20, v169 dst_sel:DWORD dst_unused:UNUSED_PAD src0_sel:WORD_1
	v_mov_b32_e32 v22, v13
	v_mov_b32_e32 v23, v14
	v_pk_mul_f32 v[16:17], v[22:23], v[16:17]
	v_rcp_f32_e32 v20, v20
	v_cvt_pk_f16_f32 v14, v16, v17
	v_cvt_f32_f16_sdwa v16, v171 dst_sel:DWORD dst_unused:UNUSED_PAD src0_sel:WORD_1
	v_pk_mov_b32 v[12:13], v[18:19], v[12:13] op_sel:[1,0]
	s_nop 0
	v_pk_mul_f32 v[12:13], v[12:13], v[20:21]
	s_nop 0
	v_cvt_pk_f16_f32 v12, v12, v13
	v_rcp_f32_e32 v13, v16
	v_alignbit_b32 v16, v12, v18, 16
	v_lshrrev_b32_e32 v18, 16, v14
	v_alignbit_b32 v17, v14, v12, 16
	v_fma_mixhi_f16 v18, v15, v13, 0
	v_lshrrev_b32_e32 v15, 4, v18
	v_and_b32_e32 v15, 0x10001, v15
	v_add3_u32 v15, v18, v15, s21
	v_cvt_f32_f16_e32 v18, v164
	v_lshrrev_b32_e32 v13, 4, v16
	v_lshrrev_b32_e32 v14, 4, v17
	v_lshrrev_b32_e32 v12, 4, v24
	v_and_b32_e32 v13, 0x10001, v13
	v_and_b32_e32 v14, 0x10001, v14
	v_rcp_f32_e32 v20, v18
	v_and_b32_e32 v12, 0x10001, v12
	v_add3_u32 v13, v16, v13, s21
	v_add3_u32 v14, v17, v14, s21
	v_lshl_add_u64 v[16:17], v[80:81], 0, s[10:11]
	s_mov_b32 s10, 0x30000
	v_add3_u32 v12, v24, v12, s21
	v_add_co_u32_e32 v18, vcc, s10, v80
	v_and_b32_e32 v12, 0xfff0fff0, v12
	v_and_b32_e32 v13, 0xfff0fff0, v13
	v_and_b32_e32 v14, 0xfff0fff0, v14
	v_and_b32_e32 v15, 0xfff0fff0, v15
	v_addc_co_u32_e32 v19, vcc, 0, v81, vcc
	global_store_dwordx4 v[18:19], v[12:15], off
	v_cvt_f32_f16_e32 v18, v165
	v_mov_b32_e32 v19, v10
	v_fma_mixlo_f16 v12, v8, v20, 0
	v_cvt_f32_f16_e32 v8, v166
	v_cvt_f32_f16_sdwa v14, v164 dst_sel:DWORD dst_unused:UNUSED_PAD src0_sel:WORD_1
	v_cvt_f32_f16_sdwa v15, v166 dst_sel:DWORD dst_unused:UNUSED_PAD src0_sel:WORD_1
	s_mov_b64 s[10:11], 0x80000
	v_rcp_f32_e32 v13, v8
	v_rcp_f32_e32 v14, v14
	v_rcp_f32_e32 v8, v15
	v_rcp_f32_e32 v15, v18
	v_mov_b32_e32 v18, v9
	v_cvt_f32_f16_e32 v9, v167
	v_pk_mul_f32 v[14:15], v[18:19], v[14:15]
	s_nop 0
	v_cvt_pk_f16_f32 v10, v14, v15
	v_pack_b32_f16 v18, v12, v10
	v_rcp_f32_e32 v9, v9
	v_cvt_f32_f16_sdwa v12, v165 dst_sel:DWORD dst_unused:UNUSED_PAD src0_sel:WORD_1
	v_mov_b32_e32 v14, v5
	v_mov_b32_e32 v15, v6
	v_pk_mul_f32 v[8:9], v[14:15], v[8:9]
	v_rcp_f32_e32 v12, v12
	v_cvt_pk_f16_f32 v6, v8, v9
	v_cvt_f32_f16_sdwa v8, v167 dst_sel:DWORD dst_unused:UNUSED_PAD src0_sel:WORD_1
	v_pk_mov_b32 v[4:5], v[10:11], v[4:5] op_sel:[1,0]
	v_mov_b32_e32 v11, v126
	v_pk_mul_f32 v[4:5], v[4:5], v[12:13]
	v_mov_b32_e32 v13, v118
	v_cvt_pk_f16_f32 v4, v4, v5
	v_rcp_f32_e32 v5, v8
	v_alignbit_b32 v8, v4, v10, 16
	v_lshrrev_b32_e32 v10, 16, v6
	v_alignbit_b32 v9, v6, v4, 16
	v_fma_mixhi_f16 v10, v7, v5, 0
	v_cvt_f32_f16_e32 v7, v160
	v_lshrrev_b32_e32 v5, 4, v8
	v_lshrrev_b32_e32 v6, 4, v9
	v_and_b32_e32 v5, 0x10001, v5
	v_and_b32_e32 v6, 0x10001, v6
	v_lshrrev_b32_e32 v4, 4, v18
	v_add3_u32 v5, v8, v5, s21
	v_add3_u32 v6, v9, v6, s21
	v_lshrrev_b32_e32 v8, 4, v10
	v_rcp_f32_e32 v9, v7
	v_and_b32_e32 v4, 0x10001, v4
	v_and_b32_e32 v8, 0x10001, v8
	v_add3_u32 v4, v18, v4, s21
	v_add3_u32 v8, v10, v8, s21
	v_and_b32_e32 v4, 0xfff0fff0, v4
	v_and_b32_e32 v5, 0xfff0fff0, v5
	v_and_b32_e32 v6, 0xfff0fff0, v6
	v_and_b32_e32 v7, 0xfff0fff0, v8
	global_store_dwordx4 v[16:17], v[4:7], off offset:256
	v_mov_b32_e32 v10, v125
	s_nop 0
	v_fma_mixlo_f16 v4, v124, v9, 0
	v_cvt_f32_f16_sdwa v6, v160 dst_sel:DWORD dst_unused:UNUSED_PAD src0_sel:WORD_1
	v_cvt_f32_f16_sdwa v7, v162 dst_sel:DWORD dst_unused:UNUSED_PAD src0_sel:WORD_1
	v_cvt_f32_f16_e32 v9, v161
	v_cvt_f32_f16_e32 v5, v162
	v_rcp_f32_e32 v6, v6
	v_rcp_f32_e32 v8, v7
	v_rcp_f32_e32 v7, v9
	v_cvt_f32_f16_e32 v9, v163
	v_rcp_f32_e32 v5, v5
	v_pk_mul_f32 v[6:7], v[10:11], v[6:7]
	s_nop 0
	v_cvt_pk_f16_f32 v10, v6, v7
	v_pack_b32_f16 v11, v4, v10
	v_cvt_f32_f16_sdwa v4, v161 dst_sel:DWORD dst_unused:UNUSED_PAD src0_sel:WORD_1
	v_rcp_f32_e32 v9, v9
	v_mov_b32_e32 v6, v145
	v_mov_b32_e32 v7, v146
	v_rcp_f32_e32 v4, v4
	v_pk_mul_f32 v[6:7], v[6:7], v[8:9]
	v_cvt_f32_f16_sdwa v9, v163 dst_sel:DWORD dst_unused:UNUSED_PAD src0_sel:WORD_1
	v_cvt_pk_f16_f32 v8, v6, v7
	v_pk_mov_b32 v[6:7], v[126:127], v[144:145] op_sel:[1,0]
	s_nop 0
	v_pk_mul_f32 v[4:5], v[6:7], v[4:5]
	s_nop 0
	v_cvt_pk_f16_f32 v4, v4, v5
	v_rcp_f32_e32 v5, v9
	v_alignbit_b32 v6, v4, v10, 16
	v_alignbit_b32 v7, v8, v4, 16
	v_lshrrev_b32_e32 v8, 16, v8
	v_fma_mixhi_f16 v8, v147, v5, 0
	v_lshrrev_b32_e32 v5, 4, v6
	v_and_b32_e32 v5, 0x10001, v5
	v_add3_u32 v5, v6, v5, s21
	v_lshrrev_b32_e32 v6, 4, v7
	v_and_b32_e32 v6, 0x10001, v6
	v_cvt_f32_f16_e32 v10, v156
	v_add3_u32 v6, v7, v6, s21
	v_lshrrev_b32_e32 v7, 4, v8
	v_lshrrev_b32_e32 v4, 4, v11
	v_and_b32_e32 v7, 0x10001, v7
	v_and_b32_e32 v4, 0x10001, v4
	v_add3_u32 v7, v8, v7, s21
	v_lshl_add_u64 v[8:9], v[80:81], 0, s[10:11]
	s_mov_b32 s10, 0x80000
	v_add3_u32 v4, v11, v4, s21
	v_rcp_f32_e32 v12, v10
	v_add_co_u32_e32 v10, vcc, s10, v80
	v_and_b32_e32 v4, 0xfff0fff0, v4
	v_and_b32_e32 v5, 0xfff0fff0, v5
	v_and_b32_e32 v6, 0xfff0fff0, v6
	v_and_b32_e32 v7, 0xfff0fff0, v7
	v_addc_co_u32_e32 v11, vcc, 0, v81, vcc
	global_store_dwordx4 v[10:11], v[4:7], off
	v_cvt_f32_f16_e32 v11, v157
	s_mov_b64 s[10:11], 0x90000
	v_cvt_f32_f16_sdwa v6, v156 dst_sel:DWORD dst_unused:UNUSED_PAD src0_sel:WORD_1
	v_cvt_f32_f16_sdwa v7, v158 dst_sel:DWORD dst_unused:UNUSED_PAD src0_sel:WORD_1
	v_fma_mixlo_f16 v4, v116, v12, 0
	v_mov_b32_e32 v12, v117
	v_rcp_f32_e32 v6, v6
	v_rcp_f32_e32 v10, v7
	v_rcp_f32_e32 v7, v11
	v_cvt_f32_f16_e32 v11, v159
	v_cvt_f32_f16_e32 v5, v158
	v_pk_mul_f32 v[6:7], v[12:13], v[6:7]
	s_nop 0
	v_cvt_pk_f16_f32 v12, v6, v7
	v_pack_b32_f16 v13, v4, v12
	v_cvt_f32_f16_sdwa v4, v157 dst_sel:DWORD dst_unused:UNUSED_PAD src0_sel:WORD_1
	v_rcp_f32_e32 v11, v11
	v_rcp_f32_e32 v5, v5
	v_mov_b32_e32 v6, v121
	v_mov_b32_e32 v7, v122
	v_rcp_f32_e32 v4, v4
	v_pk_mul_f32 v[6:7], v[6:7], v[10:11]
	v_cvt_f32_f16_sdwa v11, v159 dst_sel:DWORD dst_unused:UNUSED_PAD src0_sel:WORD_1
	v_cvt_pk_f16_f32 v10, v6, v7
	v_pk_mov_b32 v[6:7], v[118:119], v[120:121] op_sel:[1,0]
	s_nop 0
	v_pk_mul_f32 v[4:5], v[6:7], v[4:5]
	s_nop 0
	v_cvt_pk_f16_f32 v4, v4, v5
	v_rcp_f32_e32 v5, v11
	v_alignbit_b32 v6, v4, v12, 16
	v_alignbit_b32 v7, v10, v4, 16
	v_lshrrev_b32_e32 v10, 16, v10
	v_fma_mixhi_f16 v10, v123, v5, 0
	v_lshrrev_b32_e32 v5, 4, v6
	v_and_b32_e32 v5, 0x10001, v5
	v_add3_u32 v5, v6, v5, s21
	v_lshrrev_b32_e32 v6, 4, v7
	v_and_b32_e32 v6, 0x10001, v6
	v_add3_u32 v6, v7, v6, s21
	v_cvt_f32_f16_e32 v7, v152
	v_lshrrev_b32_e32 v4, 4, v13
	v_lshrrev_b32_e32 v11, 4, v10
	v_and_b32_e32 v4, 0x10001, v4
	v_and_b32_e32 v11, 0x10001, v11
	v_add3_u32 v4, v13, v4, s21
	v_rcp_f32_e32 v12, v7
	v_add3_u32 v7, v10, v11, s21
	v_and_b32_e32 v4, 0xfff0fff0, v4
	v_and_b32_e32 v5, 0xfff0fff0, v5
	v_and_b32_e32 v6, 0xfff0fff0, v6
	v_and_b32_e32 v7, 0xfff0fff0, v7
	global_store_dwordx4 v[8:9], v[4:7], off offset:256
	v_cvt_f32_f16_e32 v9, v153
	v_mov_b32_e32 v10, v105
	v_cvt_f32_f16_sdwa v6, v152 dst_sel:DWORD dst_unused:UNUSED_PAD src0_sel:WORD_1
	v_cvt_f32_f16_sdwa v7, v154 dst_sel:DWORD dst_unused:UNUSED_PAD src0_sel:WORD_1
	v_mov_b32_e32 v11, v106
	v_fma_mixlo_f16 v4, v104, v12, 0
	v_rcp_f32_e32 v6, v6
	v_rcp_f32_e32 v8, v7
	v_rcp_f32_e32 v7, v9
	v_cvt_f32_f16_e32 v9, v155
	v_cvt_f32_f16_e32 v5, v154
	v_mov_b32_e32 v13, v98
	v_pk_mul_f32 v[6:7], v[10:11], v[6:7]
	v_rcp_f32_e32 v9, v9
	v_cvt_pk_f16_f32 v10, v6, v7
	v_pack_b32_f16 v11, v4, v10
	v_cvt_f32_f16_sdwa v4, v153 dst_sel:DWORD dst_unused:UNUSED_PAD src0_sel:WORD_1
	v_rcp_f32_e32 v5, v5
	v_mov_b32_e32 v6, v113
	v_mov_b32_e32 v7, v114
	v_rcp_f32_e32 v4, v4
	v_pk_mul_f32 v[6:7], v[6:7], v[8:9]
	v_cvt_f32_f16_sdwa v9, v155 dst_sel:DWORD dst_unused:UNUSED_PAD src0_sel:WORD_1
	v_cvt_pk_f16_f32 v8, v6, v7
	v_pk_mov_b32 v[6:7], v[106:107], v[112:113] op_sel:[1,0]
	s_nop 0
	v_pk_mul_f32 v[4:5], v[6:7], v[4:5]
	s_nop 0
	v_cvt_pk_f16_f32 v4, v4, v5
	v_rcp_f32_e32 v5, v9
	v_alignbit_b32 v6, v4, v10, 16
	v_alignbit_b32 v7, v8, v4, 16
	v_lshrrev_b32_e32 v8, 16, v8
	v_fma_mixhi_f16 v8, v115, v5, 0
	v_lshrrev_b32_e32 v5, 4, v6
	v_and_b32_e32 v5, 0x10001, v5
	v_add3_u32 v5, v6, v5, s21
	v_lshrrev_b32_e32 v6, 4, v7
	v_and_b32_e32 v6, 0x10001, v6
	v_cvt_f32_f16_e32 v10, v148
	v_add3_u32 v6, v7, v6, s21
	v_lshrrev_b32_e32 v7, 4, v8
	v_lshrrev_b32_e32 v4, 4, v11
	v_and_b32_e32 v7, 0x10001, v7
	v_and_b32_e32 v4, 0x10001, v4
	v_add3_u32 v7, v8, v7, s21
	v_lshl_add_u64 v[8:9], v[80:81], 0, s[10:11]
	s_mov_b32 s10, 0x90000
	v_add3_u32 v4, v11, v4, s21
	v_rcp_f32_e32 v12, v10
	v_add_co_u32_e32 v10, vcc, s10, v80
	v_and_b32_e32 v4, 0xfff0fff0, v4
	v_and_b32_e32 v5, 0xfff0fff0, v5
	v_and_b32_e32 v6, 0xfff0fff0, v6
	v_and_b32_e32 v7, 0xfff0fff0, v7
	v_addc_co_u32_e32 v11, vcc, 0, v81, vcc
	global_store_dwordx4 v[10:11], v[4:7], off
	v_cvt_f32_f16_e32 v11, v149
	s_mov_b64 s[10:11], 0xa0000
	v_cvt_f32_f16_sdwa v6, v148 dst_sel:DWORD dst_unused:UNUSED_PAD src0_sel:WORD_1
	v_cvt_f32_f16_sdwa v7, v150 dst_sel:DWORD dst_unused:UNUSED_PAD src0_sel:WORD_1
	v_fma_mixlo_f16 v4, v96, v12, 0
	v_mov_b32_e32 v12, v97
	v_rcp_f32_e32 v6, v6
	v_rcp_f32_e32 v10, v7
	v_rcp_f32_e32 v7, v11
	v_cvt_f32_f16_e32 v11, v151
	v_cvt_f32_f16_e32 v5, v150
	v_pk_mul_f32 v[6:7], v[12:13], v[6:7]
	s_nop 0
	v_cvt_pk_f16_f32 v12, v6, v7
	v_pack_b32_f16 v13, v4, v12
	v_cvt_f32_f16_sdwa v4, v149 dst_sel:DWORD dst_unused:UNUSED_PAD src0_sel:WORD_1
	v_rcp_f32_e32 v11, v11
	v_rcp_f32_e32 v5, v5
	v_mov_b32_e32 v6, v101
	v_mov_b32_e32 v7, v102
	v_rcp_f32_e32 v4, v4
	v_pk_mul_f32 v[6:7], v[6:7], v[10:11]
	v_cvt_f32_f16_sdwa v11, v151 dst_sel:DWORD dst_unused:UNUSED_PAD src0_sel:WORD_1
	v_cvt_pk_f16_f32 v10, v6, v7
	v_pk_mov_b32 v[6:7], v[98:99], v[100:101] op_sel:[1,0]
	s_nop 0
	v_pk_mul_f32 v[4:5], v[6:7], v[4:5]
	s_nop 0
	v_cvt_pk_f16_f32 v4, v4, v5
	v_rcp_f32_e32 v5, v11
	v_alignbit_b32 v6, v4, v12, 16
	v_alignbit_b32 v7, v10, v4, 16
	v_lshrrev_b32_e32 v10, 16, v10
	v_fma_mixhi_f16 v10, v103, v5, 0
	v_lshrrev_b32_e32 v5, 4, v6
	v_and_b32_e32 v5, 0x10001, v5
	v_add3_u32 v5, v6, v5, s21
	v_lshrrev_b32_e32 v6, 4, v7
	v_and_b32_e32 v6, 0x10001, v6
	v_add3_u32 v6, v7, v6, s21
	v_cvt_f32_f16_e32 v7, v140
	v_lshrrev_b32_e32 v4, 4, v13
	v_lshrrev_b32_e32 v11, 4, v10
	v_and_b32_e32 v4, 0x10001, v4
	v_and_b32_e32 v11, 0x10001, v11
	v_add3_u32 v4, v13, v4, s21
	v_rcp_f32_e32 v12, v7
	v_add3_u32 v7, v10, v11, s21
	v_and_b32_e32 v4, 0xfff0fff0, v4
	v_and_b32_e32 v5, 0xfff0fff0, v5
	v_and_b32_e32 v6, 0xfff0fff0, v6
	v_and_b32_e32 v7, 0xfff0fff0, v7
	global_store_dwordx4 v[8:9], v[4:7], off offset:256
	v_cvt_f32_f16_e32 v9, v141
	v_mov_b32_e32 v10, v85
	v_cvt_f32_f16_sdwa v6, v140 dst_sel:DWORD dst_unused:UNUSED_PAD src0_sel:WORD_1
	v_cvt_f32_f16_sdwa v7, v142 dst_sel:DWORD dst_unused:UNUSED_PAD src0_sel:WORD_1
	v_mov_b32_e32 v11, v86
	v_fma_mixlo_f16 v4, v84, v12, 0
	v_rcp_f32_e32 v6, v6
	v_rcp_f32_e32 v8, v7
	v_rcp_f32_e32 v7, v9
	v_cvt_f32_f16_e32 v9, v143
	v_cvt_f32_f16_e32 v5, v142
	v_mov_b32_e32 v13, v66
	v_pk_mul_f32 v[6:7], v[10:11], v[6:7]
	v_rcp_f32_e32 v9, v9
	v_cvt_pk_f16_f32 v10, v6, v7
	v_pack_b32_f16 v11, v4, v10
	v_cvt_f32_f16_sdwa v4, v141 dst_sel:DWORD dst_unused:UNUSED_PAD src0_sel:WORD_1
	v_rcp_f32_e32 v5, v5
	v_mov_b32_e32 v6, v93
	v_mov_b32_e32 v7, v94
	v_rcp_f32_e32 v4, v4
	v_pk_mul_f32 v[6:7], v[6:7], v[8:9]
	v_cvt_f32_f16_sdwa v9, v143 dst_sel:DWORD dst_unused:UNUSED_PAD src0_sel:WORD_1
	v_cvt_pk_f16_f32 v8, v6, v7
	v_pk_mov_b32 v[6:7], v[86:87], v[92:93] op_sel:[1,0]
	s_nop 0
	v_pk_mul_f32 v[4:5], v[6:7], v[4:5]
	s_nop 0
	v_cvt_pk_f16_f32 v4, v4, v5
	v_rcp_f32_e32 v5, v9
	v_alignbit_b32 v6, v4, v10, 16
	v_alignbit_b32 v7, v8, v4, 16
	v_lshrrev_b32_e32 v8, 16, v8
	v_fma_mixhi_f16 v8, v95, v5, 0
	v_lshrrev_b32_e32 v5, 4, v6
	v_and_b32_e32 v5, 0x10001, v5
	v_add3_u32 v5, v6, v5, s21
	v_lshrrev_b32_e32 v6, 4, v7
	v_and_b32_e32 v6, 0x10001, v6
	v_cvt_f32_f16_e32 v10, v136
	v_add3_u32 v6, v7, v6, s21
	v_lshrrev_b32_e32 v7, 4, v8
	v_lshrrev_b32_e32 v4, 4, v11
	v_and_b32_e32 v7, 0x10001, v7
	v_and_b32_e32 v4, 0x10001, v4
	v_add3_u32 v7, v8, v7, s21
	v_lshl_add_u64 v[8:9], v[80:81], 0, s[10:11]
	s_mov_b32 s10, 0xa0000
	v_add3_u32 v4, v11, v4, s21
	v_rcp_f32_e32 v12, v10
	v_add_co_u32_e32 v10, vcc, s10, v80
	v_and_b32_e32 v4, 0xfff0fff0, v4
	v_and_b32_e32 v5, 0xfff0fff0, v5
	v_and_b32_e32 v6, 0xfff0fff0, v6
	v_and_b32_e32 v7, 0xfff0fff0, v7
	v_addc_co_u32_e32 v11, vcc, 0, v81, vcc
	global_store_dwordx4 v[10:11], v[4:7], off
	v_cvt_f32_f16_e32 v11, v137
	s_mov_b64 s[10:11], 0xb0000
	v_cvt_f32_f16_sdwa v6, v136 dst_sel:DWORD dst_unused:UNUSED_PAD src0_sel:WORD_1
	v_cvt_f32_f16_sdwa v7, v138 dst_sel:DWORD dst_unused:UNUSED_PAD src0_sel:WORD_1
	v_fma_mixlo_f16 v4, v64, v12, 0
	v_mov_b32_e32 v12, v65
	v_rcp_f32_e32 v6, v6
	v_rcp_f32_e32 v10, v7
	v_rcp_f32_e32 v7, v11
	v_cvt_f32_f16_e32 v11, v139
	v_cvt_f32_f16_e32 v5, v138
	v_pk_mul_f32 v[6:7], v[12:13], v[6:7]
	s_nop 0
	v_cvt_pk_f16_f32 v12, v6, v7
	v_pack_b32_f16 v13, v4, v12
	v_cvt_f32_f16_sdwa v4, v137 dst_sel:DWORD dst_unused:UNUSED_PAD src0_sel:WORD_1
	v_rcp_f32_e32 v11, v11
	v_rcp_f32_e32 v5, v5
	v_mov_b32_e32 v6, v77
	v_mov_b32_e32 v7, v78
	v_rcp_f32_e32 v4, v4
	v_pk_mul_f32 v[6:7], v[6:7], v[10:11]
	v_cvt_f32_f16_sdwa v11, v139 dst_sel:DWORD dst_unused:UNUSED_PAD src0_sel:WORD_1
	v_cvt_pk_f16_f32 v10, v6, v7
	v_pk_mov_b32 v[6:7], v[66:67], v[76:77] op_sel:[1,0]
	s_nop 0
	v_pk_mul_f32 v[4:5], v[6:7], v[4:5]
	s_nop 0
	v_cvt_pk_f16_f32 v4, v4, v5
	v_rcp_f32_e32 v5, v11
	v_alignbit_b32 v6, v4, v12, 16
	v_alignbit_b32 v7, v10, v4, 16
	v_lshrrev_b32_e32 v10, 16, v10
	v_fma_mixhi_f16 v10, v79, v5, 0
	v_lshrrev_b32_e32 v5, 4, v6
	v_and_b32_e32 v5, 0x10001, v5
	v_add3_u32 v5, v6, v5, s21
	v_lshrrev_b32_e32 v6, 4, v7
	v_and_b32_e32 v6, 0x10001, v6
	v_add3_u32 v6, v7, v6, s21
	v_cvt_f32_f16_e32 v7, v132
	v_lshrrev_b32_e32 v4, 4, v13
	v_lshrrev_b32_e32 v11, 4, v10
	v_and_b32_e32 v4, 0x10001, v4
	v_and_b32_e32 v11, 0x10001, v11
	v_add3_u32 v4, v13, v4, s21
	v_rcp_f32_e32 v12, v7
	v_add3_u32 v7, v10, v11, s21
	v_and_b32_e32 v4, 0xfff0fff0, v4
	v_and_b32_e32 v5, 0xfff0fff0, v5
	v_and_b32_e32 v6, 0xfff0fff0, v6
	v_and_b32_e32 v7, 0xfff0fff0, v7
	global_store_dwordx4 v[8:9], v[4:7], off offset:256
	v_cvt_f32_f16_e32 v9, v133
	v_mov_b32_e32 v10, v49
	v_cvt_f32_f16_sdwa v6, v132 dst_sel:DWORD dst_unused:UNUSED_PAD src0_sel:WORD_1
	v_cvt_f32_f16_sdwa v7, v134 dst_sel:DWORD dst_unused:UNUSED_PAD src0_sel:WORD_1
	v_mov_b32_e32 v11, v50
	v_fma_mixlo_f16 v4, v48, v12, 0
	v_rcp_f32_e32 v6, v6
	v_rcp_f32_e32 v8, v7
	v_rcp_f32_e32 v7, v9
	v_cvt_f32_f16_e32 v9, v135
	v_cvt_f32_f16_e32 v5, v134
	v_mov_b32_e32 v13, v34
	v_pk_mul_f32 v[6:7], v[10:11], v[6:7]
	v_rcp_f32_e32 v9, v9
	v_cvt_pk_f16_f32 v10, v6, v7
	v_pack_b32_f16 v11, v4, v10
	v_cvt_f32_f16_sdwa v4, v133 dst_sel:DWORD dst_unused:UNUSED_PAD src0_sel:WORD_1
	v_rcp_f32_e32 v5, v5
	v_mov_b32_e32 v6, v61
	v_mov_b32_e32 v7, v62
	v_rcp_f32_e32 v4, v4
	v_pk_mul_f32 v[6:7], v[6:7], v[8:9]
	v_cvt_f32_f16_sdwa v9, v135 dst_sel:DWORD dst_unused:UNUSED_PAD src0_sel:WORD_1
	v_cvt_pk_f16_f32 v8, v6, v7
	v_pk_mov_b32 v[6:7], v[50:51], v[60:61] op_sel:[1,0]
	s_nop 0
	v_pk_mul_f32 v[4:5], v[6:7], v[4:5]
	s_nop 0
	v_cvt_pk_f16_f32 v4, v4, v5
	v_rcp_f32_e32 v5, v9
	v_alignbit_b32 v6, v4, v10, 16
	v_alignbit_b32 v7, v8, v4, 16
	v_lshrrev_b32_e32 v8, 16, v8
	v_fma_mixhi_f16 v8, v63, v5, 0
	v_lshrrev_b32_e32 v5, 4, v6
	v_and_b32_e32 v5, 0x10001, v5
	v_add3_u32 v5, v6, v5, s21
	v_lshrrev_b32_e32 v6, 4, v7
	v_and_b32_e32 v6, 0x10001, v6
	v_cvt_f32_f16_e32 v10, v128
	v_add3_u32 v6, v7, v6, s21
	v_lshrrev_b32_e32 v7, 4, v8
	v_lshrrev_b32_e32 v4, 4, v11
	v_and_b32_e32 v7, 0x10001, v7
	v_and_b32_e32 v4, 0x10001, v4
	v_add3_u32 v7, v8, v7, s21
	v_lshl_add_u64 v[8:9], v[80:81], 0, s[10:11]
	s_mov_b32 s10, 0xb0000
	v_add3_u32 v4, v11, v4, s21
	v_rcp_f32_e32 v12, v10
	v_add_co_u32_e32 v10, vcc, s10, v80
	v_and_b32_e32 v4, 0xfff0fff0, v4
	v_and_b32_e32 v5, 0xfff0fff0, v5
	v_and_b32_e32 v6, 0xfff0fff0, v6
	v_and_b32_e32 v7, 0xfff0fff0, v7
	v_addc_co_u32_e32 v11, vcc, 0, v81, vcc
	global_store_dwordx4 v[10:11], v[4:7], off
	v_cvt_f32_f16_e32 v11, v129
	s_andn2_b64 vcc, exec, s[40:41]
	v_cvt_f32_f16_sdwa v6, v128 dst_sel:DWORD dst_unused:UNUSED_PAD src0_sel:WORD_1
	v_cvt_f32_f16_sdwa v7, v130 dst_sel:DWORD dst_unused:UNUSED_PAD src0_sel:WORD_1
	v_fma_mixlo_f16 v4, v32, v12, 0
	v_mov_b32_e32 v12, v33
	v_rcp_f32_e32 v6, v6
	v_rcp_f32_e32 v10, v7
	v_rcp_f32_e32 v7, v11
	v_cvt_f32_f16_e32 v11, v131
	v_cvt_f32_f16_e32 v5, v130
	v_pk_mul_f32 v[6:7], v[12:13], v[6:7]
	s_nop 0
	v_cvt_pk_f16_f32 v12, v6, v7
	v_pack_b32_f16 v13, v4, v12
	v_cvt_f32_f16_sdwa v4, v129 dst_sel:DWORD dst_unused:UNUSED_PAD src0_sel:WORD_1
	v_rcp_f32_e32 v11, v11
	v_rcp_f32_e32 v5, v5
	v_mov_b32_e32 v6, v45
	v_mov_b32_e32 v7, v46
	v_rcp_f32_e32 v4, v4
	v_pk_mul_f32 v[6:7], v[6:7], v[10:11]
	v_cvt_f32_f16_sdwa v11, v131 dst_sel:DWORD dst_unused:UNUSED_PAD src0_sel:WORD_1
	v_cvt_pk_f16_f32 v10, v6, v7
	v_pk_mov_b32 v[6:7], v[34:35], v[44:45] op_sel:[1,0]
	s_nop 0
	v_pk_mul_f32 v[4:5], v[6:7], v[4:5]
	s_nop 0
	v_cvt_pk_f16_f32 v4, v4, v5
	v_rcp_f32_e32 v5, v11
	v_alignbit_b32 v6, v4, v12, 16
	v_alignbit_b32 v7, v10, v4, 16
	v_lshrrev_b32_e32 v10, 16, v10
	v_fma_mixhi_f16 v10, v47, v5, 0
	v_lshrrev_b32_e32 v5, 4, v6
	v_and_b32_e32 v5, 0x10001, v5
	v_add3_u32 v5, v6, v5, s21
	v_lshrrev_b32_e32 v6, 4, v7
	v_and_b32_e32 v6, 0x10001, v6
	v_lshrrev_b32_e32 v4, 4, v13
	v_add3_u32 v6, v7, v6, s21
	v_lshrrev_b32_e32 v7, 4, v10
	v_and_b32_e32 v4, 0x10001, v4
	v_and_b32_e32 v7, 0x10001, v7
	v_add3_u32 v4, v13, v4, s21
	v_add3_u32 v7, v10, v7, s21
	v_and_b32_e32 v4, 0xfff0fff0, v4
	v_and_b32_e32 v5, 0xfff0fff0, v5
	v_and_b32_e32 v6, 0xfff0fff0, v6
	v_and_b32_e32 v7, 0xfff0fff0, v7
	global_store_dwordx4 v[8:9], v[4:7], off offset:256
	s_cbranch_vccnz .LBB0_1739
	s_waitcnt vmcnt(0)
	v_readlane_b32 s4, v251, 63
	s_cmpk_gt_u32 s4, 0xff
	s_cbranch_scc1 .LBB0_1750
	s_barrier

.LBB0_2120:
	s_add_u32 s27, s42, 0xfff80080
	s_addc_u32 s38, s43, -1
	s_add_i32 s46, 0, 0x10000
	v_add_u32_e32 v128, s46, v198
	ds_read_b128 v[108:111], v128
	ds_read_b128 v[112:115], v128 offset:1024
	ds_read_b128 v[120:123], v128 offset:2048
	ds_read_b128 v[128:131], v128 offset:3072
	s_cmp_eq_u32 s17, 28
	s_cselect_b32 s45, s35, s38
	s_cselect_b32 s44, s34, s27
	s_cselect_b32 s39, s37, s15
	s_cselect_b32 s38, s36, s14
	s_add_i32 m0, s6, 0xc000
	ds_read_b128 v[148:151], v199
	ds_read_b128 v[152:155], v199 offset:1024
	ds_read_b128 v[156:159], v199 offset:2048
	ds_read_b128 v[160:163], v199 offset:3072
	ds_read_b128 v[164:167], v199 offset:4096
	ds_read_b128 v[168:171], v199 offset:5120
	ds_read_b128 v[172:175], v199 offset:6144
	ds_read_b128 v[176:179], v199 offset:7168
	global_load_lds_dwordx4 v182, s[42:43]
	s_add_i32 m0, s6, 0xe000
	s_nop 0
	global_load_lds_dwordx4 v184, s[42:43]
	s_barrier
	s_waitcnt lgkmcnt(0)
	v_mfma_f32_16x16x32_f16 v[144:147], v[108:111], v[148:151], v[144:147]
	v_mfma_f32_16x16x32_f16 v[140:143], v[120:123], v[148:151], v[140:143]
	v_mfma_f32_16x16x32_f16 v[124:127], v[108:111], v[156:159], v[124:127]
	v_mfma_f32_16x16x32_f16 v[116:119], v[120:123], v[156:159], v[116:119]
	v_mfma_f32_16x16x32_f16 v[96:99], v[108:111], v[164:167], v[96:99]
	v_mfma_f32_16x16x32_f16 v[92:95], v[120:123], v[164:167], v[92:95]
	v_mfma_f32_16x16x32_f16 v[88:91], v[108:111], v[172:175], v[88:91]
	v_mfma_f32_16x16x32_f16 v[80:83], v[120:123], v[172:175], v[80:83]
	v_mfma_f32_16x16x32_f16 v[144:147], v[112:115], v[152:155], v[144:147]
	v_mfma_f32_16x16x32_f16 v[140:143], v[128:131], v[152:155], v[140:143]
	v_mfma_f32_16x16x32_f16 v[124:127], v[112:115], v[160:163], v[124:127]
	v_mfma_f32_16x16x32_f16 v[116:119], v[128:131], v[160:163], v[116:119]
	v_mfma_f32_16x16x32_f16 v[96:99], v[112:115], v[168:171], v[96:99]
	v_mfma_f32_16x16x32_f16 v[92:95], v[128:131], v[168:171], v[92:95]
	v_mfma_f32_16x16x32_f16 v[88:91], v[112:115], v[176:179], v[88:91]
	v_mfma_f32_16x16x32_f16 v[80:83], v[128:131], v[176:179], v[80:83]
	s_barrier
	s_add_i32 s27, 0, 0x14000
	v_add_u32_e32 v194, s27, v198
	s_add_i32 s46, s46, s5
	ds_read_b128 v[186:189], v194
	ds_read_b128 v[190:193], v194 offset:1024
	ds_read_b128 v[200:203], v194 offset:2048
	ds_read_b128 v[206:209], v194 offset:3072
	v_lshl_add_u64 v[194:195], s[38:39], 0, v[2:3]
	s_mov_b32 m0, s46
	v_lshl_add_u64 v[210:211], s[38:39], 0, v[180:181]
	global_load_lds_dwordx4 v[194:195], off
	s_add_i32 m0, s46, 0x2000
	s_nop 0
	global_load_lds_dwordx4 v[210:211], off
	s_waitcnt vmcnt(10)
	s_barrier
	s_waitcnt lgkmcnt(0)
	v_mfma_f32_16x16x32_f16 v[136:139], v[186:189], v[148:151], v[136:139]
	v_mfma_f32_16x16x32_f16 v[132:135], v[200:203], v[148:151], v[132:135]
	v_mfma_f32_16x16x32_f16 v[104:107], v[186:189], v[156:159], v[104:107]
	v_mfma_f32_16x16x32_f16 v[100:103], v[200:203], v[156:159], v[100:103]
	v_mfma_f32_16x16x32_f16 v[84:87], v[186:189], v[164:167], v[84:87]
	v_mfma_f32_16x16x32_f16 v[76:79], v[200:203], v[164:167], v[76:79]
	v_mfma_f32_16x16x32_f16 v[72:75], v[186:189], v[172:175], v[72:75]
	v_mfma_f32_16x16x32_f16 v[68:71], v[200:203], v[172:175], v[68:71]
	v_mfma_f32_16x16x32_f16 v[136:139], v[190:193], v[152:155], v[136:139]
	v_mfma_f32_16x16x32_f16 v[132:135], v[206:209], v[152:155], v[132:135]
	v_mfma_f32_16x16x32_f16 v[104:107], v[190:193], v[160:163], v[104:107]
	v_mfma_f32_16x16x32_f16 v[100:103], v[206:209], v[160:163], v[100:103]
	v_mfma_f32_16x16x32_f16 v[84:87], v[190:193], v[168:171], v[84:87]
	v_mfma_f32_16x16x32_f16 v[76:79], v[206:209], v[168:171], v[76:79]
	v_mfma_f32_16x16x32_f16 v[72:75], v[190:193], v[176:179], v[72:75]
	v_mfma_f32_16x16x32_f16 v[68:71], v[206:209], v[176:179], v[68:71]
	s_mov_b32 m0, s6
	v_lshl_add_u64 v[212:213], s[44:45], 0, v[2:3]
	s_barrier
	ds_read_b128 v[148:151], v199 offset:16384
	ds_read_b128 v[152:155], v199 offset:17408
	ds_read_b128 v[156:159], v199 offset:18432
	ds_read_b128 v[160:163], v199 offset:19456
	ds_read_b128 v[164:167], v199 offset:20480
	ds_read_b128 v[168:171], v199 offset:21504
	ds_read_b128 v[172:175], v199 offset:22528
	ds_read_b128 v[176:179], v199 offset:23552
	global_load_lds_dwordx4 v[212:213], off
	v_lshl_add_u64 v[214:215], s[44:45], 0, v[180:181]
	s_mov_b32 m0, s7
	s_nop 0
	global_load_lds_dwordx4 v[214:215], off
	s_barrier
	s_waitcnt lgkmcnt(0)
	v_mfma_f32_16x16x32_f16 v[64:67], v[108:111], v[148:151], v[64:67]
	v_mfma_f32_16x16x32_f16 v[60:63], v[120:123], v[148:151], v[60:63]
	v_mfma_f32_16x16x32_f16 v[48:51], v[108:111], v[156:159], v[48:51]
	v_mfma_f32_16x16x32_f16 v[44:47], v[120:123], v[156:159], v[44:47]
	v_mfma_f32_16x16x32_f16 v[32:35], v[108:111], v[164:167], v[32:35]
	v_mfma_f32_16x16x32_f16 v[28:31], v[120:123], v[164:167], v[28:31]
	v_mfma_f32_16x16x32_f16 v[20:23], v[108:111], v[172:175], v[20:23]
	v_mfma_f32_16x16x32_f16 v[12:15], v[120:123], v[172:175], v[12:15]
	v_mfma_f32_16x16x32_f16 v[64:67], v[112:115], v[152:155], v[64:67]
	v_mfma_f32_16x16x32_f16 v[60:63], v[128:131], v[152:155], v[60:63]
	v_mfma_f32_16x16x32_f16 v[48:51], v[112:115], v[160:163], v[48:51]
	v_mfma_f32_16x16x32_f16 v[44:47], v[128:131], v[160:163], v[44:47]
	v_mfma_f32_16x16x32_f16 v[32:35], v[112:115], v[168:171], v[32:35]
	v_mfma_f32_16x16x32_f16 v[28:31], v[128:131], v[168:171], v[28:31]
	v_mfma_f32_16x16x32_f16 v[20:23], v[112:115], v[176:179], v[20:23]
	v_mfma_f32_16x16x32_f16 v[12:15], v[128:131], v[176:179], v[12:15]
	s_barrier
	s_add_u32 s46, s38, 0x80000
	s_addc_u32 s47, s39, 0
	s_add_i32 s27, s27, s5
	v_lshl_add_u64 v[108:109], s[46:47], 0, v[2:3]
	s_mov_b32 m0, s27
	s_nop 0
	global_load_lds_dwordx4 v[108:109], off
	s_add_i32 m0, s27, 0x2000
	s_nop 0
	global_load_lds_dwordx4 v180, s[46:47]
	s_waitcnt vmcnt(8)
	s_barrier
	v_mfma_f32_16x16x32_f16 v[56:59], v[186:189], v[148:151], v[56:59]
	v_mfma_f32_16x16x32_f16 v[52:55], v[200:203], v[148:151], v[52:55]
	v_mfma_f32_16x16x32_f16 v[40:43], v[186:189], v[156:159], v[40:43]
	v_mfma_f32_16x16x32_f16 v[36:39], v[200:203], v[156:159], v[36:39]
	v_mfma_f32_16x16x32_f16 v[24:27], v[186:189], v[164:167], v[24:27]
	v_mfma_f32_16x16x32_f16 v[16:19], v[200:203], v[164:167], v[16:19]
	v_mfma_f32_16x16x32_f16 v[8:11], v[186:189], v[172:175], v[8:11]
	v_mfma_f32_16x16x32_f16 v[4:7], v[200:203], v[172:175], v[4:7]
	v_mfma_f32_16x16x32_f16 v[56:59], v[190:193], v[152:155], v[56:59]
	v_mfma_f32_16x16x32_f16 v[52:55], v[206:209], v[152:155], v[52:55]
	v_mfma_f32_16x16x32_f16 v[40:43], v[190:193], v[160:163], v[40:43]
	v_mfma_f32_16x16x32_f16 v[36:39], v[206:209], v[160:163], v[36:39]
	v_mfma_f32_16x16x32_f16 v[24:27], v[190:193], v[168:171], v[24:27]
	v_mfma_f32_16x16x32_f16 v[16:19], v[206:209], v[168:171], v[16:19]
	v_mfma_f32_16x16x32_f16 v[8:11], v[190:193], v[176:179], v[8:11]
	v_mfma_f32_16x16x32_f16 v[4:7], v[206:209], v[176:179], v[4:7]
	s_add_i32 s27, 0, 0x18000
	v_add_u32_e32 v128, s27, v198
	s_barrier
	ds_read_b128 v[108:111], v128
	ds_read_b128 v[112:115], v128 offset:1024
	ds_read_b128 v[120:123], v128 offset:2048
	ds_read_b128 v[128:131], v128 offset:3072
	s_add_u32 s44, s44, 0x80000
	s_addc_u32 s45, s45, 0
	s_mov_b32 m0, s8
	v_lshl_add_u64 v[186:187], s[44:45], 0, v[2:3]
	ds_read_b128 v[148:151], v199 offset:32768
	ds_read_b128 v[152:155], v199 offset:33792
	ds_read_b128 v[156:159], v199 offset:34816
	ds_read_b128 v[160:163], v199 offset:35840
	ds_read_b128 v[164:167], v199 offset:36864
	ds_read_b128 v[168:171], v199 offset:37888
	ds_read_b128 v[172:175], v199 offset:38912
	ds_read_b128 v[176:179], v199 offset:39936
	global_load_lds_dwordx4 v[186:187], off
	s_mov_b32 m0, s9
	s_nop 0
	global_load_lds_dwordx4 v180, s[44:45]
	s_barrier
	s_waitcnt lgkmcnt(0)
	v_mfma_f32_16x16x32_f16 v[144:147], v[108:111], v[148:151], v[144:147]
	v_mfma_f32_16x16x32_f16 v[140:143], v[120:123], v[148:151], v[140:143]
	v_mfma_f32_16x16x32_f16 v[124:127], v[108:111], v[156:159], v[124:127]
	v_mfma_f32_16x16x32_f16 v[116:119], v[120:123], v[156:159], v[116:119]
	v_mfma_f32_16x16x32_f16 v[96:99], v[108:111], v[164:167], v[96:99]
	v_mfma_f32_16x16x32_f16 v[92:95], v[120:123], v[164:167], v[92:95]
	v_mfma_f32_16x16x32_f16 v[88:91], v[108:111], v[172:175], v[88:91]
	v_mfma_f32_16x16x32_f16 v[80:83], v[120:123], v[172:175], v[80:83]
	v_mfma_f32_16x16x32_f16 v[144:147], v[112:115], v[152:155], v[144:147]
	v_mfma_f32_16x16x32_f16 v[140:143], v[128:131], v[152:155], v[140:143]
	v_mfma_f32_16x16x32_f16 v[124:127], v[112:115], v[160:163], v[124:127]
	v_mfma_f32_16x16x32_f16 v[116:119], v[128:131], v[160:163], v[116:119]
	v_mfma_f32_16x16x32_f16 v[96:99], v[112:115], v[168:171], v[96:99]
	v_mfma_f32_16x16x32_f16 v[92:95], v[128:131], v[168:171], v[92:95]
	v_mfma_f32_16x16x32_f16 v[88:91], v[112:115], v[176:179], v[88:91]
	v_mfma_f32_16x16x32_f16 v[80:83], v[128:131], v[176:179], v[80:83]
	s_barrier
	s_add_i32 s44, 0, 0x1c000
	s_add_i32 s27, s27, s5
	v_add_u32_e32 v206, s44, v198
	v_lshl_add_u64 v[194:195], v[194:195], 0, s[88:89]
	s_mov_b32 m0, s27
	ds_read_b128 v[186:189], v206
	ds_read_b128 v[190:193], v206 offset:1024
	ds_read_b128 v[200:203], v206 offset:2048
	ds_read_b128 v[206:209], v206 offset:3072
	global_load_lds_dwordx4 v[194:195], off
	v_lshl_add_u64 v[194:195], v[210:211], 0, s[88:89]
	s_add_i32 m0, s27, 0x2000
	s_nop 0
	global_load_lds_dwordx4 v[194:195], off
	s_waitcnt vmcnt(10)
	s_barrier
	s_waitcnt lgkmcnt(0)
	v_mfma_f32_16x16x32_f16 v[136:139], v[186:189], v[148:151], v[136:139]
	v_mfma_f32_16x16x32_f16 v[132:135], v[200:203], v[148:151], v[132:135]
	v_mfma_f32_16x16x32_f16 v[104:107], v[186:189], v[156:159], v[104:107]
	v_mfma_f32_16x16x32_f16 v[100:103], v[200:203], v[156:159], v[100:103]
	v_mfma_f32_16x16x32_f16 v[84:87], v[186:189], v[164:167], v[84:87]
	v_mfma_f32_16x16x32_f16 v[76:79], v[200:203], v[164:167], v[76:79]
	v_mfma_f32_16x16x32_f16 v[72:75], v[186:189], v[172:175], v[72:75]
	v_mfma_f32_16x16x32_f16 v[68:71], v[200:203], v[172:175], v[68:71]
	v_mfma_f32_16x16x32_f16 v[136:139], v[190:193], v[152:155], v[136:139]
	v_mfma_f32_16x16x32_f16 v[132:135], v[206:209], v[152:155], v[132:135]
	v_mfma_f32_16x16x32_f16 v[104:107], v[190:193], v[160:163], v[104:107]
	v_mfma_f32_16x16x32_f16 v[100:103], v[206:209], v[160:163], v[100:103]
	v_mfma_f32_16x16x32_f16 v[84:87], v[190:193], v[168:171], v[84:87]
	v_mfma_f32_16x16x32_f16 v[76:79], v[206:209], v[168:171], v[76:79]
	v_mfma_f32_16x16x32_f16 v[72:75], v[190:193], v[176:179], v[72:75]
	v_mfma_f32_16x16x32_f16 v[68:71], v[206:209], v[176:179], v[68:71]
	s_mov_b32 m0, s10
	v_lshl_add_u64 v[194:195], v[212:213], 0, s[88:89]
	s_barrier
	ds_read_b128 v[148:151], v199 offset:49152
	ds_read_b128 v[152:155], v199 offset:50176
	ds_read_b128 v[156:159], v199 offset:51200
	ds_read_b128 v[160:163], v199 offset:52224
	ds_read_b128 v[164:167], v199 offset:53248
	ds_read_b128 v[168:171], v199 offset:54272
	ds_read_b128 v[172:175], v199 offset:55296
	ds_read_b128 v[176:179], v199 offset:56320
	global_load_lds_dwordx4 v[194:195], off
	v_lshl_add_u64 v[194:195], v[214:215], 0, s[88:89]
	s_mov_b32 m0, s11
	s_nop 0
	global_load_lds_dwordx4 v[194:195], off
	s_barrier
	s_waitcnt lgkmcnt(0)
	v_mfma_f32_16x16x32_f16 v[64:67], v[108:111], v[148:151], v[64:67]
	v_mfma_f32_16x16x32_f16 v[60:63], v[120:123], v[148:151], v[60:63]
	v_mfma_f32_16x16x32_f16 v[48:51], v[108:111], v[156:159], v[48:51]
	v_mfma_f32_16x16x32_f16 v[44:47], v[120:123], v[156:159], v[44:47]
	v_mfma_f32_16x16x32_f16 v[32:35], v[108:111], v[164:167], v[32:35]
	v_mfma_f32_16x16x32_f16 v[28:31], v[120:123], v[164:167], v[28:31]
	v_mfma_f32_16x16x32_f16 v[20:23], v[108:111], v[172:175], v[20:23]
	v_mfma_f32_16x16x32_f16 v[12:15], v[120:123], v[172:175], v[12:15]
	v_mfma_f32_16x16x32_f16 v[64:67], v[112:115], v[152:155], v[64:67]
	v_mfma_f32_16x16x32_f16 v[60:63], v[128:131], v[152:155], v[60:63]
	v_mfma_f32_16x16x32_f16 v[48:51], v[112:115], v[160:163], v[48:51]
	v_mfma_f32_16x16x32_f16 v[44:47], v[128:131], v[160:163], v[44:47]
	v_mfma_f32_16x16x32_f16 v[32:35], v[112:115], v[168:171], v[32:35]
	v_mfma_f32_16x16x32_f16 v[28:31], v[128:131], v[168:171], v[28:31]
	v_mfma_f32_16x16x32_f16 v[20:23], v[112:115], v[176:179], v[20:23]
	v_mfma_f32_16x16x32_f16 v[12:15], v[128:131], v[176:179], v[12:15]
	s_barrier
	s_add_u32 s38, s38, 0x80080
	s_addc_u32 s39, s39, 0
	s_add_i32 s27, s44, s5
	v_lshl_add_u64 v[108:109], s[38:39], 0, v[2:3]
	s_mov_b32 m0, s27
	s_nop 0
	global_load_lds_dwordx4 v[108:109], off
	s_add_i32 m0, s27, 0x2000
	s_nop 0
	global_load_lds_dwordx4 v180, s[38:39]
	s_waitcnt vmcnt(8)
	s_barrier
	v_mfma_f32_16x16x32_f16 v[56:59], v[186:189], v[148:151], v[56:59]
	v_mfma_f32_16x16x32_f16 v[52:55], v[200:203], v[148:151], v[52:55]
	v_mfma_f32_16x16x32_f16 v[40:43], v[186:189], v[156:159], v[40:43]
	v_mfma_f32_16x16x32_f16 v[36:39], v[200:203], v[156:159], v[36:39]
	v_mfma_f32_16x16x32_f16 v[24:27], v[186:189], v[164:167], v[24:27]
	v_mfma_f32_16x16x32_f16 v[16:19], v[200:203], v[164:167], v[16:19]
	v_mfma_f32_16x16x32_f16 v[8:11], v[186:189], v[172:175], v[8:11]
	v_mfma_f32_16x16x32_f16 v[4:7], v[200:203], v[172:175], v[4:7]
	v_mfma_f32_16x16x32_f16 v[56:59], v[190:193], v[152:155], v[56:59]
	v_mfma_f32_16x16x32_f16 v[52:55], v[206:209], v[152:155], v[52:55]
	v_mfma_f32_16x16x32_f16 v[40:43], v[190:193], v[160:163], v[40:43]
	v_mfma_f32_16x16x32_f16 v[36:39], v[206:209], v[160:163], v[36:39]
	v_mfma_f32_16x16x32_f16 v[24:27], v[190:193], v[168:171], v[24:27]
	v_mfma_f32_16x16x32_f16 v[16:19], v[206:209], v[168:171], v[16:19]
	v_mfma_f32_16x16x32_f16 v[8:11], v[190:193], v[176:179], v[8:11]
	v_mfma_f32_16x16x32_f16 v[4:7], v[206:209], v[176:179], v[4:7]
	s_add_i32 s17, s17, 2
	s_add_u32 s42, s42, 0x100
	s_addc_u32 s43, s43, 0
	s_add_u32 s14, s14, 0x100
	s_addc_u32 s15, s15, 0
	s_cmp_gt_u32 s17, 29
	s_barrier
	s_cbranch_scc0 .LBB0_2120
	s_lshl_b32 s14, s30, 8
	v_mov_b32_e32 v148, v196
	v_mov_b32_e32 v108, v197
	s_add_i32 s17, s14, s12
	s_lshl_b32 s14, s31, 8
	s_or_b32 s14, s14, s13
	v_lshl_add_u32 v108, v108, 2, s14
	s_cmp_lt_i32 s30, 64
	s_movk_i32 s14, 0x3000
	s_cselect_b32 s14, s14, 0x6000
	s_cmp_gt_i32 s30, 31
	s_cselect_b32 s14, s14, 0
	s_lshl_b32 s14, s14, 2
	v_readlane_b32 s15, v251, 41
	s_add_u32 s14, s15, s14
	v_readlane_b32 s15, v251, 42
	v_ashrrev_i32_e32 v109, 31, v108
	s_addc_u32 s15, s15, 0
	v_lshlrev_b64 v[186:187], 2, v[108:109]
	v_lshl_add_u64 v[108:109], s[14:15], 0, v[186:187]
	s_mov_b64 s[14:15], 0x4000
	v_add_u32_e32 v148, s17, v148
	v_lshl_add_u64 v[110:111], v[108:109], 0, s[14:15]
	s_movk_i32 s14, 0x4000
	v_ashrrev_i32_e32 v149, 31, v148
	v_add_co_u32_e32 v108, vcc, s14, v108
	v_lshlrev_b64 v[190:191], 13, v[148:149]
	s_mov_b64 s[14:15], 0x20000
	v_lshl_add_u64 v[224:225], v[190:191], 0, s[14:15]
	s_mov_b64 s[14:15], 0x40000
	v_lshl_add_u64 v[194:195], v[190:191], 0, s[14:15]
	s_mov_b64 s[14:15], 0x60000
	v_addc_co_u32_e32 v109, vcc, 0, v109, vcc
	v_lshl_add_u64 v[188:189], s[18:19], 0, v[186:187]
	v_lshl_add_u64 v[192:193], v[190:191], 0, s[14:15]
	global_load_dwordx4 v[128:131], v[108:109], off
	global_load_dwordx4 v[120:123], v[110:111], off offset:64
	global_load_dwordx4 v[112:115], v[110:111], off offset:512
	s_nop 0
	global_load_dwordx4 v[108:111], v[110:111], off offset:576
	v_lshl_add_u64 v[148:149], v[188:189], 0, v[190:191]
	v_lshl_add_u64 v[150:151], v[188:189], 0, v[224:225]
	v_lshl_add_u64 v[176:177], v[188:189], 0, v[194:195]
	v_lshl_add_u64 v[160:161], v[188:189], 0, v[192:193]
	flat_load_dwordx4 v[200:203], v[150:151] offset:576
	flat_load_dwordx4 v[206:209], v[150:151] offset:512
	flat_load_dwordx4 v[210:213], v[150:151] offset:64
	flat_load_dwordx4 v[214:217], v[150:151]
	flat_load_dwordx4 v[218:221], v[148:149] offset:576
	flat_load_dwordx4 v[232:235], v[148:149] offset:512
	flat_load_dwordx4 v[236:239], v[148:149] offset:64
	flat_load_dwordx4 v[240:243], v[148:149]
	s_nop 0
	flat_load_dwordx4 v[148:151], v[160:161] offset:576
	flat_load_dwordx4 v[152:155], v[160:161] offset:512
	flat_load_dwordx4 v[156:159], v[160:161] offset:64
	s_nop 0
	flat_load_dwordx4 v[160:163], v[160:161]
	s_nop 0
	flat_load_dwordx4 v[164:167], v[176:177] offset:576
	flat_load_dwordx4 v[168:171], v[176:177] offset:512
	flat_load_dwordx4 v[172:175], v[176:177] offset:64
	s_nop 0
	flat_load_dwordx4 v[176:179], v[176:177]
	v_readlane_b32 s14, v250, 25
	v_readlane_b32 s15, v250, 26
	s_mov_b64 s[30:31], 0x100000
	s_and_b64 vcc, exec, s[40:41]
	v_lshl_add_u64 v[226:227], s[14:15], 0, v[190:191]
	v_lshl_add_u64 v[226:227], v[226:227], 0, v[186:187]
	s_mov_b64 s[38:39], s[36:37]
	s_mov_b64 s[42:43], s[34:35]
	s_waitcnt vmcnt(0) lgkmcnt(0)
	s_nop 0
	v_pk_fma_f32 v[134:135], v[134:135], v[110:111], v[220:221]
	v_pk_fma_f32 v[132:133], v[132:133], v[108:109], v[218:219]
	global_store_dwordx4 v[226:227], v[132:135], off offset:576
	v_pk_fma_f32 v[102:103], v[102:103], v[110:111], v[202:203]
	v_pk_fma_f32 v[100:101], v[100:101], v[108:109], v[200:201]
	v_lshl_add_u64 v[132:133], s[14:15], 0, v[224:225]
	v_lshl_add_u64 v[132:133], v[132:133], 0, v[186:187]
	global_store_dwordx4 v[132:133], v[100:103], off offset:576
	v_pk_fma_f32 v[106:107], v[106:107], v[114:115], v[208:209]
	v_pk_fma_f32 v[104:105], v[104:105], v[112:113], v[206:207]
	v_lshl_add_u64 v[100:101], s[14:15], 0, v[194:195]
	v_lshl_add_u64 v[100:101], v[100:101], 0, v[186:187]
	v_pk_fma_f32 v[78:79], v[78:79], v[110:111], v[166:167]
	v_pk_fma_f32 v[76:77], v[76:77], v[108:109], v[164:165]
	global_store_dwordx4 v[132:133], v[104:107], off offset:512
	v_pk_fma_f32 v[86:87], v[86:87], v[114:115], v[170:171]
	v_pk_fma_f32 v[84:85], v[84:85], v[112:113], v[168:169]
	global_store_dwordx4 v[100:101], v[76:79], off offset:576
	v_lshl_add_u64 v[106:107], v[190:191], 0, s[30:31]
	s_mov_b64 s[30:31], 0x120000
	v_lshl_add_u64 v[76:77], s[14:15], 0, v[192:193]
	global_store_dwordx4 v[100:101], v[84:87], off offset:512
	v_pk_fma_f32 v[78:79], v[90:91], v[130:131], v[162:163]
	v_pk_fma_f32 v[72:73], v[72:73], v[112:113], v[152:153]
	v_lshl_add_u64 v[84:85], v[76:77], 0, v[186:187]
	v_pk_fma_f32 v[76:77], v[88:89], v[128:129], v[160:161]
	v_lshl_add_u64 v[152:153], v[190:191], 0, s[30:31]
	s_mov_b64 s[30:31], 0x140000
	v_pk_fma_f32 v[146:147], v[146:147], v[130:131], v[242:243]
	v_pk_fma_f32 v[144:145], v[144:145], v[128:129], v[240:241]
	v_pk_fma_f32 v[142:143], v[142:143], v[122:123], v[238:239]
	v_pk_fma_f32 v[140:141], v[140:141], v[120:121], v[236:237]
	v_pk_fma_f32 v[138:139], v[138:139], v[114:115], v[234:235]
	v_pk_fma_f32 v[136:137], v[136:137], v[112:113], v[232:233]
	v_pk_fma_f32 v[126:127], v[126:127], v[130:131], v[216:217]
	v_pk_fma_f32 v[124:125], v[124:125], v[128:129], v[214:215]
	v_pk_fma_f32 v[118:119], v[118:119], v[122:123], v[212:213]
	v_pk_fma_f32 v[116:117], v[116:117], v[120:121], v[210:211]
	v_pk_fma_f32 v[98:99], v[98:99], v[130:131], v[178:179]
	v_pk_fma_f32 v[96:97], v[96:97], v[128:129], v[176:177]
	v_pk_fma_f32 v[94:95], v[94:95], v[122:123], v[174:175]
	v_pk_fma_f32 v[92:93], v[92:93], v[120:121], v[172:173]
	global_store_dwordx4 v[84:85], v[76:79], off
	v_pk_fma_f32 v[74:75], v[74:75], v[114:115], v[154:155]
	v_pk_fma_f32 v[70:71], v[70:71], v[110:111], v[150:151]
	v_pk_fma_f32 v[78:79], v[82:83], v[122:123], v[158:159]
	v_pk_fma_f32 v[76:77], v[80:81], v[120:121], v[156:157]
	v_pk_fma_f32 v[68:69], v[68:69], v[108:109], v[148:149]
	v_lshl_add_u64 v[154:155], v[190:191], 0, s[30:31]
	s_mov_b64 s[30:31], 0x160000
	global_store_dwordx4 v[226:227], v[144:147], off
	global_store_dwordx4 v[226:227], v[140:143], off offset:64
	global_store_dwordx4 v[226:227], v[136:139], off offset:512
	global_store_dwordx4 v[132:133], v[124:127], off
	global_store_dwordx4 v[132:133], v[116:119], off offset:64
	global_store_dwordx4 v[100:101], v[96:99], off
	global_store_dwordx4 v[100:101], v[92:95], off offset:64
	global_store_dwordx4 v[84:85], v[76:79], off offset:64
	global_store_dwordx4 v[84:85], v[72:75], off offset:512
	global_store_dwordx4 v[84:85], v[68:71], off offset:576
	v_lshl_add_u64 v[100:101], v[190:191], 0, s[30:31]
	v_lshl_add_u64 v[96:97], v[188:189], 0, v[154:155]
	v_lshl_add_u64 v[68:69], v[188:189], 0, v[106:107]
	v_lshl_add_u64 v[70:71], v[188:189], 0, v[152:153]
	v_lshl_add_u64 v[80:81], v[188:189], 0, v[100:101]
	flat_load_dwordx4 v[102:105], v[70:71] offset:576
	flat_load_dwordx4 v[116:119], v[70:71] offset:512
	flat_load_dwordx4 v[124:127], v[70:71] offset:64
	flat_load_dwordx4 v[132:135], v[70:71]
	flat_load_dwordx4 v[136:139], v[68:69] offset:576
	flat_load_dwordx4 v[140:143], v[68:69] offset:512
	flat_load_dwordx4 v[144:147], v[68:69] offset:64
	flat_load_dwordx4 v[148:151], v[68:69]
	s_nop 0
	flat_load_dwordx4 v[68:71], v[80:81] offset:576
	flat_load_dwordx4 v[72:75], v[80:81] offset:512
	flat_load_dwordx4 v[76:79], v[80:81] offset:64
	s_nop 0
	flat_load_dwordx4 v[80:83], v[80:81]
	s_nop 0
	flat_load_dwordx4 v[84:87], v[96:97] offset:576
	flat_load_dwordx4 v[88:91], v[96:97] offset:512
	flat_load_dwordx4 v[92:95], v[96:97] offset:64
	s_nop 0
	flat_load_dwordx4 v[96:99], v[96:97]
	v_lshl_add_u64 v[106:107], s[14:15], 0, v[106:107]
	s_waitcnt vmcnt(0) lgkmcnt(0)
	v_lshl_add_u64 v[106:107], v[106:107], 0, v[186:187]
	v_pk_fma_f32 v[54:55], v[54:55], v[110:111], v[138:139]
	v_pk_fma_f32 v[52:53], v[52:53], v[108:109], v[136:137]
	global_store_dwordx4 v[106:107], v[52:55], off offset:576
	v_pk_fma_f32 v[38:39], v[38:39], v[110:111], v[104:105]
	v_pk_fma_f32 v[36:37], v[36:37], v[108:109], v[102:103]
	v_lshl_add_u64 v[52:53], s[14:15], 0, v[152:153]
	v_lshl_add_u64 v[52:53], v[52:53], 0, v[186:187]
	global_store_dwordx4 v[52:53], v[36:39], off offset:576
	v_pk_fma_f32 v[18:19], v[18:19], v[110:111], v[86:87]
	v_pk_fma_f32 v[16:17], v[16:17], v[108:109], v[84:85]
	v_lshl_add_u64 v[36:37], s[14:15], 0, v[154:155]
	v_lshl_add_u64 v[36:37], v[36:37], 0, v[186:187]
	v_pk_fma_f32 v[26:27], v[26:27], v[114:115], v[90:91]
	v_pk_fma_f32 v[24:25], v[24:25], v[112:113], v[88:89]
	global_store_dwordx4 v[36:37], v[16:19], off offset:576
	v_pk_fma_f32 v[66:67], v[66:67], v[130:131], v[150:151]
	v_pk_fma_f32 v[64:65], v[64:65], v[128:129], v[148:149]
	v_lshl_add_u64 v[16:17], s[14:15], 0, v[100:101]
	v_pk_fma_f32 v[62:63], v[62:63], v[122:123], v[146:147]
	v_pk_fma_f32 v[60:61], v[60:61], v[120:121], v[144:145]
	v_pk_fma_f32 v[58:59], v[58:59], v[114:115], v[142:143]
	v_pk_fma_f32 v[56:57], v[56:57], v[112:113], v[140:141]
	v_pk_fma_f32 v[50:51], v[50:51], v[130:131], v[134:135]
	v_pk_fma_f32 v[48:49], v[48:49], v[128:129], v[132:133]
	v_pk_fma_f32 v[46:47], v[46:47], v[122:123], v[126:127]
	v_pk_fma_f32 v[44:45], v[44:45], v[120:121], v[124:125]
	v_pk_fma_f32 v[42:43], v[42:43], v[114:115], v[118:119]
	v_pk_fma_f32 v[40:41], v[40:41], v[112:113], v[116:117]
	v_pk_fma_f32 v[34:35], v[34:35], v[130:131], v[98:99]
	v_pk_fma_f32 v[32:33], v[32:33], v[128:129], v[96:97]
	v_pk_fma_f32 v[30:31], v[30:31], v[122:123], v[94:95]
	v_pk_fma_f32 v[28:29], v[28:29], v[120:121], v[92:93]
	global_store_dwordx4 v[36:37], v[24:27], off offset:512
	v_pk_fma_f32 v[18:19], v[22:23], v[130:131], v[82:83]
	v_pk_fma_f32 v[14:15], v[14:15], v[122:123], v[78:79]
	v_lshl_add_u64 v[24:25], v[16:17], 0, v[186:187]
	v_pk_fma_f32 v[16:17], v[20:21], v[128:129], v[80:81]
	v_pk_fma_f32 v[12:13], v[12:13], v[120:121], v[76:77]
	v_pk_fma_f32 v[10:11], v[10:11], v[114:115], v[74:75]
	v_pk_fma_f32 v[8:9], v[8:9], v[112:113], v[72:73]
	v_pk_fma_f32 v[6:7], v[6:7], v[110:111], v[70:71]
	v_pk_fma_f32 v[4:5], v[4:5], v[108:109], v[68:69]
	global_store_dwordx4 v[106:107], v[64:67], off
	global_store_dwordx4 v[106:107], v[60:63], off offset:64
	global_store_dwordx4 v[106:107], v[56:59], off offset:512
	global_store_dwordx4 v[52:53], v[48:51], off
	global_store_dwordx4 v[52:53], v[44:47], off offset:64
	global_store_dwordx4 v[52:53], v[40:43], off offset:512
	global_store_dwordx4 v[36:37], v[32:35], off
	global_store_dwordx4 v[36:37], v[28:31], off offset:64
	global_store_dwordx4 v[24:25], v[16:19], off
	global_store_dwordx4 v[24:25], v[12:15], off offset:64
	global_store_dwordx4 v[24:25], v[8:11], off offset:512
	global_store_dwordx4 v[24:25], v[4:7], off offset:576
	s_mov_b32 s31, s16
	s_mov_b32 s30, s26
	s_cbranch_vccz .LBB0_2113
	s_waitcnt vmcnt(0)
	s_cmpk_gt_u32 s4, 0xff
	s_cbranch_scc1 .LBB0_2124
	s_barrier

.LBB0_2133:
	s_add_u32 s38, s40, 0xfff80080
	s_addc_u32 s39, s41, -1
	s_add_i32 s45, 0, 0x10000
	v_add_u32_e32 v144, s45, v158
	ds_read_b128 v[132:135], v144
	ds_read_b128 v[136:139], v144 offset:1024
	ds_read_b128 v[140:143], v144 offset:2048
	ds_read_b128 v[144:147], v144 offset:3072
	s_cmp_eq_u32 s44, 4
	s_cselect_b32 s43, s27, s39
	s_cselect_b32 s42, s26, s38
	s_cselect_b32 s39, s35, s31
	s_cselect_b32 s38, s34, s19
	s_add_i32 m0, s6, 0xc000
	ds_read_b128 v[160:163], v159
	ds_read_b128 v[164:167], v159 offset:1024
	ds_read_b128 v[168:171], v159 offset:2048
	ds_read_b128 v[172:175], v159 offset:3072
	ds_read_b128 v[176:179], v159 offset:4096
	ds_read_b128 v[180:183], v159 offset:5120
	ds_read_b128 v[184:187], v159 offset:6144
	ds_read_b128 v[188:191], v159 offset:7168
	global_load_lds_dwordx4 v150, s[40:41]
	v_lshl_add_u64 v[154:155], s[40:41], 0, v[152:153]
	s_add_i32 m0, s6, 0xe000
	s_nop 0
	global_load_lds_dwordx4 v[154:155], off
	s_barrier
	s_waitcnt lgkmcnt(0)
	v_mfma_f32_16x16x32_f16 v[128:131], v[132:135], v[160:163], v[128:131]
	v_mfma_f32_16x16x32_f16 v[124:127], v[140:143], v[160:163], v[124:127]
	v_mfma_f32_16x16x32_f16 v[112:115], v[132:135], v[168:171], v[112:115]
	v_mfma_f32_16x16x32_f16 v[108:111], v[140:143], v[168:171], v[108:111]
	v_mfma_f32_16x16x32_f16 v[96:99], v[132:135], v[176:179], v[96:99]
	v_mfma_f32_16x16x32_f16 v[92:95], v[140:143], v[176:179], v[92:95]
	v_mfma_f32_16x16x32_f16 v[80:83], v[132:135], v[184:187], v[80:83]
	v_mfma_f32_16x16x32_f16 v[76:79], v[140:143], v[184:187], v[76:79]
	v_mfma_f32_16x16x32_f16 v[128:131], v[136:139], v[164:167], v[128:131]
	v_mfma_f32_16x16x32_f16 v[124:127], v[144:147], v[164:167], v[124:127]
	v_mfma_f32_16x16x32_f16 v[112:115], v[136:139], v[172:175], v[112:115]
	v_mfma_f32_16x16x32_f16 v[108:111], v[144:147], v[172:175], v[108:111]
	v_mfma_f32_16x16x32_f16 v[96:99], v[136:139], v[180:183], v[96:99]
	v_mfma_f32_16x16x32_f16 v[92:95], v[144:147], v[180:183], v[92:95]
	v_mfma_f32_16x16x32_f16 v[80:83], v[136:139], v[188:191], v[80:83]
	v_mfma_f32_16x16x32_f16 v[76:79], v[144:147], v[188:191], v[76:79]
	s_barrier
	s_add_i32 s48, 0, 0x14000
	v_add_u32_e32 v154, s48, v158
	s_add_i32 s45, s45, s5
	ds_read_b128 v[192:195], v154
	ds_read_b128 v[196:199], v154 offset:1024
	ds_read_b128 v[200:203], v154 offset:2048
	ds_read_b128 v[206:209], v154 offset:3072
	v_lshl_add_u64 v[154:155], s[38:39], 0, v[2:3]
	s_mov_b32 m0, s45
	v_lshl_add_u64 v[210:211], s[38:39], 0, v[148:149]
	global_load_lds_dwordx4 v[154:155], off
	s_add_i32 m0, s45, 0x2000
	s_nop 0
	global_load_lds_dwordx4 v[210:211], off
	s_waitcnt vmcnt(10)
	s_barrier
	s_waitcnt lgkmcnt(0)
	v_mfma_f32_16x16x32_f16 v[120:123], v[192:195], v[160:163], v[120:123]
	v_mfma_f32_16x16x32_f16 v[116:119], v[200:203], v[160:163], v[116:119]
	v_mfma_f32_16x16x32_f16 v[104:107], v[192:195], v[168:171], v[104:107]
	v_mfma_f32_16x16x32_f16 v[100:103], v[200:203], v[168:171], v[100:103]
	v_mfma_f32_16x16x32_f16 v[88:91], v[192:195], v[176:179], v[88:91]
	v_mfma_f32_16x16x32_f16 v[84:87], v[200:203], v[176:179], v[84:87]
	v_mfma_f32_16x16x32_f16 v[72:75], v[192:195], v[184:187], v[72:75]
	v_mfma_f32_16x16x32_f16 v[68:71], v[200:203], v[184:187], v[68:71]
	v_mfma_f32_16x16x32_f16 v[120:123], v[196:199], v[164:167], v[120:123]
	v_mfma_f32_16x16x32_f16 v[116:119], v[206:209], v[164:167], v[116:119]
	v_mfma_f32_16x16x32_f16 v[104:107], v[196:199], v[172:175], v[104:107]
	v_mfma_f32_16x16x32_f16 v[100:103], v[206:209], v[172:175], v[100:103]
	v_mfma_f32_16x16x32_f16 v[88:91], v[196:199], v[180:183], v[88:91]
	v_mfma_f32_16x16x32_f16 v[84:87], v[206:209], v[180:183], v[84:87]
	v_mfma_f32_16x16x32_f16 v[72:75], v[196:199], v[188:191], v[72:75]
	v_mfma_f32_16x16x32_f16 v[68:71], v[206:209], v[188:191], v[68:71]
	s_mov_b32 m0, s6
	v_lshl_add_u64 v[212:213], s[42:43], 0, v[2:3]
	s_barrier
	ds_read_b128 v[160:163], v159 offset:16384
	ds_read_b128 v[164:167], v159 offset:17408
	ds_read_b128 v[168:171], v159 offset:18432
	ds_read_b128 v[172:175], v159 offset:19456
	ds_read_b128 v[176:179], v159 offset:20480
	ds_read_b128 v[180:183], v159 offset:21504
	ds_read_b128 v[184:187], v159 offset:22528
	ds_read_b128 v[188:191], v159 offset:23552
	global_load_lds_dwordx4 v[212:213], off
	v_lshl_add_u64 v[214:215], s[42:43], 0, v[148:149]
	s_mov_b32 m0, s7
	s_nop 0
	global_load_lds_dwordx4 v[214:215], off
	s_barrier
	s_waitcnt lgkmcnt(0)
	v_mfma_f32_16x16x32_f16 v[64:67], v[132:135], v[160:163], v[64:67]
	v_mfma_f32_16x16x32_f16 v[60:63], v[140:143], v[160:163], v[60:63]
	v_mfma_f32_16x16x32_f16 v[56:59], v[132:135], v[168:171], v[56:59]
	v_mfma_f32_16x16x32_f16 v[44:47], v[140:143], v[168:171], v[44:47]
	v_mfma_f32_16x16x32_f16 v[40:43], v[132:135], v[176:179], v[40:43]
	v_mfma_f32_16x16x32_f16 v[28:31], v[140:143], v[176:179], v[28:31]
	v_mfma_f32_16x16x32_f16 v[24:27], v[132:135], v[184:187], v[24:27]
	v_mfma_f32_16x16x32_f16 v[12:15], v[140:143], v[184:187], v[12:15]
	v_mfma_f32_16x16x32_f16 v[64:67], v[136:139], v[164:167], v[64:67]
	v_mfma_f32_16x16x32_f16 v[60:63], v[144:147], v[164:167], v[60:63]
	v_mfma_f32_16x16x32_f16 v[56:59], v[136:139], v[172:175], v[56:59]
	v_mfma_f32_16x16x32_f16 v[44:47], v[144:147], v[172:175], v[44:47]
	v_mfma_f32_16x16x32_f16 v[40:43], v[136:139], v[180:183], v[40:43]
	v_mfma_f32_16x16x32_f16 v[28:31], v[144:147], v[180:183], v[28:31]
	v_mfma_f32_16x16x32_f16 v[24:27], v[136:139], v[188:191], v[24:27]
	v_mfma_f32_16x16x32_f16 v[12:15], v[144:147], v[188:191], v[12:15]
	s_barrier
	s_add_u32 s46, s38, 0x80000
	s_addc_u32 s47, s39, 0
	s_add_i32 s45, s48, s5
	v_lshl_add_u64 v[132:133], s[46:47], 0, v[2:3]
	s_mov_b32 m0, s45
	s_nop 0
	global_load_lds_dwordx4 v[132:133], off
	s_add_i32 m0, s45, 0x2000
	s_nop 0
	global_load_lds_dwordx4 v148, s[46:47]
	s_waitcnt vmcnt(8)
	s_barrier
	v_mfma_f32_16x16x32_f16 v[52:55], v[192:195], v[160:163], v[52:55]
	v_mfma_f32_16x16x32_f16 v[48:51], v[200:203], v[160:163], v[48:51]
	v_mfma_f32_16x16x32_f16 v[36:39], v[192:195], v[168:171], v[36:39]
	v_mfma_f32_16x16x32_f16 v[32:35], v[200:203], v[168:171], v[32:35]
	v_mfma_f32_16x16x32_f16 v[20:23], v[192:195], v[176:179], v[20:23]
	v_mfma_f32_16x16x32_f16 v[16:19], v[200:203], v[176:179], v[16:19]
	v_mfma_f32_16x16x32_f16 v[8:11], v[192:195], v[184:187], v[8:11]
	v_mfma_f32_16x16x32_f16 v[4:7], v[200:203], v[184:187], v[4:7]
	v_mfma_f32_16x16x32_f16 v[52:55], v[196:199], v[164:167], v[52:55]
	v_mfma_f32_16x16x32_f16 v[48:51], v[206:209], v[164:167], v[48:51]
	v_mfma_f32_16x16x32_f16 v[36:39], v[196:199], v[172:175], v[36:39]
	v_mfma_f32_16x16x32_f16 v[32:35], v[206:209], v[172:175], v[32:35]
	v_mfma_f32_16x16x32_f16 v[20:23], v[196:199], v[180:183], v[20:23]
	v_mfma_f32_16x16x32_f16 v[16:19], v[206:209], v[180:183], v[16:19]
	v_mfma_f32_16x16x32_f16 v[8:11], v[196:199], v[188:191], v[8:11]
	v_mfma_f32_16x16x32_f16 v[4:7], v[206:209], v[188:191], v[4:7]
	s_add_i32 s45, 0, 0x18000
	v_add_u32_e32 v144, s45, v158
	s_barrier
	ds_read_b128 v[132:135], v144
	ds_read_b128 v[136:139], v144 offset:1024
	ds_read_b128 v[140:143], v144 offset:2048
	ds_read_b128 v[144:147], v144 offset:3072
	s_add_u32 s42, s42, 0x80000
	s_addc_u32 s43, s43, 0
	s_mov_b32 m0, s8
	v_lshl_add_u64 v[192:193], s[42:43], 0, v[2:3]
	ds_read_b128 v[160:163], v159 offset:32768
	ds_read_b128 v[164:167], v159 offset:33792
	ds_read_b128 v[168:171], v159 offset:34816
	ds_read_b128 v[172:175], v159 offset:35840
	ds_read_b128 v[176:179], v159 offset:36864
	ds_read_b128 v[180:183], v159 offset:37888
	ds_read_b128 v[184:187], v159 offset:38912
	ds_read_b128 v[188:191], v159 offset:39936
	global_load_lds_dwordx4 v[192:193], off
	s_mov_b32 m0, s9
	s_nop 0
	global_load_lds_dwordx4 v148, s[42:43]
	s_barrier
	s_waitcnt lgkmcnt(0)
	v_mfma_f32_16x16x32_f16 v[128:131], v[132:135], v[160:163], v[128:131]
	v_mfma_f32_16x16x32_f16 v[124:127], v[140:143], v[160:163], v[124:127]
	v_mfma_f32_16x16x32_f16 v[112:115], v[132:135], v[168:171], v[112:115]
	v_mfma_f32_16x16x32_f16 v[108:111], v[140:143], v[168:171], v[108:111]
	v_mfma_f32_16x16x32_f16 v[96:99], v[132:135], v[176:179], v[96:99]
	v_mfma_f32_16x16x32_f16 v[92:95], v[140:143], v[176:179], v[92:95]
	v_mfma_f32_16x16x32_f16 v[80:83], v[132:135], v[184:187], v[80:83]
	v_mfma_f32_16x16x32_f16 v[76:79], v[140:143], v[184:187], v[76:79]
	v_mfma_f32_16x16x32_f16 v[128:131], v[136:139], v[164:167], v[128:131]
	v_mfma_f32_16x16x32_f16 v[124:127], v[144:147], v[164:167], v[124:127]
	v_mfma_f32_16x16x32_f16 v[112:115], v[136:139], v[172:175], v[112:115]
	v_mfma_f32_16x16x32_f16 v[108:111], v[144:147], v[172:175], v[108:111]
	v_mfma_f32_16x16x32_f16 v[96:99], v[136:139], v[180:183], v[96:99]
	v_mfma_f32_16x16x32_f16 v[92:95], v[144:147], v[180:183], v[92:95]
	v_mfma_f32_16x16x32_f16 v[80:83], v[136:139], v[188:191], v[80:83]
	v_mfma_f32_16x16x32_f16 v[76:79], v[144:147], v[188:191], v[76:79]
	s_barrier
	s_add_i32 s42, 0, 0x1c000
	s_add_i32 s43, s45, s5
	v_add_u32_e32 v206, s42, v158
	v_lshl_add_u64 v[154:155], v[154:155], 0, s[88:89]
	s_mov_b32 m0, s43
	ds_read_b128 v[192:195], v206
	ds_read_b128 v[196:199], v206 offset:1024
	ds_read_b128 v[200:203], v206 offset:2048
	ds_read_b128 v[206:209], v206 offset:3072
	global_load_lds_dwordx4 v[154:155], off
	v_lshl_add_u64 v[154:155], v[210:211], 0, s[88:89]
	s_add_i32 m0, s43, 0x2000
	s_nop 0
	global_load_lds_dwordx4 v[154:155], off
	s_waitcnt vmcnt(10)
	s_barrier
	s_waitcnt lgkmcnt(0)
	v_mfma_f32_16x16x32_f16 v[120:123], v[192:195], v[160:163], v[120:123]
	v_mfma_f32_16x16x32_f16 v[116:119], v[200:203], v[160:163], v[116:119]
	v_mfma_f32_16x16x32_f16 v[104:107], v[192:195], v[168:171], v[104:107]
	v_mfma_f32_16x16x32_f16 v[100:103], v[200:203], v[168:171], v[100:103]
	v_mfma_f32_16x16x32_f16 v[88:91], v[192:195], v[176:179], v[88:91]
	v_mfma_f32_16x16x32_f16 v[84:87], v[200:203], v[176:179], v[84:87]
	v_mfma_f32_16x16x32_f16 v[72:75], v[192:195], v[184:187], v[72:75]
	v_mfma_f32_16x16x32_f16 v[68:71], v[200:203], v[184:187], v[68:71]
	v_mfma_f32_16x16x32_f16 v[120:123], v[196:199], v[164:167], v[120:123]
	v_mfma_f32_16x16x32_f16 v[116:119], v[206:209], v[164:167], v[116:119]
	v_mfma_f32_16x16x32_f16 v[104:107], v[196:199], v[172:175], v[104:107]
	v_mfma_f32_16x16x32_f16 v[100:103], v[206:209], v[172:175], v[100:103]
	v_mfma_f32_16x16x32_f16 v[88:91], v[196:199], v[180:183], v[88:91]
	v_mfma_f32_16x16x32_f16 v[84:87], v[206:209], v[180:183], v[84:87]
	v_mfma_f32_16x16x32_f16 v[72:75], v[196:199], v[188:191], v[72:75]
	v_mfma_f32_16x16x32_f16 v[68:71], v[206:209], v[188:191], v[68:71]
	s_mov_b32 m0, s10
	v_lshl_add_u64 v[154:155], v[212:213], 0, s[88:89]
	s_barrier
	ds_read_b128 v[160:163], v159 offset:49152
	ds_read_b128 v[164:167], v159 offset:50176
	ds_read_b128 v[168:171], v159 offset:51200
	ds_read_b128 v[172:175], v159 offset:52224
	ds_read_b128 v[176:179], v159 offset:53248
	ds_read_b128 v[180:183], v159 offset:54272
	ds_read_b128 v[184:187], v159 offset:55296
	ds_read_b128 v[188:191], v159 offset:56320
	global_load_lds_dwordx4 v[154:155], off
	v_lshl_add_u64 v[154:155], v[214:215], 0, s[88:89]
	s_mov_b32 m0, s11
	s_nop 0
	global_load_lds_dwordx4 v[154:155], off
	s_barrier
	s_waitcnt lgkmcnt(0)
	v_mfma_f32_16x16x32_f16 v[64:67], v[132:135], v[160:163], v[64:67]
	v_mfma_f32_16x16x32_f16 v[60:63], v[140:143], v[160:163], v[60:63]
	v_mfma_f32_16x16x32_f16 v[56:59], v[132:135], v[168:171], v[56:59]
	v_mfma_f32_16x16x32_f16 v[44:47], v[140:143], v[168:171], v[44:47]
	v_mfma_f32_16x16x32_f16 v[40:43], v[132:135], v[176:179], v[40:43]
	v_mfma_f32_16x16x32_f16 v[28:31], v[140:143], v[176:179], v[28:31]
	v_mfma_f32_16x16x32_f16 v[24:27], v[132:135], v[184:187], v[24:27]
	v_mfma_f32_16x16x32_f16 v[12:15], v[140:143], v[184:187], v[12:15]
	v_mfma_f32_16x16x32_f16 v[64:67], v[136:139], v[164:167], v[64:67]
	v_mfma_f32_16x16x32_f16 v[60:63], v[144:147], v[164:167], v[60:63]
	v_mfma_f32_16x16x32_f16 v[56:59], v[136:139], v[172:175], v[56:59]
	v_mfma_f32_16x16x32_f16 v[44:47], v[144:147], v[172:175], v[44:47]
	v_mfma_f32_16x16x32_f16 v[40:43], v[136:139], v[180:183], v[40:43]
	v_mfma_f32_16x16x32_f16 v[28:31], v[144:147], v[180:183], v[28:31]
	v_mfma_f32_16x16x32_f16 v[24:27], v[136:139], v[188:191], v[24:27]
	v_mfma_f32_16x16x32_f16 v[12:15], v[144:147], v[188:191], v[12:15]
	s_barrier
	s_add_u32 s38, s38, 0x80080
	s_addc_u32 s39, s39, 0
	s_add_i32 s42, s42, s5
	v_lshl_add_u64 v[132:133], s[38:39], 0, v[2:3]
	s_mov_b32 m0, s42
	s_nop 0
	global_load_lds_dwordx4 v[132:133], off
	s_add_i32 m0, s42, 0x2000
	s_nop 0
	global_load_lds_dwordx4 v148, s[38:39]
	s_waitcnt vmcnt(8)
	s_barrier
	v_mfma_f32_16x16x32_f16 v[52:55], v[192:195], v[160:163], v[52:55]
	v_mfma_f32_16x16x32_f16 v[48:51], v[200:203], v[160:163], v[48:51]
	v_mfma_f32_16x16x32_f16 v[36:39], v[192:195], v[168:171], v[36:39]
	v_mfma_f32_16x16x32_f16 v[32:35], v[200:203], v[168:171], v[32:35]
	v_mfma_f32_16x16x32_f16 v[20:23], v[192:195], v[176:179], v[20:23]
	v_mfma_f32_16x16x32_f16 v[16:19], v[200:203], v[176:179], v[16:19]
	v_mfma_f32_16x16x32_f16 v[8:11], v[192:195], v[184:187], v[8:11]
	v_mfma_f32_16x16x32_f16 v[4:7], v[200:203], v[184:187], v[4:7]
	v_mfma_f32_16x16x32_f16 v[52:55], v[196:199], v[164:167], v[52:55]
	v_mfma_f32_16x16x32_f16 v[48:51], v[206:209], v[164:167], v[48:51]
	v_mfma_f32_16x16x32_f16 v[36:39], v[196:199], v[172:175], v[36:39]
	v_mfma_f32_16x16x32_f16 v[32:35], v[206:209], v[172:175], v[32:35]
	v_mfma_f32_16x16x32_f16 v[20:23], v[196:199], v[180:183], v[20:23]
	v_mfma_f32_16x16x32_f16 v[16:19], v[206:209], v[180:183], v[16:19]
	v_mfma_f32_16x16x32_f16 v[8:11], v[196:199], v[188:191], v[8:11]
	v_mfma_f32_16x16x32_f16 v[4:7], v[206:209], v[188:191], v[4:7]
	s_add_i32 s44, s44, 2
	s_add_u32 s40, s40, 0x100
	s_addc_u32 s41, s41, 0
	s_add_u32 s19, s19, 0x100
	s_addc_u32 s31, s31, 0
	s_cmp_gt_u32 s44, 5
	s_barrier
	s_cbranch_scc0 .LBB0_2133
	s_lshl_b32 s19, s30, 8
	s_lshl_b32 s30, s29, 8
	v_mov_b32_e32 v160, v156
	v_mov_b32_e32 v132, v157
	s_and_b32 s30, s30, 0xff00
	s_or_b32 s30, s30, s12
	v_lshl_add_u32 v132, v132, 2, s30
	v_ashrrev_i32_e32 v133, 31, v132
	v_lshlrev_b64 v[154:155], 2, v[132:133]
	v_lshl_add_u64 v[132:133], s[16:17], 0, v[154:155]
	global_load_dwordx4 v[144:147], v[132:133], off
	global_load_dwordx4 v[140:143], v[132:133], off offset:64
	global_load_dwordx4 v[136:139], v[132:133], off offset:512
	s_nop 0
	global_load_dwordx4 v[132:135], v[132:133], off offset:576
	s_ashr_i32 s30, s29, 8
	s_ashr_i32 s31, s30, 31
	s_add_i32 s19, s13, s19
	s_lshl_b64 s[30:31], s[30:31], 22
	v_readlane_b32 s38, v250, 27
	v_add_u32_e32 v160, s19, v160
	v_readlane_b32 s39, v250, 28
	s_add_u32 s30, s38, s30
	s_addc_u32 s31, s39, s31
	v_ashrrev_i32_e32 v161, 31, v160
	v_lshl_add_u64 v[154:155], s[30:31], 0, v[154:155]
	v_lshlrev_b64 v[160:161], 13, v[160:161]
	v_lshl_add_u64 v[154:155], v[154:155], 0, v[160:161]
	s_mov_b32 s19, 0x20000
	s_mov_b64 s[30:31], 0x20000
	s_mov_b32 s29, s15
	s_mov_b64 s[38:39], s[34:35]
	s_mov_b64 s[40:41], s[26:27]
	s_waitcnt vmcnt(0)
	v_pk_mul_f32 v[130:131], v[130:131], v[146:147]
	v_pk_mul_f32 v[128:129], v[128:129], v[144:145]
	v_pk_mul_f32 v[54:55], v[54:55], v[138:139]
	v_pk_mul_f32 v[118:119], v[118:119], v[134:135]
	v_pk_mul_f32 v[116:117], v[116:117], v[132:133]
	global_store_dwordx4 v[154:155], v[116:119], off offset:576
	v_pk_mul_f32 v[102:103], v[102:103], v[134:135]
	v_pk_mul_f32 v[100:101], v[100:101], v[132:133]
	v_add_co_u32_e32 v118, vcc, s19, v154
	v_lshl_add_u64 v[116:117], v[154:155], 0, s[30:31]
	s_nop 0
	v_addc_co_u32_e32 v119, vcc, 0, v155, vcc
	s_mov_b32 s19, 0x40000
	global_store_dwordx4 v[116:117], v[100:103], off offset:576
	s_mov_b64 s[30:31], 0x40000
	v_pk_mul_f32 v[86:87], v[86:87], v[134:135]
	v_add_co_u32_e32 v102, vcc, s19, v154
	v_lshl_add_u64 v[100:101], v[154:155], 0, s[30:31]
	s_nop 0
	v_addc_co_u32_e32 v103, vcc, 0, v155, vcc
	v_pk_mul_f32 v[84:85], v[84:85], v[132:133]
	s_mov_b32 s19, 0x60000
	global_store_dwordx4 v[100:101], v[84:87], off offset:576
	s_mov_b64 s[30:31], 0x60000
	v_pk_mul_f32 v[70:71], v[70:71], v[134:135]
	v_add_co_u32_e32 v86, vcc, s19, v154
	v_lshl_add_u64 v[84:85], v[154:155], 0, s[30:31]
	s_nop 0
	v_addc_co_u32_e32 v87, vcc, 0, v155, vcc
	v_pk_mul_f32 v[68:69], v[68:69], v[132:133]
	s_mov_b32 s19, 0x100000
	global_store_dwordx4 v[84:85], v[68:71], off offset:576
	s_mov_b64 s[30:31], 0x100000
	v_pk_mul_f32 v[52:53], v[52:53], v[136:137]
	v_add_co_u32_e32 v70, vcc, s19, v154
	v_lshl_add_u64 v[68:69], v[154:155], 0, s[30:31]
	s_nop 0
	v_addc_co_u32_e32 v71, vcc, 0, v155, vcc
	s_mov_b32 s19, 0x120000
	global_store_dwordx4 v[68:69], v[52:55], off offset:512
	s_mov_b64 s[30:31], 0x120000
	v_pk_mul_f32 v[38:39], v[38:39], v[138:139]
	v_add_co_u32_e32 v54, vcc, s19, v154
	v_lshl_add_u64 v[52:53], v[154:155], 0, s[30:31]
	s_nop 0
	v_addc_co_u32_e32 v55, vcc, 0, v155, vcc
	v_pk_mul_f32 v[36:37], v[36:37], v[136:137]
	s_mov_b32 s19, 0x140000
	global_store_dwordx4 v[52:53], v[36:39], off offset:512
	s_mov_b64 s[30:31], 0x140000
	v_pk_mul_f32 v[22:23], v[22:23], v[138:139]
	v_add_co_u32_e32 v38, vcc, s19, v154
	v_lshl_add_u64 v[36:37], v[154:155], 0, s[30:31]
	s_nop 0
	v_addc_co_u32_e32 v39, vcc, 0, v155, vcc
	v_pk_mul_f32 v[20:21], v[20:21], v[136:137]
	s_mov_b32 s19, 0x160000
	global_store_dwordx4 v[36:37], v[20:23], off offset:512
	v_pk_mul_f32 v[50:51], v[50:51], v[134:135]
	v_pk_mul_f32 v[48:49], v[48:49], v[132:133]
	v_add_co_u32_e32 v22, vcc, s19, v154
	v_pk_mul_f32 v[34:35], v[34:35], v[134:135]
	v_pk_mul_f32 v[32:33], v[32:33], v[132:133]
	v_pk_mul_f32 v[18:19], v[18:19], v[134:135]
	v_pk_mul_f32 v[16:17], v[16:17], v[132:133]
	s_mov_b64 s[30:31], 0x160000
	v_addc_co_u32_e32 v23, vcc, 0, v155, vcc
	v_pk_mul_f32 v[126:127], v[126:127], v[142:143]
	v_pk_mul_f32 v[124:125], v[124:125], v[140:141]
	v_pk_mul_f32 v[122:123], v[122:123], v[138:139]
	v_pk_mul_f32 v[120:121], v[120:121], v[136:137]
	v_pk_mul_f32 v[114:115], v[114:115], v[146:147]
	v_pk_mul_f32 v[112:113], v[112:113], v[144:145]
	v_pk_mul_f32 v[110:111], v[110:111], v[142:143]
	v_pk_mul_f32 v[108:109], v[108:109], v[140:141]
	v_pk_mul_f32 v[106:107], v[106:107], v[138:139]
	v_pk_mul_f32 v[104:105], v[104:105], v[136:137]
	v_pk_mul_f32 v[98:99], v[98:99], v[146:147]
	v_pk_mul_f32 v[96:97], v[96:97], v[144:145]
	v_pk_mul_f32 v[94:95], v[94:95], v[142:143]
	v_pk_mul_f32 v[92:93], v[92:93], v[140:141]
	v_pk_mul_f32 v[90:91], v[90:91], v[138:139]
	v_pk_mul_f32 v[88:89], v[88:89], v[136:137]
	v_pk_mul_f32 v[82:83], v[82:83], v[146:147]
	v_pk_mul_f32 v[80:81], v[80:81], v[144:145]
	v_pk_mul_f32 v[78:79], v[78:79], v[142:143]
	v_pk_mul_f32 v[76:77], v[76:77], v[140:141]
	v_pk_mul_f32 v[74:75], v[74:75], v[138:139]
	v_pk_mul_f32 v[72:73], v[72:73], v[136:137]
	v_pk_mul_f32 v[66:67], v[66:67], v[146:147]
	v_pk_mul_f32 v[64:65], v[64:65], v[144:145]
	v_pk_mul_f32 v[62:63], v[62:63], v[142:143]
	v_pk_mul_f32 v[60:61], v[60:61], v[140:141]
	global_store_dwordx4 v[68:69], v[48:51], off offset:576
	v_pk_mul_f32 v[46:47], v[46:47], v[142:143]
	v_pk_mul_f32 v[44:45], v[44:45], v[140:141]
	v_pk_mul_f32 v[50:51], v[58:59], v[146:147]
	v_pk_mul_f32 v[48:49], v[56:57], v[144:145]
	global_store_dwordx4 v[52:53], v[32:35], off offset:576
	v_pk_mul_f32 v[30:31], v[30:31], v[142:143]
	v_pk_mul_f32 v[28:29], v[28:29], v[140:141]
	v_pk_mul_f32 v[34:35], v[42:43], v[146:147]
	v_pk_mul_f32 v[32:33], v[40:41], v[144:145]
	global_store_dwordx4 v[36:37], v[16:19], off offset:576
	v_lshl_add_u64 v[20:21], v[154:155], 0, s[30:31]
	v_pk_mul_f32 v[14:15], v[14:15], v[142:143]
	v_pk_mul_f32 v[18:19], v[26:27], v[146:147]
	v_pk_mul_f32 v[16:17], v[24:25], v[144:145]
	v_pk_mul_f32 v[12:13], v[12:13], v[140:141]
	v_pk_mul_f32 v[10:11], v[10:11], v[138:139]
	v_pk_mul_f32 v[8:9], v[8:9], v[136:137]
	v_pk_mul_f32 v[6:7], v[6:7], v[134:135]
	v_pk_mul_f32 v[4:5], v[4:5], v[132:133]
	s_and_b64 vcc, exec, s[36:37]
	s_mov_b32 s30, s18
	global_store_dwordx4 v[154:155], v[128:131], off
	global_store_dwordx4 v[154:155], v[124:127], off offset:64
	global_store_dwordx4 v[154:155], v[120:123], off offset:512
	global_store_dwordx4 v[118:119], v[112:115], off
	global_store_dwordx4 v[116:117], v[108:111], off offset:64
	global_store_dwordx4 v[116:117], v[104:107], off offset:512
	global_store_dwordx4 v[102:103], v[96:99], off
	global_store_dwordx4 v[100:101], v[92:95], off offset:64
	global_store_dwordx4 v[100:101], v[88:91], off offset:512
	global_store_dwordx4 v[86:87], v[80:83], off
	global_store_dwordx4 v[84:85], v[76:79], off offset:64
	global_store_dwordx4 v[84:85], v[72:75], off offset:512
	global_store_dwordx4 v[70:71], v[64:67], off
	global_store_dwordx4 v[68:69], v[60:63], off offset:64
	global_store_dwordx4 v[54:55], v[48:51], off
	global_store_dwordx4 v[52:53], v[44:47], off offset:64
	global_store_dwordx4 v[38:39], v[32:35], off
	global_store_dwordx4 v[36:37], v[28:31], off offset:64
	global_store_dwordx4 v[22:23], v[16:19], off
	global_store_dwordx4 v[20:21], v[12:15], off offset:64
	global_store_dwordx4 v[20:21], v[8:11], off offset:512
	global_store_dwordx4 v[20:21], v[4:7], off offset:576
	s_cbranch_vccz .LBB0_2130
	s_waitcnt vmcnt(0)
	s_cmpk_gt_u32 s4, 0xff
	s_cbranch_scc1 .LBB0_2137
	s_barrier

.LBB0_2566:
	s_add_u32 s15, s44, 0xfff80080
	s_addc_u32 s17, s45, -1
	s_add_i32 s29, 0, 0x10000
	v_add_u32_e32 v2, s29, v202
	ds_read_b128 v[132:135], v2
	ds_read_b128 v[136:139], v2 offset:1024
	ds_read_b128 v[140:143], v2 offset:2048
	ds_read_b128 v[144:147], v2 offset:3072
	s_cmp_eq_u32 s14, 28
	s_cselect_b32 s47, s85, s17
	s_cselect_b32 s46, s84, s15
	s_cselect_b32 s39, s27, s11
	s_cselect_b32 s38, s26, s10
	s_add_i32 m0, s6, 0xc000
	ds_read_b128 v[148:151], v208
	ds_read_b128 v[152:155], v208 offset:1024
	ds_read_b128 v[156:159], v208 offset:2048
	ds_read_b128 v[160:163], v208 offset:3072
	ds_read_b128 v[164:167], v208 offset:4096
	ds_read_b128 v[168:171], v208 offset:5120
	ds_read_b128 v[172:175], v208 offset:6144
	ds_read_b128 v[188:191], v208 offset:7168
	global_load_lds_dwordx4 v184, s[44:45]
	s_add_i32 m0, s6, 0xe000
	s_nop 0
	global_load_lds_dwordx4 v186, s[44:45]
	s_barrier
	s_waitcnt lgkmcnt(0)
	v_mfma_f32_16x16x32_f16 v[128:131], v[132:135], v[148:151], v[128:131]
	v_mfma_f32_16x16x32_f16 v[88:91], v[140:143], v[148:151], v[88:91]
	v_mfma_f32_16x16x32_f16 v[120:123], v[132:135], v[156:159], v[120:123]
	v_mfma_f32_16x16x32_f16 v[92:95], v[140:143], v[156:159], v[92:95]
	v_mfma_f32_16x16x32_f16 v[112:115], v[132:135], v[164:167], v[112:115]
	v_mfma_f32_16x16x32_f16 v[80:83], v[140:143], v[164:167], v[80:83]
	v_mfma_f32_16x16x32_f16 v[104:107], v[132:135], v[172:175], v[104:107]
	v_mfma_f32_16x16x32_f16 v[68:71], v[140:143], v[172:175], v[68:71]
	v_mfma_f32_16x16x32_f16 v[128:131], v[136:139], v[152:155], v[128:131]
	v_mfma_f32_16x16x32_f16 v[88:91], v[144:147], v[152:155], v[88:91]
	v_mfma_f32_16x16x32_f16 v[120:123], v[136:139], v[160:163], v[120:123]
	v_mfma_f32_16x16x32_f16 v[92:95], v[144:147], v[160:163], v[92:95]
	v_mfma_f32_16x16x32_f16 v[112:115], v[136:139], v[168:171], v[112:115]
	v_mfma_f32_16x16x32_f16 v[80:83], v[144:147], v[168:171], v[80:83]
	v_mfma_f32_16x16x32_f16 v[104:107], v[136:139], v[188:191], v[104:107]
	v_mfma_f32_16x16x32_f16 v[68:71], v[144:147], v[188:191], v[68:71]
	s_barrier
	s_add_i32 s15, 0, 0x14000
	s_add_i32 s17, s29, s5
	v_add_u32_e32 v2, s15, v202
	v_lshl_add_u64 v[218:219], s[38:39], 0, v[178:179]
	s_mov_b32 m0, s17
	ds_read_b128 v[192:195], v2
	ds_read_b128 v[196:199], v2 offset:1024
	ds_read_b128 v[210:213], v2 offset:2048
	ds_read_b128 v[214:217], v2 offset:3072
	global_load_lds_dwordx4 v[218:219], off
	v_lshl_add_u64 v[220:221], s[38:39], 0, v[182:183]
	s_add_i32 m0, s17, 0x2000
	s_nop 0
	global_load_lds_dwordx4 v[220:221], off
	s_waitcnt vmcnt(10)
	s_barrier
	s_waitcnt lgkmcnt(0)
	v_mfma_f32_16x16x32_f16 v[124:127], v[192:195], v[148:151], v[124:127]
	v_mfma_f32_16x16x32_f16 v[96:99], v[210:213], v[148:151], v[96:99]
	v_mfma_f32_16x16x32_f16 v[116:119], v[192:195], v[156:159], v[116:119]
	v_mfma_f32_16x16x32_f16 v[84:87], v[210:213], v[156:159], v[84:87]
	v_mfma_f32_16x16x32_f16 v[108:111], v[192:195], v[164:167], v[108:111]
	v_mfma_f32_16x16x32_f16 v[76:79], v[210:213], v[164:167], v[76:79]
	v_mfma_f32_16x16x32_f16 v[100:103], v[192:195], v[172:175], v[100:103]
	v_mfma_f32_16x16x32_f16 v[72:75], v[210:213], v[172:175], v[72:75]
	v_mfma_f32_16x16x32_f16 v[124:127], v[196:199], v[152:155], v[124:127]
	v_mfma_f32_16x16x32_f16 v[96:99], v[214:217], v[152:155], v[96:99]
	v_mfma_f32_16x16x32_f16 v[116:119], v[196:199], v[160:163], v[116:119]
	v_mfma_f32_16x16x32_f16 v[84:87], v[214:217], v[160:163], v[84:87]
	v_mfma_f32_16x16x32_f16 v[108:111], v[196:199], v[168:171], v[108:111]
	v_mfma_f32_16x16x32_f16 v[76:79], v[214:217], v[168:171], v[76:79]
	v_mfma_f32_16x16x32_f16 v[100:103], v[196:199], v[188:191], v[100:103]
	v_mfma_f32_16x16x32_f16 v[72:75], v[214:217], v[188:191], v[72:75]
	s_mov_b32 m0, s6
	v_lshl_add_u64 v[224:225], s[46:47], 0, v[176:177]
	s_barrier
	ds_read_b128 v[148:151], v208 offset:16384
	ds_read_b128 v[152:155], v208 offset:17408
	ds_read_b128 v[156:159], v208 offset:18432
	ds_read_b128 v[160:163], v208 offset:19456
	ds_read_b128 v[164:167], v208 offset:20480
	ds_read_b128 v[168:171], v208 offset:21504
	ds_read_b128 v[172:175], v208 offset:22528
	ds_read_b128 v[188:191], v208 offset:23552
	global_load_lds_dwordx4 v[224:225], off
	v_lshl_add_u64 v[226:227], s[46:47], 0, v[180:181]
	s_mov_b32 m0, s7
	s_nop 0
	global_load_lds_dwordx4 v[226:227], off
	s_barrier
	s_waitcnt lgkmcnt(0)
	v_mfma_f32_16x16x32_f16 v[64:67], v[132:135], v[148:151], v[64:67]
	v_mfma_f32_16x16x32_f16 v[48:51], v[140:143], v[148:151], v[48:51]
	v_mfma_f32_16x16x32_f16 v[56:59], v[132:135], v[156:159], v[56:59]
	v_mfma_f32_16x16x32_f16 v[40:43], v[140:143], v[156:159], v[40:43]
	v_mfma_f32_16x16x32_f16 v[28:31], v[132:135], v[164:167], v[28:31]
	v_mfma_f32_16x16x32_f16 v[20:23], v[140:143], v[164:167], v[20:23]
	v_mfma_f32_16x16x32_f16 v[32:35], v[132:135], v[172:175], v[32:35]
	v_mfma_f32_16x16x32_f16 v[8:11], v[140:143], v[172:175], v[8:11]
	v_mfma_f32_16x16x32_f16 v[64:67], v[136:139], v[152:155], v[64:67]
	v_mfma_f32_16x16x32_f16 v[48:51], v[144:147], v[152:155], v[48:51]
	v_mfma_f32_16x16x32_f16 v[56:59], v[136:139], v[160:163], v[56:59]
	v_mfma_f32_16x16x32_f16 v[40:43], v[144:147], v[160:163], v[40:43]
	v_mfma_f32_16x16x32_f16 v[28:31], v[136:139], v[168:171], v[28:31]
	v_mfma_f32_16x16x32_f16 v[20:23], v[144:147], v[168:171], v[20:23]
	v_mfma_f32_16x16x32_f16 v[32:35], v[136:139], v[188:191], v[32:35]
	v_mfma_f32_16x16x32_f16 v[8:11], v[144:147], v[188:191], v[8:11]
	s_barrier
	s_add_u32 s30, s38, 0x80000
	s_addc_u32 s31, s39, 0
	s_add_i32 s15, s15, s5
	s_mov_b32 m0, s15
	s_nop 0
	global_load_lds_dwordx4 v178, s[30:31]
	s_add_i32 m0, s15, 0x2000
	s_nop 0
	global_load_lds_dwordx4 v182, s[30:31]
	s_waitcnt vmcnt(8)
	s_barrier
	v_mfma_f32_16x16x32_f16 v[60:63], v[192:195], v[148:151], v[60:63]
	v_mfma_f32_16x16x32_f16 v[44:47], v[210:213], v[148:151], v[44:47]
	v_mfma_f32_16x16x32_f16 v[52:55], v[192:195], v[156:159], v[52:55]
	v_mfma_f32_16x16x32_f16 v[36:39], v[210:213], v[156:159], v[36:39]
	v_mfma_f32_16x16x32_f16 v[16:19], v[192:195], v[164:167], v[16:19]
	v_mfma_f32_16x16x32_f16 v[12:15], v[210:213], v[164:167], v[12:15]
	v_mfma_f32_16x16x32_f16 v[24:27], v[192:195], v[172:175], v[24:27]
	v_mfma_f32_16x16x32_f16 v[4:7], v[210:213], v[172:175], v[4:7]
	v_mfma_f32_16x16x32_f16 v[60:63], v[196:199], v[152:155], v[60:63]
	v_mfma_f32_16x16x32_f16 v[44:47], v[214:217], v[152:155], v[44:47]
	v_mfma_f32_16x16x32_f16 v[52:55], v[196:199], v[160:163], v[52:55]
	v_mfma_f32_16x16x32_f16 v[36:39], v[214:217], v[160:163], v[36:39]
	v_mfma_f32_16x16x32_f16 v[16:19], v[196:199], v[168:171], v[16:19]
	v_mfma_f32_16x16x32_f16 v[12:15], v[214:217], v[168:171], v[12:15]
	v_mfma_f32_16x16x32_f16 v[24:27], v[196:199], v[188:191], v[24:27]
	v_mfma_f32_16x16x32_f16 v[4:7], v[214:217], v[188:191], v[4:7]
	s_add_i32 s15, 0, 0x18000
	v_add_u32_e32 v2, s15, v202
	s_barrier
	ds_read_b128 v[132:135], v2
	ds_read_b128 v[136:139], v2 offset:1024
	ds_read_b128 v[140:143], v2 offset:2048
	ds_read_b128 v[144:147], v2 offset:3072
	s_add_u32 s30, s46, 0x80000
	s_addc_u32 s31, s47, 0
	s_mov_b32 m0, s8
	ds_read_b128 v[148:151], v208 offset:32768
	ds_read_b128 v[152:155], v208 offset:33792
	ds_read_b128 v[156:159], v208 offset:34816
	ds_read_b128 v[160:163], v208 offset:35840
	ds_read_b128 v[164:167], v208 offset:36864
	ds_read_b128 v[168:171], v208 offset:37888
	ds_read_b128 v[172:175], v208 offset:38912
	ds_read_b128 v[188:191], v208 offset:39936
	global_load_lds_dwordx4 v176, s[30:31]
	s_mov_b32 m0, s9
	s_nop 0
	global_load_lds_dwordx4 v180, s[30:31]
	s_barrier
	s_waitcnt lgkmcnt(0)
	v_mfma_f32_16x16x32_f16 v[128:131], v[132:135], v[148:151], v[128:131]
	v_mfma_f32_16x16x32_f16 v[88:91], v[140:143], v[148:151], v[88:91]
	v_mfma_f32_16x16x32_f16 v[120:123], v[132:135], v[156:159], v[120:123]
	v_mfma_f32_16x16x32_f16 v[92:95], v[140:143], v[156:159], v[92:95]
	v_mfma_f32_16x16x32_f16 v[112:115], v[132:135], v[164:167], v[112:115]
	v_mfma_f32_16x16x32_f16 v[80:83], v[140:143], v[164:167], v[80:83]
	v_mfma_f32_16x16x32_f16 v[104:107], v[132:135], v[172:175], v[104:107]
	v_mfma_f32_16x16x32_f16 v[68:71], v[140:143], v[172:175], v[68:71]
	v_mfma_f32_16x16x32_f16 v[128:131], v[136:139], v[152:155], v[128:131]
	v_mfma_f32_16x16x32_f16 v[88:91], v[144:147], v[152:155], v[88:91]
	v_mfma_f32_16x16x32_f16 v[120:123], v[136:139], v[160:163], v[120:123]
	v_mfma_f32_16x16x32_f16 v[92:95], v[144:147], v[160:163], v[92:95]
	v_mfma_f32_16x16x32_f16 v[112:115], v[136:139], v[168:171], v[112:115]
	v_mfma_f32_16x16x32_f16 v[80:83], v[144:147], v[168:171], v[80:83]
	v_mfma_f32_16x16x32_f16 v[104:107], v[136:139], v[188:191], v[104:107]
	v_mfma_f32_16x16x32_f16 v[68:71], v[144:147], v[188:191], v[68:71]
	s_barrier
	s_add_i32 s17, 0, 0x1c000
	s_add_i32 s15, s15, s5
	v_add_u32_e32 v2, s17, v202
	v_lshl_add_u64 v[218:219], v[218:219], 0, s[88:89]
	s_mov_b32 m0, s15
	ds_read_b128 v[192:195], v2
	ds_read_b128 v[196:199], v2 offset:1024
	ds_read_b128 v[210:213], v2 offset:2048
	ds_read_b128 v[214:217], v2 offset:3072
	global_load_lds_dwordx4 v[218:219], off
	v_lshl_add_u64 v[218:219], v[220:221], 0, s[88:89]
	s_add_i32 m0, s15, 0x2000
	s_nop 0
	global_load_lds_dwordx4 v[218:219], off
	s_waitcnt vmcnt(10)
	s_barrier
	s_waitcnt lgkmcnt(0)
	v_mfma_f32_16x16x32_f16 v[124:127], v[192:195], v[148:151], v[124:127]
	v_mfma_f32_16x16x32_f16 v[96:99], v[210:213], v[148:151], v[96:99]
	v_mfma_f32_16x16x32_f16 v[116:119], v[192:195], v[156:159], v[116:119]
	v_mfma_f32_16x16x32_f16 v[84:87], v[210:213], v[156:159], v[84:87]
	v_mfma_f32_16x16x32_f16 v[108:111], v[192:195], v[164:167], v[108:111]
	v_mfma_f32_16x16x32_f16 v[76:79], v[210:213], v[164:167], v[76:79]
	v_mfma_f32_16x16x32_f16 v[100:103], v[192:195], v[172:175], v[100:103]
	v_mfma_f32_16x16x32_f16 v[72:75], v[210:213], v[172:175], v[72:75]
	v_mfma_f32_16x16x32_f16 v[124:127], v[196:199], v[152:155], v[124:127]
	v_mfma_f32_16x16x32_f16 v[96:99], v[214:217], v[152:155], v[96:99]
	v_mfma_f32_16x16x32_f16 v[116:119], v[196:199], v[160:163], v[116:119]
	v_mfma_f32_16x16x32_f16 v[84:87], v[214:217], v[160:163], v[84:87]
	v_mfma_f32_16x16x32_f16 v[108:111], v[196:199], v[168:171], v[108:111]
	v_mfma_f32_16x16x32_f16 v[76:79], v[214:217], v[168:171], v[76:79]
	v_mfma_f32_16x16x32_f16 v[100:103], v[196:199], v[188:191], v[100:103]
	v_mfma_f32_16x16x32_f16 v[72:75], v[214:217], v[188:191], v[72:75]
	s_mov_b32 m0, s69
	v_lshl_add_u64 v[218:219], v[224:225], 0, s[88:89]
	s_barrier
	ds_read_b128 v[148:151], v208 offset:49152
	ds_read_b128 v[152:155], v208 offset:50176
	ds_read_b128 v[156:159], v208 offset:51200
	ds_read_b128 v[160:163], v208 offset:52224
	ds_read_b128 v[164:167], v208 offset:53248
	ds_read_b128 v[168:171], v208 offset:54272
	ds_read_b128 v[172:175], v208 offset:55296
	ds_read_b128 v[188:191], v208 offset:56320
	global_load_lds_dwordx4 v[218:219], off
	v_lshl_add_u64 v[218:219], v[226:227], 0, s[88:89]
	s_mov_b32 m0, s70
	s_nop 0
	global_load_lds_dwordx4 v[218:219], off
	s_barrier
	s_waitcnt lgkmcnt(0)
	v_mfma_f32_16x16x32_f16 v[64:67], v[132:135], v[148:151], v[64:67]
	v_mfma_f32_16x16x32_f16 v[48:51], v[140:143], v[148:151], v[48:51]
	v_mfma_f32_16x16x32_f16 v[56:59], v[132:135], v[156:159], v[56:59]
	v_mfma_f32_16x16x32_f16 v[40:43], v[140:143], v[156:159], v[40:43]
	v_mfma_f32_16x16x32_f16 v[28:31], v[132:135], v[164:167], v[28:31]
	v_mfma_f32_16x16x32_f16 v[20:23], v[140:143], v[164:167], v[20:23]
	v_mfma_f32_16x16x32_f16 v[32:35], v[132:135], v[172:175], v[32:35]
	v_mfma_f32_16x16x32_f16 v[8:11], v[140:143], v[172:175], v[8:11]
	v_mfma_f32_16x16x32_f16 v[64:67], v[136:139], v[152:155], v[64:67]
	v_mfma_f32_16x16x32_f16 v[48:51], v[144:147], v[152:155], v[48:51]
	v_mfma_f32_16x16x32_f16 v[56:59], v[136:139], v[160:163], v[56:59]
	v_mfma_f32_16x16x32_f16 v[40:43], v[144:147], v[160:163], v[40:43]
	v_mfma_f32_16x16x32_f16 v[28:31], v[136:139], v[168:171], v[28:31]
	v_mfma_f32_16x16x32_f16 v[20:23], v[144:147], v[168:171], v[20:23]
	v_mfma_f32_16x16x32_f16 v[32:35], v[136:139], v[188:191], v[32:35]
	v_mfma_f32_16x16x32_f16 v[8:11], v[144:147], v[188:191], v[8:11]
	s_barrier
	s_add_u32 s30, s38, 0x80080
	s_addc_u32 s31, s39, 0
	s_add_i32 s15, s17, s5
	s_mov_b32 m0, s15
	s_nop 0
	global_load_lds_dwordx4 v178, s[30:31]
	s_add_i32 m0, s15, 0x2000
	s_nop 0
	global_load_lds_dwordx4 v182, s[30:31]
	s_waitcnt vmcnt(8)
	s_barrier
	v_mfma_f32_16x16x32_f16 v[60:63], v[192:195], v[148:151], v[60:63]
	v_mfma_f32_16x16x32_f16 v[44:47], v[210:213], v[148:151], v[44:47]
	v_mfma_f32_16x16x32_f16 v[52:55], v[192:195], v[156:159], v[52:55]
	v_mfma_f32_16x16x32_f16 v[36:39], v[210:213], v[156:159], v[36:39]
	v_mfma_f32_16x16x32_f16 v[16:19], v[192:195], v[164:167], v[16:19]
	v_mfma_f32_16x16x32_f16 v[12:15], v[210:213], v[164:167], v[12:15]
	v_mfma_f32_16x16x32_f16 v[24:27], v[192:195], v[172:175], v[24:27]
	v_mfma_f32_16x16x32_f16 v[4:7], v[210:213], v[172:175], v[4:7]
	v_mfma_f32_16x16x32_f16 v[60:63], v[196:199], v[152:155], v[60:63]
	v_mfma_f32_16x16x32_f16 v[44:47], v[214:217], v[152:155], v[44:47]
	v_mfma_f32_16x16x32_f16 v[52:55], v[196:199], v[160:163], v[52:55]
	v_mfma_f32_16x16x32_f16 v[36:39], v[214:217], v[160:163], v[36:39]
	v_mfma_f32_16x16x32_f16 v[16:19], v[196:199], v[168:171], v[16:19]
	v_mfma_f32_16x16x32_f16 v[12:15], v[214:217], v[168:171], v[12:15]
	v_mfma_f32_16x16x32_f16 v[24:27], v[196:199], v[188:191], v[24:27]
	v_mfma_f32_16x16x32_f16 v[4:7], v[214:217], v[188:191], v[4:7]
	s_add_i32 s14, s14, 2
	s_add_u32 s44, s44, 0x100
	s_addc_u32 s45, s45, 0
	s_add_u32 s10, s10, 0x100
	s_addc_u32 s11, s11, 0
	s_cmp_gt_u32 s14, 29
	s_barrier
	s_cbranch_scc0 .LBB0_2566
	v_mov_b32_e32 v209, v200
	v_mov_b32_e32 v2, v201
	s_mov_b64 s[38:39], 0
	v_lshlrev_b32_e32 v136, 5, v2
	v_add_u32_e32 v137, s92, v136
	v_cmp_lt_i32_e32 vcc, 14, v209
	s_and_saveexec_b64 s[10:11], vcc
	s_xor_b64 s[14:15], exec, s[10:11]
	s_cbranch_execz .LBB0_2571
	v_cmp_eq_u32_e32 vcc, 15, v209
	s_and_saveexec_b64 s[44:45], vcc
	s_mov_b64 s[38:39], exec
	ds_write_b128 v137, v[104:107] offset:128
	s_or_b64 exec, exec, s[44:45]
	s_and_b64 s[38:39], s[38:39], exec

.LBB0_3035:
	s_add_u32 s34, s26, 0x100
	s_addc_u32 s35, s27, 0
	s_add_i32 s45, 0, 0x10000
	v_add_u32_e32 v128, s45, v198
	ds_read_b128 v[108:111], v128
	ds_read_b128 v[112:115], v128 offset:1024
	ds_read_b128 v[120:123], v128 offset:2048
	ds_read_b128 v[128:131], v128 offset:3072
	s_cmpk_eq_i32 s44, 0x54
	s_cselect_b32 s39, s17, s35
	s_cselect_b32 s38, s16, s34
	s_cselect_b32 s37, s19, s15
	s_cselect_b32 s36, s18, s14
	v_lshl_add_u64 v[186:187], s[26:27], 0, v[182:183]
	s_add_i32 m0, s6, 0xc000
	ds_read_b128 v[148:151], v199
	ds_read_b128 v[152:155], v199 offset:1024
	ds_read_b128 v[156:159], v199 offset:2048
	ds_read_b128 v[160:163], v199 offset:3072
	ds_read_b128 v[164:167], v199 offset:4096
	ds_read_b128 v[168:171], v199 offset:5120
	ds_read_b128 v[172:175], v199 offset:6144
	ds_read_b128 v[176:179], v199 offset:7168
	global_load_lds_dwordx4 v[186:187], off
	v_lshl_add_u64 v[186:187], s[26:27], 0, v[184:185]
	s_add_i32 m0, s6, 0xe000
	s_nop 0
	global_load_lds_dwordx4 v[186:187], off
	s_barrier
	s_waitcnt lgkmcnt(0)
	v_mfma_f32_16x16x32_f16 v[144:147], v[108:111], v[148:151], v[144:147]
	v_mfma_f32_16x16x32_f16 v[140:143], v[120:123], v[148:151], v[140:143]
	v_mfma_f32_16x16x32_f16 v[124:127], v[108:111], v[156:159], v[124:127]
	v_mfma_f32_16x16x32_f16 v[116:119], v[120:123], v[156:159], v[116:119]
	v_mfma_f32_16x16x32_f16 v[96:99], v[108:111], v[164:167], v[96:99]
	v_mfma_f32_16x16x32_f16 v[92:95], v[120:123], v[164:167], v[92:95]
	v_mfma_f32_16x16x32_f16 v[88:91], v[108:111], v[172:175], v[88:91]
	v_mfma_f32_16x16x32_f16 v[80:83], v[120:123], v[172:175], v[80:83]
	v_mfma_f32_16x16x32_f16 v[144:147], v[112:115], v[152:155], v[144:147]
	v_mfma_f32_16x16x32_f16 v[140:143], v[128:131], v[152:155], v[140:143]
	v_mfma_f32_16x16x32_f16 v[124:127], v[112:115], v[160:163], v[124:127]
	v_mfma_f32_16x16x32_f16 v[116:119], v[128:131], v[160:163], v[116:119]
	v_mfma_f32_16x16x32_f16 v[96:99], v[112:115], v[168:171], v[96:99]
	v_mfma_f32_16x16x32_f16 v[92:95], v[128:131], v[168:171], v[92:95]
	v_mfma_f32_16x16x32_f16 v[88:91], v[112:115], v[176:179], v[88:91]
	v_mfma_f32_16x16x32_f16 v[80:83], v[128:131], v[176:179], v[80:83]
	s_barrier
	s_add_i32 s46, 0, 0x14000
	v_add_u32_e32 v194, s46, v198
	s_add_i32 s26, s45, s5
	ds_read_b128 v[186:189], v194
	ds_read_b128 v[190:193], v194 offset:1024
	ds_read_b128 v[200:203], v194 offset:2048
	ds_read_b128 v[206:209], v194 offset:3072
	v_lshl_add_u64 v[194:195], s[36:37], 0, v[2:3]
	s_mov_b32 m0, s26
	v_lshl_add_u64 v[210:211], s[36:37], 0, v[180:181]
	global_load_lds_dwordx4 v[194:195], off
	s_add_i32 m0, s26, 0x2000
	s_nop 0
	global_load_lds_dwordx4 v[210:211], off
	s_waitcnt vmcnt(10)
	s_barrier
	s_waitcnt lgkmcnt(0)
	v_mfma_f32_16x16x32_f16 v[136:139], v[186:189], v[148:151], v[136:139]
	v_mfma_f32_16x16x32_f16 v[132:135], v[200:203], v[148:151], v[132:135]
	v_mfma_f32_16x16x32_f16 v[104:107], v[186:189], v[156:159], v[104:107]
	v_mfma_f32_16x16x32_f16 v[100:103], v[200:203], v[156:159], v[100:103]
	v_mfma_f32_16x16x32_f16 v[84:87], v[186:189], v[164:167], v[84:87]
	v_mfma_f32_16x16x32_f16 v[76:79], v[200:203], v[164:167], v[76:79]
	v_mfma_f32_16x16x32_f16 v[72:75], v[186:189], v[172:175], v[72:75]
	v_mfma_f32_16x16x32_f16 v[68:71], v[200:203], v[172:175], v[68:71]
	v_mfma_f32_16x16x32_f16 v[136:139], v[190:193], v[152:155], v[136:139]
	v_mfma_f32_16x16x32_f16 v[132:135], v[206:209], v[152:155], v[132:135]
	v_mfma_f32_16x16x32_f16 v[104:107], v[190:193], v[160:163], v[104:107]
	v_mfma_f32_16x16x32_f16 v[100:103], v[206:209], v[160:163], v[100:103]
	v_mfma_f32_16x16x32_f16 v[84:87], v[190:193], v[168:171], v[84:87]
	v_mfma_f32_16x16x32_f16 v[76:79], v[206:209], v[168:171], v[76:79]
	v_mfma_f32_16x16x32_f16 v[72:75], v[190:193], v[176:179], v[72:75]
	v_mfma_f32_16x16x32_f16 v[68:71], v[206:209], v[176:179], v[68:71]
	s_mov_b32 m0, s6
	v_lshl_add_u64 v[212:213], s[38:39], 0, v[2:3]
	s_barrier
	ds_read_b128 v[148:151], v199 offset:16384
	ds_read_b128 v[152:155], v199 offset:17408
	ds_read_b128 v[156:159], v199 offset:18432
	ds_read_b128 v[160:163], v199 offset:19456
	ds_read_b128 v[164:167], v199 offset:20480
	ds_read_b128 v[168:171], v199 offset:21504
	ds_read_b128 v[172:175], v199 offset:22528
	ds_read_b128 v[176:179], v199 offset:23552
	global_load_lds_dwordx4 v[212:213], off
	v_lshl_add_u64 v[214:215], s[38:39], 0, v[180:181]
	s_mov_b32 m0, s7
	s_nop 0
	global_load_lds_dwordx4 v[214:215], off
	s_barrier
	s_waitcnt lgkmcnt(0)
	v_mfma_f32_16x16x32_f16 v[64:67], v[108:111], v[148:151], v[64:67]
	v_mfma_f32_16x16x32_f16 v[60:63], v[120:123], v[148:151], v[60:63]
	v_mfma_f32_16x16x32_f16 v[48:51], v[108:111], v[156:159], v[48:51]
	v_mfma_f32_16x16x32_f16 v[44:47], v[120:123], v[156:159], v[44:47]
	v_mfma_f32_16x16x32_f16 v[32:35], v[108:111], v[164:167], v[32:35]
	v_mfma_f32_16x16x32_f16 v[28:31], v[120:123], v[164:167], v[28:31]
	v_mfma_f32_16x16x32_f16 v[20:23], v[108:111], v[172:175], v[20:23]
	v_mfma_f32_16x16x32_f16 v[12:15], v[120:123], v[172:175], v[12:15]
	v_mfma_f32_16x16x32_f16 v[64:67], v[112:115], v[152:155], v[64:67]
	v_mfma_f32_16x16x32_f16 v[60:63], v[128:131], v[152:155], v[60:63]
	v_mfma_f32_16x16x32_f16 v[48:51], v[112:115], v[160:163], v[48:51]
	v_mfma_f32_16x16x32_f16 v[44:47], v[128:131], v[160:163], v[44:47]
	v_mfma_f32_16x16x32_f16 v[32:35], v[112:115], v[168:171], v[32:35]
	v_mfma_f32_16x16x32_f16 v[28:31], v[128:131], v[168:171], v[28:31]
	v_mfma_f32_16x16x32_f16 v[20:23], v[112:115], v[176:179], v[20:23]
	v_mfma_f32_16x16x32_f16 v[12:15], v[128:131], v[176:179], v[12:15]
	s_barrier
	s_add_u32 s26, s36, 0x160000
	s_addc_u32 s27, s37, 0
	s_add_i32 s45, s46, s5
	v_lshl_add_u64 v[108:109], s[26:27], 0, v[2:3]
	s_mov_b32 m0, s45
	s_nop 0
	global_load_lds_dwordx4 v[108:109], off
	s_add_i32 m0, s45, 0x2000
	s_nop 0
	global_load_lds_dwordx4 v180, s[26:27]
	s_waitcnt vmcnt(8)
	s_barrier
	v_mfma_f32_16x16x32_f16 v[56:59], v[186:189], v[148:151], v[56:59]
	v_mfma_f32_16x16x32_f16 v[52:55], v[200:203], v[148:151], v[52:55]
	v_mfma_f32_16x16x32_f16 v[40:43], v[186:189], v[156:159], v[40:43]
	v_mfma_f32_16x16x32_f16 v[36:39], v[200:203], v[156:159], v[36:39]
	v_mfma_f32_16x16x32_f16 v[24:27], v[186:189], v[164:167], v[24:27]
	v_mfma_f32_16x16x32_f16 v[16:19], v[200:203], v[164:167], v[16:19]
	v_mfma_f32_16x16x32_f16 v[8:11], v[186:189], v[172:175], v[8:11]
	v_mfma_f32_16x16x32_f16 v[4:7], v[200:203], v[172:175], v[4:7]
	v_mfma_f32_16x16x32_f16 v[56:59], v[190:193], v[152:155], v[56:59]
	v_mfma_f32_16x16x32_f16 v[52:55], v[206:209], v[152:155], v[52:55]
	v_mfma_f32_16x16x32_f16 v[40:43], v[190:193], v[160:163], v[40:43]
	v_mfma_f32_16x16x32_f16 v[36:39], v[206:209], v[160:163], v[36:39]
	v_mfma_f32_16x16x32_f16 v[24:27], v[190:193], v[168:171], v[24:27]
	v_mfma_f32_16x16x32_f16 v[16:19], v[206:209], v[168:171], v[16:19]
	v_mfma_f32_16x16x32_f16 v[8:11], v[190:193], v[176:179], v[8:11]
	v_mfma_f32_16x16x32_f16 v[4:7], v[206:209], v[176:179], v[4:7]
	s_add_i32 s45, 0, 0x18000
	v_add_u32_e32 v128, s45, v198
	s_barrier
	ds_read_b128 v[108:111], v128
	ds_read_b128 v[112:115], v128 offset:1024
	ds_read_b128 v[120:123], v128 offset:2048
	ds_read_b128 v[128:131], v128 offset:3072
	s_add_u32 s26, s38, 0x160000
	s_addc_u32 s27, s39, 0
	s_mov_b32 m0, s8
	v_lshl_add_u64 v[186:187], s[26:27], 0, v[2:3]
	ds_read_b128 v[148:151], v199 offset:32768
	ds_read_b128 v[152:155], v199 offset:33792
	ds_read_b128 v[156:159], v199 offset:34816
	ds_read_b128 v[160:163], v199 offset:35840
	ds_read_b128 v[164:167], v199 offset:36864
	ds_read_b128 v[168:171], v199 offset:37888
	ds_read_b128 v[172:175], v199 offset:38912
	ds_read_b128 v[176:179], v199 offset:39936
	global_load_lds_dwordx4 v[186:187], off
	s_mov_b32 m0, s9
	s_nop 0
	global_load_lds_dwordx4 v180, s[26:27]
	s_barrier
	s_waitcnt lgkmcnt(0)
	v_mfma_f32_16x16x32_f16 v[144:147], v[108:111], v[148:151], v[144:147]
	v_mfma_f32_16x16x32_f16 v[140:143], v[120:123], v[148:151], v[140:143]
	v_mfma_f32_16x16x32_f16 v[124:127], v[108:111], v[156:159], v[124:127]
	v_mfma_f32_16x16x32_f16 v[116:119], v[120:123], v[156:159], v[116:119]
	v_mfma_f32_16x16x32_f16 v[96:99], v[108:111], v[164:167], v[96:99]
	v_mfma_f32_16x16x32_f16 v[92:95], v[120:123], v[164:167], v[92:95]
	v_mfma_f32_16x16x32_f16 v[88:91], v[108:111], v[172:175], v[88:91]
	v_mfma_f32_16x16x32_f16 v[80:83], v[120:123], v[172:175], v[80:83]
	v_mfma_f32_16x16x32_f16 v[144:147], v[112:115], v[152:155], v[144:147]
	v_mfma_f32_16x16x32_f16 v[140:143], v[128:131], v[152:155], v[140:143]
	v_mfma_f32_16x16x32_f16 v[124:127], v[112:115], v[160:163], v[124:127]
	v_mfma_f32_16x16x32_f16 v[116:119], v[128:131], v[160:163], v[116:119]
	v_mfma_f32_16x16x32_f16 v[96:99], v[112:115], v[168:171], v[96:99]
	v_mfma_f32_16x16x32_f16 v[92:95], v[128:131], v[168:171], v[92:95]
	v_mfma_f32_16x16x32_f16 v[88:91], v[112:115], v[176:179], v[88:91]
	v_mfma_f32_16x16x32_f16 v[80:83], v[128:131], v[176:179], v[80:83]
	s_barrier
	s_add_i32 s38, 0, 0x1c000
	s_add_i32 s26, s45, s5
	v_add_u32_e32 v206, s38, v198
	v_lshl_add_u64 v[194:195], v[194:195], 0, s[88:89]
	s_mov_b32 m0, s26
	ds_read_b128 v[186:189], v206
	ds_read_b128 v[190:193], v206 offset:1024
	ds_read_b128 v[200:203], v206 offset:2048
	ds_read_b128 v[206:209], v206 offset:3072
	global_load_lds_dwordx4 v[194:195], off
	v_lshl_add_u64 v[194:195], v[210:211], 0, s[88:89]
	s_add_i32 m0, s26, 0x2000
	s_nop 0
	global_load_lds_dwordx4 v[194:195], off
	s_waitcnt vmcnt(10)
	s_barrier
	s_waitcnt lgkmcnt(0)
	v_mfma_f32_16x16x32_f16 v[136:139], v[186:189], v[148:151], v[136:139]
	v_mfma_f32_16x16x32_f16 v[132:135], v[200:203], v[148:151], v[132:135]
	v_mfma_f32_16x16x32_f16 v[104:107], v[186:189], v[156:159], v[104:107]
	v_mfma_f32_16x16x32_f16 v[100:103], v[200:203], v[156:159], v[100:103]
	v_mfma_f32_16x16x32_f16 v[84:87], v[186:189], v[164:167], v[84:87]
	v_mfma_f32_16x16x32_f16 v[76:79], v[200:203], v[164:167], v[76:79]
	v_mfma_f32_16x16x32_f16 v[72:75], v[186:189], v[172:175], v[72:75]
	v_mfma_f32_16x16x32_f16 v[68:71], v[200:203], v[172:175], v[68:71]
	v_mfma_f32_16x16x32_f16 v[136:139], v[190:193], v[152:155], v[136:139]
	v_mfma_f32_16x16x32_f16 v[132:135], v[206:209], v[152:155], v[132:135]
	v_mfma_f32_16x16x32_f16 v[104:107], v[190:193], v[160:163], v[104:107]
	v_mfma_f32_16x16x32_f16 v[100:103], v[206:209], v[160:163], v[100:103]
	v_mfma_f32_16x16x32_f16 v[84:87], v[190:193], v[168:171], v[84:87]
	v_mfma_f32_16x16x32_f16 v[76:79], v[206:209], v[168:171], v[76:79]
	v_mfma_f32_16x16x32_f16 v[72:75], v[190:193], v[176:179], v[72:75]
	v_mfma_f32_16x16x32_f16 v[68:71], v[206:209], v[176:179], v[68:71]
	s_mov_b32 m0, s10
	v_lshl_add_u64 v[194:195], v[212:213], 0, s[88:89]
	s_barrier
	ds_read_b128 v[148:151], v199 offset:49152
	ds_read_b128 v[152:155], v199 offset:50176
	ds_read_b128 v[156:159], v199 offset:51200
	ds_read_b128 v[160:163], v199 offset:52224
	ds_read_b128 v[164:167], v199 offset:53248
	ds_read_b128 v[168:171], v199 offset:54272
	ds_read_b128 v[172:175], v199 offset:55296
	ds_read_b128 v[176:179], v199 offset:56320
	global_load_lds_dwordx4 v[194:195], off
	v_lshl_add_u64 v[194:195], v[214:215], 0, s[88:89]
	s_mov_b32 m0, s11
	s_nop 0
	global_load_lds_dwordx4 v[194:195], off
	s_barrier
	s_waitcnt lgkmcnt(0)
	v_mfma_f32_16x16x32_f16 v[64:67], v[108:111], v[148:151], v[64:67]
	v_mfma_f32_16x16x32_f16 v[60:63], v[120:123], v[148:151], v[60:63]
	v_mfma_f32_16x16x32_f16 v[48:51], v[108:111], v[156:159], v[48:51]
	v_mfma_f32_16x16x32_f16 v[44:47], v[120:123], v[156:159], v[44:47]
	v_mfma_f32_16x16x32_f16 v[32:35], v[108:111], v[164:167], v[32:35]
	v_mfma_f32_16x16x32_f16 v[28:31], v[120:123], v[164:167], v[28:31]
	v_mfma_f32_16x16x32_f16 v[20:23], v[108:111], v[172:175], v[20:23]
	v_mfma_f32_16x16x32_f16 v[12:15], v[120:123], v[172:175], v[12:15]
	v_mfma_f32_16x16x32_f16 v[64:67], v[112:115], v[152:155], v[64:67]
	v_mfma_f32_16x16x32_f16 v[60:63], v[128:131], v[152:155], v[60:63]
	v_mfma_f32_16x16x32_f16 v[48:51], v[112:115], v[160:163], v[48:51]
	v_mfma_f32_16x16x32_f16 v[44:47], v[128:131], v[160:163], v[44:47]
	v_mfma_f32_16x16x32_f16 v[32:35], v[112:115], v[168:171], v[32:35]
	v_mfma_f32_16x16x32_f16 v[28:31], v[128:131], v[168:171], v[28:31]
	v_mfma_f32_16x16x32_f16 v[20:23], v[112:115], v[176:179], v[20:23]
	v_mfma_f32_16x16x32_f16 v[12:15], v[128:131], v[176:179], v[12:15]
	s_barrier
	s_add_u32 s26, s36, 0x160080
	s_addc_u32 s27, s37, 0
	s_add_i32 s36, s38, s5
	v_lshl_add_u64 v[108:109], s[26:27], 0, v[2:3]
	s_mov_b32 m0, s36
	s_nop 0
	global_load_lds_dwordx4 v[108:109], off
	s_add_i32 m0, s36, 0x2000
	s_nop 0
	global_load_lds_dwordx4 v180, s[26:27]
	s_waitcnt vmcnt(8)
	s_barrier
	v_mfma_f32_16x16x32_f16 v[56:59], v[186:189], v[148:151], v[56:59]
	v_mfma_f32_16x16x32_f16 v[52:55], v[200:203], v[148:151], v[52:55]
	v_mfma_f32_16x16x32_f16 v[40:43], v[186:189], v[156:159], v[40:43]
	v_mfma_f32_16x16x32_f16 v[36:39], v[200:203], v[156:159], v[36:39]
	v_mfma_f32_16x16x32_f16 v[24:27], v[186:189], v[164:167], v[24:27]
	v_mfma_f32_16x16x32_f16 v[16:19], v[200:203], v[164:167], v[16:19]
	v_mfma_f32_16x16x32_f16 v[8:11], v[186:189], v[172:175], v[8:11]
	v_mfma_f32_16x16x32_f16 v[4:7], v[200:203], v[172:175], v[4:7]
	v_mfma_f32_16x16x32_f16 v[56:59], v[190:193], v[152:155], v[56:59]
	v_mfma_f32_16x16x32_f16 v[52:55], v[206:209], v[152:155], v[52:55]
	v_mfma_f32_16x16x32_f16 v[40:43], v[190:193], v[160:163], v[40:43]
	v_mfma_f32_16x16x32_f16 v[36:39], v[206:209], v[160:163], v[36:39]
	v_mfma_f32_16x16x32_f16 v[24:27], v[190:193], v[168:171], v[24:27]
	v_mfma_f32_16x16x32_f16 v[16:19], v[206:209], v[168:171], v[16:19]
	v_mfma_f32_16x16x32_f16 v[8:11], v[190:193], v[176:179], v[8:11]
	v_mfma_f32_16x16x32_f16 v[4:7], v[206:209], v[176:179], v[4:7]
	s_add_i32 s44, s44, 2
	s_add_u32 s14, s14, 0x100
	s_addc_u32 s15, s15, 0
	s_cmpk_gt_u32 s44, 0x55
	s_mov_b64 s[26:27], s[34:35]
	s_barrier
	s_cbranch_scc0 .LBB0_3035
	s_lshl_b32 s14, s42, 8
	v_mov_b32_e32 v148, v196
	v_mov_b32_e32 v108, v197
	s_add_i32 s26, s14, s12
	s_lshl_b32 s14, s43, 8
	s_or_b32 s14, s14, s13
	v_lshl_add_u32 v108, v108, 2, s14
	s_cmp_lt_i32 s42, 64
	s_movk_i32 s14, 0x3000
	s_cselect_b32 s14, s14, 0x6000
	s_cmp_gt_i32 s42, 31
	s_cselect_b32 s14, s14, 0
	s_lshl_b32 s14, s14, 2
	v_readlane_b32 s15, v251, 41
	s_add_u32 s14, s15, s14
	v_readlane_b32 s15, v251, 42
	v_ashrrev_i32_e32 v109, 31, v108
	s_addc_u32 s15, s15, 0
	v_lshlrev_b64 v[186:187], 2, v[108:109]
	v_add_u32_e32 v148, s26, v148
	v_lshl_add_u64 v[108:109], s[14:15], 0, v[186:187]
	s_mov_b64 s[14:15], 0xa000
	v_ashrrev_i32_e32 v149, 31, v148
	v_lshl_add_u64 v[110:111], v[108:109], 0, s[14:15]
	s_mov_b32 s14, 0xa000
	v_lshlrev_b64 v[190:191], 13, v[148:149]
	s_mov_b64 s[26:27], 0x20000
	v_add_co_u32_e32 v108, vcc, s14, v108
	v_readlane_b32 s14, v250, 25
	v_lshl_add_u64 v[224:225], v[190:191], 0, s[26:27]
	s_mov_b64 s[26:27], 0x40000
	v_readlane_b32 s15, v250, 26
	v_lshl_add_u64 v[194:195], v[190:191], 0, s[26:27]
	s_mov_b64 s[26:27], 0x60000
	v_addc_co_u32_e32 v109, vcc, 0, v109, vcc
	v_lshl_add_u64 v[188:189], s[14:15], 0, v[186:187]
	v_lshl_add_u64 v[192:193], v[190:191], 0, s[26:27]
	global_load_dwordx4 v[128:131], v[108:109], off
	global_load_dwordx4 v[120:123], v[110:111], off offset:64
	global_load_dwordx4 v[112:115], v[110:111], off offset:512
	s_nop 0
	global_load_dwordx4 v[108:111], v[110:111], off offset:576
	v_lshl_add_u64 v[148:149], v[188:189], 0, v[190:191]
	v_lshl_add_u64 v[150:151], v[188:189], 0, v[224:225]
	v_lshl_add_u64 v[176:177], v[188:189], 0, v[194:195]
	v_lshl_add_u64 v[160:161], v[188:189], 0, v[192:193]
	global_load_dwordx4 v[200:203], v[150:151], off offset:576
	global_load_dwordx4 v[206:209], v[150:151], off offset:512
	global_load_dwordx4 v[210:213], v[150:151], off offset:64
	global_load_dwordx4 v[214:217], v[150:151], off
	global_load_dwordx4 v[218:221], v[148:149], off offset:576
	global_load_dwordx4 v[232:235], v[148:149], off offset:512
	global_load_dwordx4 v[236:239], v[148:149], off offset:64
	global_load_dwordx4 v[240:243], v[148:149], off
	s_nop 0
	global_load_dwordx4 v[148:151], v[160:161], off offset:576
	global_load_dwordx4 v[152:155], v[160:161], off offset:512
	global_load_dwordx4 v[156:159], v[160:161], off offset:64
	s_nop 0
	global_load_dwordx4 v[160:163], v[160:161], off
	s_nop 0
	global_load_dwordx4 v[164:167], v[176:177], off offset:576
	global_load_dwordx4 v[168:171], v[176:177], off offset:512
	global_load_dwordx4 v[172:175], v[176:177], off offset:64
	s_nop 0
	global_load_dwordx4 v[176:179], v[176:177], off
	v_lshl_add_u64 v[226:227], s[14:15], 0, v[190:191]
	v_lshl_add_u64 v[226:227], v[226:227], 0, v[186:187]
	s_mov_b64 s[26:27], 0x100000
	s_and_b64 vcc, exec, s[40:41]
	s_mov_b32 s43, s30
	s_mov_b32 s42, s31
	s_mov_b64 s[34:35], s[18:19]
	s_waitcnt vmcnt(0)
	s_nop 0
	v_pk_fma_f32 v[134:135], v[134:135], v[110:111], v[220:221]
	v_pk_fma_f32 v[132:133], v[132:133], v[108:109], v[218:219]
	global_store_dwordx4 v[226:227], v[132:135], off offset:576
	v_pk_fma_f32 v[102:103], v[102:103], v[110:111], v[202:203]
	v_pk_fma_f32 v[100:101], v[100:101], v[108:109], v[200:201]
	v_lshl_add_u64 v[132:133], s[14:15], 0, v[224:225]
	v_lshl_add_u64 v[132:133], v[132:133], 0, v[186:187]
	global_store_dwordx4 v[132:133], v[100:103], off offset:576
	v_pk_fma_f32 v[106:107], v[106:107], v[114:115], v[208:209]
	v_pk_fma_f32 v[104:105], v[104:105], v[112:113], v[206:207]
	v_lshl_add_u64 v[100:101], s[14:15], 0, v[194:195]
	v_lshl_add_u64 v[100:101], v[100:101], 0, v[186:187]
	v_pk_fma_f32 v[78:79], v[78:79], v[110:111], v[166:167]
	v_pk_fma_f32 v[76:77], v[76:77], v[108:109], v[164:165]
	global_store_dwordx4 v[132:133], v[104:107], off offset:512
	v_pk_fma_f32 v[86:87], v[86:87], v[114:115], v[170:171]
	v_pk_fma_f32 v[84:85], v[84:85], v[112:113], v[168:169]
	global_store_dwordx4 v[100:101], v[76:79], off offset:576
	v_lshl_add_u64 v[106:107], v[190:191], 0, s[26:27]
	s_mov_b64 s[26:27], 0x120000
	v_lshl_add_u64 v[76:77], s[14:15], 0, v[192:193]
	global_store_dwordx4 v[100:101], v[84:87], off offset:512
	v_pk_fma_f32 v[78:79], v[90:91], v[130:131], v[162:163]
	v_pk_fma_f32 v[72:73], v[72:73], v[112:113], v[152:153]
	v_lshl_add_u64 v[84:85], v[76:77], 0, v[186:187]
	v_pk_fma_f32 v[76:77], v[88:89], v[128:129], v[160:161]
	v_lshl_add_u64 v[152:153], v[190:191], 0, s[26:27]
	s_mov_b64 s[26:27], 0x140000
	v_pk_fma_f32 v[146:147], v[146:147], v[130:131], v[242:243]
	v_pk_fma_f32 v[144:145], v[144:145], v[128:129], v[240:241]
	v_pk_fma_f32 v[142:143], v[142:143], v[122:123], v[238:239]
	v_pk_fma_f32 v[140:141], v[140:141], v[120:121], v[236:237]
	v_pk_fma_f32 v[138:139], v[138:139], v[114:115], v[234:235]
	v_pk_fma_f32 v[136:137], v[136:137], v[112:113], v[232:233]
	v_pk_fma_f32 v[126:127], v[126:127], v[130:131], v[216:217]
	v_pk_fma_f32 v[124:125], v[124:125], v[128:129], v[214:215]
	v_pk_fma_f32 v[118:119], v[118:119], v[122:123], v[212:213]
	v_pk_fma_f32 v[116:117], v[116:117], v[120:121], v[210:211]
	v_pk_fma_f32 v[98:99], v[98:99], v[130:131], v[178:179]
	v_pk_fma_f32 v[96:97], v[96:97], v[128:129], v[176:177]
	v_pk_fma_f32 v[94:95], v[94:95], v[122:123], v[174:175]
	v_pk_fma_f32 v[92:93], v[92:93], v[120:121], v[172:173]
	global_store_dwordx4 v[84:85], v[76:79], off
	v_pk_fma_f32 v[74:75], v[74:75], v[114:115], v[154:155]
	v_pk_fma_f32 v[70:71], v[70:71], v[110:111], v[150:151]
	v_pk_fma_f32 v[78:79], v[82:83], v[122:123], v[158:159]
	v_pk_fma_f32 v[76:77], v[80:81], v[120:121], v[156:157]
	v_pk_fma_f32 v[68:69], v[68:69], v[108:109], v[148:149]
	v_lshl_add_u64 v[154:155], v[190:191], 0, s[26:27]
	s_mov_b64 s[26:27], 0x160000
	global_store_dwordx4 v[226:227], v[144:147], off
	global_store_dwordx4 v[226:227], v[140:143], off offset:64
	global_store_dwordx4 v[226:227], v[136:139], off offset:512
	global_store_dwordx4 v[132:133], v[124:127], off
	global_store_dwordx4 v[132:133], v[116:119], off offset:64
	global_store_dwordx4 v[100:101], v[96:99], off
	global_store_dwordx4 v[100:101], v[92:95], off offset:64
	global_store_dwordx4 v[84:85], v[76:79], off offset:64
	global_store_dwordx4 v[84:85], v[72:75], off offset:512
	global_store_dwordx4 v[84:85], v[68:71], off offset:576
	v_lshl_add_u64 v[100:101], v[190:191], 0, s[26:27]
	v_lshl_add_u64 v[96:97], v[188:189], 0, v[154:155]
	v_lshl_add_u64 v[68:69], v[188:189], 0, v[106:107]
	v_lshl_add_u64 v[70:71], v[188:189], 0, v[152:153]
	v_lshl_add_u64 v[80:81], v[188:189], 0, v[100:101]
	global_load_dwordx4 v[102:105], v[70:71], off offset:576
	global_load_dwordx4 v[116:119], v[70:71], off offset:512
	global_load_dwordx4 v[124:127], v[70:71], off offset:64
	global_load_dwordx4 v[132:135], v[70:71], off
	global_load_dwordx4 v[136:139], v[68:69], off offset:576
	global_load_dwordx4 v[140:143], v[68:69], off offset:512
	global_load_dwordx4 v[144:147], v[68:69], off offset:64
	global_load_dwordx4 v[148:151], v[68:69], off
	s_nop 0
	global_load_dwordx4 v[68:71], v[80:81], off offset:576
	global_load_dwordx4 v[72:75], v[80:81], off offset:512
	global_load_dwordx4 v[76:79], v[80:81], off offset:64
	s_nop 0
	global_load_dwordx4 v[80:83], v[80:81], off
	s_nop 0
	global_load_dwordx4 v[84:87], v[96:97], off offset:576
	global_load_dwordx4 v[88:91], v[96:97], off offset:512
	global_load_dwordx4 v[92:95], v[96:97], off offset:64
	s_nop 0
	global_load_dwordx4 v[96:99], v[96:97], off
	v_lshl_add_u64 v[106:107], s[14:15], 0, v[106:107]
	s_waitcnt vmcnt(0)
	v_lshl_add_u64 v[106:107], v[106:107], 0, v[186:187]
	v_pk_fma_f32 v[54:55], v[54:55], v[110:111], v[138:139]
	v_pk_fma_f32 v[52:53], v[52:53], v[108:109], v[136:137]
	global_store_dwordx4 v[106:107], v[52:55], off offset:576
	v_pk_fma_f32 v[38:39], v[38:39], v[110:111], v[104:105]
	v_pk_fma_f32 v[36:37], v[36:37], v[108:109], v[102:103]
	v_lshl_add_u64 v[52:53], s[14:15], 0, v[152:153]
	v_lshl_add_u64 v[52:53], v[52:53], 0, v[186:187]
	global_store_dwordx4 v[52:53], v[36:39], off offset:576
	v_pk_fma_f32 v[18:19], v[18:19], v[110:111], v[86:87]
	v_pk_fma_f32 v[16:17], v[16:17], v[108:109], v[84:85]
	v_lshl_add_u64 v[36:37], s[14:15], 0, v[154:155]
	v_lshl_add_u64 v[36:37], v[36:37], 0, v[186:187]
	v_pk_fma_f32 v[26:27], v[26:27], v[114:115], v[90:91]
	v_pk_fma_f32 v[24:25], v[24:25], v[112:113], v[88:89]
	global_store_dwordx4 v[36:37], v[16:19], off offset:576
	v_pk_fma_f32 v[66:67], v[66:67], v[130:131], v[150:151]
	v_pk_fma_f32 v[64:65], v[64:65], v[128:129], v[148:149]
	v_lshl_add_u64 v[16:17], s[14:15], 0, v[100:101]
	v_pk_fma_f32 v[62:63], v[62:63], v[122:123], v[146:147]
	v_pk_fma_f32 v[60:61], v[60:61], v[120:121], v[144:145]
	v_pk_fma_f32 v[58:59], v[58:59], v[114:115], v[142:143]
	v_pk_fma_f32 v[56:57], v[56:57], v[112:113], v[140:141]
	v_pk_fma_f32 v[50:51], v[50:51], v[130:131], v[134:135]
	v_pk_fma_f32 v[48:49], v[48:49], v[128:129], v[132:133]
	v_pk_fma_f32 v[46:47], v[46:47], v[122:123], v[126:127]
	v_pk_fma_f32 v[44:45], v[44:45], v[120:121], v[124:125]
	v_pk_fma_f32 v[42:43], v[42:43], v[114:115], v[118:119]
	v_pk_fma_f32 v[40:41], v[40:41], v[112:113], v[116:117]
	v_pk_fma_f32 v[34:35], v[34:35], v[130:131], v[98:99]
	v_pk_fma_f32 v[32:33], v[32:33], v[128:129], v[96:97]
	v_pk_fma_f32 v[30:31], v[30:31], v[122:123], v[94:95]
	v_pk_fma_f32 v[28:29], v[28:29], v[120:121], v[92:93]
	global_store_dwordx4 v[36:37], v[24:27], off offset:512
	v_pk_fma_f32 v[18:19], v[22:23], v[130:131], v[82:83]
	v_pk_fma_f32 v[14:15], v[14:15], v[122:123], v[78:79]
	v_lshl_add_u64 v[24:25], v[16:17], 0, v[186:187]
	v_pk_fma_f32 v[16:17], v[20:21], v[128:129], v[80:81]
	v_pk_fma_f32 v[12:13], v[12:13], v[120:121], v[76:77]
	v_pk_fma_f32 v[10:11], v[10:11], v[114:115], v[74:75]
	v_pk_fma_f32 v[8:9], v[8:9], v[112:113], v[72:73]
	v_pk_fma_f32 v[6:7], v[6:7], v[110:111], v[70:71]
	v_pk_fma_f32 v[4:5], v[4:5], v[108:109], v[68:69]
	global_store_dwordx4 v[106:107], v[64:67], off
	global_store_dwordx4 v[106:107], v[60:63], off offset:64
	global_store_dwordx4 v[106:107], v[56:59], off offset:512
	global_store_dwordx4 v[52:53], v[48:51], off
	global_store_dwordx4 v[52:53], v[44:47], off offset:64
	global_store_dwordx4 v[52:53], v[40:43], off offset:512
	global_store_dwordx4 v[36:37], v[32:35], off
	global_store_dwordx4 v[36:37], v[28:31], off offset:64
	global_store_dwordx4 v[24:25], v[16:19], off
	global_store_dwordx4 v[24:25], v[12:15], off offset:64
	global_store_dwordx4 v[24:25], v[8:11], off offset:512
	global_store_dwordx4 v[24:25], v[4:7], off offset:576
	s_mov_b64 s[26:27], s[16:17]
	s_cbranch_vccz .LBB0_3028
	s_waitcnt vmcnt(0)
	s_cmpk_gt_u32 s4, 0xff
	s_cbranch_scc1 .LBB0_3039
	s_barrier

.LBB0_3048:
	s_add_u32 s40, s36, 0x100
	s_addc_u32 s41, s37, 0
	s_add_i32 s47, 0, 0x10000
	v_add_u32_e32 v144, s47, v158
	ds_read_b128 v[132:135], v144
	ds_read_b128 v[136:139], v144 offset:1024
	ds_read_b128 v[140:143], v144 offset:2048
	ds_read_b128 v[144:147], v144 offset:3072
	s_cmp_eq_u32 s46, 4
	s_cselect_b32 s43, s19, s41
	s_cselect_b32 s42, s18, s40
	s_cselect_b32 s39, s27, s45
	s_cselect_b32 s38, s26, s44
	v_lshl_add_u64 v[154:155], s[36:37], 0, v[150:151]
	s_add_i32 m0, s6, 0xc000
	ds_read_b128 v[160:163], v159
	ds_read_b128 v[164:167], v159 offset:1024
	ds_read_b128 v[168:171], v159 offset:2048
	ds_read_b128 v[172:175], v159 offset:3072
	ds_read_b128 v[176:179], v159 offset:4096
	ds_read_b128 v[180:183], v159 offset:5120
	ds_read_b128 v[184:187], v159 offset:6144
	ds_read_b128 v[188:191], v159 offset:7168
	global_load_lds_dwordx4 v[154:155], off
	v_lshl_add_u64 v[154:155], s[36:37], 0, v[152:153]
	s_add_i32 m0, s6, 0xe000
	s_nop 0
	global_load_lds_dwordx4 v[154:155], off
	s_barrier
	s_waitcnt lgkmcnt(0)
	v_mfma_f32_16x16x32_f16 v[128:131], v[132:135], v[160:163], v[128:131]
	v_mfma_f32_16x16x32_f16 v[124:127], v[140:143], v[160:163], v[124:127]
	v_mfma_f32_16x16x32_f16 v[112:115], v[132:135], v[168:171], v[112:115]
	v_mfma_f32_16x16x32_f16 v[108:111], v[140:143], v[168:171], v[108:111]
	v_mfma_f32_16x16x32_f16 v[96:99], v[132:135], v[176:179], v[96:99]
	v_mfma_f32_16x16x32_f16 v[92:95], v[140:143], v[176:179], v[92:95]
	v_mfma_f32_16x16x32_f16 v[80:83], v[132:135], v[184:187], v[80:83]
	v_mfma_f32_16x16x32_f16 v[76:79], v[140:143], v[184:187], v[76:79]
	v_mfma_f32_16x16x32_f16 v[128:131], v[136:139], v[164:167], v[128:131]
	v_mfma_f32_16x16x32_f16 v[124:127], v[144:147], v[164:167], v[124:127]
	v_mfma_f32_16x16x32_f16 v[112:115], v[136:139], v[172:175], v[112:115]
	v_mfma_f32_16x16x32_f16 v[108:111], v[144:147], v[172:175], v[108:111]
	v_mfma_f32_16x16x32_f16 v[96:99], v[136:139], v[180:183], v[96:99]
	v_mfma_f32_16x16x32_f16 v[92:95], v[144:147], v[180:183], v[92:95]
	v_mfma_f32_16x16x32_f16 v[80:83], v[136:139], v[188:191], v[80:83]
	v_mfma_f32_16x16x32_f16 v[76:79], v[144:147], v[188:191], v[76:79]
	s_barrier
	s_add_i32 s48, 0, 0x14000
	v_add_u32_e32 v154, s48, v158
	s_add_i32 s36, s47, s5
	ds_read_b128 v[192:195], v154
	ds_read_b128 v[196:199], v154 offset:1024
	ds_read_b128 v[200:203], v154 offset:2048
	ds_read_b128 v[206:209], v154 offset:3072
	v_lshl_add_u64 v[154:155], s[38:39], 0, v[2:3]
	s_mov_b32 m0, s36
	v_lshl_add_u64 v[210:211], s[38:39], 0, v[148:149]
	global_load_lds_dwordx4 v[154:155], off
	s_add_i32 m0, s36, 0x2000
	s_nop 0
	global_load_lds_dwordx4 v[210:211], off
	s_waitcnt vmcnt(10)
	s_barrier
	s_waitcnt lgkmcnt(0)
	v_mfma_f32_16x16x32_f16 v[120:123], v[192:195], v[160:163], v[120:123]
	v_mfma_f32_16x16x32_f16 v[116:119], v[200:203], v[160:163], v[116:119]
	v_mfma_f32_16x16x32_f16 v[104:107], v[192:195], v[168:171], v[104:107]
	v_mfma_f32_16x16x32_f16 v[100:103], v[200:203], v[168:171], v[100:103]
	v_mfma_f32_16x16x32_f16 v[88:91], v[192:195], v[176:179], v[88:91]
	v_mfma_f32_16x16x32_f16 v[84:87], v[200:203], v[176:179], v[84:87]
	v_mfma_f32_16x16x32_f16 v[72:75], v[192:195], v[184:187], v[72:75]
	v_mfma_f32_16x16x32_f16 v[68:71], v[200:203], v[184:187], v[68:71]
	v_mfma_f32_16x16x32_f16 v[120:123], v[196:199], v[164:167], v[120:123]
	v_mfma_f32_16x16x32_f16 v[116:119], v[206:209], v[164:167], v[116:119]
	v_mfma_f32_16x16x32_f16 v[104:107], v[196:199], v[172:175], v[104:107]
	v_mfma_f32_16x16x32_f16 v[100:103], v[206:209], v[172:175], v[100:103]
	v_mfma_f32_16x16x32_f16 v[88:91], v[196:199], v[180:183], v[88:91]
	v_mfma_f32_16x16x32_f16 v[84:87], v[206:209], v[180:183], v[84:87]
	v_mfma_f32_16x16x32_f16 v[72:75], v[196:199], v[188:191], v[72:75]
	v_mfma_f32_16x16x32_f16 v[68:71], v[206:209], v[188:191], v[68:71]
	s_mov_b32 m0, s6
	v_lshl_add_u64 v[212:213], s[42:43], 0, v[2:3]
	s_barrier
	ds_read_b128 v[160:163], v159 offset:16384
	ds_read_b128 v[164:167], v159 offset:17408
	ds_read_b128 v[168:171], v159 offset:18432
	ds_read_b128 v[172:175], v159 offset:19456
	ds_read_b128 v[176:179], v159 offset:20480
	ds_read_b128 v[180:183], v159 offset:21504
	ds_read_b128 v[184:187], v159 offset:22528
	ds_read_b128 v[188:191], v159 offset:23552
	global_load_lds_dwordx4 v[212:213], off
	v_lshl_add_u64 v[214:215], s[42:43], 0, v[148:149]
	s_mov_b32 m0, s7
	s_nop 0
	global_load_lds_dwordx4 v[214:215], off
	s_barrier
	s_waitcnt lgkmcnt(0)
	v_mfma_f32_16x16x32_f16 v[64:67], v[132:135], v[160:163], v[64:67]
	v_mfma_f32_16x16x32_f16 v[60:63], v[140:143], v[160:163], v[60:63]
	v_mfma_f32_16x16x32_f16 v[56:59], v[132:135], v[168:171], v[56:59]
	v_mfma_f32_16x16x32_f16 v[44:47], v[140:143], v[168:171], v[44:47]
	v_mfma_f32_16x16x32_f16 v[40:43], v[132:135], v[176:179], v[40:43]
	v_mfma_f32_16x16x32_f16 v[28:31], v[140:143], v[176:179], v[28:31]
	v_mfma_f32_16x16x32_f16 v[24:27], v[132:135], v[184:187], v[24:27]
	v_mfma_f32_16x16x32_f16 v[12:15], v[140:143], v[184:187], v[12:15]
	v_mfma_f32_16x16x32_f16 v[64:67], v[136:139], v[164:167], v[64:67]
	v_mfma_f32_16x16x32_f16 v[60:63], v[144:147], v[164:167], v[60:63]
	v_mfma_f32_16x16x32_f16 v[56:59], v[136:139], v[172:175], v[56:59]
	v_mfma_f32_16x16x32_f16 v[44:47], v[144:147], v[172:175], v[44:47]
	v_mfma_f32_16x16x32_f16 v[40:43], v[136:139], v[180:183], v[40:43]
	v_mfma_f32_16x16x32_f16 v[28:31], v[144:147], v[180:183], v[28:31]
	v_mfma_f32_16x16x32_f16 v[24:27], v[136:139], v[188:191], v[24:27]
	v_mfma_f32_16x16x32_f16 v[12:15], v[144:147], v[188:191], v[12:15]
	s_barrier
	s_add_u32 s36, s38, 0x160000
	s_addc_u32 s37, s39, 0
	s_add_i32 s47, s48, s5
	v_lshl_add_u64 v[132:133], s[36:37], 0, v[2:3]
	s_mov_b32 m0, s47
	s_nop 0
	global_load_lds_dwordx4 v[132:133], off
	s_add_i32 m0, s47, 0x2000
	s_nop 0
	global_load_lds_dwordx4 v148, s[36:37]
	s_waitcnt vmcnt(8)
	s_barrier
	v_mfma_f32_16x16x32_f16 v[52:55], v[192:195], v[160:163], v[52:55]
	v_mfma_f32_16x16x32_f16 v[48:51], v[200:203], v[160:163], v[48:51]
	v_mfma_f32_16x16x32_f16 v[36:39], v[192:195], v[168:171], v[36:39]
	v_mfma_f32_16x16x32_f16 v[32:35], v[200:203], v[168:171], v[32:35]
	v_mfma_f32_16x16x32_f16 v[20:23], v[192:195], v[176:179], v[20:23]
	v_mfma_f32_16x16x32_f16 v[16:19], v[200:203], v[176:179], v[16:19]
	v_mfma_f32_16x16x32_f16 v[8:11], v[192:195], v[184:187], v[8:11]
	v_mfma_f32_16x16x32_f16 v[4:7], v[200:203], v[184:187], v[4:7]
	v_mfma_f32_16x16x32_f16 v[52:55], v[196:199], v[164:167], v[52:55]
	v_mfma_f32_16x16x32_f16 v[48:51], v[206:209], v[164:167], v[48:51]
	v_mfma_f32_16x16x32_f16 v[36:39], v[196:199], v[172:175], v[36:39]
	v_mfma_f32_16x16x32_f16 v[32:35], v[206:209], v[172:175], v[32:35]
	v_mfma_f32_16x16x32_f16 v[20:23], v[196:199], v[180:183], v[20:23]
	v_mfma_f32_16x16x32_f16 v[16:19], v[206:209], v[180:183], v[16:19]
	v_mfma_f32_16x16x32_f16 v[8:11], v[196:199], v[188:191], v[8:11]
	v_mfma_f32_16x16x32_f16 v[4:7], v[206:209], v[188:191], v[4:7]
	s_add_i32 s47, 0, 0x18000
	v_add_u32_e32 v144, s47, v158
	s_barrier
	ds_read_b128 v[132:135], v144
	ds_read_b128 v[136:139], v144 offset:1024
	ds_read_b128 v[140:143], v144 offset:2048
	ds_read_b128 v[144:147], v144 offset:3072
	s_add_u32 s36, s42, 0x160000
	s_addc_u32 s37, s43, 0
	s_mov_b32 m0, s8
	v_lshl_add_u64 v[192:193], s[36:37], 0, v[2:3]
	ds_read_b128 v[160:163], v159 offset:32768
	ds_read_b128 v[164:167], v159 offset:33792
	ds_read_b128 v[168:171], v159 offset:34816
	ds_read_b128 v[172:175], v159 offset:35840
	ds_read_b128 v[176:179], v159 offset:36864
	ds_read_b128 v[180:183], v159 offset:37888
	ds_read_b128 v[184:187], v159 offset:38912
	ds_read_b128 v[188:191], v159 offset:39936
	global_load_lds_dwordx4 v[192:193], off
	s_mov_b32 m0, s9
	s_nop 0
	global_load_lds_dwordx4 v148, s[36:37]
	s_barrier
	s_waitcnt lgkmcnt(0)
	v_mfma_f32_16x16x32_f16 v[128:131], v[132:135], v[160:163], v[128:131]
	v_mfma_f32_16x16x32_f16 v[124:127], v[140:143], v[160:163], v[124:127]
	v_mfma_f32_16x16x32_f16 v[112:115], v[132:135], v[168:171], v[112:115]
	v_mfma_f32_16x16x32_f16 v[108:111], v[140:143], v[168:171], v[108:111]
	v_mfma_f32_16x16x32_f16 v[96:99], v[132:135], v[176:179], v[96:99]
	v_mfma_f32_16x16x32_f16 v[92:95], v[140:143], v[176:179], v[92:95]
	v_mfma_f32_16x16x32_f16 v[80:83], v[132:135], v[184:187], v[80:83]
	v_mfma_f32_16x16x32_f16 v[76:79], v[140:143], v[184:187], v[76:79]
	v_mfma_f32_16x16x32_f16 v[128:131], v[136:139], v[164:167], v[128:131]
	v_mfma_f32_16x16x32_f16 v[124:127], v[144:147], v[164:167], v[124:127]
	v_mfma_f32_16x16x32_f16 v[112:115], v[136:139], v[172:175], v[112:115]
	v_mfma_f32_16x16x32_f16 v[108:111], v[144:147], v[172:175], v[108:111]
	v_mfma_f32_16x16x32_f16 v[96:99], v[136:139], v[180:183], v[96:99]
	v_mfma_f32_16x16x32_f16 v[92:95], v[144:147], v[180:183], v[92:95]
	v_mfma_f32_16x16x32_f16 v[80:83], v[136:139], v[188:191], v[80:83]
	v_mfma_f32_16x16x32_f16 v[76:79], v[144:147], v[188:191], v[76:79]
	s_barrier
	s_add_i32 s42, 0, 0x1c000
	s_add_i32 s36, s47, s5
	v_add_u32_e32 v206, s42, v158
	v_lshl_add_u64 v[154:155], v[154:155], 0, s[88:89]
	s_mov_b32 m0, s36
	ds_read_b128 v[192:195], v206
	ds_read_b128 v[196:199], v206 offset:1024
	ds_read_b128 v[200:203], v206 offset:2048
	ds_read_b128 v[206:209], v206 offset:3072
	global_load_lds_dwordx4 v[154:155], off
	v_lshl_add_u64 v[154:155], v[210:211], 0, s[88:89]
	s_add_i32 m0, s36, 0x2000
	s_nop 0
	global_load_lds_dwordx4 v[154:155], off
	s_waitcnt vmcnt(10)
	s_barrier
	s_waitcnt lgkmcnt(0)
	v_mfma_f32_16x16x32_f16 v[120:123], v[192:195], v[160:163], v[120:123]
	v_mfma_f32_16x16x32_f16 v[116:119], v[200:203], v[160:163], v[116:119]
	v_mfma_f32_16x16x32_f16 v[104:107], v[192:195], v[168:171], v[104:107]
	v_mfma_f32_16x16x32_f16 v[100:103], v[200:203], v[168:171], v[100:103]
	v_mfma_f32_16x16x32_f16 v[88:91], v[192:195], v[176:179], v[88:91]
	v_mfma_f32_16x16x32_f16 v[84:87], v[200:203], v[176:179], v[84:87]
	v_mfma_f32_16x16x32_f16 v[72:75], v[192:195], v[184:187], v[72:75]
	v_mfma_f32_16x16x32_f16 v[68:71], v[200:203], v[184:187], v[68:71]
	v_mfma_f32_16x16x32_f16 v[120:123], v[196:199], v[164:167], v[120:123]
	v_mfma_f32_16x16x32_f16 v[116:119], v[206:209], v[164:167], v[116:119]
	v_mfma_f32_16x16x32_f16 v[104:107], v[196:199], v[172:175], v[104:107]
	v_mfma_f32_16x16x32_f16 v[100:103], v[206:209], v[172:175], v[100:103]
	v_mfma_f32_16x16x32_f16 v[88:91], v[196:199], v[180:183], v[88:91]
	v_mfma_f32_16x16x32_f16 v[84:87], v[206:209], v[180:183], v[84:87]
	v_mfma_f32_16x16x32_f16 v[72:75], v[196:199], v[188:191], v[72:75]
	v_mfma_f32_16x16x32_f16 v[68:71], v[206:209], v[188:191], v[68:71]
	s_mov_b32 m0, s10
	v_lshl_add_u64 v[154:155], v[212:213], 0, s[88:89]
	s_barrier
	ds_read_b128 v[160:163], v159 offset:49152
	ds_read_b128 v[164:167], v159 offset:50176
	ds_read_b128 v[168:171], v159 offset:51200
	ds_read_b128 v[172:175], v159 offset:52224
	ds_read_b128 v[176:179], v159 offset:53248
	ds_read_b128 v[180:183], v159 offset:54272
	ds_read_b128 v[184:187], v159 offset:55296
	ds_read_b128 v[188:191], v159 offset:56320
	global_load_lds_dwordx4 v[154:155], off
	v_lshl_add_u64 v[154:155], v[214:215], 0, s[88:89]
	s_mov_b32 m0, s11
	s_nop 0
	global_load_lds_dwordx4 v[154:155], off
	s_barrier
	s_waitcnt lgkmcnt(0)
	v_mfma_f32_16x16x32_f16 v[64:67], v[132:135], v[160:163], v[64:67]
	v_mfma_f32_16x16x32_f16 v[60:63], v[140:143], v[160:163], v[60:63]
	v_mfma_f32_16x16x32_f16 v[56:59], v[132:135], v[168:171], v[56:59]
	v_mfma_f32_16x16x32_f16 v[44:47], v[140:143], v[168:171], v[44:47]
	v_mfma_f32_16x16x32_f16 v[40:43], v[132:135], v[176:179], v[40:43]
	v_mfma_f32_16x16x32_f16 v[28:31], v[140:143], v[176:179], v[28:31]
	v_mfma_f32_16x16x32_f16 v[24:27], v[132:135], v[184:187], v[24:27]
	v_mfma_f32_16x16x32_f16 v[12:15], v[140:143], v[184:187], v[12:15]
	v_mfma_f32_16x16x32_f16 v[64:67], v[136:139], v[164:167], v[64:67]
	v_mfma_f32_16x16x32_f16 v[60:63], v[144:147], v[164:167], v[60:63]
	v_mfma_f32_16x16x32_f16 v[56:59], v[136:139], v[172:175], v[56:59]
	v_mfma_f32_16x16x32_f16 v[44:47], v[144:147], v[172:175], v[44:47]
	v_mfma_f32_16x16x32_f16 v[40:43], v[136:139], v[180:183], v[40:43]
	v_mfma_f32_16x16x32_f16 v[28:31], v[144:147], v[180:183], v[28:31]
	v_mfma_f32_16x16x32_f16 v[24:27], v[136:139], v[188:191], v[24:27]
	v_mfma_f32_16x16x32_f16 v[12:15], v[144:147], v[188:191], v[12:15]
	s_barrier
	s_add_u32 s36, s38, 0x160080
	s_addc_u32 s37, s39, 0
	s_add_i32 s38, s42, s5
	v_lshl_add_u64 v[132:133], s[36:37], 0, v[2:3]
	s_mov_b32 m0, s38
	s_nop 0
	global_load_lds_dwordx4 v[132:133], off
	s_add_i32 m0, s38, 0x2000
	s_nop 0
	global_load_lds_dwordx4 v148, s[36:37]
	s_waitcnt vmcnt(8)
	s_barrier
	v_mfma_f32_16x16x32_f16 v[52:55], v[192:195], v[160:163], v[52:55]
	v_mfma_f32_16x16x32_f16 v[48:51], v[200:203], v[160:163], v[48:51]
	v_mfma_f32_16x16x32_f16 v[36:39], v[192:195], v[168:171], v[36:39]
	v_mfma_f32_16x16x32_f16 v[32:35], v[200:203], v[168:171], v[32:35]
	v_mfma_f32_16x16x32_f16 v[20:23], v[192:195], v[176:179], v[20:23]
	v_mfma_f32_16x16x32_f16 v[16:19], v[200:203], v[176:179], v[16:19]
	v_mfma_f32_16x16x32_f16 v[8:11], v[192:195], v[184:187], v[8:11]
	v_mfma_f32_16x16x32_f16 v[4:7], v[200:203], v[184:187], v[4:7]
	v_mfma_f32_16x16x32_f16 v[52:55], v[196:199], v[164:167], v[52:55]
	v_mfma_f32_16x16x32_f16 v[48:51], v[206:209], v[164:167], v[48:51]
	v_mfma_f32_16x16x32_f16 v[36:39], v[196:199], v[172:175], v[36:39]
	v_mfma_f32_16x16x32_f16 v[32:35], v[206:209], v[172:175], v[32:35]
	v_mfma_f32_16x16x32_f16 v[20:23], v[196:199], v[180:183], v[20:23]
	v_mfma_f32_16x16x32_f16 v[16:19], v[206:209], v[180:183], v[16:19]
	v_mfma_f32_16x16x32_f16 v[8:11], v[196:199], v[188:191], v[8:11]
	v_mfma_f32_16x16x32_f16 v[4:7], v[206:209], v[188:191], v[4:7]
	s_add_i32 s46, s46, 2
	s_add_u32 s44, s44, 0x100
	s_addc_u32 s45, s45, 0
	s_cmp_gt_u32 s46, 5
	s_mov_b64 s[36:37], s[40:41]
	s_barrier
	s_cbranch_scc0 .LBB0_3048
	s_lshl_b32 s36, s30, 8
	v_mov_b32_e32 v160, v156
	v_mov_b32_e32 v132, v157
	s_and_b32 s36, s36, 0xff00
	s_or_b32 s36, s36, s12
	v_lshl_add_u32 v132, v132, 2, s36
	v_ashrrev_i32_e32 v133, 31, v132
	v_lshlrev_b64 v[154:155], 2, v[132:133]
	v_lshl_add_u64 v[132:133], s[16:17], 0, v[154:155]
	global_load_dwordx4 v[144:147], v[132:133], off
	global_load_dwordx4 v[140:143], v[132:133], off offset:64
	global_load_dwordx4 v[136:139], v[132:133], off offset:512
	s_nop 0
	global_load_dwordx4 v[132:135], v[132:133], off offset:576
	s_lshl_b32 s31, s31, 8
	s_ashr_i32 s30, s30, 8
	s_add_i32 s31, s13, s31
	v_add_u32_e32 v160, s31, v160
	s_ashr_i32 s31, s30, 31
	s_lshl_b64 s[30:31], s[30:31], 22
	v_readlane_b32 s36, v250, 27
	v_readlane_b32 s37, v250, 28
	s_add_u32 s30, s36, s30
	s_addc_u32 s31, s37, s31
	v_ashrrev_i32_e32 v161, 31, v160
	v_lshl_add_u64 v[154:155], s[30:31], 0, v[154:155]
	v_lshlrev_b64 v[160:161], 13, v[160:161]
	v_lshl_add_u64 v[154:155], v[154:155], 0, v[160:161]
	s_mov_b64 s[30:31], 0x20000
	s_mov_b64 s[38:39], s[26:27]
	s_mov_b64 s[36:37], s[18:19]
	s_waitcnt vmcnt(0)
	v_pk_mul_f32 v[130:131], v[130:131], v[146:147]
	v_pk_mul_f32 v[128:129], v[128:129], v[144:145]
	v_pk_mul_f32 v[54:55], v[54:55], v[138:139]
	v_pk_mul_f32 v[118:119], v[118:119], v[134:135]
	v_pk_mul_f32 v[116:117], v[116:117], v[132:133]
	global_store_dwordx4 v[154:155], v[116:119], off offset:576
	v_pk_mul_f32 v[102:103], v[102:103], v[134:135]
	v_pk_mul_f32 v[100:101], v[100:101], v[132:133]
	v_lshl_add_u64 v[116:117], v[154:155], 0, s[30:31]
	s_mov_b32 s30, 0x20000
	v_add_co_u32_e32 v118, vcc, s30, v154
	s_mov_b64 s[30:31], 0x40000
	s_nop 0
	v_addc_co_u32_e32 v119, vcc, 0, v155, vcc
	global_store_dwordx4 v[116:117], v[100:103], off offset:576
	v_pk_mul_f32 v[86:87], v[86:87], v[134:135]
	v_pk_mul_f32 v[84:85], v[84:85], v[132:133]
	v_lshl_add_u64 v[100:101], v[154:155], 0, s[30:31]
	s_mov_b32 s30, 0x40000
	v_add_co_u32_e32 v102, vcc, s30, v154
	s_mov_b64 s[30:31], 0x60000
	s_nop 0
	v_addc_co_u32_e32 v103, vcc, 0, v155, vcc
	global_store_dwordx4 v[100:101], v[84:87], off offset:576
	v_pk_mul_f32 v[70:71], v[70:71], v[134:135]
	v_pk_mul_f32 v[68:69], v[68:69], v[132:133]
	v_lshl_add_u64 v[84:85], v[154:155], 0, s[30:31]
	s_mov_b32 s30, 0x60000
	v_add_co_u32_e32 v86, vcc, s30, v154
	s_mov_b64 s[30:31], 0x100000
	s_nop 0
	v_addc_co_u32_e32 v87, vcc, 0, v155, vcc
	global_store_dwordx4 v[84:85], v[68:71], off offset:576
	v_pk_mul_f32 v[52:53], v[52:53], v[136:137]
	v_pk_mul_f32 v[38:39], v[38:39], v[138:139]
	v_lshl_add_u64 v[68:69], v[154:155], 0, s[30:31]
	s_mov_b32 s30, 0x100000
	v_add_co_u32_e32 v70, vcc, s30, v154
	s_mov_b64 s[30:31], 0x120000
	s_nop 0
	v_addc_co_u32_e32 v71, vcc, 0, v155, vcc
	global_store_dwordx4 v[68:69], v[52:55], off offset:512
	v_pk_mul_f32 v[36:37], v[36:37], v[136:137]
	v_pk_mul_f32 v[22:23], v[22:23], v[138:139]
	v_lshl_add_u64 v[52:53], v[154:155], 0, s[30:31]
	s_mov_b32 s30, 0x120000
	v_add_co_u32_e32 v54, vcc, s30, v154
	s_mov_b64 s[30:31], 0x140000
	s_nop 0
	v_addc_co_u32_e32 v55, vcc, 0, v155, vcc
	global_store_dwordx4 v[52:53], v[36:39], off offset:512
	v_pk_mul_f32 v[20:21], v[20:21], v[136:137]
	v_pk_mul_f32 v[50:51], v[50:51], v[134:135]
	v_lshl_add_u64 v[36:37], v[154:155], 0, s[30:31]
	s_mov_b32 s30, 0x140000
	v_add_co_u32_e32 v38, vcc, s30, v154
	s_mov_b64 s[30:31], 0x160000
	s_nop 0
	v_addc_co_u32_e32 v39, vcc, 0, v155, vcc
	global_store_dwordx4 v[36:37], v[20:23], off offset:512
	v_pk_mul_f32 v[48:49], v[48:49], v[132:133]
	v_pk_mul_f32 v[34:35], v[34:35], v[134:135]
	v_lshl_add_u64 v[20:21], v[154:155], 0, s[30:31]
	s_mov_b32 s30, 0x160000
	v_add_co_u32_e32 v22, vcc, s30, v154
	v_pk_mul_f32 v[32:33], v[32:33], v[132:133]
	v_pk_mul_f32 v[18:19], v[18:19], v[134:135]
	v_pk_mul_f32 v[16:17], v[16:17], v[132:133]
	v_addc_co_u32_e32 v23, vcc, 0, v155, vcc
	v_pk_mul_f32 v[126:127], v[126:127], v[142:143]
	v_pk_mul_f32 v[124:125], v[124:125], v[140:141]
	v_pk_mul_f32 v[122:123], v[122:123], v[138:139]
	v_pk_mul_f32 v[120:121], v[120:121], v[136:137]
	v_pk_mul_f32 v[114:115], v[114:115], v[146:147]
	v_pk_mul_f32 v[112:113], v[112:113], v[144:145]
	v_pk_mul_f32 v[110:111], v[110:111], v[142:143]
	v_pk_mul_f32 v[108:109], v[108:109], v[140:141]
	v_pk_mul_f32 v[106:107], v[106:107], v[138:139]
	v_pk_mul_f32 v[104:105], v[104:105], v[136:137]
	v_pk_mul_f32 v[98:99], v[98:99], v[146:147]
	v_pk_mul_f32 v[96:97], v[96:97], v[144:145]
	v_pk_mul_f32 v[94:95], v[94:95], v[142:143]
	v_pk_mul_f32 v[92:93], v[92:93], v[140:141]
	v_pk_mul_f32 v[90:91], v[90:91], v[138:139]
	v_pk_mul_f32 v[88:89], v[88:89], v[136:137]
	v_pk_mul_f32 v[82:83], v[82:83], v[146:147]
	v_pk_mul_f32 v[80:81], v[80:81], v[144:145]
	v_pk_mul_f32 v[78:79], v[78:79], v[142:143]
	v_pk_mul_f32 v[76:77], v[76:77], v[140:141]
	v_pk_mul_f32 v[74:75], v[74:75], v[138:139]
	v_pk_mul_f32 v[72:73], v[72:73], v[136:137]
	v_pk_mul_f32 v[66:67], v[66:67], v[146:147]
	v_pk_mul_f32 v[64:65], v[64:65], v[144:145]
	v_pk_mul_f32 v[62:63], v[62:63], v[142:143]
	v_pk_mul_f32 v[60:61], v[60:61], v[140:141]
	global_store_dwordx4 v[68:69], v[48:51], off offset:576
	v_pk_mul_f32 v[46:47], v[46:47], v[142:143]
	v_pk_mul_f32 v[44:45], v[44:45], v[140:141]
	v_pk_mul_f32 v[50:51], v[58:59], v[146:147]
	v_pk_mul_f32 v[48:49], v[56:57], v[144:145]
	global_store_dwordx4 v[52:53], v[32:35], off offset:576
	v_pk_mul_f32 v[30:31], v[30:31], v[142:143]
	v_pk_mul_f32 v[28:29], v[28:29], v[140:141]
	v_pk_mul_f32 v[34:35], v[42:43], v[146:147]
	v_pk_mul_f32 v[32:33], v[40:41], v[144:145]
	global_store_dwordx4 v[36:37], v[16:19], off offset:576
	v_pk_mul_f32 v[14:15], v[14:15], v[142:143]
	v_pk_mul_f32 v[12:13], v[12:13], v[140:141]
	v_pk_mul_f32 v[18:19], v[26:27], v[146:147]
	v_pk_mul_f32 v[16:17], v[24:25], v[144:145]
	v_pk_mul_f32 v[10:11], v[10:11], v[138:139]
	v_pk_mul_f32 v[8:9], v[8:9], v[136:137]
	v_pk_mul_f32 v[6:7], v[6:7], v[134:135]
	v_pk_mul_f32 v[4:5], v[4:5], v[132:133]
	s_and_b64 vcc, exec, s[34:35]
	s_mov_b32 s30, s29
	s_mov_b32 s31, s15
	global_store_dwordx4 v[154:155], v[128:131], off
	global_store_dwordx4 v[154:155], v[124:127], off offset:64
	global_store_dwordx4 v[154:155], v[120:123], off offset:512
	global_store_dwordx4 v[118:119], v[112:115], off
	global_store_dwordx4 v[116:117], v[108:111], off offset:64
	global_store_dwordx4 v[116:117], v[104:107], off offset:512
	global_store_dwordx4 v[102:103], v[96:99], off
	global_store_dwordx4 v[100:101], v[92:95], off offset:64
	global_store_dwordx4 v[100:101], v[88:91], off offset:512
	global_store_dwordx4 v[86:87], v[80:83], off
	global_store_dwordx4 v[84:85], v[76:79], off offset:64
	global_store_dwordx4 v[84:85], v[72:75], off offset:512
	global_store_dwordx4 v[70:71], v[64:67], off
	global_store_dwordx4 v[68:69], v[60:63], off offset:64
	global_store_dwordx4 v[54:55], v[48:51], off
	global_store_dwordx4 v[52:53], v[44:47], off offset:64
	global_store_dwordx4 v[38:39], v[32:35], off
	global_store_dwordx4 v[36:37], v[28:31], off offset:64
	global_store_dwordx4 v[22:23], v[16:19], off
	global_store_dwordx4 v[20:21], v[12:15], off offset:64
	global_store_dwordx4 v[20:21], v[8:11], off offset:512
	global_store_dwordx4 v[20:21], v[4:7], off offset:576
	s_cbranch_vccz .LBB0_3045
	s_waitcnt vmcnt(0)
	s_cmpk_gt_u32 s4, 0xff
	s_cbranch_scc1 .LBB0_3052
	s_barrier
